# speedup vs baseline: 1.1771x; 1.0143x over previous
.LBB0_13:
	v_lshl_add_u64 v[40:41], v[10:11], 0, s[34:35]
	global_load_dwordx4 v[28:31], v[40:41], off offset:-2048
	global_load_dwordx4 v[32:35], v[40:41], off offset:-1024
	global_load_dwordx4 v[36:39], v[40:41], off
	s_nop 0
	global_load_dwordx4 v[40:43], v[40:41], off offset:1024
	v_add_u32_e32 v96, 0xffffc000, v20
	global_load_dwordx4 v[44:47], v[0:1], off
	v_lshlrev_b64 v[50:51], 12, v[96:97]
	v_lshl_add_u64 v[48:49], v[8:9], 0, s[34:35]
	v_lshl_add_u64 v[50:51], s[8:9], 0, v[50:51]
	v_cmp_gt_i32_e32 vcc, s36, v20
	s_add_u32 s34, s34, s12
	v_add_u32_e32 v20, s10, v20
	v_cndmask_b32_e32 v49, v51, v49, vcc
	v_cndmask_b32_e32 v48, v50, v48, vcc
	v_lshl_add_u64 v[50:51], v[48:49], 0, v[12:13]
	s_addc_u32 s35, s35, s13
	s_waitcnt vmcnt(4)
	v_mov_b32_e32 v54, v29
	s_waitcnt vmcnt(3)
	v_mov_b32_e32 v55, v33
	v_mov_b32_e32 v52, v28
	v_mov_b32_e32 v53, v32
	s_waitcnt vmcnt(2)
	v_mov_b32_e32 v62, v37
	s_waitcnt vmcnt(1)
	v_mov_b32_e32 v63, v41
	v_pk_mul_f32 v[54:55], v[54:55], v[54:55]
	v_mov_b32_e32 v56, v30
	v_mov_b32_e32 v57, v34
	v_mov_b32_e32 v60, v36
	v_mov_b32_e32 v61, v40
	v_pk_mul_f32 v[62:63], v[62:63], v[62:63]
	v_pk_fma_f32 v[52:53], v[52:53], v[52:53], v[54:55]
	v_mov_b32_e32 v58, v31
	v_mov_b32_e32 v59, v35
	v_mov_b32_e32 v64, v38
	v_mov_b32_e32 v65, v42
	v_pk_fma_f32 v[54:55], v[60:61], v[60:61], v[62:63]
	v_pk_fma_f32 v[52:53], v[56:57], v[56:57], v[52:53]
	v_mov_b32_e32 v66, v39
	v_mov_b32_e32 v67, v43
	v_pk_fma_f32 v[54:55], v[64:65], v[64:65], v[54:55]
	v_pk_fma_f32 v[52:53], v[58:59], v[58:59], v[52:53]
	v_pk_fma_f32 v[54:55], v[66:67], v[66:67], v[54:55]
	v_add_f32_e32 v27, v52, v53
	v_add_f32_e32 v27, v27, v54
	v_add_f32_e32 v27, v27, v55
	ds_bpermute_b32 v52, v21, v27
	s_waitcnt lgkmcnt(0)
	v_add_f32_e32 v27, v27, v52
	ds_bpermute_b32 v52, v22, v27
	s_waitcnt lgkmcnt(0)
	v_add_f32_e32 v27, v27, v52
	ds_bpermute_b32 v52, v23, v27
	s_waitcnt lgkmcnt(0)
	v_add_f32_e32 v27, v27, v52
	ds_bpermute_b32 v52, v24, v27
	s_waitcnt lgkmcnt(0)
	v_add_f32_e32 v27, v27, v52
	ds_bpermute_b32 v52, v25, v27
	s_waitcnt lgkmcnt(0)
	v_add_f32_e32 v27, v27, v52
	ds_bpermute_b32 v52, v26, v27
	s_waitcnt lgkmcnt(0)
	v_add_f32_e32 v27, v27, v52
	v_fmamk_f32 v27, v27, 0x3a800000, v145
	v_mul_f32_e32 v52, 0x4b800000, v27
	v_cmp_gt_f32_e32 vcc, s37, v27
	s_nop 1
	v_cndmask_b32_e32 v27, v27, v52, vcc
	v_rsq_f32_e32 v27, v27
	s_nop 0
	v_mul_f32_e32 v52, 0x45800000, v27
	v_cndmask_b32_e32 v52, v27, v52, vcc
	v_pk_mul_f32 v[28:29], v[28:29], v[52:53] op_sel_hi:[1,0]
	v_pk_mul_f32 v[30:31], v[30:31], v[52:53] op_sel_hi:[1,0]
	s_waitcnt vmcnt(0)
	v_pk_mul_f32 v[28:29], v[44:45], v[28:29]
	v_pk_mul_f32 v[30:31], v[46:47], v[30:31]
	s_nop 0
	global_store_dwordx4 v[50:51], v[28:31], off
	global_load_dwordx4 v[28:31], v[2:3], off
	v_pk_mul_f32 v[32:33], v[32:33], v[52:53] op_sel_hi:[1,0]
	v_pk_mul_f32 v[34:35], v[34:35], v[52:53] op_sel_hi:[1,0]
	v_lshl_add_u64 v[44:45], v[48:49], 0, v[14:15]
	v_cmp_lt_i32_e32 vcc, s38, v20
	s_or_b64 s[14:15], vcc, s[14:15]
	s_waitcnt vmcnt(0)
	v_pk_mul_f32 v[28:29], v[28:29], v[32:33]
	v_pk_mul_f32 v[30:31], v[30:31], v[34:35]
	s_nop 0
	global_store_dwordx4 v[44:45], v[28:31], off
	global_load_dwordx4 v[28:31], v[4:5], off
	v_pk_mul_f32 v[34:35], v[36:37], v[52:53] op_sel_hi:[1,0]
	v_pk_mul_f32 v[36:37], v[38:39], v[52:53] op_sel_hi:[1,0]
	v_lshl_add_u64 v[32:33], v[48:49], 0, v[16:17]
	s_waitcnt vmcnt(0)
	v_pk_mul_f32 v[28:29], v[34:35], v[28:29]
	v_pk_mul_f32 v[30:31], v[36:37], v[30:31]
	s_nop 0
	global_store_dwordx4 v[32:33], v[28:31], off
	global_load_dwordx4 v[28:31], v[6:7], off
	v_pk_mul_f32 v[34:35], v[40:41], v[52:53] op_sel_hi:[1,0]
	v_pk_mul_f32 v[36:37], v[42:43], v[52:53] op_sel_hi:[1,0]
	v_lshl_add_u64 v[32:33], v[48:49], 0, v[18:19]
	s_waitcnt vmcnt(0)
	v_pk_mul_f32 v[28:29], v[34:35], v[28:29]
	v_pk_mul_f32 v[30:31], v[36:37], v[30:31]
	s_nop 0
	global_store_dwordx4 v[32:33], v[28:31], off
	s_andn2_b64 exec, exec, s[14:15]
	s_cbranch_execnz .LBB0_13

.LBB0_38:
	v_lshl_add_u64 v[4:5], s[20:21], 0, v[2:3]
	global_load_dword v6, v[4:5], off
	v_add_u32_e32 v1, s6, v1
	v_cmp_lt_i32_e32 vcc, s12, v1
	s_mov_b32 s2, 0x3f2aaaab
	s_or_b64 s[8:9], vcc, s[8:9]
	v_lshl_add_u64 v[4:5], s[4:5], 0, v[2:3]
	v_lshl_add_u64 v[2:3], v[2:3], 0, s[10:11]
	s_waitcnt vmcnt(0)
	v_max_f32_e64 v7, -v6, -v6
	v_mul_f32_e64 v6, |v6|, s7
	v_exp_f32_e32 v20, v6
	v_max_f32_e32 v21, 0, v7
	v_add_f32_e32 v8, 1.0, v20
	v_add_f32_e32 v9, -1.0, v8
	v_frexp_mant_f32_e32 v10, v8
	v_cvt_f64_f32_e32 v[6:7], v8
	v_sub_f32_e32 v11, v9, v8
	v_frexp_exp_i32_f64_e32 v6, v[6:7]
	v_cmp_gt_f32_e32 vcc, s2, v10
	v_sub_f32_e32 v9, v20, v9
	v_add_f32_e32 v7, 1.0, v11
	v_subbrev_co_u32_e32 v6, vcc, 0, v6, vcc
	v_add_f32_e32 v7, v9, v7
	v_sub_u32_e32 v9, 0, v6
	v_ldexp_f32 v8, v8, v9
	v_add_f32_e32 v10, -1.0, v8
	v_add_f32_e32 v11, 1.0, v8
	v_ldexp_f32 v7, v7, v9
	v_add_f32_e32 v9, 1.0, v10
	v_add_f32_e32 v12, -1.0, v11
	v_sub_f32_e32 v9, v8, v9
	v_sub_f32_e32 v8, v8, v12
	v_add_f32_e32 v12, v7, v9
	v_add_f32_e32 v7, v7, v8
	v_add_f32_e32 v14, v11, v7
	v_rcp_f32_e32 v15, v14
	v_add_f32_e32 v9, v10, v12
	v_sub_f32_e32 v10, v9, v10
	v_sub_f32_e32 v8, v14, v11
	v_mul_f32_e32 v17, v9, v15
	v_sub_f32_e32 v16, v12, v10
	v_mul_f32_e32 v10, v14, v17
	v_sub_f32_e32 v7, v7, v8
	v_fma_f32 v12, v17, v14, -v10
	v_fmac_f32_e32 v12, v17, v7
	v_add_f32_e32 v8, v10, v12
	v_sub_f32_e32 v11, v9, v8
	v_mov_b32_e32 v13, v8
	v_pk_add_f32 v[8:9], v[8:9], v[10:11] neg_lo:[0,1] neg_hi:[0,1]
	v_cvt_f32_i32_e32 v6, v6
	v_pk_add_f32 v[8:9], v[8:9], v[12:13] neg_lo:[0,1] neg_hi:[0,1]
	s_mov_b32 s2, 0x3f317218
	v_add_f32_e32 v9, v16, v9
	v_add_f32_e32 v8, v8, v9
	v_add_f32_e32 v9, v11, v8
	v_mul_f32_e32 v13, v15, v9
	v_mul_f32_e32 v10, v14, v13
	v_sub_f32_e32 v11, v11, v9
	v_add_f32_e32 v18, v17, v13
	v_fma_f32 v12, v13, v14, -v10
	v_add_f32_e32 v16, v8, v11
	v_sub_f32_e32 v8, v18, v17
	v_fmac_f32_e32 v12, v13, v7
	v_sub_f32_e32 v7, v13, v8
	v_add_f32_e32 v8, v10, v12
	v_sub_f32_e32 v11, v9, v8
	v_mov_b32_e32 v13, v8
	v_pk_add_f32 v[8:9], v[8:9], v[10:11] neg_lo:[0,1] neg_hi:[0,1]
	v_cmp_neq_f32_e32 vcc, s13, v20
	v_pk_add_f32 v[8:9], v[8:9], v[12:13] neg_lo:[0,1] neg_hi:[0,1]
	s_nop 0
	v_add_f32_e32 v9, v16, v9
	v_add_f32_e32 v8, v8, v9
	v_add_f32_e32 v8, v11, v8
	v_mul_f32_e32 v8, v15, v8
	v_add_f32_e32 v7, v7, v8
	v_add_f32_e32 v8, v18, v7
	v_mul_f32_e32 v10, v8, v8
	v_sub_f32_e32 v11, v8, v18
	v_fmamk_f32 v12, v10, 0x3e9b6dac, v151
	v_sub_f32_e32 v11, v7, v11
	v_mul_f32_e32 v7, v8, v10
	v_fmaak_f32 v99, v10, v12, 0x3f2aaada
	v_ldexp_f32 v13, v11, 1
	v_pk_mul_f32 v[10:11], v[6:7], v[98:99]
	v_ldexp_f32 v9, v8, 1
	v_fma_f32 v8, v6, s2, -v10
	v_fmac_f32_e32 v8, 0xb102e308, v6
	v_pk_add_f32 v[6:7], v[10:11], v[8:9]
	v_mov_b32_e32 v12, v10
	v_sub_f32_e32 v16, v7, v9
	v_pk_add_f32 v[14:15], v[6:7], v[10:11] neg_lo:[0,1] neg_hi:[0,1]
	v_sub_f32_e32 v10, v11, v16
	v_add_f32_e32 v13, v13, v10
	v_pk_add_f32 v[10:11], v[6:7], v[12:13]
	v_mov_b32_e32 v9, v6
	v_mov_b32_e32 v15, v11
	v_pk_add_f32 v[18:19], v[8:9], v[14:15] neg_lo:[0,1] neg_hi:[0,1]
	v_pk_add_f32 v[8:9], v[8:9], v[14:15]
	v_mov_b32_e32 v17, v6
	v_pk_add_f32 v[14:15], v[8:9], v[6:7] op_sel:[1,0] op_sel_hi:[0,1] neg_lo:[0,1] neg_hi:[0,1]
	v_mov_b32_e32 v16, v13
	v_mov_b32_e32 v12, v11
	v_mov_b32_e32 v13, v9
	v_pk_mov_b32 v[6:7], v[6:7], v[14:15] op_sel:[1,0]
	v_pk_add_f32 v[10:11], v[10:11], v[14:15] op_sel_hi:[1,0] neg_lo:[0,1] neg_hi:[0,1]
	v_pk_add_f32 v[6:7], v[12:13], v[6:7] neg_lo:[0,1] neg_hi:[0,1]
	v_mov_b32_e32 v10, v18
	v_pk_add_f32 v[6:7], v[16:17], v[6:7] neg_lo:[0,1] neg_hi:[0,1]
	v_mov_b32_e32 v19, v9
	v_pk_add_f32 v[10:11], v[10:11], v[6:7]
	s_mov_b32 s2, 0x33800000
	v_pk_add_f32 v[12:13], v[10:11], v[10:11] op_sel:[0,1] op_sel_hi:[1,0]
	s_nop 0
	v_pk_add_f32 v[8:9], v[8:9], v[12:13] op_sel:[1,0] op_sel_hi:[0,1]
	s_nop 0
	v_mov_b32_e32 v11, v8
	v_mov_b32_e32 v7, v12
	v_pk_add_f32 v[12:13], v[10:11], v[18:19] neg_lo:[0,1] neg_hi:[0,1]
	s_nop 0
	v_sub_f32_e32 v9, v10, v12
	v_pk_add_f32 v[6:7], v[6:7], v[12:13] neg_lo:[0,1] neg_hi:[0,1]
	v_sub_f32_e32 v9, v18, v9
	v_add_f32_e32 v6, v6, v9
	v_add_f32_e32 v6, v6, v7
	v_add_f32_e32 v6, v8, v6
	v_cndmask_b32_e32 v6, v170, v6, vcc
	v_cmp_ngt_f32_e32 vcc, -1.0, v20
	s_nop 1
	v_cndmask_b32_e32 v6, v174, v6, vcc
	v_cmp_neq_f32_e32 vcc, -1.0, v20
	s_nop 1
	v_cndmask_b32_e32 v6, v175, v6, vcc
	v_cmp_lt_f32_e64 vcc, |v20|, s2
	s_nop 1
	v_cndmask_b32_e32 v6, v6, v20, vcc
	v_add_f32_e32 v6, v21, v6
	v_mul_f32_e32 v6, 0xc1000000, v6
	global_store_dword v[4:5], v6, off
	s_andn2_b64 exec, exec, s[8:9]
	s_cbranch_execnz .LBB0_38
	s_or_b64 exec, exec, s[8:9]
	v_mov_b32_e32 v1, s6

.LBB0_86:
	s_add_i32 s35, s11, 1
	s_bitcmp1_b32 s35, 0
	s_cselect_b32 s37, 0x9000, 0
	v_add_u32_e32 v110, s37, v81
	v_lshl_add_u64 v[106:107], v[94:95], 0, s[12:13]
	s_mov_b64 s[38:39], 0x6181080
	v_readfirstlane_b32 s37, v110
	v_add_u32_e32 v111, 0x1000, v110
	v_lshl_add_u64 v[108:109], v[106:107], 0, s[38:39]
	s_mov_b32 m0, s37
	s_mov_b64 s[38:39], 0x61e5080
	v_readfirstlane_b32 s37, v111
	v_add_u32_e32 v111, 0x2000, v110
	global_load_lds_dwordx4 v[108:109], off
	v_lshl_add_u64 v[108:109], v[106:107], 0, s[38:39]
	s_mov_b32 m0, s37
	s_mov_b64 s[38:39], 0x6249080
	v_readfirstlane_b32 s37, v111
	v_add_u32_e32 v111, 0x3000, v110
	global_load_lds_dwordx4 v[108:109], off
	v_lshl_add_u64 v[108:109], v[106:107], 0, s[38:39]
	s_mov_b32 m0, s37
	s_mov_b64 s[38:39], 0x62ad080
	v_readfirstlane_b32 s37, v111
	global_load_lds_dwordx4 v[108:109], off
	v_lshl_add_u64 v[108:109], v[106:107], 0, s[38:39]
	s_mov_b32 m0, s37
	s_mov_b64 s[38:39], 0x6311080
	global_load_lds_dwordx4 v[108:109], off
	v_add_u32_e32 v108, 0x4000, v110
	v_lshl_add_u64 v[106:107], v[106:107], 0, s[38:39]
	v_readfirstlane_b32 s37, v108
	s_mov_b32 m0, s37
	v_add_u32_e32 v111, 0x5000, v110
	global_load_lds_dwordx4 v[106:107], off
	v_lshl_add_u64 v[106:107], v[100:101], 0, s[12:13]
	s_mov_b64 s[38:39], 0x14531080
	v_readfirstlane_b32 s37, v111
	v_add_u32_e32 v111, 0x6000, v110
	v_lshl_add_u64 v[108:109], v[106:107], 0, s[38:39]
	s_mov_b32 m0, s37
	s_mov_b64 s[38:39], 0x14541080
	v_readfirstlane_b32 s37, v111
	v_add_u32_e32 v111, 0x7000, v110
	global_load_lds_dwordx4 v[108:109], off
	v_lshl_add_u64 v[108:109], v[106:107], 0, s[38:39]
	s_mov_b32 m0, s37
	s_mov_b64 s[38:39], 0x14551080
	v_readfirstlane_b32 s37, v111
	global_load_lds_dwordx4 v[108:109], off
	v_lshl_add_u64 v[108:109], v[106:107], 0, s[38:39]
	s_mov_b32 m0, s37
	s_mov_b64 s[38:39], 0x14561080
	global_load_lds_dwordx4 v[108:109], off
	v_add_u32_e32 v108, 0x8000, v110
	v_lshl_add_u64 v[106:107], v[106:107], 0, s[38:39]
	v_readfirstlane_b32 s37, v108
	s_mov_b32 m0, s37
	s_bitcmp1_b32 s11, 0
	global_load_lds_dwordx4 v[106:107], off
	s_cselect_b32 s11, 0x9000, 0
	s_add_i32 s11, s11, 0
	v_add_u32_e32 v114, s11, v116
	v_add_u32_e32 v115, v114, v117
	ds_read_b128 v[106:109], v115
	ds_read_b128 v[110:113], v115 offset:2048
	ds_read_b128 v[122:125], v115 offset:4096
	ds_read_b128 v[156:159], v115 offset:6144
	v_add_u32_e32 v114, v114, v118
	ds_read_b128 v[166:169], v115 offset:8192
	ds_read_b128 v[178:181], v114 offset:20480
	ds_read_b128 v[182:185], v114 offset:22528
	ds_read_b128 v[186:189], v114 offset:24576
	ds_read_b128 v[190:193], v114 offset:26624
	v_add_u32_e32 v210, s11, v119
	v_add_u32_e32 v211, v210, v117
	ds_read_b128 v[212:215], v211
	ds_read_b128 v[216:219], v211 offset:2048
	ds_read_b128 v[220:223], v211 offset:4096
	ds_read_b128 v[224:227], v211 offset:6144
	v_add_u32_e32 v228, v210, v118
	ds_read_b128 v[230:233], v211 offset:8192
	ds_read_b128 v[234:237], v228 offset:20480
	ds_read_b128 v[238:241], v228 offset:22528
	ds_read_b128 v[242:245], v228 offset:24576
	ds_read_b128 v[246:249], v228 offset:26624
	s_setprio 1
	s_waitcnt lgkmcnt(9)
	v_mfma_f32_16x16x32_bf16 v[76:79], v[178:181], v[106:109], v[76:79]
	v_mfma_f32_16x16x32_bf16 v[72:75], v[182:185], v[106:109], v[72:75]
	v_mfma_f32_16x16x32_bf16 v[68:71], v[186:189], v[106:109], v[68:71]
	v_mfma_f32_16x16x32_bf16 v[64:67], v[190:193], v[106:109], v[64:67]
	v_mfma_f32_16x16x32_bf16 v[60:63], v[178:181], v[110:113], v[60:63]
	v_mfma_f32_16x16x32_bf16 v[56:59], v[182:185], v[110:113], v[56:59]
	v_mfma_f32_16x16x32_bf16 v[52:55], v[186:189], v[110:113], v[52:55]
	v_mfma_f32_16x16x32_bf16 v[48:51], v[190:193], v[110:113], v[48:51]
	v_mfma_f32_16x16x32_bf16 v[44:47], v[178:181], v[122:125], v[44:47]
	v_mfma_f32_16x16x32_bf16 v[40:43], v[182:185], v[122:125], v[40:43]
	v_mfma_f32_16x16x32_bf16 v[36:39], v[186:189], v[122:125], v[36:39]
	v_mfma_f32_16x16x32_bf16 v[32:35], v[190:193], v[122:125], v[32:35]
	v_mfma_f32_16x16x32_bf16 v[28:31], v[178:181], v[156:159], v[28:31]
	v_mfma_f32_16x16x32_bf16 v[24:27], v[182:185], v[156:159], v[24:27]
	v_mfma_f32_16x16x32_bf16 v[20:23], v[186:189], v[156:159], v[20:23]
	v_mfma_f32_16x16x32_bf16 v[16:19], v[190:193], v[156:159], v[16:19]
	v_mfma_f32_16x16x32_bf16 v[12:15], v[178:181], v[166:169], v[12:15]
	v_mfma_f32_16x16x32_bf16 v[8:11], v[182:185], v[166:169], v[8:11]
	v_mfma_f32_16x16x32_bf16 v[4:7], v[186:189], v[166:169], v[4:7]
	v_mfma_f32_16x16x32_bf16 v[0:3], v[190:193], v[166:169], v[0:3]
	s_setprio 0
	s_setprio 1
	s_waitcnt lgkmcnt(0)
	v_mfma_f32_16x16x32_bf16 v[76:79], v[234:237], v[212:215], v[76:79]
	v_mfma_f32_16x16x32_bf16 v[72:75], v[238:241], v[212:215], v[72:75]
	v_mfma_f32_16x16x32_bf16 v[68:71], v[242:245], v[212:215], v[68:71]
	v_mfma_f32_16x16x32_bf16 v[64:67], v[246:249], v[212:215], v[64:67]
	v_mfma_f32_16x16x32_bf16 v[60:63], v[234:237], v[216:219], v[60:63]
	v_mfma_f32_16x16x32_bf16 v[56:59], v[238:241], v[216:219], v[56:59]
	v_mfma_f32_16x16x32_bf16 v[52:55], v[242:245], v[216:219], v[52:55]
	v_mfma_f32_16x16x32_bf16 v[48:51], v[246:249], v[216:219], v[48:51]
	v_mfma_f32_16x16x32_bf16 v[44:47], v[234:237], v[220:223], v[44:47]
	v_mfma_f32_16x16x32_bf16 v[40:43], v[238:241], v[220:223], v[40:43]
	v_mfma_f32_16x16x32_bf16 v[36:39], v[242:245], v[220:223], v[36:39]
	v_mfma_f32_16x16x32_bf16 v[32:35], v[246:249], v[220:223], v[32:35]
	v_mfma_f32_16x16x32_bf16 v[28:31], v[234:237], v[224:227], v[28:31]
	v_mfma_f32_16x16x32_bf16 v[24:27], v[238:241], v[224:227], v[24:27]
	v_mfma_f32_16x16x32_bf16 v[20:23], v[242:245], v[224:227], v[20:23]
	v_mfma_f32_16x16x32_bf16 v[16:19], v[246:249], v[224:227], v[16:19]
	v_mfma_f32_16x16x32_bf16 v[12:15], v[234:237], v[230:233], v[12:15]
	v_mfma_f32_16x16x32_bf16 v[8:11], v[238:241], v[230:233], v[8:11]
	v_mfma_f32_16x16x32_bf16 v[4:7], v[242:245], v[230:233], v[4:7]
	v_mfma_f32_16x16x32_bf16 v[0:3], v[246:249], v[230:233], v[0:3]
	s_setprio 0
	s_waitcnt vmcnt(0)
	s_add_u32 s12, s12, 0x80
	s_addc_u32 s13, s13, 0
	s_cmpk_lg_i32 s12, 0x780
	s_mov_b32 s11, s35
	s_waitcnt vmcnt(0)
	s_barrier
	s_cbranch_scc1 .LBB0_86
	v_add_u32_e32 v122, v120, v118
	v_add_u32_e32 v123, v120, v117
	ds_read_b128 v[106:109], v122 offset:63488
	ds_read_b128 v[110:113], v122 offset:61440
	ds_read_b128 v[156:159], v122 offset:59392
	ds_read_b128 v[166:169], v122 offset:57344
	ds_read_b128 v[178:181], v123 offset:45056
	ds_read_b128 v[182:185], v123 offset:43008
	ds_read_b128 v[186:189], v123 offset:40960
	ds_read_b128 v[190:193], v123 offset:38912
	ds_read_b128 v[194:197], v123 offset:36864
	s_setprio 1
	s_waitcnt lgkmcnt(0)
	v_mfma_f32_16x16x32_bf16 v[76:79], v[166:169], v[194:197], v[76:79]
	v_mfma_f32_16x16x32_bf16 v[72:75], v[156:159], v[194:197], v[72:75]
	v_mfma_f32_16x16x32_bf16 v[68:71], v[110:113], v[194:197], v[68:71]
	v_mfma_f32_16x16x32_bf16 v[64:67], v[106:109], v[194:197], v[64:67]
	v_mfma_f32_16x16x32_bf16 v[60:63], v[166:169], v[190:193], v[60:63]
	v_mfma_f32_16x16x32_bf16 v[56:59], v[156:159], v[190:193], v[56:59]
	v_mfma_f32_16x16x32_bf16 v[52:55], v[110:113], v[190:193], v[52:55]
	v_mfma_f32_16x16x32_bf16 v[48:51], v[106:109], v[190:193], v[48:51]
	v_mfma_f32_16x16x32_bf16 v[44:47], v[166:169], v[186:189], v[44:47]
	v_mfma_f32_16x16x32_bf16 v[40:43], v[156:159], v[186:189], v[40:43]
	v_mfma_f32_16x16x32_bf16 v[36:39], v[110:113], v[186:189], v[36:39]
	v_mfma_f32_16x16x32_bf16 v[32:35], v[106:109], v[186:189], v[32:35]
	v_mfma_f32_16x16x32_bf16 v[28:31], v[166:169], v[182:185], v[28:31]
	v_mfma_f32_16x16x32_bf16 v[24:27], v[156:159], v[182:185], v[24:27]
	v_mfma_f32_16x16x32_bf16 v[20:23], v[110:113], v[182:185], v[20:23]
	v_mfma_f32_16x16x32_bf16 v[16:19], v[106:109], v[182:185], v[16:19]
	v_mfma_f32_16x16x32_bf16 v[12:15], v[166:169], v[178:181], v[12:15]
	v_mfma_f32_16x16x32_bf16 v[8:11], v[156:159], v[178:181], v[8:11]
	v_mfma_f32_16x16x32_bf16 v[4:7], v[110:113], v[178:181], v[4:7]
	v_mfma_f32_16x16x32_bf16 v[0:3], v[106:109], v[178:181], v[0:3]
	s_setprio 0
	v_add_u32_e32 v124, v121, v117
	ds_read_b128 v[106:109], v124 offset:36864
	ds_read_b128 v[110:113], v124 offset:38912
	ds_read_b128 v[156:159], v124 offset:40960
	ds_read_b128 v[166:169], v124 offset:43008
	v_add_u32_e32 v125, v121, v118
	ds_read_b128 v[178:181], v124 offset:45056
	ds_read_b128 v[182:185], v125 offset:57344
	ds_read_b128 v[186:189], v125 offset:59392
	ds_read_b128 v[190:193], v125 offset:61440
	ds_read_b128 v[194:197], v125 offset:63488
	s_setprio 1
	s_waitcnt lgkmcnt(1)
	v_mfma_f32_16x16x32_bf16 v[68:71], v[190:193], v[106:109], v[68:71]
	s_waitcnt lgkmcnt(0)
	v_mfma_f32_16x16x32_bf16 v[64:67], v[194:197], v[106:109], v[64:67]
	v_mfma_f32_16x16x32_bf16 v[60:63], v[182:185], v[110:113], v[60:63]
	v_mfma_f32_16x16x32_bf16 v[56:59], v[186:189], v[110:113], v[56:59]
	v_mfma_f32_16x16x32_bf16 v[52:55], v[190:193], v[110:113], v[52:55]
	v_mfma_f32_16x16x32_bf16 v[48:51], v[194:197], v[110:113], v[48:51]
	v_mfma_f32_16x16x32_bf16 v[44:47], v[182:185], v[156:159], v[44:47]
	v_mfma_f32_16x16x32_bf16 v[40:43], v[186:189], v[156:159], v[40:43]
	v_mfma_f32_16x16x32_bf16 v[36:39], v[190:193], v[156:159], v[36:39]
	v_mfma_f32_16x16x32_bf16 v[32:35], v[194:197], v[156:159], v[32:35]
	v_mfma_f32_16x16x32_bf16 v[28:31], v[182:185], v[166:169], v[28:31]
	v_mfma_f32_16x16x32_bf16 v[24:27], v[186:189], v[166:169], v[24:27]
	v_mfma_f32_16x16x32_bf16 v[20:23], v[190:193], v[166:169], v[20:23]
	v_mfma_f32_16x16x32_bf16 v[16:19], v[194:197], v[166:169], v[16:19]
	v_mfma_f32_16x16x32_bf16 v[12:15], v[182:185], v[178:181], v[12:15]
	v_mfma_f32_16x16x32_bf16 v[8:11], v[186:189], v[178:181], v[8:11]
	v_mfma_f32_16x16x32_bf16 v[4:7], v[190:193], v[178:181], v[4:7]
	v_mfma_f32_16x16x32_bf16 v[0:3], v[194:197], v[178:181], v[0:3]
	v_mfma_f32_16x16x32_bf16 v[198:201], v[182:185], v[106:109], v[76:79]
	v_mfma_f32_16x16x32_bf16 v[206:209], v[186:189], v[106:109], v[72:75]
	s_setprio 0
	s_nop 1
	v_mov_b32_e32 v72, v97
	s_waitcnt vmcnt(0)
	s_barrier
	s_mul_i32 s12, s36, 0xa0
	v_add_u32_e32 v72, v72, v176
	v_ashrrev_i32_e32 v73, 7, v72
	v_and_b32_e32 v74, 64, v72
	v_lshrrev_b32_e32 v75, 2, v72
	v_and_or_b32 v72, v72, 15, s12
	s_movk_i32 s11, 0x50
	s_mov_b32 s35, 0
	v_and_b32_e32 v75, 12, v75
	v_mad_u64_u32 v[72:73], s[36:37], v73, s11, v[72:73]
	s_lshl_b32 s13, s10, 7
	v_or3_b32 v112, v74, v75, s13
	v_mov_b64_e32 v[74:75], s[0:1]
	s_movk_i32 s36, 0x3200
	v_ashrrev_i32_e32 v73, 31, v72
	v_mad_i64_i32 v[76:77], s[10:11], v72, s36, v[74:75]
	s_mov_b64 s[38:39], 0x1800
	v_lshl_add_u64 v[114:115], v[76:77], 0, s[38:39]
	v_lshlrev_b64 v[76:77], 12, v[72:73]
	v_ashrrev_i32_e32 v113, 31, v112
	v_lshl_add_u64 v[106:107], s[4:5], 0, v[76:77]
	v_lshlrev_b64 v[76:77], 1, v[112:113]
	v_lshl_add_u64 v[108:109], v[114:115], 0, v[76:77]
	global_load_dwordx2 v[108:109], v[108:109], off
	v_lshlrev_b64 v[78:79], 2, v[112:113]
	v_lshl_add_u64 v[110:111], v[106:107], 0, v[78:79]
	s_waitcnt vmcnt(0)
	v_and_b32_e32 v107, 0xffff0000, v108
	v_lshlrev_b32_e32 v106, 16, v108
	v_and_b32_e32 v157, 0xffff0000, v109
	v_lshlrev_b32_e32 v156, 16, v109
	v_pk_mul_f32 v[106:107], v[198:199], v[106:107]
	v_pk_mul_f32 v[108:109], v[200:201], v[156:157]
	s_nop 0
	global_store_dwordx4 v[110:111], v[106:109], off
	s_nop 1
	v_or_b32_e32 v106, 16, v112
	v_ashrrev_i32_e32 v107, 31, v106
	v_lshlrev_b64 v[106:107], 1, v[106:107]
	v_lshl_add_u64 v[108:109], v[114:115], 0, v[106:107]
	global_load_dwordx2 v[108:109], v[108:109], off
	s_waitcnt vmcnt(0)
	v_and_b32_e32 v157, 0xffff0000, v108
	v_lshlrev_b32_e32 v156, 16, v108
	v_or_b32_e32 v108, 32, v112
	v_and_b32_e32 v159, 0xffff0000, v109
	v_lshlrev_b32_e32 v158, 16, v109
	v_ashrrev_i32_e32 v109, 31, v108
	v_pk_mul_f32 v[156:157], v[206:207], v[156:157]
	v_pk_mul_f32 v[158:159], v[208:209], v[158:159]
	v_lshlrev_b64 v[108:109], 1, v[108:109]
	global_store_dwordx4 v[110:111], v[156:159], off offset:64
	s_nop 1
	v_lshl_add_u64 v[156:157], v[114:115], 0, v[108:109]
	global_load_dwordx2 v[156:157], v[156:157], off
	s_waitcnt vmcnt(0)
	v_and_b32_e32 v159, 0xffff0000, v156
	v_lshlrev_b32_e32 v158, 16, v156
	v_pk_mul_f32 v[68:69], v[68:69], v[158:159]
	v_and_b32_e32 v159, 0xffff0000, v157
	v_lshlrev_b32_e32 v158, 16, v157
	v_pk_mul_f32 v[70:71], v[70:71], v[158:159]
	s_nop 0
	global_store_dwordx4 v[110:111], v[68:71], off offset:128
	s_nop 1
	v_or_b32_e32 v68, 48, v112
	v_ashrrev_i32_e32 v69, 31, v68
	v_lshlrev_b64 v[68:69], 1, v[68:69]
	v_lshl_add_u64 v[70:71], v[114:115], 0, v[68:69]
	global_load_dwordx2 v[70:71], v[70:71], off
	s_waitcnt vmcnt(0)
	v_and_b32_e32 v113, 0xffff0000, v70
	v_lshlrev_b32_e32 v112, 16, v70
	v_pk_mul_f32 v[64:65], v[64:65], v[112:113]
	v_and_b32_e32 v113, 0xffff0000, v71
	v_lshlrev_b32_e32 v112, 16, v71
	v_pk_mul_f32 v[66:67], v[66:67], v[112:113]
	s_nop 0
	global_store_dwordx4 v[110:111], v[64:67], off offset:192
	s_nop 1
	v_add_u32_e32 v64, 16, v72
	v_mad_i64_i32 v[66:67], s[10:11], v64, s36, v[74:75]
	v_lshl_add_u64 v[66:67], v[66:67], 0, s[38:39]
	v_lshl_add_u64 v[70:71], v[66:67], 0, v[76:77]
	global_load_dwordx2 v[70:71], v[70:71], off
	v_ashrrev_i32_e32 v65, 31, v64
	v_lshlrev_b64 v[64:65], 12, v[64:65]
	v_lshl_add_u64 v[64:65], s[4:5], 0, v[64:65]
	v_lshl_add_u64 v[64:65], v[64:65], 0, v[78:79]
	s_waitcnt vmcnt(0)
	v_and_b32_e32 v111, 0xffff0000, v70
	v_lshlrev_b32_e32 v110, 16, v70
	v_pk_mul_f32 v[60:61], v[60:61], v[110:111]
	v_and_b32_e32 v111, 0xffff0000, v71
	v_lshlrev_b32_e32 v110, 16, v71
	v_pk_mul_f32 v[62:63], v[62:63], v[110:111]
	s_nop 0
	global_store_dwordx4 v[64:65], v[60:63], off
	s_nop 1
	v_lshl_add_u64 v[60:61], v[66:67], 0, v[106:107]
	global_load_dwordx2 v[60:61], v[60:61], off
	s_waitcnt vmcnt(0)
	v_and_b32_e32 v63, 0xffff0000, v60
	v_lshlrev_b32_e32 v62, 16, v60
	v_pk_mul_f32 v[56:57], v[56:57], v[62:63]
	v_and_b32_e32 v63, 0xffff0000, v61
	v_lshlrev_b32_e32 v62, 16, v61
	v_pk_mul_f32 v[58:59], v[58:59], v[62:63]
	s_nop 0
	global_store_dwordx4 v[64:65], v[56:59], off offset:64
	s_nop 1
	v_lshl_add_u64 v[56:57], v[66:67], 0, v[108:109]
	global_load_dwordx2 v[56:57], v[56:57], off
	s_waitcnt vmcnt(0)
	v_and_b32_e32 v59, 0xffff0000, v56
	v_lshlrev_b32_e32 v58, 16, v56
	v_pk_mul_f32 v[52:53], v[52:53], v[58:59]
	v_and_b32_e32 v59, 0xffff0000, v57
	v_lshlrev_b32_e32 v58, 16, v57
	v_pk_mul_f32 v[54:55], v[54:55], v[58:59]
	s_nop 0
	global_store_dwordx4 v[64:65], v[52:55], off offset:128
	s_nop 1
	v_lshl_add_u64 v[52:53], v[66:67], 0, v[68:69]
	global_load_dwordx2 v[52:53], v[52:53], off
	s_waitcnt vmcnt(0)
	v_and_b32_e32 v55, 0xffff0000, v52
	v_lshlrev_b32_e32 v54, 16, v52
	v_pk_mul_f32 v[48:49], v[48:49], v[54:55]
	v_and_b32_e32 v55, 0xffff0000, v53
	v_lshlrev_b32_e32 v54, 16, v53
	v_pk_mul_f32 v[50:51], v[50:51], v[54:55]
	s_nop 0
	global_store_dwordx4 v[64:65], v[48:51], off offset:192
	s_nop 1
	v_add_u32_e32 v48, 32, v72
	v_mad_i64_i32 v[50:51], s[10:11], v48, s36, v[74:75]
	v_lshl_add_u64 v[50:51], v[50:51], 0, s[38:39]
	v_lshl_add_u64 v[52:53], v[50:51], 0, v[76:77]
	global_load_dwordx2 v[52:53], v[52:53], off
	v_ashrrev_i32_e32 v49, 31, v48
	v_lshlrev_b64 v[48:49], 12, v[48:49]
	v_lshl_add_u64 v[48:49], s[4:5], 0, v[48:49]
	v_lshl_add_u64 v[48:49], v[48:49], 0, v[78:79]
	s_waitcnt vmcnt(0)
	v_and_b32_e32 v55, 0xffff0000, v52
	v_lshlrev_b32_e32 v54, 16, v52
	v_pk_mul_f32 v[44:45], v[44:45], v[54:55]
	v_and_b32_e32 v55, 0xffff0000, v53
	v_lshlrev_b32_e32 v54, 16, v53
	v_pk_mul_f32 v[46:47], v[46:47], v[54:55]
	s_nop 0
	global_store_dwordx4 v[48:49], v[44:47], off
	s_nop 1
	v_lshl_add_u64 v[44:45], v[50:51], 0, v[106:107]
	global_load_dwordx2 v[44:45], v[44:45], off
	s_waitcnt vmcnt(0)
	v_and_b32_e32 v47, 0xffff0000, v44
	v_lshlrev_b32_e32 v46, 16, v44
	v_pk_mul_f32 v[40:41], v[40:41], v[46:47]
	v_and_b32_e32 v47, 0xffff0000, v45
	v_lshlrev_b32_e32 v46, 16, v45
	v_pk_mul_f32 v[42:43], v[42:43], v[46:47]
	s_nop 0
	global_store_dwordx4 v[48:49], v[40:43], off offset:64
	s_nop 1
	v_lshl_add_u64 v[40:41], v[50:51], 0, v[108:109]
	global_load_dwordx2 v[40:41], v[40:41], off
	s_waitcnt vmcnt(0)
	v_and_b32_e32 v43, 0xffff0000, v40
	v_lshlrev_b32_e32 v42, 16, v40
	v_pk_mul_f32 v[36:37], v[36:37], v[42:43]
	v_and_b32_e32 v43, 0xffff0000, v41
	v_lshlrev_b32_e32 v42, 16, v41
	v_pk_mul_f32 v[38:39], v[38:39], v[42:43]
	s_nop 0
	global_store_dwordx4 v[48:49], v[36:39], off offset:128
	s_nop 1
	v_lshl_add_u64 v[36:37], v[50:51], 0, v[68:69]
	global_load_dwordx2 v[36:37], v[36:37], off
	s_waitcnt vmcnt(0)
	v_and_b32_e32 v39, 0xffff0000, v36
	v_lshlrev_b32_e32 v38, 16, v36
	v_pk_mul_f32 v[32:33], v[32:33], v[38:39]
	v_and_b32_e32 v39, 0xffff0000, v37
	v_lshlrev_b32_e32 v38, 16, v37
	v_pk_mul_f32 v[34:35], v[34:35], v[38:39]
	s_nop 0
	global_store_dwordx4 v[48:49], v[32:35], off offset:192
	s_nop 1
	v_add_u32_e32 v32, 48, v72
	v_mad_i64_i32 v[34:35], s[10:11], v32, s36, v[74:75]
	v_lshl_add_u64 v[34:35], v[34:35], 0, s[38:39]
	v_lshl_add_u64 v[36:37], v[34:35], 0, v[76:77]
	global_load_dwordx2 v[36:37], v[36:37], off
	v_ashrrev_i32_e32 v33, 31, v32
	v_lshlrev_b64 v[32:33], 12, v[32:33]
	v_lshl_add_u64 v[32:33], s[4:5], 0, v[32:33]
	v_lshl_add_u64 v[32:33], v[32:33], 0, v[78:79]
	s_waitcnt vmcnt(0)
	v_and_b32_e32 v39, 0xffff0000, v36
	v_lshlrev_b32_e32 v38, 16, v36
	v_pk_mul_f32 v[28:29], v[28:29], v[38:39]
	v_and_b32_e32 v39, 0xffff0000, v37
	v_lshlrev_b32_e32 v38, 16, v37
	v_pk_mul_f32 v[30:31], v[30:31], v[38:39]
	s_nop 0
	global_store_dwordx4 v[32:33], v[28:31], off
	s_nop 1
	v_lshl_add_u64 v[28:29], v[34:35], 0, v[106:107]
	global_load_dwordx2 v[28:29], v[28:29], off
	s_waitcnt vmcnt(0)
	v_and_b32_e32 v31, 0xffff0000, v28
	v_lshlrev_b32_e32 v30, 16, v28
	v_pk_mul_f32 v[24:25], v[24:25], v[30:31]
	v_and_b32_e32 v31, 0xffff0000, v29
	v_lshlrev_b32_e32 v30, 16, v29
	v_pk_mul_f32 v[26:27], v[26:27], v[30:31]
	s_nop 0
	global_store_dwordx4 v[32:33], v[24:27], off offset:64
	s_nop 1
	v_lshl_add_u64 v[24:25], v[34:35], 0, v[108:109]
	global_load_dwordx2 v[24:25], v[24:25], off
	s_waitcnt vmcnt(0)
	v_and_b32_e32 v27, 0xffff0000, v24
	v_lshlrev_b32_e32 v26, 16, v24
	v_pk_mul_f32 v[20:21], v[20:21], v[26:27]
	v_and_b32_e32 v27, 0xffff0000, v25
	v_lshlrev_b32_e32 v26, 16, v25
	v_pk_mul_f32 v[22:23], v[22:23], v[26:27]
	s_nop 0
	global_store_dwordx4 v[32:33], v[20:23], off offset:128
	s_nop 1
	v_lshl_add_u64 v[20:21], v[34:35], 0, v[68:69]
	global_load_dwordx2 v[20:21], v[20:21], off
	s_waitcnt vmcnt(0)
	v_and_b32_e32 v23, 0xffff0000, v20
	v_lshlrev_b32_e32 v22, 16, v20
	v_pk_mul_f32 v[16:17], v[16:17], v[22:23]
	v_and_b32_e32 v23, 0xffff0000, v21
	v_lshlrev_b32_e32 v22, 16, v21
	v_pk_mul_f32 v[18:19], v[18:19], v[22:23]
	s_nop 0
	global_store_dwordx4 v[32:33], v[16:19], off offset:192
	s_nop 1
	v_add_u32_e32 v16, 64, v72
	v_mad_i64_i32 v[18:19], s[10:11], v16, s36, v[74:75]
	v_lshl_add_u64 v[18:19], v[18:19], 0, s[38:39]
	v_lshl_add_u64 v[20:21], v[18:19], 0, v[76:77]
	global_load_dwordx2 v[20:21], v[20:21], off
	v_ashrrev_i32_e32 v17, 31, v16
	v_lshlrev_b64 v[16:17], 12, v[16:17]
	v_lshl_add_u64 v[16:17], s[4:5], 0, v[16:17]
	v_lshl_add_u64 v[16:17], v[16:17], 0, v[78:79]
	s_mov_b64 s[10:11], 0x800
	s_waitcnt vmcnt(0)
	v_and_b32_e32 v23, 0xffff0000, v20
	v_lshlrev_b32_e32 v22, 16, v20
	v_pk_mul_f32 v[12:13], v[12:13], v[22:23]
	v_and_b32_e32 v23, 0xffff0000, v21
	v_lshlrev_b32_e32 v22, 16, v21
	v_pk_mul_f32 v[14:15], v[14:15], v[22:23]
	s_nop 0
	global_store_dwordx4 v[16:17], v[12:15], off
	s_nop 1
	v_lshl_add_u64 v[12:13], v[18:19], 0, v[106:107]
	global_load_dwordx2 v[12:13], v[12:13], off
	s_waitcnt vmcnt(0)
	v_and_b32_e32 v15, 0xffff0000, v12
	v_lshlrev_b32_e32 v14, 16, v12
	v_pk_mul_f32 v[8:9], v[8:9], v[14:15]
	v_and_b32_e32 v15, 0xffff0000, v13
	v_lshlrev_b32_e32 v14, 16, v13
	v_pk_mul_f32 v[10:11], v[10:11], v[14:15]
	s_nop 0
	global_store_dwordx4 v[16:17], v[8:11], off offset:64
	s_nop 1
	v_lshl_add_u64 v[8:9], v[18:19], 0, v[108:109]
	global_load_dwordx2 v[8:9], v[8:9], off
	s_waitcnt vmcnt(0)
	v_and_b32_e32 v11, 0xffff0000, v8
	v_lshlrev_b32_e32 v10, 16, v8
	v_pk_mul_f32 v[4:5], v[4:5], v[10:11]
	v_and_b32_e32 v11, 0xffff0000, v9
	v_lshlrev_b32_e32 v10, 16, v9
	v_pk_mul_f32 v[6:7], v[6:7], v[10:11]
	s_nop 0
	global_store_dwordx4 v[16:17], v[4:7], off offset:128
	s_nop 1
	v_lshl_add_u64 v[4:5], v[18:19], 0, v[68:69]
	global_load_dwordx2 v[4:5], v[4:5], off
	s_waitcnt vmcnt(0)
	v_and_b32_e32 v7, 0xffff0000, v4
	v_lshlrev_b32_e32 v6, 16, v4
	v_pk_mul_f32 v[0:1], v[0:1], v[6:7]
	v_and_b32_e32 v7, 0xffff0000, v5
	v_lshlrev_b32_e32 v6, 16, v5
	v_pk_mul_f32 v[2:3], v[2:3], v[6:7]
	s_nop 0
	global_store_dwordx4 v[16:17], v[0:3], off offset:192
	s_nop 1
	v_lshl_add_u64 v[0:1], v[104:105], 0, s[10:11]
	v_readfirstlane_b32 s10, v81
	s_mov_b32 m0, s10
	s_mov_b64 s[10:11], 0x64800
	global_load_lds_dwordx4 v[0:1], off
	v_lshl_add_u64 v[0:1], v[104:105], 0, s[10:11]
	v_readfirstlane_b32 s10, v133
	s_mov_b32 m0, s10
	s_mov_b64 s[10:11], 0xc8800
	global_load_lds_dwordx4 v[0:1], off
	v_lshl_add_u64 v[0:1], v[104:105], 0, s[10:11]
	v_readfirstlane_b32 s10, v132
	s_mov_b32 m0, s10
	s_mov_b64 s[10:11], 0x12c800
	global_load_lds_dwordx4 v[0:1], off
	v_lshl_add_u64 v[0:1], v[104:105], 0, s[10:11]
	v_readfirstlane_b32 s10, v131
	s_mov_b32 m0, s10
	s_mov_b64 s[10:11], 0x190800
	global_load_lds_dwordx4 v[0:1], off
	v_lshl_add_u64 v[0:1], v[104:105], 0, s[10:11]
	v_readfirstlane_b32 s10, v130
	s_mov_b32 m0, s10
	v_readfirstlane_b32 s10, v129
	global_load_lds_dwordx4 v[0:1], off
	v_lshl_add_u64 v[0:1], v[86:87], 0, s[8:9]
	s_mov_b32 m0, s10
	v_readfirstlane_b32 s10, v128
	global_load_lds_dwordx4 v[0:1], off
	v_lshl_add_u64 v[2:3], v[0:1], 0, s[40:41]
	s_mov_b32 m0, s10
	s_mov_b64 s[10:11], 0x20000
	global_load_lds_dwordx4 v[2:3], off
	v_lshl_add_u64 v[2:3], v[0:1], 0, s[10:11]
	v_readfirstlane_b32 s10, v127
	s_mov_b32 m0, s10
	s_mov_b64 s[10:11], 0x30000
	v_lshl_add_u64 v[0:1], v[0:1], 0, s[10:11]
	v_readfirstlane_b32 s10, v126
	global_load_lds_dwordx4 v[2:3], off
	s_mov_b32 m0, s10
	s_mov_b64 s[10:11], 0
	global_load_lds_dwordx4 v[0:1], off
	s_waitcnt vmcnt(0)
	v_mov_b32_e32 v0, 0
	v_mov_b32_e32 v1, v0
	v_mov_b32_e32 v2, v0
	v_mov_b32_e32 v3, v0
	v_mov_b32_e32 v4, v0
	v_mov_b32_e32 v5, v0
	v_mov_b32_e32 v6, v0
	v_mov_b32_e32 v7, v0
	v_mov_b32_e32 v8, v0
	v_mov_b32_e32 v9, v0
	v_mov_b32_e32 v10, v0
	v_mov_b32_e32 v11, v0
	v_mov_b32_e32 v12, v0
	v_mov_b32_e32 v13, v0
	v_mov_b32_e32 v14, v0
	v_mov_b32_e32 v15, v0
	v_mov_b32_e32 v16, v0
	v_mov_b32_e32 v17, v0
	v_mov_b32_e32 v18, v0
	v_mov_b32_e32 v19, v0
	v_mov_b32_e32 v20, v0
	v_mov_b32_e32 v21, v0
	v_mov_b32_e32 v22, v0
	v_mov_b32_e32 v23, v0
	v_mov_b32_e32 v24, v0
	v_mov_b32_e32 v25, v0
	v_mov_b32_e32 v26, v0
	v_mov_b32_e32 v27, v0
	v_mov_b32_e32 v28, v0
	v_mov_b32_e32 v29, v0
	v_mov_b32_e32 v30, v0
	v_mov_b32_e32 v31, v0
	v_mov_b32_e32 v32, v0
	v_mov_b32_e32 v33, v0
	v_mov_b32_e32 v34, v0
	v_mov_b32_e32 v35, v0
	v_mov_b32_e32 v36, v0
	v_mov_b32_e32 v37, v0
	v_mov_b32_e32 v38, v0
	v_mov_b32_e32 v39, v0
	v_mov_b32_e32 v40, v0
	v_mov_b32_e32 v41, v0
	v_mov_b32_e32 v42, v0
	v_mov_b32_e32 v43, v0
	v_mov_b32_e32 v44, v0
	v_mov_b32_e32 v45, v0
	v_mov_b32_e32 v46, v0
	v_mov_b32_e32 v47, v0
	v_mov_b32_e32 v48, v0
	v_mov_b32_e32 v49, v0
	v_mov_b32_e32 v50, v0
	v_mov_b32_e32 v51, v0
	v_mov_b32_e32 v52, v0
	v_mov_b32_e32 v53, v0
	v_mov_b32_e32 v54, v0
	v_mov_b32_e32 v55, v0
	v_mov_b32_e32 v56, v0
	v_mov_b32_e32 v57, v0
	v_mov_b32_e32 v58, v0
	v_mov_b32_e32 v59, v0
	v_mov_b32_e32 v60, v0
	v_mov_b32_e32 v61, v0
	v_mov_b32_e32 v62, v0
	v_mov_b32_e32 v63, v0
	v_mov_b32_e32 v64, v0
	v_mov_b32_e32 v65, v0
	v_mov_b32_e32 v66, v0
	v_mov_b32_e32 v67, v0
	v_mov_b32_e32 v68, v0
	v_mov_b32_e32 v69, v0
	v_mov_b32_e32 v70, v0
	v_mov_b32_e32 v71, v0
	v_mov_b32_e32 v72, v0
	v_mov_b32_e32 v73, v0
	v_mov_b32_e32 v74, v0
	v_mov_b32_e32 v75, v0
	v_mov_b32_e32 v76, v0
	v_mov_b32_e32 v77, v0
	v_mov_b32_e32 v78, v0
	v_mov_b32_e32 v79, v0
	s_waitcnt vmcnt(0) lgkmcnt(0)
	s_barrier
.LBB0_88:
	s_add_i32 s36, s35, 1
	s_bitcmp1_b32 s36, 0
	s_cselect_b32 s37, 0x9000, 0
	v_add_u32_e32 v108, s37, v81
	v_lshl_add_u64 v[104:105], v[94:95], 0, s[10:11]
	s_mov_b64 s[38:39], 0x6181880
	v_readfirstlane_b32 s37, v108
	v_add_u32_e32 v109, 0x1000, v108
	v_lshl_add_u64 v[106:107], v[104:105], 0, s[38:39]
	s_mov_b32 m0, s37
	s_mov_b64 s[38:39], 0x61e5880
	v_readfirstlane_b32 s37, v109
	v_add_u32_e32 v109, 0x2000, v108
	global_load_lds_dwordx4 v[106:107], off
	v_lshl_add_u64 v[106:107], v[104:105], 0, s[38:39]
	s_mov_b32 m0, s37
	s_mov_b64 s[38:39], 0x6249880
	v_readfirstlane_b32 s37, v109
	v_add_u32_e32 v109, 0x3000, v108
	global_load_lds_dwordx4 v[106:107], off
	v_lshl_add_u64 v[106:107], v[104:105], 0, s[38:39]
	s_mov_b32 m0, s37
	s_mov_b64 s[38:39], 0x62ad880
	v_readfirstlane_b32 s37, v109
	global_load_lds_dwordx4 v[106:107], off
	v_lshl_add_u64 v[106:107], v[104:105], 0, s[38:39]
	s_mov_b32 m0, s37
	s_mov_b64 s[38:39], 0x6311880
	global_load_lds_dwordx4 v[106:107], off
	v_add_u32_e32 v106, 0x4000, v108
	v_lshl_add_u64 v[104:105], v[104:105], 0, s[38:39]
	v_readfirstlane_b32 s37, v106
	s_mov_b32 m0, s37
	v_add_u32_e32 v109, 0x5000, v108
	global_load_lds_dwordx4 v[104:105], off
	v_lshl_add_u64 v[104:105], v[100:101], 0, s[10:11]
	s_mov_b64 s[38:39], 0x14731080
	v_readfirstlane_b32 s37, v109
	v_add_u32_e32 v109, 0x6000, v108
	v_lshl_add_u64 v[106:107], v[104:105], 0, s[38:39]
	s_mov_b32 m0, s37
	s_mov_b64 s[38:39], 0x14741080
	v_readfirstlane_b32 s37, v109
	v_add_u32_e32 v109, 0x7000, v108
	global_load_lds_dwordx4 v[106:107], off
	v_lshl_add_u64 v[106:107], v[104:105], 0, s[38:39]
	s_mov_b32 m0, s37
	s_mov_b64 s[38:39], 0x14751080
	v_readfirstlane_b32 s37, v109
	global_load_lds_dwordx4 v[106:107], off
	v_lshl_add_u64 v[106:107], v[104:105], 0, s[38:39]
	s_mov_b32 m0, s37
	s_mov_b64 s[38:39], 0x14761080
	global_load_lds_dwordx4 v[106:107], off
	v_add_u32_e32 v106, 0x8000, v108
	v_lshl_add_u64 v[104:105], v[104:105], 0, s[38:39]
	v_readfirstlane_b32 s37, v106
	s_mov_b32 m0, s37
	s_bitcmp1_b32 s35, 0
	global_load_lds_dwordx4 v[104:105], off
	s_cselect_b32 s35, 0x9000, 0
	s_add_i32 s35, s35, 0
	v_add_u32_e32 v166, s35, v116
	v_add_u32_e32 v167, v166, v117
	ds_read_b128 v[104:107], v167
	ds_read_b128 v[108:111], v167 offset:2048
	ds_read_b128 v[112:115], v167 offset:4096
	ds_read_b128 v[156:159], v167 offset:6144
	v_add_u32_e32 v177, v166, v118
	ds_read_b128 v[166:169], v167 offset:8192
	ds_read_b128 v[178:181], v177 offset:20480
	ds_read_b128 v[182:185], v177 offset:22528
	ds_read_b128 v[186:189], v177 offset:24576
	ds_read_b128 v[190:193], v177 offset:26624
	v_add_u32_e32 v210, s35, v119
	v_add_u32_e32 v211, v210, v117
	ds_read_b128 v[212:215], v211
	ds_read_b128 v[216:219], v211 offset:2048
	ds_read_b128 v[220:223], v211 offset:4096
	ds_read_b128 v[224:227], v211 offset:6144
	v_add_u32_e32 v228, v210, v118
	ds_read_b128 v[230:233], v211 offset:8192
	ds_read_b128 v[234:237], v228 offset:20480
	ds_read_b128 v[238:241], v228 offset:22528
	ds_read_b128 v[242:245], v228 offset:24576
	ds_read_b128 v[246:249], v228 offset:26624
	s_setprio 1
	s_waitcnt lgkmcnt(9)
	v_mfma_f32_16x16x32_bf16 v[76:79], v[178:181], v[104:107], v[76:79]
	v_mfma_f32_16x16x32_bf16 v[72:75], v[182:185], v[104:107], v[72:75]
	v_mfma_f32_16x16x32_bf16 v[68:71], v[186:189], v[104:107], v[68:71]
	v_mfma_f32_16x16x32_bf16 v[64:67], v[190:193], v[104:107], v[64:67]
	v_mfma_f32_16x16x32_bf16 v[60:63], v[178:181], v[108:111], v[60:63]
	v_mfma_f32_16x16x32_bf16 v[56:59], v[182:185], v[108:111], v[56:59]
	v_mfma_f32_16x16x32_bf16 v[52:55], v[186:189], v[108:111], v[52:55]
	v_mfma_f32_16x16x32_bf16 v[48:51], v[190:193], v[108:111], v[48:51]
	v_mfma_f32_16x16x32_bf16 v[44:47], v[178:181], v[112:115], v[44:47]
	v_mfma_f32_16x16x32_bf16 v[40:43], v[182:185], v[112:115], v[40:43]
	v_mfma_f32_16x16x32_bf16 v[36:39], v[186:189], v[112:115], v[36:39]
	v_mfma_f32_16x16x32_bf16 v[32:35], v[190:193], v[112:115], v[32:35]
	v_mfma_f32_16x16x32_bf16 v[28:31], v[178:181], v[156:159], v[28:31]
	v_mfma_f32_16x16x32_bf16 v[24:27], v[182:185], v[156:159], v[24:27]
	v_mfma_f32_16x16x32_bf16 v[20:23], v[186:189], v[156:159], v[20:23]
	v_mfma_f32_16x16x32_bf16 v[16:19], v[190:193], v[156:159], v[16:19]
	v_mfma_f32_16x16x32_bf16 v[12:15], v[178:181], v[166:169], v[12:15]
	v_mfma_f32_16x16x32_bf16 v[8:11], v[182:185], v[166:169], v[8:11]
	v_mfma_f32_16x16x32_bf16 v[4:7], v[186:189], v[166:169], v[4:7]
	v_mfma_f32_16x16x32_bf16 v[0:3], v[190:193], v[166:169], v[0:3]
	s_setprio 0
	s_setprio 1
	s_waitcnt lgkmcnt(0)
	v_mfma_f32_16x16x32_bf16 v[76:79], v[234:237], v[212:215], v[76:79]
	v_mfma_f32_16x16x32_bf16 v[72:75], v[238:241], v[212:215], v[72:75]
	v_mfma_f32_16x16x32_bf16 v[68:71], v[242:245], v[212:215], v[68:71]
	v_mfma_f32_16x16x32_bf16 v[64:67], v[246:249], v[212:215], v[64:67]
	v_mfma_f32_16x16x32_bf16 v[60:63], v[234:237], v[216:219], v[60:63]
	v_mfma_f32_16x16x32_bf16 v[56:59], v[238:241], v[216:219], v[56:59]
	v_mfma_f32_16x16x32_bf16 v[52:55], v[242:245], v[216:219], v[52:55]
	v_mfma_f32_16x16x32_bf16 v[48:51], v[246:249], v[216:219], v[48:51]
	v_mfma_f32_16x16x32_bf16 v[44:47], v[234:237], v[220:223], v[44:47]
	v_mfma_f32_16x16x32_bf16 v[40:43], v[238:241], v[220:223], v[40:43]
	v_mfma_f32_16x16x32_bf16 v[36:39], v[242:245], v[220:223], v[36:39]
	v_mfma_f32_16x16x32_bf16 v[32:35], v[246:249], v[220:223], v[32:35]
	v_mfma_f32_16x16x32_bf16 v[28:31], v[234:237], v[224:227], v[28:31]
	v_mfma_f32_16x16x32_bf16 v[24:27], v[238:241], v[224:227], v[24:27]
	v_mfma_f32_16x16x32_bf16 v[20:23], v[242:245], v[224:227], v[20:23]
	v_mfma_f32_16x16x32_bf16 v[16:19], v[246:249], v[224:227], v[16:19]
	v_mfma_f32_16x16x32_bf16 v[12:15], v[234:237], v[230:233], v[12:15]
	v_mfma_f32_16x16x32_bf16 v[8:11], v[238:241], v[230:233], v[8:11]
	v_mfma_f32_16x16x32_bf16 v[4:7], v[242:245], v[230:233], v[4:7]
	v_mfma_f32_16x16x32_bf16 v[0:3], v[246:249], v[230:233], v[0:3]
	s_setprio 0
	s_waitcnt vmcnt(0)
	s_add_u32 s10, s10, 0x80
	s_addc_u32 s11, s11, 0
	s_cmpk_lg_i32 s10, 0x780
	s_mov_b32 s35, s36
	s_waitcnt vmcnt(0)
	s_barrier
	s_cbranch_scc1 .LBB0_88
	ds_read_b128 v[104:107], v122 offset:63488
	ds_read_b128 v[108:111], v122 offset:61440
	ds_read_b128 v[112:115], v122 offset:59392
	ds_read_b128 v[156:159], v122 offset:57344
	ds_read_b128 v[166:169], v123 offset:45056
	ds_read_b128 v[178:181], v123 offset:43008
	ds_read_b128 v[182:185], v123 offset:40960
	ds_read_b128 v[186:189], v123 offset:38912
	ds_read_b128 v[190:193], v123 offset:36864
	s_setprio 1
	s_waitcnt lgkmcnt(0)
	v_mfma_f32_16x16x32_bf16 v[76:79], v[156:159], v[190:193], v[76:79]
	v_mfma_f32_16x16x32_bf16 v[72:75], v[112:115], v[190:193], v[72:75]
	v_mfma_f32_16x16x32_bf16 v[68:71], v[108:111], v[190:193], v[68:71]
	v_mfma_f32_16x16x32_bf16 v[64:67], v[104:107], v[190:193], v[64:67]
	v_mfma_f32_16x16x32_bf16 v[60:63], v[156:159], v[186:189], v[60:63]
	v_mfma_f32_16x16x32_bf16 v[56:59], v[112:115], v[186:189], v[56:59]
	v_mfma_f32_16x16x32_bf16 v[52:55], v[108:111], v[186:189], v[52:55]
	v_mfma_f32_16x16x32_bf16 v[48:51], v[104:107], v[186:189], v[48:51]
	v_mfma_f32_16x16x32_bf16 v[44:47], v[156:159], v[182:185], v[44:47]
	v_mfma_f32_16x16x32_bf16 v[40:43], v[112:115], v[182:185], v[40:43]
	v_mfma_f32_16x16x32_bf16 v[36:39], v[108:111], v[182:185], v[36:39]
	v_mfma_f32_16x16x32_bf16 v[32:35], v[104:107], v[182:185], v[32:35]
	v_mfma_f32_16x16x32_bf16 v[28:31], v[156:159], v[178:181], v[28:31]
	v_mfma_f32_16x16x32_bf16 v[24:27], v[112:115], v[178:181], v[24:27]
	v_mfma_f32_16x16x32_bf16 v[20:23], v[108:111], v[178:181], v[20:23]
	v_mfma_f32_16x16x32_bf16 v[16:19], v[104:107], v[178:181], v[16:19]
	v_mfma_f32_16x16x32_bf16 v[12:15], v[156:159], v[166:169], v[12:15]
	v_mfma_f32_16x16x32_bf16 v[8:11], v[112:115], v[166:169], v[8:11]
	v_mfma_f32_16x16x32_bf16 v[4:7], v[108:111], v[166:169], v[4:7]
	v_mfma_f32_16x16x32_bf16 v[0:3], v[104:107], v[166:169], v[0:3]
	s_setprio 0
	ds_read_b128 v[104:107], v124 offset:36864
	ds_read_b128 v[108:111], v124 offset:38912
	ds_read_b128 v[112:115], v124 offset:40960
	ds_read_b128 v[156:159], v124 offset:43008
	ds_read_b128 v[166:169], v124 offset:45056
	ds_read_b128 v[178:181], v125 offset:57344
	ds_read_b128 v[182:185], v125 offset:59392
	ds_read_b128 v[186:189], v125 offset:61440
	ds_read_b128 v[190:193], v125 offset:63488
	s_setprio 1
	s_waitcnt lgkmcnt(3)
	v_mfma_f32_16x16x32_bf16 v[76:79], v[178:181], v[104:107], v[76:79]
	s_waitcnt lgkmcnt(0)
	v_mfma_f32_16x16x32_bf16 v[64:67], v[190:193], v[104:107], v[64:67]
	v_mfma_f32_16x16x32_bf16 v[60:63], v[178:181], v[108:111], v[60:63]
	v_mfma_f32_16x16x32_bf16 v[56:59], v[182:185], v[108:111], v[56:59]
	v_mfma_f32_16x16x32_bf16 v[52:55], v[186:189], v[108:111], v[52:55]
	v_mfma_f32_16x16x32_bf16 v[48:51], v[190:193], v[108:111], v[48:51]
	v_mfma_f32_16x16x32_bf16 v[44:47], v[178:181], v[112:115], v[44:47]
	v_mfma_f32_16x16x32_bf16 v[40:43], v[182:185], v[112:115], v[40:43]
	v_mfma_f32_16x16x32_bf16 v[36:39], v[186:189], v[112:115], v[36:39]
	v_mfma_f32_16x16x32_bf16 v[32:35], v[190:193], v[112:115], v[32:35]
	v_mfma_f32_16x16x32_bf16 v[28:31], v[178:181], v[156:159], v[28:31]
	v_mfma_f32_16x16x32_bf16 v[24:27], v[182:185], v[156:159], v[24:27]
	v_mfma_f32_16x16x32_bf16 v[20:23], v[186:189], v[156:159], v[20:23]
	v_mfma_f32_16x16x32_bf16 v[16:19], v[190:193], v[156:159], v[16:19]
	v_mfma_f32_16x16x32_bf16 v[12:15], v[178:181], v[166:169], v[12:15]
	v_mfma_f32_16x16x32_bf16 v[8:11], v[182:185], v[166:169], v[8:11]
	v_mfma_f32_16x16x32_bf16 v[4:7], v[186:189], v[166:169], v[4:7]
	v_mfma_f32_16x16x32_bf16 v[0:3], v[190:193], v[166:169], v[0:3]
	v_mfma_f32_16x16x32_bf16 v[194:197], v[182:185], v[104:107], v[72:75]
	v_mfma_f32_16x16x32_bf16 v[198:201], v[186:189], v[104:107], v[68:71]
	s_setprio 0
	s_nop 1
	v_mov_b32_e32 v68, v97
	s_waitcnt vmcnt(0)
	s_barrier
	s_movk_i32 s11, 0x50
	v_add_u32_e32 v68, v68, v176
	v_ashrrev_i32_e32 v69, 7, v68
	v_and_b32_e32 v70, 64, v68
	v_lshrrev_b32_e32 v71, 2, v68
	v_and_or_b32 v68, v68, 15, s12
	s_mov_b32 s10, 0
	v_and_b32_e32 v71, 12, v71
	v_mad_u64_u32 v[68:69], s[36:37], v69, s11, v[68:69]
	v_or3_b32 v104, v70, v71, s13
	v_mov_b64_e32 v[70:71], s[0:1]
	s_movk_i32 s11, 0x3200
	v_ashrrev_i32_e32 v69, 31, v68
	v_mad_i64_i32 v[72:73], s[36:37], v68, s11, v[70:71]
	s_mov_b64 s[38:39], 0x2000
	v_lshl_add_u64 v[112:113], v[72:73], 0, s[38:39]
	v_lshlrev_b64 v[72:73], 12, v[68:69]
	v_ashrrev_i32_e32 v105, 31, v104
	v_lshl_add_u64 v[106:107], s[4:5], 0, v[72:73]
	v_lshlrev_b64 v[72:73], 1, v[104:105]
	v_lshl_add_u64 v[108:109], v[112:113], 0, v[72:73]
	v_lshlrev_b64 v[74:75], 2, v[104:105]
	v_lshl_add_u64 v[106:107], v[106:107], 0, v[74:75]
	global_load_dwordx2 v[114:115], v[108:109], off
	s_waitcnt vmcnt(0)
	v_and_b32_e32 v157, 0xffff0000, v114
	global_load_dwordx4 v[108:111], v[106:107], off
	v_lshlrev_b32_e32 v156, 16, v114
	s_waitcnt vmcnt(0)
	v_pk_fma_f32 v[76:77], v[76:77], v[156:157], v[108:109]
	v_and_b32_e32 v109, 0xffff0000, v115
	v_lshlrev_b32_e32 v108, 16, v115
	v_pk_fma_f32 v[78:79], v[78:79], v[108:109], v[110:111]
	s_nop 0
	global_store_dwordx4 v[106:107], v[76:79], off
	global_load_dwordx4 v[108:111], v[106:107], off offset:64
	s_nop 0
	v_or_b32_e32 v76, 16, v104
	v_ashrrev_i32_e32 v77, 31, v76
	v_lshlrev_b64 v[76:77], 1, v[76:77]
	v_lshl_add_u64 v[78:79], v[112:113], 0, v[76:77]
	global_load_dwordx2 v[78:79], v[78:79], off
	s_waitcnt vmcnt(0)
	v_and_b32_e32 v115, 0xffff0000, v78
	v_lshlrev_b32_e32 v114, 16, v78
	v_or_b32_e32 v78, 32, v104
	v_pk_fma_f32 v[108:109], v[194:195], v[114:115], v[108:109]
	v_and_b32_e32 v115, 0xffff0000, v79
	v_lshlrev_b32_e32 v114, 16, v79
	v_ashrrev_i32_e32 v79, 31, v78
	v_pk_fma_f32 v[110:111], v[196:197], v[114:115], v[110:111]
	v_lshlrev_b64 v[78:79], 1, v[78:79]
	global_store_dwordx4 v[106:107], v[108:111], off offset:64
	v_or_b32_e32 v104, 48, v104
	v_ashrrev_i32_e32 v105, 31, v104
	v_lshl_add_u64 v[108:109], v[112:113], 0, v[78:79]
	global_load_dwordx2 v[114:115], v[108:109], off
	v_lshlrev_b64 v[104:105], 1, v[104:105]
	global_load_dwordx4 v[108:111], v[106:107], off offset:128
	s_waitcnt vmcnt(1)
	v_and_b32_e32 v157, 0xffff0000, v114
	v_lshlrev_b32_e32 v156, 16, v114
	s_waitcnt vmcnt(0)
	v_pk_fma_f32 v[108:109], v[198:199], v[156:157], v[108:109]
	v_and_b32_e32 v157, 0xffff0000, v115
	v_lshlrev_b32_e32 v156, 16, v115
	v_pk_fma_f32 v[110:111], v[200:201], v[156:157], v[110:111]
	s_nop 0
	global_store_dwordx4 v[106:107], v[108:111], off offset:128
	s_nop 1
	v_lshl_add_u64 v[108:109], v[112:113], 0, v[104:105]
	global_load_dwordx2 v[112:113], v[108:109], off
	s_waitcnt vmcnt(0)
	v_and_b32_e32 v115, 0xffff0000, v112
	global_load_dwordx4 v[108:111], v[106:107], off offset:192
	v_lshlrev_b32_e32 v114, 16, v112
	s_waitcnt vmcnt(0)
	v_pk_fma_f32 v[64:65], v[64:65], v[114:115], v[108:109]
	v_and_b32_e32 v109, 0xffff0000, v113
	v_lshlrev_b32_e32 v108, 16, v113
	v_pk_fma_f32 v[66:67], v[66:67], v[108:109], v[110:111]
	s_nop 0
	global_store_dwordx4 v[106:107], v[64:67], off offset:192
	s_nop 1
	v_add_u32_e32 v64, 16, v68
	v_ashrrev_i32_e32 v65, 31, v64
	v_mad_i64_i32 v[66:67], s[36:37], v64, s11, v[70:71]
	v_lshl_add_u64 v[66:67], v[66:67], 0, s[38:39]
	v_lshlrev_b64 v[64:65], 12, v[64:65]
	v_lshl_add_u64 v[64:65], s[4:5], 0, v[64:65]
	v_lshl_add_u64 v[106:107], v[66:67], 0, v[72:73]
	v_lshl_add_u64 v[64:65], v[64:65], 0, v[74:75]
	global_load_dwordx2 v[110:111], v[106:107], off
	s_waitcnt vmcnt(0)
	v_and_b32_e32 v113, 0xffff0000, v110
	global_load_dwordx4 v[106:109], v[64:65], off
	v_lshlrev_b32_e32 v112, 16, v110
	s_waitcnt vmcnt(0)
	v_pk_fma_f32 v[60:61], v[60:61], v[112:113], v[106:107]
	v_and_b32_e32 v107, 0xffff0000, v111
	v_lshlrev_b32_e32 v106, 16, v111
	v_pk_fma_f32 v[62:63], v[62:63], v[106:107], v[108:109]
	s_nop 0
	global_store_dwordx4 v[64:65], v[60:63], off
	s_nop 1
	v_lshl_add_u64 v[60:61], v[66:67], 0, v[76:77]
	global_load_dwordx2 v[106:107], v[60:61], off
	s_waitcnt vmcnt(0)
	v_and_b32_e32 v109, 0xffff0000, v106
	global_load_dwordx4 v[60:63], v[64:65], off offset:64
	v_lshlrev_b32_e32 v108, 16, v106
	s_waitcnt vmcnt(0)
	v_pk_fma_f32 v[56:57], v[56:57], v[108:109], v[60:61]
	v_and_b32_e32 v61, 0xffff0000, v107
	v_lshlrev_b32_e32 v60, 16, v107
	v_pk_fma_f32 v[58:59], v[58:59], v[60:61], v[62:63]
	s_nop 0
	global_store_dwordx4 v[64:65], v[56:59], off offset:64
	s_nop 1
	v_lshl_add_u64 v[56:57], v[66:67], 0, v[78:79]
	global_load_dwordx2 v[60:61], v[56:57], off
	s_waitcnt vmcnt(0)
	v_and_b32_e32 v63, 0xffff0000, v60
	global_load_dwordx4 v[56:59], v[64:65], off offset:128
	v_lshlrev_b32_e32 v62, 16, v60
	s_waitcnt vmcnt(0)
	v_pk_fma_f32 v[52:53], v[52:53], v[62:63], v[56:57]
	v_and_b32_e32 v57, 0xffff0000, v61
	v_lshlrev_b32_e32 v56, 16, v61
	v_pk_fma_f32 v[54:55], v[54:55], v[56:57], v[58:59]
	s_nop 0
	global_store_dwordx4 v[64:65], v[52:55], off offset:128
	s_nop 1
	v_lshl_add_u64 v[52:53], v[66:67], 0, v[104:105]
	global_load_dwordx2 v[56:57], v[52:53], off
	s_waitcnt vmcnt(0)
	v_and_b32_e32 v59, 0xffff0000, v56
	global_load_dwordx4 v[52:55], v[64:65], off offset:192
	v_lshlrev_b32_e32 v58, 16, v56
	s_waitcnt vmcnt(0)
	v_pk_fma_f32 v[48:49], v[48:49], v[58:59], v[52:53]
	v_and_b32_e32 v53, 0xffff0000, v57
	v_lshlrev_b32_e32 v52, 16, v57
	v_pk_fma_f32 v[50:51], v[50:51], v[52:53], v[54:55]
	s_nop 0
	global_store_dwordx4 v[64:65], v[48:51], off offset:192
	s_nop 1
	v_add_u32_e32 v48, 32, v68
	v_ashrrev_i32_e32 v49, 31, v48
	v_mad_i64_i32 v[50:51], s[36:37], v48, s11, v[70:71]
	v_lshl_add_u64 v[54:55], v[50:51], 0, s[38:39]
	v_lshlrev_b64 v[48:49], 12, v[48:49]
	v_lshl_add_u64 v[48:49], s[4:5], 0, v[48:49]
	v_lshl_add_u64 v[50:51], v[54:55], 0, v[72:73]
	v_lshl_add_u64 v[48:49], v[48:49], 0, v[74:75]
	global_load_dwordx2 v[56:57], v[50:51], off
	s_waitcnt vmcnt(0)
	v_and_b32_e32 v59, 0xffff0000, v56
	global_load_dwordx4 v[50:53], v[48:49], off
	v_lshlrev_b32_e32 v58, 16, v56
	s_waitcnt vmcnt(0)
	v_pk_fma_f32 v[44:45], v[44:45], v[58:59], v[50:51]
	v_and_b32_e32 v51, 0xffff0000, v57
	v_lshlrev_b32_e32 v50, 16, v57
	v_pk_fma_f32 v[46:47], v[46:47], v[50:51], v[52:53]
	s_nop 0
	global_store_dwordx4 v[48:49], v[44:47], off
	s_nop 1
	v_lshl_add_u64 v[44:45], v[54:55], 0, v[76:77]
	global_load_dwordx2 v[50:51], v[44:45], off
	s_waitcnt vmcnt(0)
	v_and_b32_e32 v53, 0xffff0000, v50
	global_load_dwordx4 v[44:47], v[48:49], off offset:64
	v_lshlrev_b32_e32 v52, 16, v50
	s_waitcnt vmcnt(0)
	v_pk_fma_f32 v[40:41], v[40:41], v[52:53], v[44:45]
	v_and_b32_e32 v45, 0xffff0000, v51
	v_lshlrev_b32_e32 v44, 16, v51
	v_pk_fma_f32 v[42:43], v[42:43], v[44:45], v[46:47]
	s_nop 0
	global_store_dwordx4 v[48:49], v[40:43], off offset:64
	s_nop 1
	v_lshl_add_u64 v[40:41], v[54:55], 0, v[78:79]
	global_load_dwordx2 v[44:45], v[40:41], off
	s_waitcnt vmcnt(0)
	v_and_b32_e32 v47, 0xffff0000, v44
	global_load_dwordx4 v[40:43], v[48:49], off offset:128
	v_lshlrev_b32_e32 v46, 16, v44
	s_waitcnt vmcnt(0)
	v_pk_fma_f32 v[36:37], v[36:37], v[46:47], v[40:41]
	v_and_b32_e32 v41, 0xffff0000, v45
	v_lshlrev_b32_e32 v40, 16, v45
	v_pk_fma_f32 v[38:39], v[38:39], v[40:41], v[42:43]
	s_nop 0
	global_store_dwordx4 v[48:49], v[36:39], off offset:128
	s_nop 1
	v_lshl_add_u64 v[36:37], v[54:55], 0, v[104:105]
	global_load_dwordx2 v[40:41], v[36:37], off
	s_waitcnt vmcnt(0)
	v_and_b32_e32 v43, 0xffff0000, v40
	global_load_dwordx4 v[36:39], v[48:49], off offset:192
	v_lshlrev_b32_e32 v42, 16, v40
	s_waitcnt vmcnt(0)
	v_pk_fma_f32 v[32:33], v[32:33], v[42:43], v[36:37]
	v_and_b32_e32 v37, 0xffff0000, v41
	v_lshlrev_b32_e32 v36, 16, v41
	v_pk_fma_f32 v[34:35], v[34:35], v[36:37], v[38:39]
	s_nop 0
	global_store_dwordx4 v[48:49], v[32:35], off offset:192
	s_nop 1
	v_add_u32_e32 v32, 48, v68
	v_ashrrev_i32_e32 v33, 31, v32
	v_mad_i64_i32 v[34:35], s[36:37], v32, s11, v[70:71]
	v_lshl_add_u64 v[38:39], v[34:35], 0, s[38:39]
	v_lshlrev_b64 v[32:33], 12, v[32:33]
	v_lshl_add_u64 v[32:33], s[4:5], 0, v[32:33]
	v_lshl_add_u64 v[34:35], v[38:39], 0, v[72:73]
	v_lshl_add_u64 v[32:33], v[32:33], 0, v[74:75]
	global_load_dwordx2 v[40:41], v[34:35], off
	s_waitcnt vmcnt(0)
	v_and_b32_e32 v43, 0xffff0000, v40
	global_load_dwordx4 v[34:37], v[32:33], off
	v_lshlrev_b32_e32 v42, 16, v40
	s_waitcnt vmcnt(0)
	v_pk_fma_f32 v[28:29], v[28:29], v[42:43], v[34:35]
	v_and_b32_e32 v35, 0xffff0000, v41
	v_lshlrev_b32_e32 v34, 16, v41
	v_pk_fma_f32 v[30:31], v[30:31], v[34:35], v[36:37]
	s_nop 0
	global_store_dwordx4 v[32:33], v[28:31], off
	s_nop 1
	v_lshl_add_u64 v[28:29], v[38:39], 0, v[76:77]
	global_load_dwordx2 v[34:35], v[28:29], off
	s_waitcnt vmcnt(0)
	v_and_b32_e32 v37, 0xffff0000, v34
	global_load_dwordx4 v[28:31], v[32:33], off offset:64
	v_lshlrev_b32_e32 v36, 16, v34
	s_waitcnt vmcnt(0)
	v_pk_fma_f32 v[24:25], v[24:25], v[36:37], v[28:29]
	v_and_b32_e32 v29, 0xffff0000, v35
	v_lshlrev_b32_e32 v28, 16, v35
	v_pk_fma_f32 v[26:27], v[26:27], v[28:29], v[30:31]
	s_nop 0
	global_store_dwordx4 v[32:33], v[24:27], off offset:64
	s_nop 1
	v_lshl_add_u64 v[24:25], v[38:39], 0, v[78:79]
	global_load_dwordx2 v[28:29], v[24:25], off
	s_waitcnt vmcnt(0)
	v_and_b32_e32 v31, 0xffff0000, v28
	global_load_dwordx4 v[24:27], v[32:33], off offset:128
	v_lshlrev_b32_e32 v30, 16, v28
	s_waitcnt vmcnt(0)
	v_pk_fma_f32 v[20:21], v[20:21], v[30:31], v[24:25]
	v_and_b32_e32 v25, 0xffff0000, v29
	v_lshlrev_b32_e32 v24, 16, v29
	v_pk_fma_f32 v[22:23], v[22:23], v[24:25], v[26:27]
	s_nop 0
	global_store_dwordx4 v[32:33], v[20:23], off offset:128
	s_nop 1
	v_lshl_add_u64 v[20:21], v[38:39], 0, v[104:105]
	global_load_dwordx2 v[24:25], v[20:21], off
	s_waitcnt vmcnt(0)
	v_and_b32_e32 v27, 0xffff0000, v24
	global_load_dwordx4 v[20:23], v[32:33], off offset:192
	v_lshlrev_b32_e32 v26, 16, v24
	s_waitcnt vmcnt(0)
	v_pk_fma_f32 v[16:17], v[16:17], v[26:27], v[20:21]
	v_and_b32_e32 v21, 0xffff0000, v25
	v_lshlrev_b32_e32 v20, 16, v25
	v_pk_fma_f32 v[18:19], v[18:19], v[20:21], v[22:23]
	s_nop 0
	global_store_dwordx4 v[32:33], v[16:19], off offset:192
	s_nop 1
	v_add_u32_e32 v16, 64, v68
	v_ashrrev_i32_e32 v17, 31, v16
	v_mad_i64_i32 v[18:19], s[36:37], v16, s11, v[70:71]
	v_lshl_add_u64 v[20:21], v[18:19], 0, s[38:39]
	v_lshlrev_b64 v[16:17], 12, v[16:17]
	v_lshl_add_u64 v[16:17], s[4:5], 0, v[16:17]
	v_lshl_add_u64 v[18:19], v[20:21], 0, v[72:73]
	v_lshl_add_u64 v[22:23], v[16:17], 0, v[74:75]
	global_load_dwordx2 v[24:25], v[18:19], off
	s_mov_b64 s[36:37], 0x1000
	global_load_dwordx4 v[16:19], v[22:23], off
	v_readfirstlane_b32 s11, v81
	s_mov_b32 m0, s11
	v_readfirstlane_b32 s11, v133
	s_waitcnt vmcnt(1)
	v_and_b32_e32 v27, 0xffff0000, v24
	v_lshlrev_b32_e32 v26, 16, v24
	s_waitcnt vmcnt(0)
	v_pk_fma_f32 v[12:13], v[12:13], v[26:27], v[16:17]
	v_and_b32_e32 v17, 0xffff0000, v25
	v_lshlrev_b32_e32 v16, 16, v25
	v_pk_fma_f32 v[14:15], v[14:15], v[16:17], v[18:19]
	s_nop 0
	global_store_dwordx4 v[22:23], v[12:15], off
	s_nop 1
	v_lshl_add_u64 v[12:13], v[20:21], 0, v[76:77]
	global_load_dwordx2 v[16:17], v[12:13], off
	s_waitcnt vmcnt(0)
	v_and_b32_e32 v19, 0xffff0000, v16
	global_load_dwordx4 v[12:15], v[22:23], off offset:64
	v_lshlrev_b32_e32 v18, 16, v16
	s_waitcnt vmcnt(0)
	v_pk_fma_f32 v[8:9], v[8:9], v[18:19], v[12:13]
	v_and_b32_e32 v13, 0xffff0000, v17
	v_lshlrev_b32_e32 v12, 16, v17
	v_pk_fma_f32 v[10:11], v[10:11], v[12:13], v[14:15]
	s_nop 0
	global_store_dwordx4 v[22:23], v[8:11], off offset:64
	s_nop 1
	v_lshl_add_u64 v[8:9], v[20:21], 0, v[78:79]
	global_load_dwordx2 v[12:13], v[8:9], off
	s_waitcnt vmcnt(0)
	v_and_b32_e32 v15, 0xffff0000, v12
	global_load_dwordx4 v[8:11], v[22:23], off offset:128
	v_lshlrev_b32_e32 v14, 16, v12
	s_waitcnt vmcnt(0)
	v_pk_fma_f32 v[4:5], v[4:5], v[14:15], v[8:9]
	v_and_b32_e32 v9, 0xffff0000, v13
	v_lshlrev_b32_e32 v8, 16, v13
	v_pk_fma_f32 v[6:7], v[6:7], v[8:9], v[10:11]
	s_nop 0
	global_store_dwordx4 v[22:23], v[4:7], off offset:128
	s_nop 1
	v_lshl_add_u64 v[4:5], v[20:21], 0, v[104:105]
	global_load_dwordx2 v[8:9], v[4:5], off
	s_waitcnt vmcnt(0)
	v_and_b32_e32 v11, 0xffff0000, v8
	global_load_dwordx4 v[4:7], v[22:23], off offset:192
	v_lshlrev_b32_e32 v10, 16, v8
	s_waitcnt vmcnt(0)
	v_pk_fma_f32 v[0:1], v[0:1], v[10:11], v[4:5]
	v_and_b32_e32 v5, 0xffff0000, v9
	v_lshlrev_b32_e32 v4, 16, v9
	v_pk_fma_f32 v[2:3], v[2:3], v[4:5], v[6:7]
	s_nop 0
	global_store_dwordx4 v[22:23], v[0:3], off offset:192
	s_nop 1
	v_lshl_add_u64 v[0:1], v[102:103], 0, v[96:97]
	v_lshl_add_u64 v[2:3], v[0:1], 0, s[36:37]
	s_mov_b64 s[36:37], 0x65000
	global_load_lds_dwordx4 v[2:3], off
	v_lshl_add_u64 v[2:3], v[0:1], 0, s[36:37]
	s_mov_b32 m0, s11
	s_mov_b64 s[36:37], 0xc9000
	v_readfirstlane_b32 s11, v132
	global_load_lds_dwordx4 v[2:3], off
	v_lshl_add_u64 v[2:3], v[0:1], 0, s[36:37]
	s_mov_b32 m0, s11
	s_mov_b64 s[36:37], 0x12d000
	v_readfirstlane_b32 s11, v131
	global_load_lds_dwordx4 v[2:3], off
	v_lshl_add_u64 v[2:3], v[0:1], 0, s[36:37]
	s_mov_b32 m0, s11
	s_mov_b64 s[36:37], 0x191000
	v_readfirstlane_b32 s11, v130
	global_load_lds_dwordx4 v[2:3], off
	v_lshl_add_u64 v[0:1], v[0:1], 0, s[36:37]
	s_mov_b32 m0, s11
	s_nop 0
	global_load_lds_dwordx4 v[0:1], off
	v_lshl_add_u64 v[0:1], v[88:89], 0, s[8:9]
	v_readfirstlane_b32 s8, v129
	s_mov_b32 m0, s8
	v_readfirstlane_b32 s8, v128
	global_load_lds_dwordx4 v[0:1], off
	v_lshl_add_u64 v[2:3], v[0:1], 0, s[40:41]
	s_mov_b32 m0, s8
	s_mov_b64 s[8:9], 0x20000
	global_load_lds_dwordx4 v[2:3], off
	v_lshl_add_u64 v[2:3], v[0:1], 0, s[8:9]
	v_readfirstlane_b32 s8, v127
	s_mov_b32 m0, s8
	s_mov_b64 s[8:9], 0x30000
	v_lshl_add_u64 v[0:1], v[0:1], 0, s[8:9]
	v_readfirstlane_b32 s8, v126
	global_load_lds_dwordx4 v[2:3], off
	s_mov_b32 m0, s8
	s_mov_b64 s[8:9], 0
	global_load_lds_dwordx4 v[0:1], off
	s_waitcnt vmcnt(0)
	v_mov_b32_e32 v0, 0
	v_mov_b32_e32 v1, v0
	v_mov_b32_e32 v2, v0
	v_mov_b32_e32 v3, v0
	v_mov_b32_e32 v4, v0
	v_mov_b32_e32 v5, v0
	v_mov_b32_e32 v6, v0
	v_mov_b32_e32 v7, v0
	v_mov_b32_e32 v8, v0
	v_mov_b32_e32 v9, v0
	v_mov_b32_e32 v10, v0
	v_mov_b32_e32 v11, v0
	v_mov_b32_e32 v12, v0
	v_mov_b32_e32 v13, v0
	v_mov_b32_e32 v14, v0
	v_mov_b32_e32 v15, v0
	v_mov_b32_e32 v16, v0
	v_mov_b32_e32 v17, v0
	v_mov_b32_e32 v18, v0
	v_mov_b32_e32 v19, v0
	v_mov_b32_e32 v20, v0
	v_mov_b32_e32 v21, v0
	v_mov_b32_e32 v22, v0
	v_mov_b32_e32 v23, v0
	v_mov_b32_e32 v24, v0
	v_mov_b32_e32 v25, v0
	v_mov_b32_e32 v26, v0
	v_mov_b32_e32 v27, v0
	v_mov_b32_e32 v28, v0
	v_mov_b32_e32 v29, v0
	v_mov_b32_e32 v30, v0
	v_mov_b32_e32 v31, v0
	v_mov_b32_e32 v32, v0
	v_mov_b32_e32 v33, v0
	v_mov_b32_e32 v34, v0
	v_mov_b32_e32 v35, v0
	v_mov_b32_e32 v36, v0
	v_mov_b32_e32 v37, v0
	v_mov_b32_e32 v38, v0
	v_mov_b32_e32 v39, v0
	v_mov_b32_e32 v40, v0
	v_mov_b32_e32 v41, v0
	v_mov_b32_e32 v42, v0
	v_mov_b32_e32 v43, v0
	v_mov_b32_e32 v44, v0
	v_mov_b32_e32 v45, v0
	v_mov_b32_e32 v46, v0
	v_mov_b32_e32 v47, v0
	v_mov_b32_e32 v48, v0
	v_mov_b32_e32 v49, v0
	v_mov_b32_e32 v50, v0
	v_mov_b32_e32 v51, v0
	v_mov_b32_e32 v52, v0
	v_mov_b32_e32 v53, v0
	v_mov_b32_e32 v54, v0
	v_mov_b32_e32 v55, v0
	v_mov_b32_e32 v56, v0
	v_mov_b32_e32 v57, v0
	v_mov_b32_e32 v58, v0
	v_mov_b32_e32 v59, v0
	v_mov_b32_e32 v60, v0
	v_mov_b32_e32 v61, v0
	v_mov_b32_e32 v62, v0
	v_mov_b32_e32 v63, v0
	v_mov_b32_e32 v64, v0
	v_mov_b32_e32 v65, v0
	v_mov_b32_e32 v66, v0
	v_mov_b32_e32 v67, v0
	v_mov_b32_e32 v68, v0
	v_mov_b32_e32 v69, v0
	v_mov_b32_e32 v70, v0
	v_mov_b32_e32 v71, v0
	v_mov_b32_e32 v72, v0
	v_mov_b32_e32 v73, v0
	v_mov_b32_e32 v74, v0
	v_mov_b32_e32 v75, v0
	v_mov_b32_e32 v76, v0
	v_mov_b32_e32 v77, v0
	v_mov_b32_e32 v78, v0
	v_mov_b32_e32 v79, v0
	s_waitcnt vmcnt(0) lgkmcnt(0)
	s_barrier

.LBB0_137:
	s_add_i32 s37, s11, 1
	s_bitcmp1_b32 s37, 0
	s_cselect_b32 s39, 0x9000, 0
	v_add_u32_e32 v94, s39, v177
	v_lshl_add_u64 v[90:91], v[86:87], 0, s[12:13]
	v_readfirstlane_b32 s39, v94
	v_add_u32_e32 v95, 0x1000, v94
	v_lshl_add_u64 v[92:93], v[90:91], 0, s[44:45]
	s_mov_b32 m0, s39
	v_readfirstlane_b32 s39, v95
	v_add_u32_e32 v95, 0x2000, v94
	global_load_lds_dwordx4 v[92:93], off
	v_lshl_add_u64 v[92:93], v[90:91], 0, s[46:47]
	s_mov_b32 m0, s39
	v_readfirstlane_b32 s39, v95
	v_add_u32_e32 v95, 0x3000, v94
	global_load_lds_dwordx4 v[92:93], off
	v_lshl_add_u64 v[92:93], v[90:91], 0, s[48:49]
	s_mov_b32 m0, s39
	v_readfirstlane_b32 s39, v95
	global_load_lds_dwordx4 v[92:93], off
	v_lshl_add_u64 v[92:93], v[90:91], 0, s[52:53]
	s_mov_b32 m0, s39
	s_mov_b64 s[40:41], 0x4141080
	global_load_lds_dwordx4 v[92:93], off
	v_add_u32_e32 v92, 0x4000, v94
	v_lshl_add_u64 v[90:91], v[90:91], 0, s[40:41]
	v_readfirstlane_b32 s39, v92
	s_mov_b32 m0, s39
	v_add_u32_e32 v95, 0x5000, v94
	global_load_lds_dwordx4 v[90:91], off
	v_lshl_add_u64 v[90:91], v[88:89], 0, s[12:13]
	v_readfirstlane_b32 s39, v95
	v_add_u32_e32 v95, 0x6000, v94
	v_lshl_add_u64 v[92:93], v[90:91], 0, s[54:55]
	s_mov_b32 m0, s39
	v_readfirstlane_b32 s39, v95
	v_add_u32_e32 v95, 0x7000, v94
	global_load_lds_dwordx4 v[92:93], off
	v_lshl_add_u64 v[92:93], v[90:91], 0, s[56:57]
	s_mov_b32 m0, s39
	v_readfirstlane_b32 s39, v95
	global_load_lds_dwordx4 v[92:93], off
	v_lshl_add_u64 v[92:93], v[90:91], 0, s[58:59]
	s_mov_b32 m0, s39
	v_lshl_add_u64 v[90:91], v[90:91], 0, s[60:61]
	global_load_lds_dwordx4 v[92:93], off
	v_add_u32_e32 v92, 0x8000, v94
	s_bitcmp1_b32 s11, 0
	v_readfirstlane_b32 s39, v92
	s_mov_b32 m0, s39
	s_cselect_b32 s11, 0x9000, 0
	global_load_lds_dwordx4 v[90:91], off
	s_add_i32 s11, s11, 0
	v_add_u32_e32 v94, s11, v178
	v_add_u32_e32 v95, v94, v179
	ds_read_b128 v[90:93], v95
	ds_read_b128 v[100:103], v95 offset:2048
	ds_read_b128 v[104:107], v95 offset:4096
	ds_read_b128 v[108:111], v95 offset:6144
	v_add_u32_e32 v94, v94, v180
	ds_read_b128 v[112:115], v95 offset:8192
	ds_read_b128 v[116:119], v94 offset:20480
	ds_read_b128 v[120:123], v94 offset:22528
	ds_read_b128 v[124:127], v94 offset:24576
	ds_read_b128 v[128:131], v94 offset:26624
	v_add_u32_e32 v206, s11, v181
	v_add_u32_e32 v207, v206, v179
	ds_read_b128 v[208:211], v207
	ds_read_b128 v[212:215], v207 offset:2048
	ds_read_b128 v[216:219], v207 offset:4096
	ds_read_b128 v[220:223], v207 offset:6144
	v_add_u32_e32 v224, v206, v180
	ds_read_b128 v[226:229], v207 offset:8192
	ds_read_b128 v[230:233], v224 offset:20480
	ds_read_b128 v[234:237], v224 offset:22528
	ds_read_b128 v[238:241], v224 offset:24576
	ds_read_b128 v[242:245], v224 offset:26624
	s_setprio 1
	s_waitcnt lgkmcnt(9)
	v_mfma_f32_16x16x32_bf16 v[76:79], v[116:119], v[90:93], v[76:79]
	v_mfma_f32_16x16x32_bf16 v[72:75], v[120:123], v[90:93], v[72:75]
	v_mfma_f32_16x16x32_bf16 v[68:71], v[124:127], v[90:93], v[68:71]
	v_mfma_f32_16x16x32_bf16 v[64:67], v[128:131], v[90:93], v[64:67]
	v_mfma_f32_16x16x32_bf16 v[60:63], v[116:119], v[100:103], v[60:63]
	v_mfma_f32_16x16x32_bf16 v[56:59], v[120:123], v[100:103], v[56:59]
	v_mfma_f32_16x16x32_bf16 v[52:55], v[124:127], v[100:103], v[52:55]
	v_mfma_f32_16x16x32_bf16 v[48:51], v[128:131], v[100:103], v[48:51]
	v_mfma_f32_16x16x32_bf16 v[44:47], v[116:119], v[104:107], v[44:47]
	v_mfma_f32_16x16x32_bf16 v[40:43], v[120:123], v[104:107], v[40:43]
	v_mfma_f32_16x16x32_bf16 v[36:39], v[124:127], v[104:107], v[36:39]
	v_mfma_f32_16x16x32_bf16 v[32:35], v[128:131], v[104:107], v[32:35]
	v_mfma_f32_16x16x32_bf16 v[28:31], v[116:119], v[108:111], v[28:31]
	v_mfma_f32_16x16x32_bf16 v[24:27], v[120:123], v[108:111], v[24:27]
	v_mfma_f32_16x16x32_bf16 v[20:23], v[124:127], v[108:111], v[20:23]
	v_mfma_f32_16x16x32_bf16 v[16:19], v[128:131], v[108:111], v[16:19]
	v_mfma_f32_16x16x32_bf16 v[12:15], v[116:119], v[112:115], v[12:15]
	v_mfma_f32_16x16x32_bf16 v[8:11], v[120:123], v[112:115], v[8:11]
	v_mfma_f32_16x16x32_bf16 v[4:7], v[124:127], v[112:115], v[4:7]
	v_mfma_f32_16x16x32_bf16 v[0:3], v[128:131], v[112:115], v[0:3]
	s_setprio 0
	s_setprio 1
	s_waitcnt lgkmcnt(0)
	v_mfma_f32_16x16x32_bf16 v[76:79], v[230:233], v[208:211], v[76:79]
	v_mfma_f32_16x16x32_bf16 v[72:75], v[234:237], v[208:211], v[72:75]
	v_mfma_f32_16x16x32_bf16 v[68:71], v[238:241], v[208:211], v[68:71]
	v_mfma_f32_16x16x32_bf16 v[64:67], v[242:245], v[208:211], v[64:67]
	v_mfma_f32_16x16x32_bf16 v[60:63], v[230:233], v[212:215], v[60:63]
	v_mfma_f32_16x16x32_bf16 v[56:59], v[234:237], v[212:215], v[56:59]
	v_mfma_f32_16x16x32_bf16 v[52:55], v[238:241], v[212:215], v[52:55]
	v_mfma_f32_16x16x32_bf16 v[48:51], v[242:245], v[212:215], v[48:51]
	v_mfma_f32_16x16x32_bf16 v[44:47], v[230:233], v[216:219], v[44:47]
	v_mfma_f32_16x16x32_bf16 v[40:43], v[234:237], v[216:219], v[40:43]
	v_mfma_f32_16x16x32_bf16 v[36:39], v[238:241], v[216:219], v[36:39]
	v_mfma_f32_16x16x32_bf16 v[32:35], v[242:245], v[216:219], v[32:35]
	v_mfma_f32_16x16x32_bf16 v[28:31], v[230:233], v[220:223], v[28:31]
	v_mfma_f32_16x16x32_bf16 v[24:27], v[234:237], v[220:223], v[24:27]
	v_mfma_f32_16x16x32_bf16 v[20:23], v[238:241], v[220:223], v[20:23]
	v_mfma_f32_16x16x32_bf16 v[16:19], v[242:245], v[220:223], v[16:19]
	v_mfma_f32_16x16x32_bf16 v[12:15], v[230:233], v[226:229], v[12:15]
	v_mfma_f32_16x16x32_bf16 v[8:11], v[234:237], v[226:229], v[8:11]
	v_mfma_f32_16x16x32_bf16 v[4:7], v[238:241], v[226:229], v[4:7]
	v_mfma_f32_16x16x32_bf16 v[0:3], v[242:245], v[226:229], v[0:3]
	s_setprio 0
	s_waitcnt vmcnt(0)
	s_add_u32 s12, s12, 0x80
	s_addc_u32 s13, s13, 0
	s_cmpk_lg_i32 s12, 0x780
	s_mov_b32 s11, s37
	s_waitcnt vmcnt(0)
	s_barrier
	s_cbranch_scc1 .LBB0_137
	v_add_u32_e32 v94, v182, v180
	ds_read_b128 v[86:89], v94 offset:63488
	ds_read_b128 v[90:93], v94 offset:61440
	ds_read_b128 v[100:103], v94 offset:59392
	ds_read_b128 v[104:107], v94 offset:57344
	v_add_u32_e32 v94, v182, v179
	ds_read_b128 v[108:111], v94 offset:45056
	ds_read_b128 v[112:115], v94 offset:43008
	ds_read_b128 v[116:119], v94 offset:40960
	ds_read_b128 v[120:123], v94 offset:38912
	ds_read_b128 v[124:127], v94 offset:36864
	s_setprio 1
	s_waitcnt lgkmcnt(0)
	v_mfma_f32_16x16x32_bf16 v[76:79], v[104:107], v[124:127], v[76:79]
	v_mfma_f32_16x16x32_bf16 v[72:75], v[100:103], v[124:127], v[72:75]
	v_mfma_f32_16x16x32_bf16 v[68:71], v[90:93], v[124:127], v[68:71]
	v_mfma_f32_16x16x32_bf16 v[64:67], v[86:89], v[124:127], v[64:67]
	v_mfma_f32_16x16x32_bf16 v[60:63], v[104:107], v[120:123], v[60:63]
	v_mfma_f32_16x16x32_bf16 v[56:59], v[100:103], v[120:123], v[56:59]
	v_mfma_f32_16x16x32_bf16 v[52:55], v[90:93], v[120:123], v[52:55]
	v_mfma_f32_16x16x32_bf16 v[48:51], v[86:89], v[120:123], v[48:51]
	v_mfma_f32_16x16x32_bf16 v[44:47], v[104:107], v[116:119], v[44:47]
	v_mfma_f32_16x16x32_bf16 v[40:43], v[100:103], v[116:119], v[40:43]
	v_mfma_f32_16x16x32_bf16 v[36:39], v[90:93], v[116:119], v[36:39]
	v_mfma_f32_16x16x32_bf16 v[32:35], v[86:89], v[116:119], v[32:35]
	v_mfma_f32_16x16x32_bf16 v[28:31], v[104:107], v[112:115], v[28:31]
	v_mfma_f32_16x16x32_bf16 v[24:27], v[100:103], v[112:115], v[24:27]
	v_mfma_f32_16x16x32_bf16 v[20:23], v[90:93], v[112:115], v[20:23]
	v_mfma_f32_16x16x32_bf16 v[16:19], v[86:89], v[112:115], v[16:19]
	v_mfma_f32_16x16x32_bf16 v[12:15], v[104:107], v[108:111], v[12:15]
	v_mfma_f32_16x16x32_bf16 v[8:11], v[100:103], v[108:111], v[8:11]
	v_mfma_f32_16x16x32_bf16 v[4:7], v[90:93], v[108:111], v[4:7]
	v_mfma_f32_16x16x32_bf16 v[0:3], v[86:89], v[108:111], v[0:3]
	s_setprio 0
	v_add_u32_e32 v94, v183, v179
	ds_read_b128 v[86:89], v94 offset:36864
	ds_read_b128 v[90:93], v94 offset:38912
	ds_read_b128 v[100:103], v94 offset:40960
	ds_read_b128 v[104:107], v94 offset:43008
	v_add_u32_e32 v95, v183, v180
	ds_read_b128 v[108:111], v94 offset:45056
	ds_read_b128 v[112:115], v95 offset:57344
	ds_read_b128 v[116:119], v95 offset:59392
	ds_read_b128 v[120:123], v95 offset:61440
	ds_read_b128 v[124:127], v95 offset:63488
	s_setprio 1
	s_waitcnt lgkmcnt(3)
	v_mfma_f32_16x16x32_bf16 v[76:79], v[112:115], v[86:89], v[76:79]
	s_waitcnt lgkmcnt(2)
	v_mfma_f32_16x16x32_bf16 v[72:75], v[116:119], v[86:89], v[72:75]
	s_waitcnt lgkmcnt(1)
	v_mfma_f32_16x16x32_bf16 v[68:71], v[120:123], v[86:89], v[68:71]
	s_waitcnt lgkmcnt(0)
	v_mfma_f32_16x16x32_bf16 v[64:67], v[124:127], v[86:89], v[64:67]
	v_mfma_f32_16x16x32_bf16 v[60:63], v[112:115], v[90:93], v[60:63]
	v_mfma_f32_16x16x32_bf16 v[56:59], v[116:119], v[90:93], v[56:59]
	v_mfma_f32_16x16x32_bf16 v[52:55], v[120:123], v[90:93], v[52:55]
	v_mfma_f32_16x16x32_bf16 v[48:51], v[124:127], v[90:93], v[48:51]
	v_mfma_f32_16x16x32_bf16 v[44:47], v[112:115], v[100:103], v[44:47]
	v_mfma_f32_16x16x32_bf16 v[40:43], v[116:119], v[100:103], v[40:43]
	v_mfma_f32_16x16x32_bf16 v[36:39], v[120:123], v[100:103], v[36:39]
	v_mfma_f32_16x16x32_bf16 v[32:35], v[124:127], v[100:103], v[32:35]
	v_mfma_f32_16x16x32_bf16 v[28:31], v[112:115], v[104:107], v[28:31]
	v_mfma_f32_16x16x32_bf16 v[24:27], v[116:119], v[104:107], v[24:27]
	v_mfma_f32_16x16x32_bf16 v[20:23], v[120:123], v[104:107], v[20:23]
	v_mfma_f32_16x16x32_bf16 v[16:19], v[124:127], v[104:107], v[16:19]
	v_mfma_f32_16x16x32_bf16 v[12:15], v[112:115], v[108:111], v[12:15]
	v_mfma_f32_16x16x32_bf16 v[8:11], v[116:119], v[108:111], v[8:11]
	v_mfma_f32_16x16x32_bf16 v[4:7], v[120:123], v[108:111], v[4:7]
	v_mfma_f32_16x16x32_bf16 v[0:3], v[124:127], v[108:111], v[0:3]
	s_setprio 0
	v_mov_b32_e32 v86, v97
	s_waitcnt vmcnt(0)
	s_barrier
	s_mulk_i32 s38, 0xa0
	v_add_u32_e32 v87, v86, v176
	v_ashrrev_i32_e32 v88, 7, v87
	v_and_or_b32 v86, v87, 15, s38
	s_movk_i32 s11, 0x50
	v_mad_u64_u32 v[88:89], s[12:13], v88, s11, v[86:87]
	s_lshl_b32 s10, s10, 7
	v_lshrrev_b32_e32 v86, 2, v87
	v_and_b32_e32 v92, 64, v87
	s_and_b32 s11, s10, 0x380
	v_and_b32_e32 v89, 12, v86
	v_or3_b32 v158, v92, s11, v89
	v_cmp_lt_i32_e32 vcc, v140, v138
	s_ashr_i32 s11, s10, 31
	s_lshl_b64 s[10:11], s[10:11], 1
	v_cndmask_b32_e32 v86, v137, v140, vcc
	v_cmp_lt_i32_e32 vcc, v139, v138
	v_lshlrev_b32_e32 v184, 2, v86
	s_add_u32 s10, s34, s10
	v_cndmask_b32_e32 v86, v137, v139, vcc
	v_lshlrev_b32_e32 v185, 2, v86
	s_addc_u32 s11, s35, s11
	v_lshlrev_b32_e32 v86, 1, v92
	v_mov_b32_e32 v87, v97
	s_mov_b32 s37, 0
	v_lshlrev_b32_e32 v96, 1, v158
	v_lshl_add_u64 v[86:87], s[10:11], 0, v[86:87]
	v_lshlrev_b32_e32 v92, 1, v89
	v_mov_b32_e32 v93, v97
	v_lshl_add_u64 v[90:91], s[6:7], 0, v[96:97]
	v_lshl_add_u64 v[86:87], v[86:87], 0, v[92:93]
	v_ashrrev_i32_e32 v89, 31, v88
	v_lshlrev_b64 v[92:93], 11, v[88:89]
	v_lshl_add_u64 v[94:95], v[90:91], 0, v[92:93]
	global_load_dwordx2 v[102:103], v[94:95], off
	global_load_dwordx2 v[100:101], v[94:95], off offset:32
	s_mov_b32 s38, 0x3c800000
	s_mov_b32 s12, 0x800000
	s_movk_i32 s13, 0x3200
	s_waitcnt vmcnt(1)
	v_lshlrev_b32_e32 v132, 16, v102
	s_waitcnt vmcnt(0)
	v_lshlrev_b32_e32 v123, 16, v100
	v_and_b32_e32 v119, 0xffff0000, v100
	v_alignbit_b32 v89, v101, v100, 16
	v_and_b32_e32 v121, 0xffff0000, v101
	global_load_dwordx2 v[100:101], v[94:95], off offset:64
	v_and_b32_e32 v125, 0xffff0000, v89
	v_and_b32_e32 v129, 0xffff0000, v103
	v_and_b32_e32 v130, 0xffff0000, v102
	v_mov_b32_e32 v128, v132
	v_mov_b32_e32 v131, v132
	v_mul_f32_e32 v108, v132, v132
	v_mul_f32_e32 v122, v123, v123
	v_mul_f32_e32 v118, v119, v119
	v_mul_f32_e32 v124, v125, v125
	v_mul_f32_e32 v120, v121, v121
	s_waitcnt vmcnt(0)
	v_lshlrev_b32_e32 v115, 16, v100
	v_and_b32_e32 v111, 0xffff0000, v100
	v_alignbit_b32 v89, v101, v100, 16
	v_and_b32_e32 v113, 0xffff0000, v101
	global_load_dwordx2 v[100:101], v[94:95], off offset:96
	v_and_b32_e32 v117, 0xffff0000, v89
	v_mul_f32_e32 v114, v115, v115
	v_mul_f32_e32 v110, v111, v111
	v_mul_f32_e32 v116, v117, v117
	v_mul_f32_e32 v112, v113, v113
	s_waitcnt vmcnt(0)
	v_alignbit_b32 v89, v101, v100, 16
	v_and_b32_e32 v107, 0xffff0000, v89
	v_alignbit_b32 v89, v103, v102, 16
	v_and_b32_e32 v103, 0xffff0000, v89
	v_and_b32_e32 v102, 16, v102
	v_mov_b32_e32 v89, v132
	v_pk_add_f32 v[126:127], v[102:103], v[128:129]
	v_pk_add_f32 v[156:157], v[130:131], v[88:89] op_sel_hi:[0,1]
	v_mov_b32_e32 v109, v127
	v_pk_mul_f32 v[126:127], v[130:131], v[130:131]
	v_mov_b32_e32 v128, v103
	v_mul_f32_e32 v102, v129, v129
	v_mov_b32_e32 v133, v103
	v_mov_b32_e32 v127, v157
	v_pk_fma_f32 v[102:103], v[128:129], v[128:129], v[102:103] op_sel_hi:[1,1,0]
	v_pk_add_f32 v[108:109], v[108:109], v[126:127]
	v_mov_b32_e32 v103, v97
	v_pk_add_f32 v[102:103], v[108:109], v[102:103]
	v_pk_add_f32 v[108:109], v[122:123], v[118:119]
	v_pk_add_f32 v[126:127], v[124:125], v[120:121]
	v_lshlrev_b32_e32 v105, 16, v100
	v_pk_add_f32 v[108:109], v[108:109], v[126:127]
	v_and_b32_e32 v95, 0xffff0000, v100
	v_and_b32_e32 v101, 0xffff0000, v101
	v_pk_add_f32 v[102:103], v[102:103], v[108:109]
	v_pk_add_f32 v[108:109], v[114:115], v[110:111]
	v_pk_add_f32 v[126:127], v[116:117], v[112:113]
	v_mul_f32_e32 v104, v105, v105
	v_mul_f32_e32 v94, v95, v95
	v_mul_f32_e32 v106, v107, v107
	v_mul_f32_e32 v100, v101, v101
	v_pk_add_f32 v[108:109], v[108:109], v[126:127]
	v_pk_add_f32 v[126:127], v[106:107], v[100:101]
	v_pk_add_f32 v[102:103], v[102:103], v[108:109]
	v_pk_add_f32 v[108:109], v[104:105], v[94:95]
	v_mul_f32_e32 v100, 0xbfb8aa3b, v76
	v_pk_add_f32 v[108:109], v[108:109], v[126:127]
	v_exp_f32_e32 v186, v100
	v_pk_add_f32 v[102:103], v[102:103], v[108:109]
	s_nop 0
	ds_bpermute_b32 v109, v184, v103
	ds_bpermute_b32 v108, v184, v102
	v_mul_f32_e32 v100, 0xbfb8aa3b, v77
	v_exp_f32_e32 v126, v100
	v_mul_f32_e32 v100, 0xbfb8aa3b, v78
	v_exp_f32_e32 v187, v100
	s_waitcnt lgkmcnt(0)
	v_pk_add_f32 v[102:103], v[102:103], v[108:109]
	s_nop 0
	ds_bpermute_b32 v109, v185, v103
	ds_bpermute_b32 v108, v185, v102
	v_mov_b32_e32 v131, v129
	v_mul_f32_e32 v100, 0xbfb8aa3b, v79
	v_exp_f32_e32 v127, v100
	v_mov_b32_e32 v124, v123
	s_waitcnt lgkmcnt(0)
	v_pk_add_f32 v[102:103], v[102:103], v[108:109]
	v_lshl_add_u64 v[108:109], s[8:9], 0, v[92:93]
	v_pk_mul_f32 v[102:103], v[102:103], s[38:39] op_sel_hi:[1,0]
	v_lshl_add_u64 v[108:109], v[108:109], 0, v[96:97]
	v_fma_f32 v89, -v103, v103, v102
	v_max_f32_e32 v89, 0, v89
	v_add_f32_e32 v89, 0x3a27c5ac, v89
	v_cmp_gt_f32_e32 vcc, s12, v89
	v_mul_f32_e32 v94, 0x4b800000, v89
	v_pk_add_f32 v[132:133], v[132:133], v[102:103] op_sel:[0,1] neg_lo:[0,1] neg_hi:[0,1]
	v_cndmask_b32_e32 v89, v89, v94, vcc
	v_rsq_f32_e32 v89, v89
	v_pk_add_f32 v[128:129], v[130:131], v[102:103] op_sel:[0,1] neg_lo:[0,1] neg_hi:[0,1]
	v_pk_add_f32 v[126:127], v[126:127], 1.0 op_sel_hi:[1,0]
	v_mad_i64_i32 v[92:93], s[10:11], v88, s13, v[86:87]
	v_mul_f32_e32 v94, 0x45800000, v89
	v_cndmask_b32_e32 v94, v89, v94, vcc
	v_lshlrev_b32_e32 v89, 2, v158
	global_load_dwordx4 v[156:159], v89, s[0:1]
	global_load_dwordx4 v[166:169], v89, s[4:5]
	v_pk_mul_f32 v[132:133], v[132:133], v[94:95] op_sel_hi:[1,0]
	v_pk_mul_f32 v[128:129], v[128:129], v[94:95] op_sel_hi:[1,0]
	v_pk_add_f32 v[122:123], v[124:125], v[102:103] op_sel:[0,1] neg_lo:[0,1] neg_hi:[0,1]
	v_mov_b32_e32 v120, v119
	v_pk_mul_f32 v[122:123], v[122:123], v[94:95] op_sel_hi:[1,0]
	v_pk_add_f32 v[118:119], v[120:121], v[102:103] op_sel:[0,1] neg_lo:[0,1] neg_hi:[0,1]
	v_mov_b32_e32 v116, v115
	v_pk_mul_f32 v[118:119], v[118:119], v[94:95] op_sel_hi:[1,0]
	v_pk_add_f32 v[114:115], v[116:117], v[102:103] op_sel:[0,1] neg_lo:[0,1] neg_hi:[0,1]
	s_waitcnt vmcnt(1)
	v_mov_b32_e32 v188, v156
	v_mov_b32_e32 v189, v158
	s_waitcnt vmcnt(0)
	v_mov_b32_e32 v190, v166
	v_mov_b32_e32 v191, v168
	v_pk_fma_f32 v[132:133], v[188:189], v[132:133], v[190:191]
	global_load_dwordx2 v[188:189], v[108:109], off
	v_mov_b32_e32 v158, v157
	v_mov_b32_e32 v168, v167
	v_pk_fma_f32 v[128:129], v[158:159], v[128:129], v[168:169]
	v_pk_mul_f32 v[114:115], v[114:115], v[94:95] op_sel_hi:[1,0]
	s_waitcnt vmcnt(0)
	v_and_b32_e32 v131, 0xffff0000, v189
	v_and_b32_e32 v130, 0xffff0000, v188
	v_pk_add_f32 v[128:129], v[128:129], v[130:131]
	v_pk_add_f32 v[130:131], v[186:187], 1.0 op_sel_hi:[1,0]
	v_lshlrev_b32_e32 v191, 16, v189
	v_lshlrev_b32_e32 v190, 16, v188
	v_pk_add_f32 v[132:133], v[132:133], v[190:191]
	v_rcp_f32_e32 v100, v131
	s_nop 0
	v_mul_f32_e32 v131, v78, v100
	s_nop 0
	v_rcp_f32_e32 v78, v130
	s_nop 0
	v_mul_f32_e32 v130, v76, v78
	v_pk_mul_f32 v[130:131], v[130:131], v[132:133]
	v_rcp_f32_e32 v76, v127
	s_nop 0
	v_mul_f32_e32 v79, v79, v76
	s_nop 0
	v_rcp_f32_e32 v76, v126
	s_nop 0
	v_mul_f32_e32 v78, v77, v76
	v_pk_mul_f32 v[76:77], v[78:79], v[128:129]
	v_and_b32_sdwa v78, v131, v154 dst_sel:DWORD dst_unused:UNUSED_PAD src0_sel:WORD_1 src1_sel:DWORD
	v_and_b32_sdwa v100, v77, v154 dst_sel:DWORD dst_unused:UNUSED_PAD src0_sel:WORD_1 src1_sel:DWORD
	v_and_b32_sdwa v104, v76, v154 dst_sel:DWORD dst_unused:UNUSED_PAD src0_sel:WORD_1 src1_sel:DWORD
	v_and_b32_sdwa v79, v130, v154 dst_sel:DWORD dst_unused:UNUSED_PAD src0_sel:WORD_1 src1_sel:DWORD
	v_add3_u32 v77, v77, v100, s33
	v_add3_u32 v76, v76, v104, s33
	v_add3_u32 v79, v130, v79, s33
	v_add3_u32 v78, v131, v78, s33
	v_and_b32_e32 v77, 0xffff0000, v77
	v_and_b32_e32 v76, 0xffff0000, v76
	v_or_b32_sdwa v77, v77, v78 dst_sel:DWORD dst_unused:UNUSED_PAD src0_sel:DWORD src1_sel:WORD_1
	v_or_b32_sdwa v76, v76, v79 dst_sel:DWORD dst_unused:UNUSED_PAD src0_sel:DWORD src1_sel:WORD_1
	global_store_dwordx2 v[92:93], v[76:77], off
	global_load_dwordx4 v[126:129], v89, s[0:1] offset:64
	global_load_dwordx4 v[130:133], v89, s[4:5] offset:64
	v_mul_f32_e32 v76, 0xbfb8aa3b, v72
	v_mul_f32_e32 v77, 0xbfb8aa3b, v74
	v_exp_f32_e32 v78, v76
	v_exp_f32_e32 v79, v77
	v_mul_f32_e32 v76, 0xbfb8aa3b, v73
	v_mul_f32_e32 v77, 0xbfb8aa3b, v75
	v_exp_f32_e32 v76, v76
	v_pk_add_f32 v[78:79], v[78:79], 1.0 op_sel_hi:[1,0]
	v_exp_f32_e32 v77, v77
	s_nop 0
	v_pk_add_f32 v[76:77], v[76:77], 1.0 op_sel_hi:[1,0]
	v_rcp_f32_e32 v100, v79
	s_nop 0
	v_mul_f32_e32 v79, v74, v100
	v_mov_b32_e32 v112, v111
	v_rcp_f32_e32 v74, v78
	s_nop 0
	v_mul_f32_e32 v78, v72, v74
	v_pk_add_f32 v[110:111], v[112:113], v[102:103] op_sel:[0,1] neg_lo:[0,1] neg_hi:[0,1]
	v_rcp_f32_e32 v72, v77
	s_nop 0
	v_mul_f32_e32 v75, v75, v72
	v_pk_mul_f32 v[110:111], v[110:111], v[94:95] op_sel_hi:[1,0]
	v_rcp_f32_e32 v72, v76
	s_nop 0
	v_mul_f32_e32 v74, v73, v72
	s_waitcnt vmcnt(1)
	v_mov_b32_e32 v124, v126
	v_mov_b32_e32 v125, v128
	s_waitcnt vmcnt(0)
	v_mov_b32_e32 v156, v130
	v_mov_b32_e32 v157, v132
	v_pk_fma_f32 v[122:123], v[122:123], v[124:125], v[156:157]
	global_load_dwordx2 v[124:125], v[108:109], off offset:32
	v_mov_b32_e32 v128, v127
	v_mov_b32_e32 v132, v131
	v_pk_fma_f32 v[118:119], v[118:119], v[128:129], v[132:133]
	s_waitcnt vmcnt(0)
	v_and_b32_e32 v121, 0xffff0000, v125
	v_and_b32_e32 v120, 0xffff0000, v124
	v_lshlrev_b32_e32 v157, 16, v125
	v_lshlrev_b32_e32 v156, 16, v124
	v_pk_add_f32 v[118:119], v[118:119], v[120:121]
	v_pk_add_f32 v[122:123], v[122:123], v[156:157]
	v_pk_mul_f32 v[72:73], v[74:75], v[118:119]
	v_pk_mul_f32 v[78:79], v[78:79], v[122:123]
	v_and_b32_sdwa v76, v73, v154 dst_sel:DWORD dst_unused:UNUSED_PAD src0_sel:WORD_1 src1_sel:DWORD
	v_and_b32_sdwa v77, v72, v154 dst_sel:DWORD dst_unused:UNUSED_PAD src0_sel:WORD_1 src1_sel:DWORD
	v_and_b32_sdwa v74, v79, v154 dst_sel:DWORD dst_unused:UNUSED_PAD src0_sel:WORD_1 src1_sel:DWORD
	v_and_b32_sdwa v75, v78, v154 dst_sel:DWORD dst_unused:UNUSED_PAD src0_sel:WORD_1 src1_sel:DWORD
	v_add3_u32 v73, v73, v76, s33
	v_add3_u32 v72, v72, v77, s33
	v_add3_u32 v75, v78, v75, s33
	v_add3_u32 v74, v79, v74, s33
	v_and_b32_e32 v73, 0xffff0000, v73
	v_and_b32_e32 v72, 0xffff0000, v72
	v_or_b32_sdwa v73, v73, v74 dst_sel:DWORD dst_unused:UNUSED_PAD src0_sel:DWORD src1_sel:WORD_1
	v_or_b32_sdwa v72, v72, v75 dst_sel:DWORD dst_unused:UNUSED_PAD src0_sel:DWORD src1_sel:WORD_1
	global_store_dwordx2 v[92:93], v[72:73], off offset:32
	global_load_dwordx4 v[74:77], v89, s[0:1] offset:128
	global_load_dwordx4 v[118:121], v89, s[4:5] offset:128
	v_mul_f32_e32 v72, 0xbfb8aa3b, v68
	v_mul_f32_e32 v73, 0xbfb8aa3b, v70
	v_exp_f32_e32 v78, v72
	v_exp_f32_e32 v79, v73
	v_mul_f32_e32 v72, 0xbfb8aa3b, v69
	v_mul_f32_e32 v73, 0xbfb8aa3b, v71
	v_exp_f32_e32 v72, v72
	v_exp_f32_e32 v73, v73
	s_waitcnt vmcnt(1)
	v_mov_b32_e32 v116, v74
	v_mov_b32_e32 v117, v76
	s_waitcnt vmcnt(0)
	v_mov_b32_e32 v122, v118
	v_mov_b32_e32 v123, v120
	v_pk_fma_f32 v[114:115], v[114:115], v[116:117], v[122:123]
	global_load_dwordx2 v[116:117], v[108:109], off offset:64
	v_mov_b32_e32 v76, v75
	v_mov_b32_e32 v120, v119
	v_pk_fma_f32 v[74:75], v[110:111], v[76:77], v[120:121]
	v_pk_add_f32 v[72:73], v[72:73], 1.0 op_sel_hi:[1,0]
	s_waitcnt vmcnt(0)
	v_and_b32_e32 v77, 0xffff0000, v117
	v_and_b32_e32 v76, 0xffff0000, v116
	v_pk_add_f32 v[74:75], v[74:75], v[76:77]
	v_pk_add_f32 v[76:77], v[78:79], 1.0 op_sel_hi:[1,0]
	v_lshlrev_b32_e32 v123, 16, v117
	v_lshlrev_b32_e32 v122, 16, v116
	v_pk_add_f32 v[114:115], v[114:115], v[122:123]
	v_rcp_f32_e32 v78, v77
	s_nop 0
	v_mul_f32_e32 v77, v70, v78
	v_mov_b32_e32 v106, v105
	v_rcp_f32_e32 v70, v76
	s_nop 0
	v_mul_f32_e32 v76, v68, v70
	v_pk_mul_f32 v[76:77], v[76:77], v[114:115]
	v_pk_add_f32 v[104:105], v[106:107], v[102:103] op_sel:[0,1] neg_lo:[0,1] neg_hi:[0,1]
	v_rcp_f32_e32 v68, v73
	s_nop 0
	v_mul_f32_e32 v71, v71, v68
	v_pk_mul_f32 v[104:105], v[104:105], v[94:95] op_sel_hi:[1,0]
	v_mov_b32_e32 v100, v95
	v_pk_add_f32 v[100:101], v[100:101], v[102:103] op_sel:[0,1] neg_lo:[0,1] neg_hi:[0,1]
	v_rcp_f32_e32 v68, v72
	s_nop 0
	v_mul_f32_e32 v70, v69, v68
	v_pk_mul_f32 v[68:69], v[70:71], v[74:75]
	v_and_b32_sdwa v70, v77, v154 dst_sel:DWORD dst_unused:UNUSED_PAD src0_sel:WORD_1 src1_sel:DWORD
	v_and_b32_sdwa v72, v69, v154 dst_sel:DWORD dst_unused:UNUSED_PAD src0_sel:WORD_1 src1_sel:DWORD
	v_and_b32_sdwa v73, v68, v154 dst_sel:DWORD dst_unused:UNUSED_PAD src0_sel:WORD_1 src1_sel:DWORD
	v_and_b32_sdwa v71, v76, v154 dst_sel:DWORD dst_unused:UNUSED_PAD src0_sel:WORD_1 src1_sel:DWORD
	v_add3_u32 v69, v69, v72, s33
	v_add3_u32 v68, v68, v73, s33
	v_add3_u32 v71, v76, v71, s33
	v_add3_u32 v70, v77, v70, s33
	v_and_b32_e32 v69, 0xffff0000, v69
	v_and_b32_e32 v68, 0xffff0000, v68
	v_or_b32_sdwa v69, v69, v70 dst_sel:DWORD dst_unused:UNUSED_PAD src0_sel:DWORD src1_sel:WORD_1
	v_or_b32_sdwa v68, v68, v71 dst_sel:DWORD dst_unused:UNUSED_PAD src0_sel:DWORD src1_sel:WORD_1
	global_store_dwordx2 v[92:93], v[68:69], off offset:64
	global_load_dwordx4 v[70:73], v89, s[0:1] offset:192
	global_load_dwordx4 v[74:77], v89, s[4:5] offset:192
	v_mul_f32_e32 v68, 0xbfb8aa3b, v64
	v_mul_f32_e32 v69, 0xbfb8aa3b, v66
	v_exp_f32_e32 v78, v68
	v_exp_f32_e32 v79, v69
	v_pk_mul_f32 v[94:95], v[100:101], v[94:95] op_sel_hi:[1,0]
	v_mul_f32_e32 v68, 0xbfb8aa3b, v65
	v_mul_f32_e32 v69, 0xbfb8aa3b, v67
	v_exp_f32_e32 v68, v68
	v_exp_f32_e32 v69, v69
	s_waitcnt vmcnt(1)
	v_mov_b32_e32 v106, v70
	v_mov_b32_e32 v107, v72
	s_waitcnt vmcnt(0)
	v_mov_b32_e32 v110, v74
	v_mov_b32_e32 v111, v76
	v_pk_fma_f32 v[104:105], v[104:105], v[106:107], v[110:111]
	global_load_dwordx2 v[106:107], v[108:109], off offset:96
	v_mov_b32_e32 v72, v71
	v_mov_b32_e32 v76, v75
	v_pk_fma_f32 v[70:71], v[94:95], v[72:73], v[76:77]
	v_pk_add_f32 v[68:69], v[68:69], 1.0 op_sel_hi:[1,0]
	s_waitcnt vmcnt(0)
	v_and_b32_e32 v73, 0xffff0000, v107
	v_and_b32_e32 v72, 0xffff0000, v106
	v_pk_add_f32 v[70:71], v[70:71], v[72:73]
	v_pk_add_f32 v[72:73], v[78:79], 1.0 op_sel_hi:[1,0]
	v_lshlrev_b32_e32 v109, 16, v107
	v_lshlrev_b32_e32 v108, 16, v106
	v_pk_add_f32 v[104:105], v[104:105], v[108:109]
	v_rcp_f32_e32 v74, v73
	s_nop 0
	v_mul_f32_e32 v73, v66, v74
	s_nop 0
	v_rcp_f32_e32 v66, v72
	s_nop 0
	v_mul_f32_e32 v72, v64, v66
	v_pk_mul_f32 v[72:73], v[72:73], v[104:105]
	v_rcp_f32_e32 v64, v69
	s_nop 0
	v_mul_f32_e32 v67, v67, v64
	s_nop 0
	v_rcp_f32_e32 v64, v68
	s_nop 0
	v_mul_f32_e32 v66, v65, v64
	v_pk_mul_f32 v[64:65], v[66:67], v[70:71]
	v_and_b32_sdwa v66, v73, v154 dst_sel:DWORD dst_unused:UNUSED_PAD src0_sel:WORD_1 src1_sel:DWORD
	v_and_b32_sdwa v68, v65, v154 dst_sel:DWORD dst_unused:UNUSED_PAD src0_sel:WORD_1 src1_sel:DWORD
	v_and_b32_sdwa v69, v64, v154 dst_sel:DWORD dst_unused:UNUSED_PAD src0_sel:WORD_1 src1_sel:DWORD
	v_and_b32_sdwa v67, v72, v154 dst_sel:DWORD dst_unused:UNUSED_PAD src0_sel:WORD_1 src1_sel:DWORD
	v_add3_u32 v65, v65, v68, s33
	v_add3_u32 v64, v64, v69, s33
	v_add3_u32 v67, v72, v67, s33
	v_add3_u32 v66, v73, v66, s33
	v_and_b32_e32 v65, 0xffff0000, v65
	v_and_b32_e32 v64, 0xffff0000, v64
	v_or_b32_sdwa v65, v65, v66 dst_sel:DWORD dst_unused:UNUSED_PAD src0_sel:DWORD src1_sel:WORD_1
	v_or_b32_sdwa v64, v64, v67 dst_sel:DWORD dst_unused:UNUSED_PAD src0_sel:DWORD src1_sel:WORD_1
	global_store_dwordx2 v[92:93], v[64:65], off offset:96
	v_add_u32_e32 v64, 16, v88
	v_ashrrev_i32_e32 v65, 31, v64
	v_lshlrev_b64 v[76:77], 11, v[64:65]
	v_lshl_add_u64 v[66:67], v[90:91], 0, v[76:77]
	global_load_dwordx2 v[70:71], v[66:67], off
	global_load_dwordx2 v[68:69], v[66:67], off offset:32
	v_lshl_add_u64 v[76:77], s[8:9], 0, v[76:77]
	v_lshl_add_u64 v[76:77], v[76:77], 0, v[96:97]
	s_waitcnt vmcnt(1)
	v_lshlrev_b32_e32 v118, 16, v70
	s_waitcnt vmcnt(0)
	v_lshlrev_b32_e32 v107, 16, v68
	v_and_b32_e32 v103, 0xffff0000, v68
	v_alignbit_b32 v65, v69, v68, 16
	v_and_b32_e32 v105, 0xffff0000, v69
	global_load_dwordx2 v[68:69], v[66:67], off offset:64
	v_and_b32_e32 v109, 0xffff0000, v65
	v_and_b32_e32 v113, 0xffff0000, v71
	v_and_b32_e32 v116, 0xffff0000, v70
	v_mov_b32_e32 v112, v118
	v_mov_b32_e32 v117, v118
	v_mul_f32_e32 v110, v118, v118
	v_mul_f32_e32 v106, v107, v107
	v_mul_f32_e32 v102, v103, v103
	v_mul_f32_e32 v108, v109, v109
	v_mul_f32_e32 v104, v105, v105
	s_waitcnt vmcnt(0)
	v_lshlrev_b32_e32 v95, 16, v68
	v_and_b32_e32 v79, 0xffff0000, v68
	v_alignbit_b32 v65, v69, v68, 16
	v_and_b32_e32 v93, 0xffff0000, v69
	global_load_dwordx2 v[68:69], v[66:67], off offset:96
	v_and_b32_e32 v101, 0xffff0000, v65
	v_mul_f32_e32 v94, v95, v95
	v_mul_f32_e32 v78, v79, v79
	v_mul_f32_e32 v100, v101, v101
	v_mul_f32_e32 v92, v93, v93
	s_waitcnt vmcnt(0)
	v_alignbit_b32 v65, v69, v68, 16
	v_and_b32_e32 v75, 0xffff0000, v65
	v_alignbit_b32 v65, v71, v70, 16
	v_and_b32_e32 v71, 0xffff0000, v65
	v_and_b32_e32 v70, 16, v70
	v_mov_b32_e32 v65, v118
	v_pk_add_f32 v[114:115], v[70:71], v[112:113]
	v_pk_add_f32 v[120:121], v[116:117], v[64:65] op_sel_hi:[0,1]
	v_mov_b32_e32 v111, v115
	v_pk_mul_f32 v[114:115], v[116:117], v[116:117]
	v_mov_b32_e32 v112, v71
	v_mov_b32_e32 v115, v121
	global_load_dwordx4 v[120:123], v89, s[0:1]
	global_load_dwordx4 v[124:127], v89, s[4:5]
	v_mul_f32_e32 v70, v113, v113
	v_mov_b32_e32 v119, v71
	v_pk_fma_f32 v[70:71], v[112:113], v[112:113], v[70:71] op_sel_hi:[1,1,0]
	v_pk_add_f32 v[110:111], v[110:111], v[114:115]
	v_mov_b32_e32 v71, v97
	v_pk_add_f32 v[70:71], v[110:111], v[70:71]
	v_pk_add_f32 v[110:111], v[106:107], v[102:103]
	v_pk_add_f32 v[114:115], v[108:109], v[104:105]
	v_lshlrev_b32_e32 v73, 16, v68
	v_pk_add_f32 v[110:111], v[110:111], v[114:115]
	v_and_b32_e32 v67, 0xffff0000, v68
	v_and_b32_e32 v69, 0xffff0000, v69
	v_pk_add_f32 v[70:71], v[70:71], v[110:111]
	v_pk_add_f32 v[110:111], v[94:95], v[78:79]
	v_pk_add_f32 v[114:115], v[100:101], v[92:93]
	v_mul_f32_e32 v72, v73, v73
	v_mul_f32_e32 v66, v67, v67
	v_mul_f32_e32 v74, v75, v75
	v_mul_f32_e32 v68, v69, v69
	v_pk_add_f32 v[110:111], v[110:111], v[114:115]
	v_pk_add_f32 v[114:115], v[74:75], v[68:69]
	v_pk_add_f32 v[70:71], v[70:71], v[110:111]
	v_pk_add_f32 v[110:111], v[72:73], v[66:67]
	v_mul_f32_e32 v68, 0xbfb8aa3b, v60
	v_pk_add_f32 v[110:111], v[110:111], v[114:115]
	v_exp_f32_e32 v114, v68
	v_pk_add_f32 v[70:71], v[70:71], v[110:111]
	s_nop 0
	ds_bpermute_b32 v111, v184, v71
	ds_bpermute_b32 v110, v184, v70
	v_mul_f32_e32 v68, 0xbfb8aa3b, v61
	v_mov_b32_e32 v117, v113
	v_mov_b32_e32 v108, v107
	v_mov_b32_e32 v104, v103
	s_waitcnt lgkmcnt(0)
	v_pk_add_f32 v[70:71], v[70:71], v[110:111]
	s_nop 0
	ds_bpermute_b32 v111, v185, v71
	ds_bpermute_b32 v110, v185, v70
	v_mov_b32_e32 v100, v95
	s_waitcnt lgkmcnt(0)
	v_pk_add_f32 v[70:71], v[70:71], v[110:111]
	s_nop 0
	v_pk_mul_f32 v[70:71], v[70:71], s[38:39] op_sel_hi:[1,0]
	v_exp_f32_e32 v110, v68
	v_fma_f32 v65, -v71, v71, v70
	v_max_f32_e32 v65, 0, v65
	v_add_f32_e32 v65, 0x3a27c5ac, v65
	v_cmp_gt_f32_e32 vcc, s12, v65
	v_mul_f32_e32 v66, 0x4b800000, v65
	v_pk_add_f32 v[118:119], v[118:119], v[70:71] op_sel:[0,1] neg_lo:[0,1] neg_hi:[0,1]
	v_cndmask_b32_e32 v65, v65, v66, vcc
	v_rsq_f32_e32 v65, v65
	v_mul_f32_e32 v68, 0xbfb8aa3b, v62
	v_exp_f32_e32 v115, v68
	v_mul_f32_e32 v68, 0xbfb8aa3b, v63
	v_mul_f32_e32 v66, 0x45800000, v65
	v_cndmask_b32_e32 v66, v65, v66, vcc
	v_pk_mul_f32 v[118:119], v[118:119], v[66:67] op_sel_hi:[1,0]
	v_pk_add_f32 v[114:115], v[114:115], 1.0 op_sel_hi:[1,0]
	v_exp_f32_e32 v111, v68
	s_nop 0
	v_pk_add_f32 v[110:111], v[110:111], 1.0 op_sel_hi:[1,0]
	v_pk_add_f32 v[112:113], v[116:117], v[70:71] op_sel:[0,1] neg_lo:[0,1] neg_hi:[0,1]
	v_mad_i64_i32 v[64:65], s[10:11], v64, s13, v[86:87]
	v_rcp_f32_e32 v68, v115
	s_nop 0
	v_mul_f32_e32 v115, v62, v68
	s_waitcnt vmcnt(1)
	v_mov_b32_e32 v128, v120
	v_mov_b32_e32 v129, v122
	s_waitcnt vmcnt(0)
	v_mov_b32_e32 v130, v124
	v_mov_b32_e32 v131, v126
	v_pk_fma_f32 v[118:119], v[128:129], v[118:119], v[130:131]
	global_load_dwordx2 v[128:129], v[76:77], off
	v_pk_mul_f32 v[112:113], v[112:113], v[66:67] op_sel_hi:[1,0]
	v_mov_b32_e32 v122, v121
	v_mov_b32_e32 v126, v125
	v_rcp_f32_e32 v62, v114
	s_nop 0
	v_mul_f32_e32 v114, v60, v62
	v_pk_fma_f32 v[112:113], v[122:123], v[112:113], v[126:127]
	v_pk_add_f32 v[106:107], v[108:109], v[70:71] op_sel:[0,1] neg_lo:[0,1] neg_hi:[0,1]
	v_pk_add_f32 v[102:103], v[104:105], v[70:71] op_sel:[0,1] neg_lo:[0,1] neg_hi:[0,1]
	v_rcp_f32_e32 v60, v111
	s_nop 0
	v_mul_f32_e32 v63, v63, v60
	v_pk_mul_f32 v[106:107], v[106:107], v[66:67] op_sel_hi:[1,0]
	v_pk_mul_f32 v[102:103], v[102:103], v[66:67] op_sel_hi:[1,0]
	v_pk_add_f32 v[94:95], v[100:101], v[70:71] op_sel:[0,1] neg_lo:[0,1] neg_hi:[0,1]
	v_rcp_f32_e32 v60, v110
	s_nop 0
	v_mul_f32_e32 v62, v61, v60
	v_pk_mul_f32 v[94:95], v[94:95], v[66:67] op_sel_hi:[1,0]
	s_waitcnt vmcnt(0)
	v_and_b32_e32 v117, 0xffff0000, v129
	v_and_b32_e32 v116, 0xffff0000, v128
	v_lshlrev_b32_e32 v131, 16, v129
	v_lshlrev_b32_e32 v130, 16, v128
	v_pk_add_f32 v[112:113], v[112:113], v[116:117]
	v_pk_add_f32 v[118:119], v[118:119], v[130:131]
	v_pk_mul_f32 v[60:61], v[62:63], v[112:113]
	v_pk_mul_f32 v[114:115], v[114:115], v[118:119]
	v_and_b32_sdwa v68, v61, v154 dst_sel:DWORD dst_unused:UNUSED_PAD src0_sel:WORD_1 src1_sel:DWORD
	v_and_b32_sdwa v72, v60, v154 dst_sel:DWORD dst_unused:UNUSED_PAD src0_sel:WORD_1 src1_sel:DWORD
	v_and_b32_sdwa v62, v115, v154 dst_sel:DWORD dst_unused:UNUSED_PAD src0_sel:WORD_1 src1_sel:DWORD
	v_and_b32_sdwa v63, v114, v154 dst_sel:DWORD dst_unused:UNUSED_PAD src0_sel:WORD_1 src1_sel:DWORD
	v_add3_u32 v61, v61, v68, s33
	v_add3_u32 v60, v60, v72, s33
	v_add3_u32 v63, v114, v63, s33
	v_add3_u32 v62, v115, v62, s33
	v_and_b32_e32 v61, 0xffff0000, v61
	v_and_b32_e32 v60, 0xffff0000, v60
	v_or_b32_sdwa v61, v61, v62 dst_sel:DWORD dst_unused:UNUSED_PAD src0_sel:DWORD src1_sel:WORD_1
	v_or_b32_sdwa v60, v60, v63 dst_sel:DWORD dst_unused:UNUSED_PAD src0_sel:DWORD src1_sel:WORD_1
	global_store_dwordx2 v[64:65], v[60:61], off
	global_load_dwordx4 v[110:113], v89, s[0:1] offset:64
	global_load_dwordx4 v[114:117], v89, s[4:5] offset:64
	v_mul_f32_e32 v60, 0xbfb8aa3b, v56
	v_mul_f32_e32 v61, 0xbfb8aa3b, v58
	v_exp_f32_e32 v62, v60
	v_exp_f32_e32 v63, v61
	v_mul_f32_e32 v60, 0xbfb8aa3b, v57
	v_mul_f32_e32 v61, 0xbfb8aa3b, v59
	v_exp_f32_e32 v60, v60
	v_pk_add_f32 v[62:63], v[62:63], 1.0 op_sel_hi:[1,0]
	v_exp_f32_e32 v61, v61
	s_nop 0
	v_pk_add_f32 v[60:61], v[60:61], 1.0 op_sel_hi:[1,0]
	v_rcp_f32_e32 v68, v63
	s_nop 0
	v_mul_f32_e32 v63, v58, v68
	v_mov_b32_e32 v92, v79
	v_rcp_f32_e32 v58, v62
	s_nop 0
	v_mul_f32_e32 v62, v56, v58
	v_pk_add_f32 v[78:79], v[92:93], v[70:71] op_sel:[0,1] neg_lo:[0,1] neg_hi:[0,1]
	v_rcp_f32_e32 v56, v61
	s_nop 0
	v_mul_f32_e32 v59, v59, v56
	v_pk_mul_f32 v[78:79], v[78:79], v[66:67] op_sel_hi:[1,0]
	v_rcp_f32_e32 v56, v60
	s_nop 0
	v_mul_f32_e32 v58, v57, v56
	s_waitcnt vmcnt(1)
	v_mov_b32_e32 v108, v110
	v_mov_b32_e32 v109, v112
	s_waitcnt vmcnt(0)
	v_mov_b32_e32 v118, v114
	v_mov_b32_e32 v119, v116
	v_pk_fma_f32 v[106:107], v[106:107], v[108:109], v[118:119]
	global_load_dwordx2 v[108:109], v[76:77], off offset:32
	v_mov_b32_e32 v112, v111
	v_mov_b32_e32 v116, v115
	v_pk_fma_f32 v[102:103], v[102:103], v[112:113], v[116:117]
	s_waitcnt vmcnt(0)
	v_and_b32_e32 v105, 0xffff0000, v109
	v_and_b32_e32 v104, 0xffff0000, v108
	v_lshlrev_b32_e32 v119, 16, v109
	v_lshlrev_b32_e32 v118, 16, v108
	v_pk_add_f32 v[102:103], v[102:103], v[104:105]
	v_pk_add_f32 v[106:107], v[106:107], v[118:119]
	v_pk_mul_f32 v[56:57], v[58:59], v[102:103]
	v_pk_mul_f32 v[62:63], v[62:63], v[106:107]
	v_and_b32_sdwa v60, v57, v154 dst_sel:DWORD dst_unused:UNUSED_PAD src0_sel:WORD_1 src1_sel:DWORD
	v_and_b32_sdwa v61, v56, v154 dst_sel:DWORD dst_unused:UNUSED_PAD src0_sel:WORD_1 src1_sel:DWORD
	v_and_b32_sdwa v58, v63, v154 dst_sel:DWORD dst_unused:UNUSED_PAD src0_sel:WORD_1 src1_sel:DWORD
	v_and_b32_sdwa v59, v62, v154 dst_sel:DWORD dst_unused:UNUSED_PAD src0_sel:WORD_1 src1_sel:DWORD
	v_add3_u32 v57, v57, v60, s33
	v_add3_u32 v56, v56, v61, s33
	v_add3_u32 v59, v62, v59, s33
	v_add3_u32 v58, v63, v58, s33
	v_and_b32_e32 v57, 0xffff0000, v57
	v_and_b32_e32 v56, 0xffff0000, v56
	v_or_b32_sdwa v57, v57, v58 dst_sel:DWORD dst_unused:UNUSED_PAD src0_sel:DWORD src1_sel:WORD_1
	v_or_b32_sdwa v56, v56, v59 dst_sel:DWORD dst_unused:UNUSED_PAD src0_sel:DWORD src1_sel:WORD_1
	global_store_dwordx2 v[64:65], v[56:57], off offset:32
	global_load_dwordx4 v[58:61], v89, s[0:1] offset:128
	global_load_dwordx4 v[102:105], v89, s[4:5] offset:128
	v_mul_f32_e32 v56, 0xbfb8aa3b, v52
	v_mul_f32_e32 v57, 0xbfb8aa3b, v54
	v_exp_f32_e32 v62, v56
	v_exp_f32_e32 v63, v57
	v_mul_f32_e32 v56, 0xbfb8aa3b, v53
	v_mul_f32_e32 v57, 0xbfb8aa3b, v55
	v_exp_f32_e32 v56, v56
	v_exp_f32_e32 v57, v57
	s_waitcnt vmcnt(1)
	v_mov_b32_e32 v100, v58
	v_mov_b32_e32 v101, v60
	s_waitcnt vmcnt(0)
	v_mov_b32_e32 v106, v102
	v_mov_b32_e32 v107, v104
	v_pk_fma_f32 v[94:95], v[94:95], v[100:101], v[106:107]
	global_load_dwordx2 v[100:101], v[76:77], off offset:64
	v_mov_b32_e32 v60, v59
	v_mov_b32_e32 v104, v103
	v_pk_fma_f32 v[58:59], v[78:79], v[60:61], v[104:105]
	v_pk_add_f32 v[56:57], v[56:57], 1.0 op_sel_hi:[1,0]
	s_waitcnt vmcnt(0)
	v_and_b32_e32 v61, 0xffff0000, v101
	v_and_b32_e32 v60, 0xffff0000, v100
	v_pk_add_f32 v[58:59], v[58:59], v[60:61]
	v_pk_add_f32 v[60:61], v[62:63], 1.0 op_sel_hi:[1,0]
	v_lshlrev_b32_e32 v107, 16, v101
	v_lshlrev_b32_e32 v106, 16, v100
	v_pk_add_f32 v[94:95], v[94:95], v[106:107]
	v_rcp_f32_e32 v62, v61
	s_nop 0
	v_mul_f32_e32 v61, v54, v62
	v_mov_b32_e32 v74, v73
	v_rcp_f32_e32 v54, v60
	s_nop 0
	v_mul_f32_e32 v60, v52, v54
	v_pk_mul_f32 v[60:61], v[60:61], v[94:95]
	v_pk_add_f32 v[72:73], v[74:75], v[70:71] op_sel:[0,1] neg_lo:[0,1] neg_hi:[0,1]
	v_rcp_f32_e32 v52, v57
	s_nop 0
	v_mul_f32_e32 v55, v55, v52
	v_pk_mul_f32 v[72:73], v[72:73], v[66:67] op_sel_hi:[1,0]
	v_mov_b32_e32 v68, v67
	v_pk_add_f32 v[68:69], v[68:69], v[70:71] op_sel:[0,1] neg_lo:[0,1] neg_hi:[0,1]
	v_rcp_f32_e32 v52, v56
	s_nop 0
	v_mul_f32_e32 v54, v53, v52
	v_pk_mul_f32 v[52:53], v[54:55], v[58:59]
	v_and_b32_sdwa v54, v61, v154 dst_sel:DWORD dst_unused:UNUSED_PAD src0_sel:WORD_1 src1_sel:DWORD
	v_and_b32_sdwa v56, v53, v154 dst_sel:DWORD dst_unused:UNUSED_PAD src0_sel:WORD_1 src1_sel:DWORD
	v_and_b32_sdwa v57, v52, v154 dst_sel:DWORD dst_unused:UNUSED_PAD src0_sel:WORD_1 src1_sel:DWORD
	v_and_b32_sdwa v55, v60, v154 dst_sel:DWORD dst_unused:UNUSED_PAD src0_sel:WORD_1 src1_sel:DWORD
	v_add3_u32 v53, v53, v56, s33
	v_add3_u32 v52, v52, v57, s33
	v_add3_u32 v55, v60, v55, s33
	v_add3_u32 v54, v61, v54, s33
	v_and_b32_e32 v53, 0xffff0000, v53
	v_and_b32_e32 v52, 0xffff0000, v52
	v_or_b32_sdwa v53, v53, v54 dst_sel:DWORD dst_unused:UNUSED_PAD src0_sel:DWORD src1_sel:WORD_1
	v_or_b32_sdwa v52, v52, v55 dst_sel:DWORD dst_unused:UNUSED_PAD src0_sel:DWORD src1_sel:WORD_1
	global_store_dwordx2 v[64:65], v[52:53], off offset:64
	global_load_dwordx4 v[54:57], v89, s[0:1] offset:192
	global_load_dwordx4 v[58:61], v89, s[4:5] offset:192
	v_mul_f32_e32 v52, 0xbfb8aa3b, v48
	v_mul_f32_e32 v53, 0xbfb8aa3b, v50
	v_exp_f32_e32 v62, v52
	v_exp_f32_e32 v63, v53
	v_pk_mul_f32 v[66:67], v[68:69], v[66:67] op_sel_hi:[1,0]
	v_mul_f32_e32 v52, 0xbfb8aa3b, v49
	v_mul_f32_e32 v53, 0xbfb8aa3b, v51
	v_exp_f32_e32 v52, v52
	v_exp_f32_e32 v53, v53
	s_waitcnt vmcnt(1)
	v_mov_b32_e32 v74, v54
	v_mov_b32_e32 v75, v56
	s_waitcnt vmcnt(0)
	v_mov_b32_e32 v78, v58
	v_mov_b32_e32 v79, v60
	v_pk_fma_f32 v[72:73], v[72:73], v[74:75], v[78:79]
	global_load_dwordx2 v[74:75], v[76:77], off offset:96
	v_mov_b32_e32 v56, v55
	v_mov_b32_e32 v60, v59
	v_pk_fma_f32 v[54:55], v[66:67], v[56:57], v[60:61]
	v_pk_add_f32 v[52:53], v[52:53], 1.0 op_sel_hi:[1,0]
	s_waitcnt vmcnt(0)
	v_and_b32_e32 v57, 0xffff0000, v75
	v_and_b32_e32 v56, 0xffff0000, v74
	v_pk_add_f32 v[54:55], v[54:55], v[56:57]
	v_pk_add_f32 v[56:57], v[62:63], 1.0 op_sel_hi:[1,0]
	v_lshlrev_b32_e32 v77, 16, v75
	v_lshlrev_b32_e32 v76, 16, v74
	v_pk_add_f32 v[72:73], v[72:73], v[76:77]
	v_rcp_f32_e32 v58, v57
	s_nop 0
	v_mul_f32_e32 v57, v50, v58
	s_nop 0
	v_rcp_f32_e32 v50, v56
	s_nop 0
	v_mul_f32_e32 v56, v48, v50
	v_pk_mul_f32 v[56:57], v[56:57], v[72:73]
	v_rcp_f32_e32 v48, v53
	s_nop 0
	v_mul_f32_e32 v51, v51, v48
	s_nop 0
	v_rcp_f32_e32 v48, v52
	s_nop 0
	v_mul_f32_e32 v50, v49, v48
	v_pk_mul_f32 v[48:49], v[50:51], v[54:55]
	v_and_b32_sdwa v50, v57, v154 dst_sel:DWORD dst_unused:UNUSED_PAD src0_sel:WORD_1 src1_sel:DWORD
	v_and_b32_sdwa v52, v49, v154 dst_sel:DWORD dst_unused:UNUSED_PAD src0_sel:WORD_1 src1_sel:DWORD
	v_and_b32_sdwa v53, v48, v154 dst_sel:DWORD dst_unused:UNUSED_PAD src0_sel:WORD_1 src1_sel:DWORD
	v_and_b32_sdwa v51, v56, v154 dst_sel:DWORD dst_unused:UNUSED_PAD src0_sel:WORD_1 src1_sel:DWORD
	v_add3_u32 v49, v49, v52, s33
	v_add3_u32 v48, v48, v53, s33
	v_add3_u32 v51, v56, v51, s33
	v_add3_u32 v50, v57, v50, s33
	v_and_b32_e32 v49, 0xffff0000, v49
	v_and_b32_e32 v48, 0xffff0000, v48
	v_or_b32_sdwa v49, v49, v50 dst_sel:DWORD dst_unused:UNUSED_PAD src0_sel:DWORD src1_sel:WORD_1
	v_or_b32_sdwa v48, v48, v51 dst_sel:DWORD dst_unused:UNUSED_PAD src0_sel:DWORD src1_sel:WORD_1
	global_store_dwordx2 v[64:65], v[48:49], off offset:96
	v_add_u32_e32 v48, 32, v88
	v_ashrrev_i32_e32 v49, 31, v48
	v_lshlrev_b64 v[60:61], 11, v[48:49]
	v_lshl_add_u64 v[50:51], v[90:91], 0, v[60:61]
	global_load_dwordx2 v[54:55], v[50:51], off
	global_load_dwordx2 v[52:53], v[50:51], off offset:32
	v_lshl_add_u64 v[60:61], s[8:9], 0, v[60:61]
	v_lshl_add_u64 v[60:61], v[60:61], 0, v[96:97]
	s_waitcnt vmcnt(1)
	v_lshlrev_b32_e32 v102, 16, v54
	s_waitcnt vmcnt(0)
	v_lshlrev_b32_e32 v75, 16, v52
	v_and_b32_e32 v71, 0xffff0000, v52
	v_alignbit_b32 v49, v53, v52, 16
	v_and_b32_e32 v73, 0xffff0000, v53
	global_load_dwordx2 v[52:53], v[50:51], off offset:64
	v_and_b32_e32 v77, 0xffff0000, v49
	v_and_b32_e32 v93, 0xffff0000, v55
	v_and_b32_e32 v100, 0xffff0000, v54
	v_mov_b32_e32 v92, v102
	v_mov_b32_e32 v101, v102
	v_mul_f32_e32 v78, v102, v102
	v_mul_f32_e32 v74, v75, v75
	v_mul_f32_e32 v70, v71, v71
	v_mul_f32_e32 v76, v77, v77
	v_mul_f32_e32 v72, v73, v73
	s_waitcnt vmcnt(0)
	v_lshlrev_b32_e32 v67, 16, v52
	v_and_b32_e32 v63, 0xffff0000, v52
	v_alignbit_b32 v49, v53, v52, 16
	v_and_b32_e32 v65, 0xffff0000, v53
	global_load_dwordx2 v[52:53], v[50:51], off offset:96
	v_and_b32_e32 v69, 0xffff0000, v49
	v_mul_f32_e32 v66, v67, v67
	v_mul_f32_e32 v62, v63, v63
	v_mul_f32_e32 v68, v69, v69
	v_mul_f32_e32 v64, v65, v65
	s_waitcnt vmcnt(0)
	v_alignbit_b32 v49, v53, v52, 16
	v_and_b32_e32 v59, 0xffff0000, v49
	v_alignbit_b32 v49, v55, v54, 16
	v_and_b32_e32 v55, 0xffff0000, v49
	v_and_b32_e32 v54, 16, v54
	v_mov_b32_e32 v49, v102
	v_pk_add_f32 v[94:95], v[54:55], v[92:93]
	v_pk_add_f32 v[104:105], v[100:101], v[48:49] op_sel_hi:[0,1]
	v_mov_b32_e32 v79, v95
	v_pk_mul_f32 v[94:95], v[100:101], v[100:101]
	v_mov_b32_e32 v92, v55
	v_mov_b32_e32 v95, v105
	global_load_dwordx4 v[104:107], v89, s[0:1]
	global_load_dwordx4 v[108:111], v89, s[4:5]
	v_mul_f32_e32 v54, v93, v93
	v_mov_b32_e32 v103, v55
	v_pk_fma_f32 v[54:55], v[92:93], v[92:93], v[54:55] op_sel_hi:[1,1,0]
	v_pk_add_f32 v[78:79], v[78:79], v[94:95]
	v_mov_b32_e32 v55, v97
	v_pk_add_f32 v[54:55], v[78:79], v[54:55]
	v_pk_add_f32 v[78:79], v[74:75], v[70:71]
	v_pk_add_f32 v[94:95], v[76:77], v[72:73]
	v_lshlrev_b32_e32 v57, 16, v52
	v_pk_add_f32 v[78:79], v[78:79], v[94:95]
	v_and_b32_e32 v51, 0xffff0000, v52
	v_and_b32_e32 v53, 0xffff0000, v53
	v_pk_add_f32 v[54:55], v[54:55], v[78:79]
	v_pk_add_f32 v[78:79], v[66:67], v[62:63]
	v_pk_add_f32 v[94:95], v[68:69], v[64:65]
	v_mul_f32_e32 v56, v57, v57
	v_mul_f32_e32 v50, v51, v51
	v_mul_f32_e32 v58, v59, v59
	v_mul_f32_e32 v52, v53, v53
	v_pk_add_f32 v[78:79], v[78:79], v[94:95]
	v_pk_add_f32 v[94:95], v[58:59], v[52:53]
	v_pk_add_f32 v[54:55], v[54:55], v[78:79]
	v_pk_add_f32 v[78:79], v[56:57], v[50:51]
	v_mul_f32_e32 v52, 0xbfb8aa3b, v44
	v_pk_add_f32 v[78:79], v[78:79], v[94:95]
	v_exp_f32_e32 v94, v52
	v_pk_add_f32 v[54:55], v[54:55], v[78:79]
	s_nop 0
	ds_bpermute_b32 v79, v184, v55
	ds_bpermute_b32 v78, v184, v54
	v_mul_f32_e32 v52, 0xbfb8aa3b, v45
	v_mov_b32_e32 v101, v93
	v_mov_b32_e32 v76, v75
	v_mov_b32_e32 v72, v71
	s_waitcnt lgkmcnt(0)
	v_pk_add_f32 v[54:55], v[54:55], v[78:79]
	s_nop 0
	ds_bpermute_b32 v79, v185, v55
	ds_bpermute_b32 v78, v185, v54
	v_mov_b32_e32 v68, v67
	s_waitcnt lgkmcnt(0)
	v_pk_add_f32 v[54:55], v[54:55], v[78:79]
	s_nop 0
	v_pk_mul_f32 v[54:55], v[54:55], s[38:39] op_sel_hi:[1,0]
	v_exp_f32_e32 v78, v52
	v_fma_f32 v49, -v55, v55, v54
	v_max_f32_e32 v49, 0, v49
	v_add_f32_e32 v49, 0x3a27c5ac, v49
	v_cmp_gt_f32_e32 vcc, s12, v49
	v_mul_f32_e32 v50, 0x4b800000, v49
	v_pk_add_f32 v[102:103], v[102:103], v[54:55] op_sel:[0,1] neg_lo:[0,1] neg_hi:[0,1]
	v_cndmask_b32_e32 v49, v49, v50, vcc
	v_rsq_f32_e32 v49, v49
	v_mul_f32_e32 v52, 0xbfb8aa3b, v46
	v_exp_f32_e32 v95, v52
	v_mul_f32_e32 v52, 0xbfb8aa3b, v47
	v_mul_f32_e32 v50, 0x45800000, v49
	v_cndmask_b32_e32 v50, v49, v50, vcc
	v_pk_mul_f32 v[102:103], v[102:103], v[50:51] op_sel_hi:[1,0]
	v_pk_add_f32 v[94:95], v[94:95], 1.0 op_sel_hi:[1,0]
	v_exp_f32_e32 v79, v52
	s_nop 0
	v_pk_add_f32 v[78:79], v[78:79], 1.0 op_sel_hi:[1,0]
	v_pk_add_f32 v[92:93], v[100:101], v[54:55] op_sel:[0,1] neg_lo:[0,1] neg_hi:[0,1]
	v_mad_i64_i32 v[48:49], s[10:11], v48, s13, v[86:87]
	v_rcp_f32_e32 v52, v95
	s_nop 0
	v_mul_f32_e32 v95, v46, v52
	s_waitcnt vmcnt(1)
	v_mov_b32_e32 v112, v104
	v_mov_b32_e32 v113, v106
	s_waitcnt vmcnt(0)
	v_mov_b32_e32 v114, v108
	v_mov_b32_e32 v115, v110
	v_pk_fma_f32 v[102:103], v[112:113], v[102:103], v[114:115]
	global_load_dwordx2 v[112:113], v[60:61], off
	v_pk_mul_f32 v[92:93], v[92:93], v[50:51] op_sel_hi:[1,0]
	v_mov_b32_e32 v106, v105
	v_mov_b32_e32 v110, v109
	v_rcp_f32_e32 v46, v94
	s_nop 0
	v_mul_f32_e32 v94, v44, v46
	v_pk_fma_f32 v[92:93], v[106:107], v[92:93], v[110:111]
	v_pk_add_f32 v[74:75], v[76:77], v[54:55] op_sel:[0,1] neg_lo:[0,1] neg_hi:[0,1]
	v_pk_add_f32 v[70:71], v[72:73], v[54:55] op_sel:[0,1] neg_lo:[0,1] neg_hi:[0,1]
	v_rcp_f32_e32 v44, v79
	s_nop 0
	v_mul_f32_e32 v47, v47, v44
	v_pk_mul_f32 v[74:75], v[74:75], v[50:51] op_sel_hi:[1,0]
	v_pk_mul_f32 v[70:71], v[70:71], v[50:51] op_sel_hi:[1,0]
	v_pk_add_f32 v[66:67], v[68:69], v[54:55] op_sel:[0,1] neg_lo:[0,1] neg_hi:[0,1]
	v_rcp_f32_e32 v44, v78
	s_nop 0
	v_mul_f32_e32 v46, v45, v44
	v_pk_mul_f32 v[66:67], v[66:67], v[50:51] op_sel_hi:[1,0]
	s_waitcnt vmcnt(0)
	v_and_b32_e32 v101, 0xffff0000, v113
	v_and_b32_e32 v100, 0xffff0000, v112
	v_lshlrev_b32_e32 v115, 16, v113
	v_lshlrev_b32_e32 v114, 16, v112
	v_pk_add_f32 v[92:93], v[92:93], v[100:101]
	v_pk_add_f32 v[102:103], v[102:103], v[114:115]
	v_pk_mul_f32 v[44:45], v[46:47], v[92:93]
	v_pk_mul_f32 v[94:95], v[94:95], v[102:103]
	v_and_b32_sdwa v52, v45, v154 dst_sel:DWORD dst_unused:UNUSED_PAD src0_sel:WORD_1 src1_sel:DWORD
	v_and_b32_sdwa v56, v44, v154 dst_sel:DWORD dst_unused:UNUSED_PAD src0_sel:WORD_1 src1_sel:DWORD
	v_and_b32_sdwa v46, v95, v154 dst_sel:DWORD dst_unused:UNUSED_PAD src0_sel:WORD_1 src1_sel:DWORD
	v_and_b32_sdwa v47, v94, v154 dst_sel:DWORD dst_unused:UNUSED_PAD src0_sel:WORD_1 src1_sel:DWORD
	v_add3_u32 v45, v45, v52, s33
	v_add3_u32 v44, v44, v56, s33
	v_add3_u32 v47, v94, v47, s33
	v_add3_u32 v46, v95, v46, s33
	v_and_b32_e32 v45, 0xffff0000, v45
	v_and_b32_e32 v44, 0xffff0000, v44
	v_or_b32_sdwa v45, v45, v46 dst_sel:DWORD dst_unused:UNUSED_PAD src0_sel:DWORD src1_sel:WORD_1
	v_or_b32_sdwa v44, v44, v47 dst_sel:DWORD dst_unused:UNUSED_PAD src0_sel:DWORD src1_sel:WORD_1
	global_store_dwordx2 v[48:49], v[44:45], off
	global_load_dwordx4 v[92:95], v89, s[0:1] offset:64
	global_load_dwordx4 v[100:103], v89, s[4:5] offset:64
	v_mul_f32_e32 v44, 0xbfb8aa3b, v40
	v_mul_f32_e32 v45, 0xbfb8aa3b, v42
	v_exp_f32_e32 v46, v44
	v_exp_f32_e32 v47, v45
	v_mul_f32_e32 v44, 0xbfb8aa3b, v41
	v_mul_f32_e32 v45, 0xbfb8aa3b, v43
	v_exp_f32_e32 v44, v44
	v_pk_add_f32 v[46:47], v[46:47], 1.0 op_sel_hi:[1,0]
	v_exp_f32_e32 v45, v45
	s_nop 0
	v_pk_add_f32 v[44:45], v[44:45], 1.0 op_sel_hi:[1,0]
	v_rcp_f32_e32 v52, v47
	s_nop 0
	v_mul_f32_e32 v47, v42, v52
	v_mov_b32_e32 v64, v63
	v_rcp_f32_e32 v42, v46
	s_nop 0
	v_mul_f32_e32 v46, v40, v42
	v_pk_add_f32 v[62:63], v[64:65], v[54:55] op_sel:[0,1] neg_lo:[0,1] neg_hi:[0,1]
	v_rcp_f32_e32 v40, v45
	s_nop 0
	v_mul_f32_e32 v43, v43, v40
	v_pk_mul_f32 v[62:63], v[62:63], v[50:51] op_sel_hi:[1,0]
	v_rcp_f32_e32 v40, v44
	s_nop 0
	v_mul_f32_e32 v42, v41, v40
	s_waitcnt vmcnt(1)
	v_mov_b32_e32 v76, v92
	v_mov_b32_e32 v77, v94
	s_waitcnt vmcnt(0)
	v_mov_b32_e32 v78, v100
	v_mov_b32_e32 v79, v102
	v_pk_fma_f32 v[74:75], v[74:75], v[76:77], v[78:79]
	global_load_dwordx2 v[76:77], v[60:61], off offset:32
	v_mov_b32_e32 v94, v93
	v_mov_b32_e32 v102, v101
	v_pk_fma_f32 v[70:71], v[70:71], v[94:95], v[102:103]
	s_waitcnt vmcnt(0)
	v_and_b32_e32 v73, 0xffff0000, v77
	v_and_b32_e32 v72, 0xffff0000, v76
	v_lshlrev_b32_e32 v79, 16, v77
	v_lshlrev_b32_e32 v78, 16, v76
	v_pk_add_f32 v[70:71], v[70:71], v[72:73]
	v_pk_add_f32 v[74:75], v[74:75], v[78:79]
	v_pk_mul_f32 v[40:41], v[42:43], v[70:71]
	v_pk_mul_f32 v[46:47], v[46:47], v[74:75]
	v_and_b32_sdwa v44, v41, v154 dst_sel:DWORD dst_unused:UNUSED_PAD src0_sel:WORD_1 src1_sel:DWORD
	v_and_b32_sdwa v45, v40, v154 dst_sel:DWORD dst_unused:UNUSED_PAD src0_sel:WORD_1 src1_sel:DWORD
	v_and_b32_sdwa v42, v47, v154 dst_sel:DWORD dst_unused:UNUSED_PAD src0_sel:WORD_1 src1_sel:DWORD
	v_and_b32_sdwa v43, v46, v154 dst_sel:DWORD dst_unused:UNUSED_PAD src0_sel:WORD_1 src1_sel:DWORD
	v_add3_u32 v41, v41, v44, s33
	v_add3_u32 v40, v40, v45, s33
	v_add3_u32 v43, v46, v43, s33
	v_add3_u32 v42, v47, v42, s33
	v_and_b32_e32 v41, 0xffff0000, v41
	v_and_b32_e32 v40, 0xffff0000, v40
	v_or_b32_sdwa v41, v41, v42 dst_sel:DWORD dst_unused:UNUSED_PAD src0_sel:DWORD src1_sel:WORD_1
	v_or_b32_sdwa v40, v40, v43 dst_sel:DWORD dst_unused:UNUSED_PAD src0_sel:DWORD src1_sel:WORD_1
	global_store_dwordx2 v[48:49], v[40:41], off offset:32
	global_load_dwordx4 v[42:45], v89, s[0:1] offset:128
	global_load_dwordx4 v[70:73], v89, s[4:5] offset:128
	v_mul_f32_e32 v40, 0xbfb8aa3b, v36
	v_mul_f32_e32 v41, 0xbfb8aa3b, v38
	v_exp_f32_e32 v46, v40
	v_exp_f32_e32 v47, v41
	v_mul_f32_e32 v40, 0xbfb8aa3b, v37
	v_mul_f32_e32 v41, 0xbfb8aa3b, v39
	v_exp_f32_e32 v40, v40
	v_exp_f32_e32 v41, v41
	s_waitcnt vmcnt(1)
	v_mov_b32_e32 v68, v42
	v_mov_b32_e32 v69, v44
	s_waitcnt vmcnt(0)
	v_mov_b32_e32 v74, v70
	v_mov_b32_e32 v75, v72
	v_pk_fma_f32 v[66:67], v[66:67], v[68:69], v[74:75]
	global_load_dwordx2 v[68:69], v[60:61], off offset:64
	v_mov_b32_e32 v44, v43
	v_mov_b32_e32 v72, v71
	v_pk_fma_f32 v[42:43], v[62:63], v[44:45], v[72:73]
	v_pk_add_f32 v[40:41], v[40:41], 1.0 op_sel_hi:[1,0]
	s_waitcnt vmcnt(0)
	v_and_b32_e32 v45, 0xffff0000, v69
	v_and_b32_e32 v44, 0xffff0000, v68
	v_pk_add_f32 v[42:43], v[42:43], v[44:45]
	v_pk_add_f32 v[44:45], v[46:47], 1.0 op_sel_hi:[1,0]
	v_lshlrev_b32_e32 v75, 16, v69
	v_lshlrev_b32_e32 v74, 16, v68
	v_pk_add_f32 v[66:67], v[66:67], v[74:75]
	v_rcp_f32_e32 v46, v45
	s_nop 0
	v_mul_f32_e32 v45, v38, v46
	v_mov_b32_e32 v58, v57
	v_rcp_f32_e32 v38, v44
	s_nop 0
	v_mul_f32_e32 v44, v36, v38
	v_pk_mul_f32 v[44:45], v[44:45], v[66:67]
	v_pk_add_f32 v[56:57], v[58:59], v[54:55] op_sel:[0,1] neg_lo:[0,1] neg_hi:[0,1]
	v_rcp_f32_e32 v36, v41
	s_nop 0
	v_mul_f32_e32 v39, v39, v36
	v_pk_mul_f32 v[56:57], v[56:57], v[50:51] op_sel_hi:[1,0]
	v_mov_b32_e32 v52, v51
	v_pk_add_f32 v[52:53], v[52:53], v[54:55] op_sel:[0,1] neg_lo:[0,1] neg_hi:[0,1]
	v_rcp_f32_e32 v36, v40
	s_nop 0
	v_mul_f32_e32 v38, v37, v36
	v_pk_mul_f32 v[36:37], v[38:39], v[42:43]
	v_and_b32_sdwa v38, v45, v154 dst_sel:DWORD dst_unused:UNUSED_PAD src0_sel:WORD_1 src1_sel:DWORD
	v_and_b32_sdwa v40, v37, v154 dst_sel:DWORD dst_unused:UNUSED_PAD src0_sel:WORD_1 src1_sel:DWORD
	v_and_b32_sdwa v41, v36, v154 dst_sel:DWORD dst_unused:UNUSED_PAD src0_sel:WORD_1 src1_sel:DWORD
	v_and_b32_sdwa v39, v44, v154 dst_sel:DWORD dst_unused:UNUSED_PAD src0_sel:WORD_1 src1_sel:DWORD
	v_add3_u32 v37, v37, v40, s33
	v_add3_u32 v36, v36, v41, s33
	v_add3_u32 v39, v44, v39, s33
	v_add3_u32 v38, v45, v38, s33
	v_and_b32_e32 v37, 0xffff0000, v37
	v_and_b32_e32 v36, 0xffff0000, v36
	v_or_b32_sdwa v37, v37, v38 dst_sel:DWORD dst_unused:UNUSED_PAD src0_sel:DWORD src1_sel:WORD_1
	v_or_b32_sdwa v36, v36, v39 dst_sel:DWORD dst_unused:UNUSED_PAD src0_sel:DWORD src1_sel:WORD_1
	global_store_dwordx2 v[48:49], v[36:37], off offset:64
	global_load_dwordx4 v[38:41], v89, s[0:1] offset:192
	global_load_dwordx4 v[42:45], v89, s[4:5] offset:192
	v_mul_f32_e32 v36, 0xbfb8aa3b, v32
	v_mul_f32_e32 v37, 0xbfb8aa3b, v34
	v_exp_f32_e32 v46, v36
	v_exp_f32_e32 v47, v37
	v_pk_mul_f32 v[50:51], v[52:53], v[50:51] op_sel_hi:[1,0]
	v_mul_f32_e32 v36, 0xbfb8aa3b, v33
	v_mul_f32_e32 v37, 0xbfb8aa3b, v35
	v_exp_f32_e32 v36, v36
	v_exp_f32_e32 v37, v37
	s_waitcnt vmcnt(1)
	v_mov_b32_e32 v58, v38
	v_mov_b32_e32 v59, v40
	s_waitcnt vmcnt(0)
	v_mov_b32_e32 v62, v42
	v_mov_b32_e32 v63, v44
	v_pk_fma_f32 v[56:57], v[56:57], v[58:59], v[62:63]
	global_load_dwordx2 v[58:59], v[60:61], off offset:96
	v_mov_b32_e32 v40, v39
	v_mov_b32_e32 v44, v43
	v_pk_fma_f32 v[38:39], v[50:51], v[40:41], v[44:45]
	v_pk_add_f32 v[36:37], v[36:37], 1.0 op_sel_hi:[1,0]
	s_waitcnt vmcnt(0)
	v_and_b32_e32 v41, 0xffff0000, v59
	v_and_b32_e32 v40, 0xffff0000, v58
	v_pk_add_f32 v[38:39], v[38:39], v[40:41]
	v_pk_add_f32 v[40:41], v[46:47], 1.0 op_sel_hi:[1,0]
	v_lshlrev_b32_e32 v61, 16, v59
	v_lshlrev_b32_e32 v60, 16, v58
	v_pk_add_f32 v[56:57], v[56:57], v[60:61]
	v_rcp_f32_e32 v42, v41
	s_nop 0
	v_mul_f32_e32 v41, v34, v42
	s_nop 0
	v_rcp_f32_e32 v34, v40
	s_nop 0
	v_mul_f32_e32 v40, v32, v34
	v_pk_mul_f32 v[40:41], v[40:41], v[56:57]
	v_rcp_f32_e32 v32, v37
	s_nop 0
	v_mul_f32_e32 v35, v35, v32
	s_nop 0
	v_rcp_f32_e32 v32, v36
	s_nop 0
	v_mul_f32_e32 v34, v33, v32
	v_pk_mul_f32 v[32:33], v[34:35], v[38:39]
	v_and_b32_sdwa v34, v41, v154 dst_sel:DWORD dst_unused:UNUSED_PAD src0_sel:WORD_1 src1_sel:DWORD
	v_and_b32_sdwa v36, v33, v154 dst_sel:DWORD dst_unused:UNUSED_PAD src0_sel:WORD_1 src1_sel:DWORD
	v_and_b32_sdwa v37, v32, v154 dst_sel:DWORD dst_unused:UNUSED_PAD src0_sel:WORD_1 src1_sel:DWORD
	v_and_b32_sdwa v35, v40, v154 dst_sel:DWORD dst_unused:UNUSED_PAD src0_sel:WORD_1 src1_sel:DWORD
	v_add3_u32 v33, v33, v36, s33
	v_add3_u32 v32, v32, v37, s33
	v_add3_u32 v35, v40, v35, s33
	v_add3_u32 v34, v41, v34, s33
	v_and_b32_e32 v33, 0xffff0000, v33
	v_and_b32_e32 v32, 0xffff0000, v32
	v_or_b32_sdwa v33, v33, v34 dst_sel:DWORD dst_unused:UNUSED_PAD src0_sel:DWORD src1_sel:WORD_1
	v_or_b32_sdwa v32, v32, v35 dst_sel:DWORD dst_unused:UNUSED_PAD src0_sel:DWORD src1_sel:WORD_1
	global_store_dwordx2 v[48:49], v[32:33], off offset:96
	v_add_u32_e32 v32, 48, v88
	v_ashrrev_i32_e32 v33, 31, v32
	v_lshlrev_b64 v[44:45], 11, v[32:33]
	v_lshl_add_u64 v[34:35], v[90:91], 0, v[44:45]
	global_load_dwordx2 v[38:39], v[34:35], off
	global_load_dwordx2 v[36:37], v[34:35], off offset:32
	v_lshl_add_u64 v[44:45], s[8:9], 0, v[44:45]
	v_lshl_add_u64 v[44:45], v[44:45], 0, v[96:97]
	s_waitcnt vmcnt(1)
	v_lshlrev_b32_e32 v70, 16, v38
	s_waitcnt vmcnt(0)
	v_lshlrev_b32_e32 v59, 16, v36
	v_and_b32_e32 v55, 0xffff0000, v36
	v_alignbit_b32 v33, v37, v36, 16
	v_and_b32_e32 v57, 0xffff0000, v37
	global_load_dwordx2 v[36:37], v[34:35], off offset:64
	v_and_b32_e32 v61, 0xffff0000, v33
	v_and_b32_e32 v65, 0xffff0000, v39
	v_and_b32_e32 v68, 0xffff0000, v38
	v_mov_b32_e32 v64, v70
	v_mov_b32_e32 v69, v70
	v_mul_f32_e32 v62, v70, v70
	v_mul_f32_e32 v58, v59, v59
	v_mul_f32_e32 v54, v55, v55
	v_mul_f32_e32 v60, v61, v61
	v_mul_f32_e32 v56, v57, v57
	s_waitcnt vmcnt(0)
	v_lshlrev_b32_e32 v51, 16, v36
	v_and_b32_e32 v47, 0xffff0000, v36
	v_alignbit_b32 v33, v37, v36, 16
	v_and_b32_e32 v49, 0xffff0000, v37
	global_load_dwordx2 v[36:37], v[34:35], off offset:96
	v_and_b32_e32 v53, 0xffff0000, v33
	v_mul_f32_e32 v50, v51, v51
	v_mul_f32_e32 v46, v47, v47
	v_mul_f32_e32 v52, v53, v53
	v_mul_f32_e32 v48, v49, v49
	s_waitcnt vmcnt(0)
	v_alignbit_b32 v33, v37, v36, 16
	v_and_b32_e32 v43, 0xffff0000, v33
	v_alignbit_b32 v33, v39, v38, 16
	v_and_b32_e32 v39, 0xffff0000, v33
	v_and_b32_e32 v38, 16, v38
	v_mov_b32_e32 v33, v70
	v_pk_add_f32 v[66:67], v[38:39], v[64:65]
	v_pk_add_f32 v[72:73], v[68:69], v[32:33] op_sel_hi:[0,1]
	v_mov_b32_e32 v63, v67
	v_pk_mul_f32 v[66:67], v[68:69], v[68:69]
	v_mov_b32_e32 v64, v39
	v_mov_b32_e32 v67, v73
	global_load_dwordx4 v[72:75], v89, s[0:1]
	global_load_dwordx4 v[76:79], v89, s[4:5]
	v_mul_f32_e32 v38, v65, v65
	v_mov_b32_e32 v71, v39
	v_pk_fma_f32 v[38:39], v[64:65], v[64:65], v[38:39] op_sel_hi:[1,1,0]
	v_pk_add_f32 v[62:63], v[62:63], v[66:67]
	v_mov_b32_e32 v39, v97
	v_pk_add_f32 v[38:39], v[62:63], v[38:39]
	v_pk_add_f32 v[62:63], v[58:59], v[54:55]
	v_pk_add_f32 v[66:67], v[60:61], v[56:57]
	v_lshlrev_b32_e32 v41, 16, v36
	v_pk_add_f32 v[62:63], v[62:63], v[66:67]
	v_and_b32_e32 v35, 0xffff0000, v36
	v_and_b32_e32 v37, 0xffff0000, v37
	v_pk_add_f32 v[38:39], v[38:39], v[62:63]
	v_pk_add_f32 v[62:63], v[50:51], v[46:47]
	v_pk_add_f32 v[66:67], v[52:53], v[48:49]
	v_mul_f32_e32 v40, v41, v41
	v_mul_f32_e32 v34, v35, v35
	v_mul_f32_e32 v42, v43, v43
	v_mul_f32_e32 v36, v37, v37
	v_pk_add_f32 v[62:63], v[62:63], v[66:67]
	v_pk_add_f32 v[66:67], v[42:43], v[36:37]
	v_pk_add_f32 v[38:39], v[38:39], v[62:63]
	v_pk_add_f32 v[62:63], v[40:41], v[34:35]
	v_mul_f32_e32 v36, 0xbfb8aa3b, v28
	v_pk_add_f32 v[62:63], v[62:63], v[66:67]
	v_exp_f32_e32 v66, v36
	v_pk_add_f32 v[38:39], v[38:39], v[62:63]
	s_nop 0
	ds_bpermute_b32 v63, v184, v39
	ds_bpermute_b32 v62, v184, v38
	v_mul_f32_e32 v36, 0xbfb8aa3b, v29
	v_mov_b32_e32 v69, v65
	v_mov_b32_e32 v60, v59
	v_mov_b32_e32 v56, v55
	s_waitcnt lgkmcnt(0)
	v_pk_add_f32 v[38:39], v[38:39], v[62:63]
	s_nop 0
	ds_bpermute_b32 v63, v185, v39
	ds_bpermute_b32 v62, v185, v38
	v_mov_b32_e32 v52, v51
	s_waitcnt lgkmcnt(0)
	v_pk_add_f32 v[38:39], v[38:39], v[62:63]
	s_nop 0
	v_pk_mul_f32 v[38:39], v[38:39], s[38:39] op_sel_hi:[1,0]
	v_exp_f32_e32 v62, v36
	v_fma_f32 v33, -v39, v39, v38
	v_max_f32_e32 v33, 0, v33
	v_add_f32_e32 v33, 0x3a27c5ac, v33
	v_cmp_gt_f32_e32 vcc, s12, v33
	v_mul_f32_e32 v34, 0x4b800000, v33
	v_pk_add_f32 v[70:71], v[70:71], v[38:39] op_sel:[0,1] neg_lo:[0,1] neg_hi:[0,1]
	v_cndmask_b32_e32 v33, v33, v34, vcc
	v_rsq_f32_e32 v33, v33
	v_mul_f32_e32 v36, 0xbfb8aa3b, v30
	v_exp_f32_e32 v67, v36
	v_mul_f32_e32 v36, 0xbfb8aa3b, v31
	v_mul_f32_e32 v34, 0x45800000, v33
	v_cndmask_b32_e32 v34, v33, v34, vcc
	v_pk_mul_f32 v[70:71], v[70:71], v[34:35] op_sel_hi:[1,0]
	v_pk_add_f32 v[66:67], v[66:67], 1.0 op_sel_hi:[1,0]
	v_exp_f32_e32 v63, v36
	s_nop 0
	v_pk_add_f32 v[62:63], v[62:63], 1.0 op_sel_hi:[1,0]
	v_pk_add_f32 v[64:65], v[68:69], v[38:39] op_sel:[0,1] neg_lo:[0,1] neg_hi:[0,1]
	v_mad_i64_i32 v[32:33], s[10:11], v32, s13, v[86:87]
	v_rcp_f32_e32 v36, v67
	s_nop 0
	v_mul_f32_e32 v67, v30, v36
	s_waitcnt vmcnt(1)
	v_mov_b32_e32 v92, v72
	v_mov_b32_e32 v93, v74
	s_waitcnt vmcnt(0)
	v_mov_b32_e32 v94, v76
	v_mov_b32_e32 v95, v78
	v_pk_fma_f32 v[70:71], v[92:93], v[70:71], v[94:95]
	global_load_dwordx2 v[92:93], v[44:45], off
	v_pk_mul_f32 v[64:65], v[64:65], v[34:35] op_sel_hi:[1,0]
	v_mov_b32_e32 v74, v73
	v_mov_b32_e32 v78, v77
	v_rcp_f32_e32 v30, v66
	s_nop 0
	v_mul_f32_e32 v66, v28, v30
	v_pk_fma_f32 v[64:65], v[74:75], v[64:65], v[78:79]
	v_pk_add_f32 v[58:59], v[60:61], v[38:39] op_sel:[0,1] neg_lo:[0,1] neg_hi:[0,1]
	v_pk_add_f32 v[54:55], v[56:57], v[38:39] op_sel:[0,1] neg_lo:[0,1] neg_hi:[0,1]
	v_rcp_f32_e32 v28, v63
	s_nop 0
	v_mul_f32_e32 v31, v31, v28
	v_pk_mul_f32 v[58:59], v[58:59], v[34:35] op_sel_hi:[1,0]
	v_pk_mul_f32 v[54:55], v[54:55], v[34:35] op_sel_hi:[1,0]
	v_pk_add_f32 v[50:51], v[52:53], v[38:39] op_sel:[0,1] neg_lo:[0,1] neg_hi:[0,1]
	v_rcp_f32_e32 v28, v62
	s_nop 0
	v_mul_f32_e32 v30, v29, v28
	v_pk_mul_f32 v[50:51], v[50:51], v[34:35] op_sel_hi:[1,0]
	s_waitcnt vmcnt(0)
	v_and_b32_e32 v69, 0xffff0000, v93
	v_and_b32_e32 v68, 0xffff0000, v92
	v_lshlrev_b32_e32 v95, 16, v93
	v_lshlrev_b32_e32 v94, 16, v92
	v_pk_add_f32 v[64:65], v[64:65], v[68:69]
	v_pk_add_f32 v[70:71], v[70:71], v[94:95]
	v_pk_mul_f32 v[28:29], v[30:31], v[64:65]
	v_pk_mul_f32 v[66:67], v[66:67], v[70:71]
	v_and_b32_sdwa v36, v29, v154 dst_sel:DWORD dst_unused:UNUSED_PAD src0_sel:WORD_1 src1_sel:DWORD
	v_and_b32_sdwa v40, v28, v154 dst_sel:DWORD dst_unused:UNUSED_PAD src0_sel:WORD_1 src1_sel:DWORD
	v_and_b32_sdwa v30, v67, v154 dst_sel:DWORD dst_unused:UNUSED_PAD src0_sel:WORD_1 src1_sel:DWORD
	v_and_b32_sdwa v31, v66, v154 dst_sel:DWORD dst_unused:UNUSED_PAD src0_sel:WORD_1 src1_sel:DWORD
	v_add3_u32 v29, v29, v36, s33
	v_add3_u32 v28, v28, v40, s33
	v_add3_u32 v31, v66, v31, s33
	v_add3_u32 v30, v67, v30, s33
	v_and_b32_e32 v29, 0xffff0000, v29
	v_and_b32_e32 v28, 0xffff0000, v28
	v_or_b32_sdwa v29, v29, v30 dst_sel:DWORD dst_unused:UNUSED_PAD src0_sel:DWORD src1_sel:WORD_1
	v_or_b32_sdwa v28, v28, v31 dst_sel:DWORD dst_unused:UNUSED_PAD src0_sel:DWORD src1_sel:WORD_1
	global_store_dwordx2 v[32:33], v[28:29], off
	global_load_dwordx4 v[62:65], v89, s[0:1] offset:64
	global_load_dwordx4 v[66:69], v89, s[4:5] offset:64
	v_mul_f32_e32 v28, 0xbfb8aa3b, v24
	v_mul_f32_e32 v29, 0xbfb8aa3b, v26
	v_exp_f32_e32 v30, v28
	v_exp_f32_e32 v31, v29
	v_mul_f32_e32 v28, 0xbfb8aa3b, v25
	v_mul_f32_e32 v29, 0xbfb8aa3b, v27
	v_exp_f32_e32 v28, v28
	v_pk_add_f32 v[30:31], v[30:31], 1.0 op_sel_hi:[1,0]
	v_exp_f32_e32 v29, v29
	s_nop 0
	v_pk_add_f32 v[28:29], v[28:29], 1.0 op_sel_hi:[1,0]
	v_rcp_f32_e32 v36, v31
	s_nop 0
	v_mul_f32_e32 v31, v26, v36
	v_mov_b32_e32 v48, v47
	v_rcp_f32_e32 v26, v30
	s_nop 0
	v_mul_f32_e32 v30, v24, v26
	v_pk_add_f32 v[46:47], v[48:49], v[38:39] op_sel:[0,1] neg_lo:[0,1] neg_hi:[0,1]
	v_rcp_f32_e32 v24, v29
	s_nop 0
	v_mul_f32_e32 v27, v27, v24
	v_pk_mul_f32 v[46:47], v[46:47], v[34:35] op_sel_hi:[1,0]
	v_rcp_f32_e32 v24, v28
	s_nop 0
	v_mul_f32_e32 v26, v25, v24
	s_waitcnt vmcnt(1)
	v_mov_b32_e32 v60, v62
	v_mov_b32_e32 v61, v64
	s_waitcnt vmcnt(0)
	v_mov_b32_e32 v70, v66
	v_mov_b32_e32 v71, v68
	v_pk_fma_f32 v[58:59], v[58:59], v[60:61], v[70:71]
	global_load_dwordx2 v[60:61], v[44:45], off offset:32
	v_mov_b32_e32 v64, v63
	v_mov_b32_e32 v68, v67
	v_pk_fma_f32 v[54:55], v[54:55], v[64:65], v[68:69]
	s_waitcnt vmcnt(0)
	v_and_b32_e32 v57, 0xffff0000, v61
	v_and_b32_e32 v56, 0xffff0000, v60
	v_lshlrev_b32_e32 v71, 16, v61
	v_lshlrev_b32_e32 v70, 16, v60
	v_pk_add_f32 v[54:55], v[54:55], v[56:57]
	v_pk_add_f32 v[58:59], v[58:59], v[70:71]
	v_pk_mul_f32 v[24:25], v[26:27], v[54:55]
	v_pk_mul_f32 v[30:31], v[30:31], v[58:59]
	v_and_b32_sdwa v28, v25, v154 dst_sel:DWORD dst_unused:UNUSED_PAD src0_sel:WORD_1 src1_sel:DWORD
	v_and_b32_sdwa v29, v24, v154 dst_sel:DWORD dst_unused:UNUSED_PAD src0_sel:WORD_1 src1_sel:DWORD
	v_and_b32_sdwa v26, v31, v154 dst_sel:DWORD dst_unused:UNUSED_PAD src0_sel:WORD_1 src1_sel:DWORD
	v_and_b32_sdwa v27, v30, v154 dst_sel:DWORD dst_unused:UNUSED_PAD src0_sel:WORD_1 src1_sel:DWORD
	v_add3_u32 v25, v25, v28, s33
	v_add3_u32 v24, v24, v29, s33
	v_add3_u32 v27, v30, v27, s33
	v_add3_u32 v26, v31, v26, s33
	v_and_b32_e32 v25, 0xffff0000, v25
	v_and_b32_e32 v24, 0xffff0000, v24
	v_or_b32_sdwa v25, v25, v26 dst_sel:DWORD dst_unused:UNUSED_PAD src0_sel:DWORD src1_sel:WORD_1
	v_or_b32_sdwa v24, v24, v27 dst_sel:DWORD dst_unused:UNUSED_PAD src0_sel:DWORD src1_sel:WORD_1
	global_store_dwordx2 v[32:33], v[24:25], off offset:32
	global_load_dwordx4 v[26:29], v89, s[0:1] offset:128
	global_load_dwordx4 v[54:57], v89, s[4:5] offset:128
	v_mul_f32_e32 v24, 0xbfb8aa3b, v20
	v_mul_f32_e32 v25, 0xbfb8aa3b, v22
	v_exp_f32_e32 v30, v24
	v_exp_f32_e32 v31, v25
	v_mul_f32_e32 v24, 0xbfb8aa3b, v21
	v_mul_f32_e32 v25, 0xbfb8aa3b, v23
	v_exp_f32_e32 v24, v24
	v_exp_f32_e32 v25, v25
	s_waitcnt vmcnt(1)
	v_mov_b32_e32 v52, v26
	v_mov_b32_e32 v53, v28
	s_waitcnt vmcnt(0)
	v_mov_b32_e32 v58, v54
	v_mov_b32_e32 v59, v56
	v_pk_fma_f32 v[50:51], v[50:51], v[52:53], v[58:59]
	global_load_dwordx2 v[52:53], v[44:45], off offset:64
	v_mov_b32_e32 v28, v27
	v_mov_b32_e32 v56, v55
	v_pk_fma_f32 v[26:27], v[46:47], v[28:29], v[56:57]
	v_pk_add_f32 v[24:25], v[24:25], 1.0 op_sel_hi:[1,0]
	s_waitcnt vmcnt(0)
	v_and_b32_e32 v29, 0xffff0000, v53
	v_and_b32_e32 v28, 0xffff0000, v52
	v_pk_add_f32 v[26:27], v[26:27], v[28:29]
	v_pk_add_f32 v[28:29], v[30:31], 1.0 op_sel_hi:[1,0]
	v_lshlrev_b32_e32 v59, 16, v53
	v_lshlrev_b32_e32 v58, 16, v52
	v_pk_add_f32 v[50:51], v[50:51], v[58:59]
	v_rcp_f32_e32 v30, v29
	s_nop 0
	v_mul_f32_e32 v29, v22, v30
	v_mov_b32_e32 v42, v41
	v_rcp_f32_e32 v22, v28
	s_nop 0
	v_mul_f32_e32 v28, v20, v22
	v_pk_mul_f32 v[28:29], v[28:29], v[50:51]
	v_pk_add_f32 v[40:41], v[42:43], v[38:39] op_sel:[0,1] neg_lo:[0,1] neg_hi:[0,1]
	v_rcp_f32_e32 v20, v25
	s_nop 0
	v_mul_f32_e32 v23, v23, v20
	v_pk_mul_f32 v[40:41], v[40:41], v[34:35] op_sel_hi:[1,0]
	v_mov_b32_e32 v36, v35
	v_pk_add_f32 v[36:37], v[36:37], v[38:39] op_sel:[0,1] neg_lo:[0,1] neg_hi:[0,1]
	v_rcp_f32_e32 v20, v24
	s_nop 0
	v_mul_f32_e32 v22, v21, v20
	v_pk_mul_f32 v[20:21], v[22:23], v[26:27]
	v_and_b32_sdwa v22, v29, v154 dst_sel:DWORD dst_unused:UNUSED_PAD src0_sel:WORD_1 src1_sel:DWORD
	v_and_b32_sdwa v24, v21, v154 dst_sel:DWORD dst_unused:UNUSED_PAD src0_sel:WORD_1 src1_sel:DWORD
	v_and_b32_sdwa v25, v20, v154 dst_sel:DWORD dst_unused:UNUSED_PAD src0_sel:WORD_1 src1_sel:DWORD
	v_and_b32_sdwa v23, v28, v154 dst_sel:DWORD dst_unused:UNUSED_PAD src0_sel:WORD_1 src1_sel:DWORD
	v_add3_u32 v21, v21, v24, s33
	v_add3_u32 v20, v20, v25, s33
	v_add3_u32 v23, v28, v23, s33
	v_add3_u32 v22, v29, v22, s33
	v_and_b32_e32 v21, 0xffff0000, v21
	v_and_b32_e32 v20, 0xffff0000, v20
	v_or_b32_sdwa v21, v21, v22 dst_sel:DWORD dst_unused:UNUSED_PAD src0_sel:DWORD src1_sel:WORD_1
	v_or_b32_sdwa v20, v20, v23 dst_sel:DWORD dst_unused:UNUSED_PAD src0_sel:DWORD src1_sel:WORD_1
	global_store_dwordx2 v[32:33], v[20:21], off offset:64
	global_load_dwordx4 v[22:25], v89, s[0:1] offset:192
	global_load_dwordx4 v[26:29], v89, s[4:5] offset:192
	v_mul_f32_e32 v20, 0xbfb8aa3b, v16
	v_mul_f32_e32 v21, 0xbfb8aa3b, v18
	v_exp_f32_e32 v30, v20
	v_exp_f32_e32 v31, v21
	v_pk_mul_f32 v[34:35], v[36:37], v[34:35] op_sel_hi:[1,0]
	v_mul_f32_e32 v20, 0xbfb8aa3b, v17
	v_mul_f32_e32 v21, 0xbfb8aa3b, v19
	v_exp_f32_e32 v20, v20
	v_exp_f32_e32 v21, v21
	s_waitcnt vmcnt(1)
	v_mov_b32_e32 v42, v22
	v_mov_b32_e32 v43, v24
	s_waitcnt vmcnt(0)
	v_mov_b32_e32 v46, v26
	v_mov_b32_e32 v47, v28
	v_pk_fma_f32 v[40:41], v[40:41], v[42:43], v[46:47]
	global_load_dwordx2 v[42:43], v[44:45], off offset:96
	v_mov_b32_e32 v24, v23
	v_mov_b32_e32 v28, v27
	v_pk_fma_f32 v[22:23], v[34:35], v[24:25], v[28:29]
	v_pk_add_f32 v[20:21], v[20:21], 1.0 op_sel_hi:[1,0]
	s_waitcnt vmcnt(0)
	v_and_b32_e32 v25, 0xffff0000, v43
	v_and_b32_e32 v24, 0xffff0000, v42
	v_pk_add_f32 v[22:23], v[22:23], v[24:25]
	v_pk_add_f32 v[24:25], v[30:31], 1.0 op_sel_hi:[1,0]
	v_lshlrev_b32_e32 v45, 16, v43
	v_lshlrev_b32_e32 v44, 16, v42
	v_pk_add_f32 v[40:41], v[40:41], v[44:45]
	v_rcp_f32_e32 v26, v25
	s_nop 0
	v_mul_f32_e32 v25, v18, v26
	s_nop 0
	v_rcp_f32_e32 v18, v24
	s_nop 0
	v_mul_f32_e32 v24, v16, v18
	v_pk_mul_f32 v[24:25], v[24:25], v[40:41]
	v_rcp_f32_e32 v16, v21
	s_nop 0
	v_mul_f32_e32 v19, v19, v16
	s_nop 0
	v_rcp_f32_e32 v16, v20
	s_nop 0
	v_mul_f32_e32 v18, v17, v16
	v_pk_mul_f32 v[16:17], v[18:19], v[22:23]
	v_and_b32_sdwa v18, v25, v154 dst_sel:DWORD dst_unused:UNUSED_PAD src0_sel:WORD_1 src1_sel:DWORD
	v_and_b32_sdwa v20, v17, v154 dst_sel:DWORD dst_unused:UNUSED_PAD src0_sel:WORD_1 src1_sel:DWORD
	v_and_b32_sdwa v21, v16, v154 dst_sel:DWORD dst_unused:UNUSED_PAD src0_sel:WORD_1 src1_sel:DWORD
	v_and_b32_sdwa v19, v24, v154 dst_sel:DWORD dst_unused:UNUSED_PAD src0_sel:WORD_1 src1_sel:DWORD
	v_add3_u32 v17, v17, v20, s33
	v_add3_u32 v16, v16, v21, s33
	v_add3_u32 v19, v24, v19, s33
	v_add3_u32 v18, v25, v18, s33
	v_and_b32_e32 v17, 0xffff0000, v17
	v_and_b32_e32 v16, 0xffff0000, v16
	v_or_b32_sdwa v17, v17, v18 dst_sel:DWORD dst_unused:UNUSED_PAD src0_sel:DWORD src1_sel:WORD_1
	v_or_b32_sdwa v16, v16, v19 dst_sel:DWORD dst_unused:UNUSED_PAD src0_sel:DWORD src1_sel:WORD_1
	global_store_dwordx2 v[32:33], v[16:17], off offset:96
	v_add_u32_e32 v16, 64, v88
	v_ashrrev_i32_e32 v17, 31, v16
	v_lshlrev_b64 v[28:29], 11, v[16:17]
	v_lshl_add_u64 v[18:19], v[90:91], 0, v[28:29]
	global_load_dwordx2 v[22:23], v[18:19], off
	global_load_dwordx2 v[20:21], v[18:19], off offset:32
	v_lshl_add_u64 v[28:29], s[8:9], 0, v[28:29]
	v_lshl_add_u64 v[28:29], v[28:29], 0, v[96:97]
	s_waitcnt vmcnt(1)
	v_lshlrev_b32_e32 v54, 16, v22
	s_waitcnt vmcnt(0)
	v_lshlrev_b32_e32 v43, 16, v20
	v_and_b32_e32 v39, 0xffff0000, v20
	v_alignbit_b32 v17, v21, v20, 16
	v_and_b32_e32 v41, 0xffff0000, v21
	global_load_dwordx2 v[20:21], v[18:19], off offset:64
	v_and_b32_e32 v45, 0xffff0000, v17
	v_and_b32_e32 v49, 0xffff0000, v23
	v_and_b32_e32 v52, 0xffff0000, v22
	v_mov_b32_e32 v48, v54
	v_mov_b32_e32 v53, v54
	v_mul_f32_e32 v46, v54, v54
	v_mul_f32_e32 v42, v43, v43
	v_mul_f32_e32 v38, v39, v39
	v_mul_f32_e32 v44, v45, v45
	v_mul_f32_e32 v40, v41, v41
	s_waitcnt vmcnt(0)
	v_lshlrev_b32_e32 v35, 16, v20
	v_and_b32_e32 v31, 0xffff0000, v20
	v_alignbit_b32 v17, v21, v20, 16
	v_and_b32_e32 v33, 0xffff0000, v21
	global_load_dwordx2 v[20:21], v[18:19], off offset:96
	v_and_b32_e32 v37, 0xffff0000, v17
	v_mul_f32_e32 v34, v35, v35
	v_mul_f32_e32 v30, v31, v31
	v_mul_f32_e32 v36, v37, v37
	v_mul_f32_e32 v32, v33, v33
	s_waitcnt vmcnt(0)
	v_alignbit_b32 v17, v21, v20, 16
	v_and_b32_e32 v27, 0xffff0000, v17
	v_alignbit_b32 v17, v23, v22, 16
	v_and_b32_e32 v23, 0xffff0000, v17
	v_and_b32_e32 v22, 16, v22
	v_mov_b32_e32 v17, v54
	v_pk_add_f32 v[50:51], v[22:23], v[48:49]
	v_pk_add_f32 v[56:57], v[52:53], v[16:17] op_sel_hi:[0,1]
	v_mov_b32_e32 v47, v51
	v_pk_mul_f32 v[50:51], v[52:53], v[52:53]
	v_mov_b32_e32 v48, v23
	v_mov_b32_e32 v51, v57
	global_load_dwordx4 v[56:59], v89, s[0:1]
	global_load_dwordx4 v[60:63], v89, s[4:5]
	v_mul_f32_e32 v22, v49, v49
	v_mov_b32_e32 v55, v23
	v_pk_fma_f32 v[22:23], v[48:49], v[48:49], v[22:23] op_sel_hi:[1,1,0]
	v_pk_add_f32 v[46:47], v[46:47], v[50:51]
	v_mov_b32_e32 v23, v97
	v_pk_add_f32 v[22:23], v[46:47], v[22:23]
	v_pk_add_f32 v[46:47], v[42:43], v[38:39]
	v_pk_add_f32 v[50:51], v[44:45], v[40:41]
	v_lshlrev_b32_e32 v25, 16, v20
	v_pk_add_f32 v[46:47], v[46:47], v[50:51]
	v_and_b32_e32 v19, 0xffff0000, v20
	v_and_b32_e32 v21, 0xffff0000, v21
	v_pk_add_f32 v[22:23], v[22:23], v[46:47]
	v_pk_add_f32 v[46:47], v[34:35], v[30:31]
	v_pk_add_f32 v[50:51], v[36:37], v[32:33]
	v_mul_f32_e32 v24, v25, v25
	v_mul_f32_e32 v18, v19, v19
	v_mul_f32_e32 v26, v27, v27
	v_mul_f32_e32 v20, v21, v21
	v_pk_add_f32 v[46:47], v[46:47], v[50:51]
	v_pk_add_f32 v[50:51], v[26:27], v[20:21]
	v_pk_add_f32 v[22:23], v[22:23], v[46:47]
	v_pk_add_f32 v[46:47], v[24:25], v[18:19]
	v_mul_f32_e32 v20, 0xbfb8aa3b, v12
	v_pk_add_f32 v[46:47], v[46:47], v[50:51]
	v_exp_f32_e32 v50, v20
	v_pk_add_f32 v[22:23], v[22:23], v[46:47]
	s_nop 0
	ds_bpermute_b32 v47, v184, v23
	ds_bpermute_b32 v46, v184, v22
	v_mul_f32_e32 v20, 0xbfb8aa3b, v13
	v_mov_b32_e32 v53, v49
	v_mov_b32_e32 v44, v43
	v_mov_b32_e32 v40, v39
	s_waitcnt lgkmcnt(0)
	v_pk_add_f32 v[22:23], v[22:23], v[46:47]
	s_nop 0
	ds_bpermute_b32 v47, v185, v23
	ds_bpermute_b32 v46, v185, v22
	v_mov_b32_e32 v36, v35
	s_waitcnt lgkmcnt(0)
	v_pk_add_f32 v[22:23], v[22:23], v[46:47]
	s_nop 0
	v_pk_mul_f32 v[22:23], v[22:23], s[38:39] op_sel_hi:[1,0]
	v_exp_f32_e32 v46, v20
	v_fma_f32 v17, -v23, v23, v22
	v_max_f32_e32 v17, 0, v17
	v_add_f32_e32 v17, 0x3a27c5ac, v17
	v_cmp_gt_f32_e32 vcc, s12, v17
	v_mul_f32_e32 v18, 0x4b800000, v17
	v_pk_add_f32 v[54:55], v[54:55], v[22:23] op_sel:[0,1] neg_lo:[0,1] neg_hi:[0,1]
	v_cndmask_b32_e32 v17, v17, v18, vcc
	v_rsq_f32_e32 v17, v17
	v_mul_f32_e32 v20, 0xbfb8aa3b, v14
	v_exp_f32_e32 v51, v20
	v_mul_f32_e32 v20, 0xbfb8aa3b, v15
	v_mul_f32_e32 v18, 0x45800000, v17
	v_cndmask_b32_e32 v18, v17, v18, vcc
	v_pk_mul_f32 v[54:55], v[54:55], v[18:19] op_sel_hi:[1,0]
	v_pk_add_f32 v[50:51], v[50:51], 1.0 op_sel_hi:[1,0]
	v_exp_f32_e32 v47, v20
	s_nop 0
	v_pk_add_f32 v[46:47], v[46:47], 1.0 op_sel_hi:[1,0]
	v_pk_add_f32 v[48:49], v[52:53], v[22:23] op_sel:[0,1] neg_lo:[0,1] neg_hi:[0,1]
	v_mad_i64_i32 v[16:17], s[10:11], v16, s13, v[86:87]
	v_rcp_f32_e32 v20, v51
	s_nop 0
	v_mul_f32_e32 v51, v14, v20
	s_waitcnt vmcnt(1)
	v_mov_b32_e32 v64, v56
	v_mov_b32_e32 v65, v58
	s_waitcnt vmcnt(0)
	v_mov_b32_e32 v66, v60
	v_mov_b32_e32 v67, v62
	v_pk_fma_f32 v[54:55], v[64:65], v[54:55], v[66:67]
	global_load_dwordx2 v[64:65], v[28:29], off
	v_pk_mul_f32 v[48:49], v[48:49], v[18:19] op_sel_hi:[1,0]
	v_mov_b32_e32 v58, v57
	v_mov_b32_e32 v62, v61
	v_rcp_f32_e32 v14, v50
	s_nop 0
	v_mul_f32_e32 v50, v12, v14
	v_pk_fma_f32 v[48:49], v[58:59], v[48:49], v[62:63]
	v_pk_add_f32 v[42:43], v[44:45], v[22:23] op_sel:[0,1] neg_lo:[0,1] neg_hi:[0,1]
	v_pk_add_f32 v[38:39], v[40:41], v[22:23] op_sel:[0,1] neg_lo:[0,1] neg_hi:[0,1]
	v_rcp_f32_e32 v12, v47
	s_nop 0
	v_mul_f32_e32 v15, v15, v12
	v_pk_mul_f32 v[42:43], v[42:43], v[18:19] op_sel_hi:[1,0]
	v_pk_mul_f32 v[38:39], v[38:39], v[18:19] op_sel_hi:[1,0]
	v_pk_add_f32 v[34:35], v[36:37], v[22:23] op_sel:[0,1] neg_lo:[0,1] neg_hi:[0,1]
	v_rcp_f32_e32 v12, v46
	s_nop 0
	v_mul_f32_e32 v14, v13, v12
	v_pk_mul_f32 v[34:35], v[34:35], v[18:19] op_sel_hi:[1,0]
	s_waitcnt vmcnt(0)
	v_and_b32_e32 v53, 0xffff0000, v65
	v_and_b32_e32 v52, 0xffff0000, v64
	v_lshlrev_b32_e32 v67, 16, v65
	v_lshlrev_b32_e32 v66, 16, v64
	v_pk_add_f32 v[48:49], v[48:49], v[52:53]
	v_pk_add_f32 v[54:55], v[54:55], v[66:67]
	v_pk_mul_f32 v[12:13], v[14:15], v[48:49]
	v_pk_mul_f32 v[50:51], v[50:51], v[54:55]
	v_and_b32_sdwa v20, v13, v154 dst_sel:DWORD dst_unused:UNUSED_PAD src0_sel:WORD_1 src1_sel:DWORD
	v_and_b32_sdwa v24, v12, v154 dst_sel:DWORD dst_unused:UNUSED_PAD src0_sel:WORD_1 src1_sel:DWORD
	v_and_b32_sdwa v14, v51, v154 dst_sel:DWORD dst_unused:UNUSED_PAD src0_sel:WORD_1 src1_sel:DWORD
	v_and_b32_sdwa v15, v50, v154 dst_sel:DWORD dst_unused:UNUSED_PAD src0_sel:WORD_1 src1_sel:DWORD
	v_add3_u32 v13, v13, v20, s33
	v_add3_u32 v12, v12, v24, s33
	v_add3_u32 v15, v50, v15, s33
	v_add3_u32 v14, v51, v14, s33
	v_and_b32_e32 v13, 0xffff0000, v13
	v_and_b32_e32 v12, 0xffff0000, v12
	v_or_b32_sdwa v13, v13, v14 dst_sel:DWORD dst_unused:UNUSED_PAD src0_sel:DWORD src1_sel:WORD_1
	v_or_b32_sdwa v12, v12, v15 dst_sel:DWORD dst_unused:UNUSED_PAD src0_sel:DWORD src1_sel:WORD_1
	global_store_dwordx2 v[16:17], v[12:13], off
	global_load_dwordx4 v[46:49], v89, s[0:1] offset:64
	global_load_dwordx4 v[50:53], v89, s[4:5] offset:64
	v_mul_f32_e32 v12, 0xbfb8aa3b, v8
	v_mul_f32_e32 v13, 0xbfb8aa3b, v10
	v_exp_f32_e32 v14, v12
	v_exp_f32_e32 v15, v13
	v_mul_f32_e32 v12, 0xbfb8aa3b, v9
	v_mul_f32_e32 v13, 0xbfb8aa3b, v11
	v_exp_f32_e32 v12, v12
	v_pk_add_f32 v[14:15], v[14:15], 1.0 op_sel_hi:[1,0]
	v_exp_f32_e32 v13, v13
	s_nop 0
	v_pk_add_f32 v[12:13], v[12:13], 1.0 op_sel_hi:[1,0]
	v_rcp_f32_e32 v20, v15
	s_nop 0
	v_mul_f32_e32 v15, v10, v20
	v_mov_b32_e32 v32, v31
	v_rcp_f32_e32 v10, v14
	s_nop 0
	v_mul_f32_e32 v14, v8, v10
	v_pk_add_f32 v[30:31], v[32:33], v[22:23] op_sel:[0,1] neg_lo:[0,1] neg_hi:[0,1]
	v_rcp_f32_e32 v8, v13
	s_nop 0
	v_mul_f32_e32 v11, v11, v8
	v_pk_mul_f32 v[30:31], v[30:31], v[18:19] op_sel_hi:[1,0]
	v_rcp_f32_e32 v8, v12
	s_nop 0
	v_mul_f32_e32 v10, v9, v8
	s_waitcnt vmcnt(1)
	v_mov_b32_e32 v44, v46
	v_mov_b32_e32 v45, v48
	s_waitcnt vmcnt(0)
	v_mov_b32_e32 v54, v50
	v_mov_b32_e32 v55, v52
	v_pk_fma_f32 v[42:43], v[42:43], v[44:45], v[54:55]
	global_load_dwordx2 v[44:45], v[28:29], off offset:32
	v_mov_b32_e32 v48, v47
	v_mov_b32_e32 v52, v51
	v_pk_fma_f32 v[38:39], v[38:39], v[48:49], v[52:53]
	s_waitcnt vmcnt(0)
	v_and_b32_e32 v41, 0xffff0000, v45
	v_and_b32_e32 v40, 0xffff0000, v44
	v_lshlrev_b32_e32 v55, 16, v45
	v_lshlrev_b32_e32 v54, 16, v44
	v_pk_add_f32 v[38:39], v[38:39], v[40:41]
	v_pk_add_f32 v[42:43], v[42:43], v[54:55]
	v_pk_mul_f32 v[8:9], v[10:11], v[38:39]
	v_pk_mul_f32 v[14:15], v[14:15], v[42:43]
	v_and_b32_sdwa v12, v9, v154 dst_sel:DWORD dst_unused:UNUSED_PAD src0_sel:WORD_1 src1_sel:DWORD
	v_and_b32_sdwa v13, v8, v154 dst_sel:DWORD dst_unused:UNUSED_PAD src0_sel:WORD_1 src1_sel:DWORD
	v_and_b32_sdwa v10, v15, v154 dst_sel:DWORD dst_unused:UNUSED_PAD src0_sel:WORD_1 src1_sel:DWORD
	v_and_b32_sdwa v11, v14, v154 dst_sel:DWORD dst_unused:UNUSED_PAD src0_sel:WORD_1 src1_sel:DWORD
	v_add3_u32 v9, v9, v12, s33
	v_add3_u32 v8, v8, v13, s33
	v_add3_u32 v11, v14, v11, s33
	v_add3_u32 v10, v15, v10, s33
	v_and_b32_e32 v9, 0xffff0000, v9
	v_and_b32_e32 v8, 0xffff0000, v8
	v_or_b32_sdwa v9, v9, v10 dst_sel:DWORD dst_unused:UNUSED_PAD src0_sel:DWORD src1_sel:WORD_1
	v_or_b32_sdwa v8, v8, v11 dst_sel:DWORD dst_unused:UNUSED_PAD src0_sel:DWORD src1_sel:WORD_1
	global_store_dwordx2 v[16:17], v[8:9], off offset:32
	global_load_dwordx4 v[10:13], v89, s[0:1] offset:128
	global_load_dwordx4 v[38:41], v89, s[4:5] offset:128
	v_mul_f32_e32 v8, 0xbfb8aa3b, v4
	v_mul_f32_e32 v9, 0xbfb8aa3b, v6
	v_exp_f32_e32 v14, v8
	v_exp_f32_e32 v15, v9
	v_mul_f32_e32 v8, 0xbfb8aa3b, v5
	v_mul_f32_e32 v9, 0xbfb8aa3b, v7
	v_exp_f32_e32 v8, v8
	v_exp_f32_e32 v9, v9
	s_waitcnt vmcnt(1)
	v_mov_b32_e32 v36, v10
	v_mov_b32_e32 v37, v12
	s_waitcnt vmcnt(0)
	v_mov_b32_e32 v42, v38
	v_mov_b32_e32 v43, v40
	v_pk_fma_f32 v[34:35], v[34:35], v[36:37], v[42:43]
	global_load_dwordx2 v[36:37], v[28:29], off offset:64
	v_mov_b32_e32 v12, v11
	v_mov_b32_e32 v40, v39
	v_pk_fma_f32 v[10:11], v[30:31], v[12:13], v[40:41]
	v_pk_add_f32 v[8:9], v[8:9], 1.0 op_sel_hi:[1,0]
	s_waitcnt vmcnt(0)
	v_and_b32_e32 v13, 0xffff0000, v37
	v_and_b32_e32 v12, 0xffff0000, v36
	v_pk_add_f32 v[10:11], v[10:11], v[12:13]
	v_pk_add_f32 v[12:13], v[14:15], 1.0 op_sel_hi:[1,0]
	v_lshlrev_b32_e32 v43, 16, v37
	v_lshlrev_b32_e32 v42, 16, v36
	v_pk_add_f32 v[34:35], v[34:35], v[42:43]
	v_rcp_f32_e32 v14, v13
	s_nop 0
	v_mul_f32_e32 v13, v6, v14
	v_mov_b32_e32 v26, v25
	v_rcp_f32_e32 v6, v12
	s_nop 0
	v_mul_f32_e32 v12, v4, v6
	v_pk_mul_f32 v[12:13], v[12:13], v[34:35]
	v_pk_add_f32 v[24:25], v[26:27], v[22:23] op_sel:[0,1] neg_lo:[0,1] neg_hi:[0,1]
	v_rcp_f32_e32 v4, v9
	s_nop 0
	v_mul_f32_e32 v7, v7, v4
	v_pk_mul_f32 v[24:25], v[24:25], v[18:19] op_sel_hi:[1,0]
	v_mov_b32_e32 v20, v19
	v_pk_add_f32 v[20:21], v[20:21], v[22:23] op_sel:[0,1] neg_lo:[0,1] neg_hi:[0,1]
	v_rcp_f32_e32 v4, v8
	s_nop 0
	v_mul_f32_e32 v6, v5, v4
	v_pk_mul_f32 v[4:5], v[6:7], v[10:11]
	v_and_b32_sdwa v6, v13, v154 dst_sel:DWORD dst_unused:UNUSED_PAD src0_sel:WORD_1 src1_sel:DWORD
	v_and_b32_sdwa v8, v5, v154 dst_sel:DWORD dst_unused:UNUSED_PAD src0_sel:WORD_1 src1_sel:DWORD
	v_and_b32_sdwa v9, v4, v154 dst_sel:DWORD dst_unused:UNUSED_PAD src0_sel:WORD_1 src1_sel:DWORD
	v_and_b32_sdwa v7, v12, v154 dst_sel:DWORD dst_unused:UNUSED_PAD src0_sel:WORD_1 src1_sel:DWORD
	v_add3_u32 v5, v5, v8, s33
	v_add3_u32 v4, v4, v9, s33
	v_add3_u32 v7, v12, v7, s33
	v_add3_u32 v6, v13, v6, s33
	v_and_b32_e32 v5, 0xffff0000, v5
	v_and_b32_e32 v4, 0xffff0000, v4
	v_or_b32_sdwa v5, v5, v6 dst_sel:DWORD dst_unused:UNUSED_PAD src0_sel:DWORD src1_sel:WORD_1
	v_or_b32_sdwa v4, v4, v7 dst_sel:DWORD dst_unused:UNUSED_PAD src0_sel:DWORD src1_sel:WORD_1
	global_store_dwordx2 v[16:17], v[4:5], off offset:64
	global_load_dwordx4 v[6:9], v89, s[0:1] offset:192
	global_load_dwordx4 v[10:13], v89, s[4:5] offset:192
	v_mul_f32_e32 v4, 0xbfb8aa3b, v0
	v_mul_f32_e32 v5, 0xbfb8aa3b, v2
	v_exp_f32_e32 v14, v4
	v_exp_f32_e32 v15, v5
	v_pk_mul_f32 v[18:19], v[20:21], v[18:19] op_sel_hi:[1,0]
	v_mul_f32_e32 v4, 0xbfb8aa3b, v1
	v_mul_f32_e32 v5, 0xbfb8aa3b, v3
	v_exp_f32_e32 v4, v4
	v_exp_f32_e32 v5, v5
	s_waitcnt vmcnt(1)
	v_mov_b32_e32 v26, v6
	v_mov_b32_e32 v27, v8
	s_waitcnt vmcnt(0)
	v_mov_b32_e32 v30, v10
	v_mov_b32_e32 v31, v12
	v_pk_fma_f32 v[24:25], v[24:25], v[26:27], v[30:31]
	global_load_dwordx2 v[26:27], v[28:29], off offset:96
	v_mov_b32_e32 v8, v7
	v_mov_b32_e32 v12, v11
	v_pk_fma_f32 v[6:7], v[18:19], v[8:9], v[12:13]
	v_pk_add_f32 v[4:5], v[4:5], 1.0 op_sel_hi:[1,0]
	s_waitcnt vmcnt(0)
	v_and_b32_e32 v9, 0xffff0000, v27
	v_and_b32_e32 v8, 0xffff0000, v26
	v_pk_add_f32 v[6:7], v[6:7], v[8:9]
	v_pk_add_f32 v[8:9], v[14:15], 1.0 op_sel_hi:[1,0]
	v_lshlrev_b32_e32 v29, 16, v27
	v_lshlrev_b32_e32 v28, 16, v26
	v_pk_add_f32 v[24:25], v[24:25], v[28:29]
	v_rcp_f32_e32 v10, v9
	s_nop 0
	v_mul_f32_e32 v9, v2, v10
	s_nop 0
	v_rcp_f32_e32 v2, v8
	s_nop 0
	v_mul_f32_e32 v8, v0, v2
	v_pk_mul_f32 v[8:9], v[8:9], v[24:25]
	v_rcp_f32_e32 v0, v5
	s_nop 0
	v_mul_f32_e32 v3, v3, v0
	s_nop 0
	v_rcp_f32_e32 v0, v4
	s_nop 0
	v_mul_f32_e32 v2, v1, v0
	v_pk_mul_f32 v[0:1], v[2:3], v[6:7]
	v_and_b32_sdwa v2, v9, v154 dst_sel:DWORD dst_unused:UNUSED_PAD src0_sel:WORD_1 src1_sel:DWORD
	v_and_b32_sdwa v4, v1, v154 dst_sel:DWORD dst_unused:UNUSED_PAD src0_sel:WORD_1 src1_sel:DWORD
	v_and_b32_sdwa v5, v0, v154 dst_sel:DWORD dst_unused:UNUSED_PAD src0_sel:WORD_1 src1_sel:DWORD
	v_and_b32_sdwa v3, v8, v154 dst_sel:DWORD dst_unused:UNUSED_PAD src0_sel:WORD_1 src1_sel:DWORD
	v_add3_u32 v1, v1, v4, s33
	v_add3_u32 v0, v0, v5, s33
	v_add3_u32 v3, v8, v3, s33
	v_add3_u32 v2, v9, v2, s33
	v_and_b32_e32 v1, 0xffff0000, v1
	v_and_b32_e32 v0, 0xffff0000, v0
	v_or_b32_sdwa v1, v1, v2 dst_sel:DWORD dst_unused:UNUSED_PAD src0_sel:DWORD src1_sel:WORD_1
	v_or_b32_sdwa v0, v0, v3 dst_sel:DWORD dst_unused:UNUSED_PAD src0_sel:DWORD src1_sel:WORD_1
	global_store_dwordx2 v[16:17], v[0:1], off offset:96

.LBB0_214:
	s_add_i32 s59, s58, 0x8000
	s_and_b32 s58, s58, 0x8000
	s_add_i32 s58, s58, 0
	v_add_u32_e32 v79, s58, v95
	v_add_u32_e32 v88, v79, v100
	v_add_u32_e32 v79, v79, v93
	ds_read_b128 v[80:83], v88
	ds_read_b128 v[84:87], v88 offset:2048
	ds_read_b128 v[110:113], v88 offset:4096
	ds_read_b128 v[114:117], v88 offset:6144
	ds_read_b128 v[118:121], v79 offset:16384
	ds_read_b128 v[122:125], v79 offset:18432
	ds_read_b128 v[126:129], v79 offset:20480
	ds_read_b128 v[130:133], v79 offset:22528
	v_add_u32_e32 v206, s58, v101
	v_add_u32_e32 v207, v206, v100
	v_add_u32_e32 v208, v206, v93
	ds_read_b128 v[210:213], v207
	ds_read_b128 v[214:217], v207 offset:2048
	ds_read_b128 v[218:221], v207 offset:4096
	ds_read_b128 v[222:225], v207 offset:6144
	ds_read_b128 v[226:229], v208 offset:16384
	ds_read_b128 v[230:233], v208 offset:18432
	ds_read_b128 v[234:237], v208 offset:20480
	ds_read_b128 v[238:241], v208 offset:22528
	s_setprio 1
	s_waitcnt lgkmcnt(8)
	v_mfma_f32_16x16x32_bf16 v[60:63], v[118:121], v[80:83], v[60:63]
	v_mfma_f32_16x16x32_bf16 v[56:59], v[122:125], v[80:83], v[56:59]
	v_mfma_f32_16x16x32_bf16 v[52:55], v[126:129], v[80:83], v[52:55]
	v_mfma_f32_16x16x32_bf16 v[48:51], v[130:133], v[80:83], v[48:51]
	v_mfma_f32_16x16x32_bf16 v[44:47], v[118:121], v[84:87], v[44:47]
	v_mfma_f32_16x16x32_bf16 v[40:43], v[122:125], v[84:87], v[40:43]
	v_mfma_f32_16x16x32_bf16 v[36:39], v[126:129], v[84:87], v[36:39]
	v_mfma_f32_16x16x32_bf16 v[32:35], v[130:133], v[84:87], v[32:35]
	v_mfma_f32_16x16x32_bf16 v[28:31], v[118:121], v[110:113], v[28:31]
	v_mfma_f32_16x16x32_bf16 v[24:27], v[122:125], v[110:113], v[24:27]
	v_mfma_f32_16x16x32_bf16 v[20:23], v[126:129], v[110:113], v[20:23]
	v_mfma_f32_16x16x32_bf16 v[16:19], v[130:133], v[110:113], v[16:19]
	v_mfma_f32_16x16x32_bf16 v[12:15], v[118:121], v[114:117], v[12:15]
	v_mfma_f32_16x16x32_bf16 v[8:11], v[122:125], v[114:117], v[8:11]
	v_mfma_f32_16x16x32_bf16 v[4:7], v[126:129], v[114:117], v[4:7]
	v_mfma_f32_16x16x32_bf16 v[0:3], v[130:133], v[114:117], v[0:3]
	s_setprio 0
	s_setprio 1
	s_waitcnt lgkmcnt(0)
	s_setprio 0
	s_barrier
	s_add_u32 s6, s6, 0x80
	s_addc_u32 s7, s7, 0
	s_mov_b32 s60, s58
	v_add_u32_e32 v79, s60, v91
	v_lshl_add_u64 v[80:81], v[74:75], 0, s[6:7]
	v_add_u32_e32 v88, 0x4000, v79
	v_readfirstlane_b32 s60, v79
	v_lshl_add_u64 v[82:83], v[80:81], 0, s[88:89]
	v_lshl_add_u64 v[84:85], v[76:77], 0, s[6:7]
	s_mov_b32 m0, s60
	v_readfirstlane_b32 s60, v88
	v_lshl_add_u64 v[86:87], v[84:85], 0, s[92:93]
	global_load_lds_dwordx4 v[82:83], off
	s_mov_b32 m0, s60
	v_lshl_add_u64 v[82:83], v[80:81], 0, s[90:91]
	global_load_lds_dwordx4 v[86:87], off
	v_add_u32_e32 v86, 0x1000, v79
	s_nop 0
	v_readfirstlane_b32 s60, v86
	v_add_u32_e32 v86, 0x5000, v79
	s_mov_b32 m0, s60
	v_readfirstlane_b32 s60, v86
	v_add_u32_e32 v86, 0x2000, v79
	global_load_lds_dwordx4 v[82:83], off
	v_lshl_add_u64 v[82:83], v[84:85], 0, s[38:39]
	s_mov_b32 m0, s60
	v_readfirstlane_b32 s60, v86
	v_add_u32_e32 v86, 0x6000, v79
	global_load_lds_dwordx4 v[82:83], off
	v_lshl_add_u64 v[82:83], v[80:81], 0, s[94:95]
	s_mov_b32 m0, s60
	v_readfirstlane_b32 s60, v86
	global_load_lds_dwordx4 v[82:83], off
	v_lshl_add_u64 v[82:83], v[84:85], 0, s[62:63]
	s_mov_b32 m0, s60
	v_lshl_add_u64 v[80:81], v[80:81], 0, vcc
	global_load_lds_dwordx4 v[82:83], off
	v_add_u32_e32 v82, 0x3000, v79
	v_add_u32_e32 v79, 0x7000, v79
	v_readfirstlane_b32 s60, v82
	s_mov_b32 m0, s60
	v_readfirstlane_b32 s60, v79
	global_load_lds_dwordx4 v[80:81], off
	v_lshl_add_u64 v[80:81], v[84:85], 0, s[68:69]
	s_mov_b32 m0, s60
	s_nop 0
	global_load_lds_dwordx4 v[80:81], off
	s_setprio 1
	v_mfma_f32_16x16x32_bf16 v[60:63], v[226:229], v[210:213], v[60:63]
	v_mfma_f32_16x16x32_bf16 v[56:59], v[230:233], v[210:213], v[56:59]
	v_mfma_f32_16x16x32_bf16 v[52:55], v[234:237], v[210:213], v[52:55]
	v_mfma_f32_16x16x32_bf16 v[48:51], v[238:241], v[210:213], v[48:51]
	v_mfma_f32_16x16x32_bf16 v[44:47], v[226:229], v[214:217], v[44:47]
	v_mfma_f32_16x16x32_bf16 v[40:43], v[230:233], v[214:217], v[40:43]
	v_mfma_f32_16x16x32_bf16 v[36:39], v[234:237], v[214:217], v[36:39]
	v_mfma_f32_16x16x32_bf16 v[32:35], v[238:241], v[214:217], v[32:35]
	v_mfma_f32_16x16x32_bf16 v[28:31], v[226:229], v[218:221], v[28:31]
	v_mfma_f32_16x16x32_bf16 v[24:27], v[230:233], v[218:221], v[24:27]
	v_mfma_f32_16x16x32_bf16 v[20:23], v[234:237], v[218:221], v[20:23]
	v_mfma_f32_16x16x32_bf16 v[16:19], v[238:241], v[218:221], v[16:19]
	v_mfma_f32_16x16x32_bf16 v[12:15], v[226:229], v[222:225], v[12:15]
	v_mfma_f32_16x16x32_bf16 v[8:11], v[230:233], v[222:225], v[8:11]
	v_mfma_f32_16x16x32_bf16 v[4:7], v[234:237], v[222:225], v[4:7]
	v_mfma_f32_16x16x32_bf16 v[0:3], v[238:241], v[222:225], v[0:3]
	s_setprio 0
	s_cmpk_lg_i32 s6, 0x700
	s_mov_b32 s58, s59
	s_waitcnt vmcnt(8)
	s_barrier
	s_cbranch_scc1 .LBB0_214
	s_add_i32 s59, s58, 0x8000
	s_and_b32 s58, s58, 0x8000
	s_add_i32 s58, s58, 0
	v_add_u32_e32 v79, s58, v95
	v_add_u32_e32 v88, v79, v100
	v_add_u32_e32 v79, v79, v93
	ds_read_b128 v[80:83], v88
	ds_read_b128 v[84:87], v88 offset:2048
	ds_read_b128 v[110:113], v88 offset:4096
	ds_read_b128 v[114:117], v88 offset:6144
	ds_read_b128 v[118:121], v79 offset:16384
	ds_read_b128 v[122:125], v79 offset:18432
	ds_read_b128 v[126:129], v79 offset:20480
	ds_read_b128 v[130:133], v79 offset:22528
	v_add_u32_e32 v206, s58, v101
	v_add_u32_e32 v207, v206, v100
	v_add_u32_e32 v208, v206, v93
	ds_read_b128 v[210:213], v207
	ds_read_b128 v[214:217], v207 offset:2048
	ds_read_b128 v[218:221], v207 offset:4096
	ds_read_b128 v[222:225], v207 offset:6144
	ds_read_b128 v[226:229], v208 offset:16384
	ds_read_b128 v[230:233], v208 offset:18432
	ds_read_b128 v[234:237], v208 offset:20480
	ds_read_b128 v[238:241], v208 offset:22528
	s_setprio 1
	s_waitcnt lgkmcnt(8)
	v_mfma_f32_16x16x32_bf16 v[60:63], v[118:121], v[80:83], v[60:63]
	v_mfma_f32_16x16x32_bf16 v[56:59], v[122:125], v[80:83], v[56:59]
	v_mfma_f32_16x16x32_bf16 v[52:55], v[126:129], v[80:83], v[52:55]
	v_mfma_f32_16x16x32_bf16 v[48:51], v[130:133], v[80:83], v[48:51]
	v_mfma_f32_16x16x32_bf16 v[44:47], v[118:121], v[84:87], v[44:47]
	v_mfma_f32_16x16x32_bf16 v[40:43], v[122:125], v[84:87], v[40:43]
	v_mfma_f32_16x16x32_bf16 v[36:39], v[126:129], v[84:87], v[36:39]
	v_mfma_f32_16x16x32_bf16 v[32:35], v[130:133], v[84:87], v[32:35]
	v_mfma_f32_16x16x32_bf16 v[28:31], v[118:121], v[110:113], v[28:31]
	v_mfma_f32_16x16x32_bf16 v[24:27], v[122:125], v[110:113], v[24:27]
	v_mfma_f32_16x16x32_bf16 v[20:23], v[126:129], v[110:113], v[20:23]
	v_mfma_f32_16x16x32_bf16 v[16:19], v[130:133], v[110:113], v[16:19]
	v_mfma_f32_16x16x32_bf16 v[12:15], v[118:121], v[114:117], v[12:15]
	v_mfma_f32_16x16x32_bf16 v[8:11], v[122:125], v[114:117], v[8:11]
	v_mfma_f32_16x16x32_bf16 v[4:7], v[126:129], v[114:117], v[4:7]
	v_mfma_f32_16x16x32_bf16 v[0:3], v[130:133], v[114:117], v[0:3]
	s_setprio 0
	s_setprio 1
	s_waitcnt lgkmcnt(0)
	v_mfma_f32_16x16x32_bf16 v[60:63], v[226:229], v[210:213], v[60:63]
	v_mfma_f32_16x16x32_bf16 v[56:59], v[230:233], v[210:213], v[56:59]
	v_mfma_f32_16x16x32_bf16 v[52:55], v[234:237], v[210:213], v[52:55]
	v_mfma_f32_16x16x32_bf16 v[48:51], v[238:241], v[210:213], v[48:51]
	v_mfma_f32_16x16x32_bf16 v[44:47], v[226:229], v[214:217], v[44:47]
	v_mfma_f32_16x16x32_bf16 v[40:43], v[230:233], v[214:217], v[40:43]
	v_mfma_f32_16x16x32_bf16 v[36:39], v[234:237], v[214:217], v[36:39]
	v_mfma_f32_16x16x32_bf16 v[32:35], v[238:241], v[214:217], v[32:35]
	v_mfma_f32_16x16x32_bf16 v[28:31], v[226:229], v[218:221], v[28:31]
	v_mfma_f32_16x16x32_bf16 v[24:27], v[230:233], v[218:221], v[24:27]
	v_mfma_f32_16x16x32_bf16 v[20:23], v[234:237], v[218:221], v[20:23]
	v_mfma_f32_16x16x32_bf16 v[16:19], v[238:241], v[218:221], v[16:19]
	v_mfma_f32_16x16x32_bf16 v[12:15], v[226:229], v[222:225], v[12:15]
	v_mfma_f32_16x16x32_bf16 v[8:11], v[230:233], v[222:225], v[8:11]
	v_mfma_f32_16x16x32_bf16 v[4:7], v[234:237], v[222:225], v[4:7]
	v_mfma_f32_16x16x32_bf16 v[0:3], v[238:241], v[222:225], v[0:3]
	s_setprio 0
	s_mov_b32 s58, s59
	s_waitcnt vmcnt(0)
	s_barrier
	v_add_u32_e32 v79, v104, v93
	ds_read_b128 v[74:77], v79 offset:55296
	ds_read_b128 v[80:83], v79 offset:53248
	ds_read_b128 v[84:87], v79 offset:51200
	ds_read_b128 v[110:113], v79 offset:49152
	v_add_u32_e32 v79, v104, v100
	ds_read_b128 v[114:117], v79 offset:38912
	ds_read_b128 v[118:121], v79 offset:36864
	ds_read_b128 v[122:125], v79 offset:34816
	ds_read_b128 v[126:129], v79 offset:32768
	s_setprio 1
	s_waitcnt lgkmcnt(0)
	v_mfma_f32_16x16x32_bf16 v[60:63], v[110:113], v[126:129], v[60:63]
	v_mfma_f32_16x16x32_bf16 v[56:59], v[84:87], v[126:129], v[56:59]
	v_mfma_f32_16x16x32_bf16 v[52:55], v[80:83], v[126:129], v[52:55]
	v_mfma_f32_16x16x32_bf16 v[48:51], v[74:77], v[126:129], v[48:51]
	v_mfma_f32_16x16x32_bf16 v[44:47], v[110:113], v[122:125], v[44:47]
	v_mfma_f32_16x16x32_bf16 v[40:43], v[84:87], v[122:125], v[40:43]
	v_mfma_f32_16x16x32_bf16 v[36:39], v[80:83], v[122:125], v[36:39]
	v_mfma_f32_16x16x32_bf16 v[32:35], v[74:77], v[122:125], v[32:35]
	v_mfma_f32_16x16x32_bf16 v[28:31], v[110:113], v[118:121], v[28:31]
	v_mfma_f32_16x16x32_bf16 v[24:27], v[84:87], v[118:121], v[24:27]
	v_mfma_f32_16x16x32_bf16 v[20:23], v[80:83], v[118:121], v[20:23]
	v_mfma_f32_16x16x32_bf16 v[16:19], v[74:77], v[118:121], v[16:19]
	v_mfma_f32_16x16x32_bf16 v[12:15], v[110:113], v[114:117], v[12:15]
	v_mfma_f32_16x16x32_bf16 v[8:11], v[84:87], v[114:117], v[8:11]
	v_mfma_f32_16x16x32_bf16 v[4:7], v[80:83], v[114:117], v[4:7]
	v_mfma_f32_16x16x32_bf16 v[0:3], v[74:77], v[114:117], v[0:3]
	s_setprio 0
	v_add_u32_e32 v79, v105, v100
	ds_read_b128 v[74:77], v79 offset:32768
	ds_read_b128 v[80:83], v79 offset:34816
	ds_read_b128 v[84:87], v79 offset:36864
	ds_read_b128 v[110:113], v79 offset:38912
	v_add_u32_e32 v79, v105, v93
	ds_read_b128 v[114:117], v79 offset:49152
	ds_read_b128 v[118:121], v79 offset:51200
	ds_read_b128 v[122:125], v79 offset:53248
	ds_read_b128 v[126:129], v79 offset:55296
	s_setprio 1
	s_waitcnt lgkmcnt(3)
	v_mfma_f32_16x16x32_bf16 v[60:63], v[114:117], v[74:77], v[60:63]
	s_waitcnt lgkmcnt(2)
	v_mfma_f32_16x16x32_bf16 v[56:59], v[118:121], v[74:77], v[56:59]
	s_waitcnt lgkmcnt(1)
	v_mfma_f32_16x16x32_bf16 v[52:55], v[122:125], v[74:77], v[52:55]
	s_waitcnt lgkmcnt(0)
	v_mfma_f32_16x16x32_bf16 v[48:51], v[126:129], v[74:77], v[48:51]
	v_mfma_f32_16x16x32_bf16 v[44:47], v[114:117], v[80:83], v[44:47]
	v_mfma_f32_16x16x32_bf16 v[40:43], v[118:121], v[80:83], v[40:43]
	v_mfma_f32_16x16x32_bf16 v[36:39], v[122:125], v[80:83], v[36:39]
	v_mfma_f32_16x16x32_bf16 v[32:35], v[126:129], v[80:83], v[32:35]
	v_mfma_f32_16x16x32_bf16 v[28:31], v[114:117], v[84:87], v[28:31]
	v_mfma_f32_16x16x32_bf16 v[24:27], v[118:121], v[84:87], v[24:27]
	v_mfma_f32_16x16x32_bf16 v[20:23], v[122:125], v[84:87], v[20:23]
	v_mfma_f32_16x16x32_bf16 v[16:19], v[126:129], v[84:87], v[16:19]
	v_mfma_f32_16x16x32_bf16 v[12:15], v[114:117], v[110:113], v[12:15]
	v_mfma_f32_16x16x32_bf16 v[8:11], v[118:121], v[110:113], v[8:11]
	v_mfma_f32_16x16x32_bf16 v[4:7], v[122:125], v[110:113], v[4:7]
	v_mfma_f32_16x16x32_bf16 v[0:3], v[126:129], v[110:113], v[0:3]
	s_setprio 0
	s_waitcnt vmcnt(0)
	v_and_b32_e32 v74, 0xfffff8, v78
	v_cmp_ne_u32_e32 vcc, 16, v74
	s_mov_b64 s[6:7], s[0:1]
	s_barrier
	s_and_saveexec_b64 s[58:59], vcc
	s_mov_b64 s[92:93], s[52:53]
	s_cbranch_execz .LBB0_160
	v_readlane_b32 s6, v254, 29
	v_readlane_b32 s7, v254, 30
	v_cmp_lt_u32_e32 vcc, 23, v78
	v_lshlrev_b32_e32 v80, 7, v67
	v_lshl_add_u64 v[74:75], v[96:97], 1, s[6:7]
	v_mul_f32_e32 v83, 0xbfb8aa3b, v60
	v_mul_f32_e32 v84, 0xbfb8aa3b, v61
	v_mul_f32_e32 v79, 0xbfb8aa3b, v62
	v_mul_f32_e32 v82, 0xbfb8aa3b, v63
	v_mul_f32_e32 v126, 0xbfb8aa3b, v56
	v_mul_f32_e32 v127, 0xbfb8aa3b, v57
	v_mul_f32_e32 v124, 0xbfb8aa3b, v58
	v_mul_f32_e32 v125, 0xbfb8aa3b, v59
	v_mul_f32_e32 v122, 0xbfb8aa3b, v52
	v_mul_f32_e32 v123, 0xbfb8aa3b, v53
	v_mul_f32_e32 v120, 0xbfb8aa3b, v54
	v_mul_f32_e32 v121, 0xbfb8aa3b, v55
	v_mul_f32_e32 v118, 0xbfb8aa3b, v48
	v_mul_f32_e32 v119, 0xbfb8aa3b, v49
	v_mul_f32_e32 v116, 0xbfb8aa3b, v50
	v_mul_f32_e32 v117, 0xbfb8aa3b, v51
	v_mul_f32_e32 v114, 0xbfb8aa3b, v44
	v_mul_f32_e32 v115, 0xbfb8aa3b, v45
	v_mul_f32_e32 v112, 0xbfb8aa3b, v46
	v_mul_f32_e32 v113, 0xbfb8aa3b, v47
	v_mul_f32_e32 v110, 0xbfb8aa3b, v40
	v_mul_f32_e32 v111, 0xbfb8aa3b, v41
	v_mul_f32_e32 v67, 0xbfb8aa3b, v42
	v_mul_f32_e32 v109, 0xbfb8aa3b, v43
	s_and_saveexec_b64 s[6:7], vcc
	s_xor_b64 s[60:61], exec, s[6:7]
	s_cbranch_execz .LBB0_218
	v_mov_b32_e32 v40, v97
	s_nop 0
	v_add_u32_e32 v40, v40, v176
	v_ashrrev_i32_e32 v42, 1, v40
	v_and_b32_e32 v41, 64, v40
	v_and_b32_e32 v42, 0xffffffc0, v42
	v_lshrrev_b32_e32 v43, 2, v40
	v_and_or_b32 v40, v40, 15, v80
	v_and_or_b32 v43, v43, 12, v41
	v_add_u32_e32 v42, v40, v42
	v_exp_f32_e32 v44, v83
	v_exp_f32_e32 v45, v79
	v_lshlrev_b32_e32 v96, 1, v43
	v_exp_f32_e32 v46, v84
	v_exp_f32_e32 v47, v82
	v_pk_add_f32 v[44:45], v[44:45], 1.0 op_sel_hi:[1,0]
	s_movk_i32 s67, 0x3200
	v_mad_i64_i32 v[40:41], s[6:7], v42, s67, v[74:75]
	v_lshl_add_u64 v[40:41], v[40:41], 0, v[96:97]
	v_rcp_f32_e32 v43, v44
	s_nop 0
	v_rcp_f32_e32 v48, v45
	v_pk_add_f32 v[44:45], v[46:47], 1.0 op_sel_hi:[1,0]
	s_nop 0
	s_nop 0
	v_rcp_f32_e32 v44, v44
	s_nop 0
	v_rcp_f32_e32 v45, v45
	v_and_b32_sdwa v46, v48, v154 dst_sel:DWORD dst_unused:UNUSED_PAD src0_sel:WORD_1 src1_sel:DWORD
	v_and_b32_sdwa v47, v43, v154 dst_sel:DWORD dst_unused:UNUSED_PAD src0_sel:WORD_1 src1_sel:DWORD
	v_add3_u32 v43, v43, v47, s33
	v_add3_u32 v46, v48, v46, s33
	v_and_b32_sdwa v47, v45, v154 dst_sel:DWORD dst_unused:UNUSED_PAD src0_sel:WORD_1 src1_sel:DWORD
	v_and_b32_sdwa v48, v44, v154 dst_sel:DWORD dst_unused:UNUSED_PAD src0_sel:WORD_1 src1_sel:DWORD
	v_add3_u32 v45, v45, v47, s33
	v_add3_u32 v44, v44, v48, s33
	v_and_b32_e32 v45, 0xffff0000, v45
	v_and_b32_e32 v44, 0xffff0000, v44
	v_or_b32_sdwa v45, v45, v46 dst_sel:DWORD dst_unused:UNUSED_PAD src0_sel:DWORD src1_sel:WORD_1
	v_or_b32_sdwa v44, v44, v43 dst_sel:DWORD dst_unused:UNUSED_PAD src0_sel:DWORD src1_sel:WORD_1
	global_store_dwordx2 v[40:41], v[44:45], off
	v_exp_f32_e32 v44, v126
	v_exp_f32_e32 v45, v124
	v_exp_f32_e32 v46, v127
	v_exp_f32_e32 v47, v125
	v_pk_add_f32 v[44:45], v[44:45], 1.0 op_sel_hi:[1,0]
	s_nop 0
	s_nop 0
	v_rcp_f32_e32 v43, v44
	s_nop 0
	v_rcp_f32_e32 v48, v45
	v_pk_add_f32 v[44:45], v[46:47], 1.0 op_sel_hi:[1,0]
	s_nop 0
	s_nop 0
	v_rcp_f32_e32 v44, v44
	s_nop 0
	v_rcp_f32_e32 v45, v45
	v_and_b32_sdwa v46, v48, v154 dst_sel:DWORD dst_unused:UNUSED_PAD src0_sel:WORD_1 src1_sel:DWORD
	v_and_b32_sdwa v47, v43, v154 dst_sel:DWORD dst_unused:UNUSED_PAD src0_sel:WORD_1 src1_sel:DWORD
	v_add3_u32 v43, v43, v47, s33
	v_add3_u32 v46, v48, v46, s33
	v_and_b32_sdwa v47, v45, v154 dst_sel:DWORD dst_unused:UNUSED_PAD src0_sel:WORD_1 src1_sel:DWORD
	v_and_b32_sdwa v48, v44, v154 dst_sel:DWORD dst_unused:UNUSED_PAD src0_sel:WORD_1 src1_sel:DWORD
	v_add3_u32 v45, v45, v47, s33
	v_add3_u32 v44, v44, v48, s33
	v_and_b32_e32 v45, 0xffff0000, v45
	v_and_b32_e32 v44, 0xffff0000, v44
	v_or_b32_sdwa v45, v45, v46 dst_sel:DWORD dst_unused:UNUSED_PAD src0_sel:DWORD src1_sel:WORD_1
	v_or_b32_sdwa v44, v44, v43 dst_sel:DWORD dst_unused:UNUSED_PAD src0_sel:DWORD src1_sel:WORD_1
	global_store_dwordx2 v[40:41], v[44:45], off offset:32
	v_exp_f32_e32 v44, v122
	v_exp_f32_e32 v45, v120
	v_exp_f32_e32 v46, v123
	v_exp_f32_e32 v47, v121
	v_pk_add_f32 v[44:45], v[44:45], 1.0 op_sel_hi:[1,0]
	s_nop 0
	s_nop 0
	v_rcp_f32_e32 v43, v44
	s_nop 0
	v_rcp_f32_e32 v48, v45
	v_pk_add_f32 v[44:45], v[46:47], 1.0 op_sel_hi:[1,0]
	s_nop 0
	s_nop 0
	v_rcp_f32_e32 v44, v44
	s_nop 0
	v_rcp_f32_e32 v45, v45
	v_and_b32_sdwa v46, v48, v154 dst_sel:DWORD dst_unused:UNUSED_PAD src0_sel:WORD_1 src1_sel:DWORD
	v_and_b32_sdwa v47, v43, v154 dst_sel:DWORD dst_unused:UNUSED_PAD src0_sel:WORD_1 src1_sel:DWORD
	v_add3_u32 v43, v43, v47, s33
	v_add3_u32 v46, v48, v46, s33
	v_and_b32_sdwa v47, v45, v154 dst_sel:DWORD dst_unused:UNUSED_PAD src0_sel:WORD_1 src1_sel:DWORD
	v_and_b32_sdwa v48, v44, v154 dst_sel:DWORD dst_unused:UNUSED_PAD src0_sel:WORD_1 src1_sel:DWORD
	v_add3_u32 v45, v45, v47, s33
	v_add3_u32 v44, v44, v48, s33
	v_and_b32_e32 v45, 0xffff0000, v45
	v_and_b32_e32 v44, 0xffff0000, v44
	v_or_b32_sdwa v45, v45, v46 dst_sel:DWORD dst_unused:UNUSED_PAD src0_sel:DWORD src1_sel:WORD_1
	v_or_b32_sdwa v44, v44, v43 dst_sel:DWORD dst_unused:UNUSED_PAD src0_sel:DWORD src1_sel:WORD_1
	global_store_dwordx2 v[40:41], v[44:45], off offset:64
	v_exp_f32_e32 v44, v118
	v_exp_f32_e32 v45, v116
	v_exp_f32_e32 v46, v119
	v_exp_f32_e32 v47, v117
	v_pk_add_f32 v[44:45], v[44:45], 1.0 op_sel_hi:[1,0]
	s_nop 0
	s_nop 0
	v_rcp_f32_e32 v43, v44
	s_nop 0
	v_rcp_f32_e32 v48, v45
	v_pk_add_f32 v[44:45], v[46:47], 1.0 op_sel_hi:[1,0]
	s_nop 0
	s_nop 0
	v_rcp_f32_e32 v44, v44
	s_nop 0
	v_rcp_f32_e32 v45, v45
	v_and_b32_sdwa v46, v48, v154 dst_sel:DWORD dst_unused:UNUSED_PAD src0_sel:WORD_1 src1_sel:DWORD
	v_and_b32_sdwa v47, v43, v154 dst_sel:DWORD dst_unused:UNUSED_PAD src0_sel:WORD_1 src1_sel:DWORD
	v_add3_u32 v43, v43, v47, s33
	v_add3_u32 v46, v48, v46, s33
	v_and_b32_sdwa v47, v45, v154 dst_sel:DWORD dst_unused:UNUSED_PAD src0_sel:WORD_1 src1_sel:DWORD
	v_and_b32_sdwa v48, v44, v154 dst_sel:DWORD dst_unused:UNUSED_PAD src0_sel:WORD_1 src1_sel:DWORD
	v_add3_u32 v45, v45, v47, s33
	v_add3_u32 v44, v44, v48, s33
	v_and_b32_e32 v45, 0xffff0000, v45
	v_and_b32_e32 v44, 0xffff0000, v44
	v_or_b32_sdwa v45, v45, v46 dst_sel:DWORD dst_unused:UNUSED_PAD src0_sel:DWORD src1_sel:WORD_1
	v_or_b32_sdwa v44, v44, v43 dst_sel:DWORD dst_unused:UNUSED_PAD src0_sel:DWORD src1_sel:WORD_1
	global_store_dwordx2 v[40:41], v[44:45], off offset:96
	v_exp_f32_e32 v44, v114
	v_exp_f32_e32 v45, v112
	v_exp_f32_e32 v46, v115
	v_exp_f32_e32 v47, v113
	v_or_b32_e32 v40, 16, v42
	v_pk_add_f32 v[44:45], v[44:45], 1.0 op_sel_hi:[1,0]
	v_mad_i64_i32 v[40:41], s[6:7], v40, s67, v[74:75]
	v_lshl_add_u64 v[40:41], v[40:41], 0, v[96:97]
	v_mul_f32_e32 v37, 0xbfb8aa3b, v37
	v_mul_f32_e32 v36, 0xbfb8aa3b, v36
	v_rcp_f32_e32 v43, v44
	v_exp_f32_e32 v36, v36
	v_mul_f32_e32 v33, 0xbfb8aa3b, v33
	v_mul_f32_e32 v32, 0xbfb8aa3b, v32
	v_rcp_f32_e32 v48, v45
	v_pk_add_f32 v[44:45], v[46:47], 1.0 op_sel_hi:[1,0]
	v_exp_f32_e32 v32, v32
	s_nop 0
	v_rcp_f32_e32 v44, v44
	s_nop 0
	v_rcp_f32_e32 v45, v45
	v_and_b32_sdwa v46, v48, v154 dst_sel:DWORD dst_unused:UNUSED_PAD src0_sel:WORD_1 src1_sel:DWORD
	v_and_b32_sdwa v47, v43, v154 dst_sel:DWORD dst_unused:UNUSED_PAD src0_sel:WORD_1 src1_sel:DWORD
	v_add3_u32 v43, v43, v47, s33
	v_add3_u32 v46, v48, v46, s33
	v_and_b32_sdwa v47, v45, v154 dst_sel:DWORD dst_unused:UNUSED_PAD src0_sel:WORD_1 src1_sel:DWORD
	v_and_b32_sdwa v48, v44, v154 dst_sel:DWORD dst_unused:UNUSED_PAD src0_sel:WORD_1 src1_sel:DWORD
	v_add3_u32 v45, v45, v47, s33
	v_add3_u32 v44, v44, v48, s33
	v_and_b32_e32 v45, 0xffff0000, v45
	v_and_b32_e32 v44, 0xffff0000, v44
	v_or_b32_sdwa v45, v45, v46 dst_sel:DWORD dst_unused:UNUSED_PAD src0_sel:DWORD src1_sel:WORD_1
	v_or_b32_sdwa v44, v44, v43 dst_sel:DWORD dst_unused:UNUSED_PAD src0_sel:DWORD src1_sel:WORD_1
	global_store_dwordx2 v[40:41], v[44:45], off
	v_exp_f32_e32 v44, v110
	v_exp_f32_e32 v45, v67
	v_exp_f32_e32 v46, v111
	v_exp_f32_e32 v47, v109
	v_pk_add_f32 v[44:45], v[44:45], 1.0 op_sel_hi:[1,0]
	s_nop 0
	s_nop 0
	v_rcp_f32_e32 v43, v44
	s_nop 0
	v_rcp_f32_e32 v48, v45
	v_pk_add_f32 v[44:45], v[46:47], 1.0 op_sel_hi:[1,0]
	s_nop 0
	s_nop 0
	v_rcp_f32_e32 v44, v44
	s_nop 0
	v_rcp_f32_e32 v45, v45
	v_and_b32_sdwa v46, v48, v154 dst_sel:DWORD dst_unused:UNUSED_PAD src0_sel:WORD_1 src1_sel:DWORD
	v_and_b32_sdwa v47, v43, v154 dst_sel:DWORD dst_unused:UNUSED_PAD src0_sel:WORD_1 src1_sel:DWORD
	v_add3_u32 v43, v43, v47, s33
	v_add3_u32 v46, v48, v46, s33
	v_and_b32_sdwa v47, v45, v154 dst_sel:DWORD dst_unused:UNUSED_PAD src0_sel:WORD_1 src1_sel:DWORD
	v_and_b32_sdwa v48, v44, v154 dst_sel:DWORD dst_unused:UNUSED_PAD src0_sel:WORD_1 src1_sel:DWORD
	v_add3_u32 v45, v45, v47, s33
	v_add3_u32 v44, v44, v48, s33
	v_and_b32_e32 v45, 0xffff0000, v45
	v_and_b32_e32 v44, 0xffff0000, v44
	v_or_b32_sdwa v45, v45, v46 dst_sel:DWORD dst_unused:UNUSED_PAD src0_sel:DWORD src1_sel:WORD_1
	v_or_b32_sdwa v44, v44, v43 dst_sel:DWORD dst_unused:UNUSED_PAD src0_sel:DWORD src1_sel:WORD_1
	global_store_dwordx2 v[40:41], v[44:45], off offset:32
	v_exp_f32_e32 v44, v37
	v_mul_f32_e32 v37, 0xbfb8aa3b, v38
	v_exp_f32_e32 v37, v37
	v_mul_f32_e32 v38, 0xbfb8aa3b, v39
	v_exp_f32_e32 v45, v38
	v_pk_add_f32 v[36:37], v[36:37], 1.0 op_sel_hi:[1,0]
	s_nop 0
	s_nop 0
	v_rcp_f32_e32 v38, v36
	s_nop 0
	v_rcp_f32_e32 v39, v37
	v_pk_add_f32 v[36:37], v[44:45], 1.0 op_sel_hi:[1,0]
	s_nop 0
	s_nop 0
	v_rcp_f32_e32 v36, v36
	s_nop 0
	v_rcp_f32_e32 v37, v37
	v_and_b32_sdwa v43, v39, v154 dst_sel:DWORD dst_unused:UNUSED_PAD src0_sel:WORD_1 src1_sel:DWORD
	v_and_b32_sdwa v44, v38, v154 dst_sel:DWORD dst_unused:UNUSED_PAD src0_sel:WORD_1 src1_sel:DWORD
	v_add3_u32 v38, v38, v44, s33
	v_add3_u32 v39, v39, v43, s33
	v_and_b32_sdwa v43, v37, v154 dst_sel:DWORD dst_unused:UNUSED_PAD src0_sel:WORD_1 src1_sel:DWORD
	v_and_b32_sdwa v44, v36, v154 dst_sel:DWORD dst_unused:UNUSED_PAD src0_sel:WORD_1 src1_sel:DWORD
	v_add3_u32 v37, v37, v43, s33
	v_add3_u32 v36, v36, v44, s33
	v_and_b32_e32 v37, 0xffff0000, v37
	v_and_b32_e32 v36, 0xffff0000, v36
	v_or_b32_sdwa v37, v37, v39 dst_sel:DWORD dst_unused:UNUSED_PAD src0_sel:DWORD src1_sel:WORD_1
	v_or_b32_sdwa v36, v36, v38 dst_sel:DWORD dst_unused:UNUSED_PAD src0_sel:DWORD src1_sel:WORD_1
	global_store_dwordx2 v[40:41], v[36:37], off offset:64
	v_exp_f32_e32 v36, v33
	v_mul_f32_e32 v33, 0xbfb8aa3b, v34
	v_exp_f32_e32 v33, v33
	v_mul_f32_e32 v34, 0xbfb8aa3b, v35
	v_exp_f32_e32 v37, v34
	v_pk_add_f32 v[32:33], v[32:33], 1.0 op_sel_hi:[1,0]
	s_nop 0
	s_nop 0
	v_rcp_f32_e32 v34, v32
	s_nop 0
	v_rcp_f32_e32 v35, v33
	v_pk_add_f32 v[32:33], v[36:37], 1.0 op_sel_hi:[1,0]
	s_nop 0
	s_nop 0
	v_rcp_f32_e32 v32, v32
	s_nop 0
	v_rcp_f32_e32 v33, v33
	v_and_b32_sdwa v36, v35, v154 dst_sel:DWORD dst_unused:UNUSED_PAD src0_sel:WORD_1 src1_sel:DWORD
	v_and_b32_sdwa v37, v34, v154 dst_sel:DWORD dst_unused:UNUSED_PAD src0_sel:WORD_1 src1_sel:DWORD
	v_add3_u32 v34, v34, v37, s33
	v_add3_u32 v35, v35, v36, s33
	v_and_b32_sdwa v36, v33, v154 dst_sel:DWORD dst_unused:UNUSED_PAD src0_sel:WORD_1 src1_sel:DWORD
	v_and_b32_sdwa v37, v32, v154 dst_sel:DWORD dst_unused:UNUSED_PAD src0_sel:WORD_1 src1_sel:DWORD
	v_add3_u32 v33, v33, v36, s33
	v_add3_u32 v32, v32, v37, s33
	v_and_b32_e32 v33, 0xffff0000, v33
	v_and_b32_e32 v32, 0xffff0000, v32
	v_or_b32_sdwa v33, v33, v35 dst_sel:DWORD dst_unused:UNUSED_PAD src0_sel:DWORD src1_sel:WORD_1
	v_or_b32_sdwa v32, v32, v34 dst_sel:DWORD dst_unused:UNUSED_PAD src0_sel:DWORD src1_sel:WORD_1
	global_store_dwordx2 v[40:41], v[32:33], off offset:96
	v_mul_f32_e32 v28, 0xbfb8aa3b, v28
	v_exp_f32_e32 v34, v28
	v_mul_f32_e32 v28, 0xbfb8aa3b, v29
	v_exp_f32_e32 v36, v28
	v_mul_f32_e32 v28, 0xbfb8aa3b, v30
	v_exp_f32_e32 v35, v28
	v_or_b32_e32 v32, 32, v42
	v_mad_i64_i32 v[32:33], s[6:7], v32, s67, v[74:75]
	v_mul_f32_e32 v28, 0xbfb8aa3b, v31
	v_pk_add_f32 v[30:31], v[34:35], 1.0 op_sel_hi:[1,0]
	v_exp_f32_e32 v37, v28
	v_lshl_add_u64 v[28:29], v[32:33], 0, v[96:97]
	v_mul_f32_e32 v25, 0xbfb8aa3b, v25
	v_mul_f32_e32 v24, 0xbfb8aa3b, v24
	v_exp_f32_e32 v24, v24
	v_rcp_f32_e32 v32, v30
	v_mul_f32_e32 v21, 0xbfb8aa3b, v21
	v_mul_f32_e32 v20, 0xbfb8aa3b, v20
	v_exp_f32_e32 v20, v20
	v_rcp_f32_e32 v33, v31
	v_pk_add_f32 v[30:31], v[36:37], 1.0 op_sel_hi:[1,0]
	v_mul_f32_e32 v17, 0xbfb8aa3b, v17
	v_mul_f32_e32 v16, 0xbfb8aa3b, v16
	v_exp_f32_e32 v16, v16
	v_rcp_f32_e32 v30, v30
	s_nop 0
	v_rcp_f32_e32 v31, v31
	v_and_b32_sdwa v34, v33, v154 dst_sel:DWORD dst_unused:UNUSED_PAD src0_sel:WORD_1 src1_sel:DWORD
	v_and_b32_sdwa v35, v32, v154 dst_sel:DWORD dst_unused:UNUSED_PAD src0_sel:WORD_1 src1_sel:DWORD
	v_add3_u32 v32, v32, v35, s33
	v_add3_u32 v33, v33, v34, s33
	v_and_b32_sdwa v34, v31, v154 dst_sel:DWORD dst_unused:UNUSED_PAD src0_sel:WORD_1 src1_sel:DWORD
	v_and_b32_sdwa v35, v30, v154 dst_sel:DWORD dst_unused:UNUSED_PAD src0_sel:WORD_1 src1_sel:DWORD
	v_add3_u32 v31, v31, v34, s33
	v_add3_u32 v30, v30, v35, s33
	v_and_b32_e32 v31, 0xffff0000, v31
	v_and_b32_e32 v30, 0xffff0000, v30
	v_or_b32_sdwa v31, v31, v33 dst_sel:DWORD dst_unused:UNUSED_PAD src0_sel:DWORD src1_sel:WORD_1
	v_or_b32_sdwa v30, v30, v32 dst_sel:DWORD dst_unused:UNUSED_PAD src0_sel:DWORD src1_sel:WORD_1
	global_store_dwordx2 v[28:29], v[30:31], off
	v_exp_f32_e32 v30, v25
	v_mul_f32_e32 v25, 0xbfb8aa3b, v26
	v_exp_f32_e32 v25, v25
	v_mul_f32_e32 v26, 0xbfb8aa3b, v27
	v_exp_f32_e32 v31, v26
	v_pk_add_f32 v[24:25], v[24:25], 1.0 op_sel_hi:[1,0]
	s_nop 0
	s_nop 0
	v_rcp_f32_e32 v26, v24
	s_nop 0
	v_rcp_f32_e32 v27, v25
	v_pk_add_f32 v[24:25], v[30:31], 1.0 op_sel_hi:[1,0]
	s_nop 0
	s_nop 0
	v_rcp_f32_e32 v24, v24
	s_nop 0
	v_rcp_f32_e32 v25, v25
	v_and_b32_sdwa v30, v27, v154 dst_sel:DWORD dst_unused:UNUSED_PAD src0_sel:WORD_1 src1_sel:DWORD
	v_and_b32_sdwa v31, v26, v154 dst_sel:DWORD dst_unused:UNUSED_PAD src0_sel:WORD_1 src1_sel:DWORD
	v_add3_u32 v26, v26, v31, s33
	v_add3_u32 v27, v27, v30, s33
	v_and_b32_sdwa v30, v25, v154 dst_sel:DWORD dst_unused:UNUSED_PAD src0_sel:WORD_1 src1_sel:DWORD
	v_and_b32_sdwa v31, v24, v154 dst_sel:DWORD dst_unused:UNUSED_PAD src0_sel:WORD_1 src1_sel:DWORD
	v_add3_u32 v25, v25, v30, s33
	v_add3_u32 v24, v24, v31, s33
	v_and_b32_e32 v25, 0xffff0000, v25
	v_and_b32_e32 v24, 0xffff0000, v24
	v_or_b32_sdwa v25, v25, v27 dst_sel:DWORD dst_unused:UNUSED_PAD src0_sel:DWORD src1_sel:WORD_1
	v_or_b32_sdwa v24, v24, v26 dst_sel:DWORD dst_unused:UNUSED_PAD src0_sel:DWORD src1_sel:WORD_1
	global_store_dwordx2 v[28:29], v[24:25], off offset:32
	v_exp_f32_e32 v24, v21
	v_mul_f32_e32 v21, 0xbfb8aa3b, v22
	v_exp_f32_e32 v21, v21
	v_mul_f32_e32 v22, 0xbfb8aa3b, v23
	v_exp_f32_e32 v25, v22
	v_pk_add_f32 v[20:21], v[20:21], 1.0 op_sel_hi:[1,0]
	s_nop 0
	s_nop 0
	v_rcp_f32_e32 v22, v20
	s_nop 0
	v_rcp_f32_e32 v23, v21
	v_pk_add_f32 v[20:21], v[24:25], 1.0 op_sel_hi:[1,0]
	s_nop 0
	s_nop 0
	v_rcp_f32_e32 v20, v20
	s_nop 0
	v_rcp_f32_e32 v21, v21
	v_and_b32_sdwa v24, v23, v154 dst_sel:DWORD dst_unused:UNUSED_PAD src0_sel:WORD_1 src1_sel:DWORD
	v_and_b32_sdwa v25, v22, v154 dst_sel:DWORD dst_unused:UNUSED_PAD src0_sel:WORD_1 src1_sel:DWORD
	v_add3_u32 v22, v22, v25, s33
	v_add3_u32 v23, v23, v24, s33
	v_and_b32_sdwa v24, v21, v154 dst_sel:DWORD dst_unused:UNUSED_PAD src0_sel:WORD_1 src1_sel:DWORD
	v_and_b32_sdwa v25, v20, v154 dst_sel:DWORD dst_unused:UNUSED_PAD src0_sel:WORD_1 src1_sel:DWORD
	v_add3_u32 v21, v21, v24, s33
	v_add3_u32 v20, v20, v25, s33
	v_and_b32_e32 v21, 0xffff0000, v21
	v_and_b32_e32 v20, 0xffff0000, v20
	v_or_b32_sdwa v21, v21, v23 dst_sel:DWORD dst_unused:UNUSED_PAD src0_sel:DWORD src1_sel:WORD_1
	v_or_b32_sdwa v20, v20, v22 dst_sel:DWORD dst_unused:UNUSED_PAD src0_sel:DWORD src1_sel:WORD_1
	global_store_dwordx2 v[28:29], v[20:21], off offset:64
	v_exp_f32_e32 v20, v17
	v_mul_f32_e32 v17, 0xbfb8aa3b, v18
	v_exp_f32_e32 v17, v17
	v_mul_f32_e32 v18, 0xbfb8aa3b, v19
	v_exp_f32_e32 v21, v18
	v_pk_add_f32 v[16:17], v[16:17], 1.0 op_sel_hi:[1,0]
	s_nop 0
	s_nop 0
	v_rcp_f32_e32 v18, v16
	s_nop 0
	v_rcp_f32_e32 v19, v17
	v_pk_add_f32 v[16:17], v[20:21], 1.0 op_sel_hi:[1,0]
	s_nop 0
	s_nop 0
	v_rcp_f32_e32 v16, v16
	s_nop 0
	v_rcp_f32_e32 v17, v17
	v_and_b32_sdwa v20, v19, v154 dst_sel:DWORD dst_unused:UNUSED_PAD src0_sel:WORD_1 src1_sel:DWORD
	v_and_b32_sdwa v21, v18, v154 dst_sel:DWORD dst_unused:UNUSED_PAD src0_sel:WORD_1 src1_sel:DWORD
	v_add3_u32 v18, v18, v21, s33
	v_add3_u32 v19, v19, v20, s33
	v_and_b32_sdwa v20, v17, v154 dst_sel:DWORD dst_unused:UNUSED_PAD src0_sel:WORD_1 src1_sel:DWORD
	v_and_b32_sdwa v21, v16, v154 dst_sel:DWORD dst_unused:UNUSED_PAD src0_sel:WORD_1 src1_sel:DWORD
	v_add3_u32 v17, v17, v20, s33
	v_add3_u32 v16, v16, v21, s33
	v_and_b32_e32 v17, 0xffff0000, v17
	v_and_b32_e32 v16, 0xffff0000, v16
	v_or_b32_sdwa v17, v17, v19 dst_sel:DWORD dst_unused:UNUSED_PAD src0_sel:DWORD src1_sel:WORD_1
	v_or_b32_sdwa v16, v16, v18 dst_sel:DWORD dst_unused:UNUSED_PAD src0_sel:DWORD src1_sel:WORD_1
	global_store_dwordx2 v[28:29], v[16:17], off offset:96
	v_mul_f32_e32 v12, 0xbfb8aa3b, v12
	v_exp_f32_e32 v18, v12
	v_mul_f32_e32 v12, 0xbfb8aa3b, v13
	v_exp_f32_e32 v20, v12
	v_mul_f32_e32 v12, 0xbfb8aa3b, v14
	v_exp_f32_e32 v19, v12
	v_or_b32_e32 v16, 48, v42
	v_mad_i64_i32 v[16:17], s[6:7], v16, s67, v[74:75]
	v_mul_f32_e32 v12, 0xbfb8aa3b, v15
	v_pk_add_f32 v[14:15], v[18:19], 1.0 op_sel_hi:[1,0]
	v_exp_f32_e32 v21, v12
	v_lshl_add_u64 v[12:13], v[16:17], 0, v[96:97]
	v_mul_f32_e32 v9, 0xbfb8aa3b, v9
	v_mul_f32_e32 v8, 0xbfb8aa3b, v8
	v_exp_f32_e32 v8, v8
	v_rcp_f32_e32 v16, v14
	v_mul_f32_e32 v5, 0xbfb8aa3b, v5
	v_mul_f32_e32 v4, 0xbfb8aa3b, v4
	v_exp_f32_e32 v4, v4
	v_rcp_f32_e32 v17, v15
	v_pk_add_f32 v[14:15], v[20:21], 1.0 op_sel_hi:[1,0]
	v_mul_f32_e32 v0, 0xbfb8aa3b, v0
	v_exp_f32_e32 v0, v0
	v_rcp_f32_e32 v14, v14
	v_add_f32_e32 v0, 1.0, v0
	v_rcp_f32_e32 v15, v15
	v_and_b32_sdwa v18, v17, v154 dst_sel:DWORD dst_unused:UNUSED_PAD src0_sel:WORD_1 src1_sel:DWORD
	v_and_b32_sdwa v19, v16, v154 dst_sel:DWORD dst_unused:UNUSED_PAD src0_sel:WORD_1 src1_sel:DWORD
	v_add3_u32 v16, v16, v19, s33
	v_add3_u32 v17, v17, v18, s33
	v_and_b32_sdwa v18, v15, v154 dst_sel:DWORD dst_unused:UNUSED_PAD src0_sel:WORD_1 src1_sel:DWORD
	v_and_b32_sdwa v19, v14, v154 dst_sel:DWORD dst_unused:UNUSED_PAD src0_sel:WORD_1 src1_sel:DWORD
	v_add3_u32 v15, v15, v18, s33
	v_add3_u32 v14, v14, v19, s33
	v_and_b32_e32 v15, 0xffff0000, v15
	v_and_b32_e32 v14, 0xffff0000, v14
	v_or_b32_sdwa v15, v15, v17 dst_sel:DWORD dst_unused:UNUSED_PAD src0_sel:DWORD src1_sel:WORD_1
	v_or_b32_sdwa v14, v14, v16 dst_sel:DWORD dst_unused:UNUSED_PAD src0_sel:DWORD src1_sel:WORD_1
	global_store_dwordx2 v[12:13], v[14:15], off
	v_exp_f32_e32 v14, v9
	v_mul_f32_e32 v9, 0xbfb8aa3b, v10
	v_exp_f32_e32 v9, v9
	v_mul_f32_e32 v10, 0xbfb8aa3b, v11
	v_exp_f32_e32 v15, v10
	v_pk_add_f32 v[8:9], v[8:9], 1.0 op_sel_hi:[1,0]
	s_nop 0
	s_nop 0
	v_rcp_f32_e32 v10, v8
	s_nop 0
	v_rcp_f32_e32 v11, v9
	v_pk_add_f32 v[8:9], v[14:15], 1.0 op_sel_hi:[1,0]
	s_nop 0
	s_nop 0
	v_rcp_f32_e32 v8, v8
	s_nop 0
	v_rcp_f32_e32 v9, v9
	v_and_b32_sdwa v14, v11, v154 dst_sel:DWORD dst_unused:UNUSED_PAD src0_sel:WORD_1 src1_sel:DWORD
	v_and_b32_sdwa v15, v10, v154 dst_sel:DWORD dst_unused:UNUSED_PAD src0_sel:WORD_1 src1_sel:DWORD
	v_add3_u32 v10, v10, v15, s33
	v_add3_u32 v11, v11, v14, s33
	v_and_b32_sdwa v14, v9, v154 dst_sel:DWORD dst_unused:UNUSED_PAD src0_sel:WORD_1 src1_sel:DWORD
	v_and_b32_sdwa v15, v8, v154 dst_sel:DWORD dst_unused:UNUSED_PAD src0_sel:WORD_1 src1_sel:DWORD
	v_add3_u32 v9, v9, v14, s33
	v_add3_u32 v8, v8, v15, s33
	v_and_b32_e32 v9, 0xffff0000, v9
	v_and_b32_e32 v8, 0xffff0000, v8
	v_or_b32_sdwa v9, v9, v11 dst_sel:DWORD dst_unused:UNUSED_PAD src0_sel:DWORD src1_sel:WORD_1
	v_or_b32_sdwa v8, v8, v10 dst_sel:DWORD dst_unused:UNUSED_PAD src0_sel:DWORD src1_sel:WORD_1
	global_store_dwordx2 v[12:13], v[8:9], off offset:32
	v_exp_f32_e32 v8, v5
	v_mul_f32_e32 v5, 0xbfb8aa3b, v6
	v_exp_f32_e32 v5, v5
	v_mul_f32_e32 v6, 0xbfb8aa3b, v7
	v_exp_f32_e32 v9, v6
	v_pk_add_f32 v[4:5], v[4:5], 1.0 op_sel_hi:[1,0]
	s_nop 0
	s_nop 0
	v_rcp_f32_e32 v6, v4
	s_nop 0
	v_rcp_f32_e32 v7, v5
	v_pk_add_f32 v[4:5], v[8:9], 1.0 op_sel_hi:[1,0]
	s_nop 0
	s_nop 0
	v_rcp_f32_e32 v4, v4
	s_nop 0
	v_rcp_f32_e32 v5, v5
	v_and_b32_sdwa v8, v7, v154 dst_sel:DWORD dst_unused:UNUSED_PAD src0_sel:WORD_1 src1_sel:DWORD
	v_and_b32_sdwa v9, v6, v154 dst_sel:DWORD dst_unused:UNUSED_PAD src0_sel:WORD_1 src1_sel:DWORD
	v_add3_u32 v6, v6, v9, s33
	v_add3_u32 v7, v7, v8, s33
	v_and_b32_sdwa v8, v5, v154 dst_sel:DWORD dst_unused:UNUSED_PAD src0_sel:WORD_1 src1_sel:DWORD
	v_and_b32_sdwa v9, v4, v154 dst_sel:DWORD dst_unused:UNUSED_PAD src0_sel:WORD_1 src1_sel:DWORD
	v_add3_u32 v5, v5, v8, s33
	v_add3_u32 v4, v4, v9, s33
	v_and_b32_e32 v5, 0xffff0000, v5
	v_and_b32_e32 v4, 0xffff0000, v4
	v_or_b32_sdwa v5, v5, v7 dst_sel:DWORD dst_unused:UNUSED_PAD src0_sel:DWORD src1_sel:WORD_1
	v_or_b32_sdwa v4, v4, v6 dst_sel:DWORD dst_unused:UNUSED_PAD src0_sel:DWORD src1_sel:WORD_1
	global_store_dwordx2 v[12:13], v[4:5], off offset:64
	s_nop 0
	v_rcp_f32_e32 v4, v0
	v_mul_f32_e32 v0, 0xbfb8aa3b, v1
	v_exp_f32_e32 v0, v0
	s_nop 0
	v_add_f32_e32 v0, 1.0, v0
	s_nop 0
	v_rcp_f32_e32 v5, v0
	v_mul_f32_e32 v0, 0xbfb8aa3b, v2
	v_exp_f32_e32 v1, v0
	v_mul_f32_e32 v0, 0xbfb8aa3b, v3
	v_exp_f32_e32 v0, v0
	v_bfe_u32 v2, v4, 16, 1
	v_add3_u32 v2, v4, v2, s33
	v_bfe_u32 v3, v5, 16, 1
	v_pk_add_f32 v[0:1], v[0:1], 1.0 op_sel_hi:[1,0]
	v_add3_u32 v3, v5, v3, s33
	v_lshrrev_b32_e32 v2, 16, v2
	v_rcp_f32_e32 v0, v0
	s_mov_b32 s6, 0xffff0000
	v_and_or_b32 v2, v3, s6, v2
	global_store_dword v[12:13], v2, off offset:96
	v_rcp_f32_e32 v1, v1
	s_nop 0
	v_and_b32_sdwa v4, v1, v154 dst_sel:DWORD dst_unused:UNUSED_PAD src0_sel:WORD_1 src1_sel:DWORD
	v_and_b32_sdwa v5, v0, v154 dst_sel:DWORD dst_unused:UNUSED_PAD src0_sel:WORD_1 src1_sel:DWORD
	v_add3_u32 v1, v1, v4, s33
	v_add3_u32 v0, v0, v5, s33
	v_lshrrev_b32_e32 v1, 16, v1
	v_and_or_b32 v81, v0, s6, v1
	s_mov_b64 s[6:7], 0x60
	v_lshl_add_u64 v[76:77], v[12:13], 0, s[6:7]
.LBB0_218:
	s_andn2_saveexec_b64 s[60:61], s[60:61]
	s_cbranch_execz .LBB0_159
	v_cmp_gt_u32_e32 vcc, 8, v78
	v_mov_b32_e32 v78, v97
	v_readlane_b32 s6, v254, 11
	v_add_u32_e32 v78, v78, v176
	v_cndmask_b32_e32 v76, v251, v148, vcc
	v_mov_b32_e32 v77, v97
	v_readlane_b32 s7, v254, 12
	v_ashrrev_i32_e32 v85, 1, v78
	v_and_b32_e32 v81, 64, v78
	v_lshl_add_u64 v[76:77], s[6:7], 0, v[76:77]
	v_and_b32_e32 v85, 0xffffffc0, v85
	v_lshrrev_b32_e32 v86, 2, v78
	v_and_or_b32 v78, v78, 15, v80
	v_and_or_b32 v132, v86, 12, v81
	v_add_u32_e32 v80, v78, v85
	s_movk_i32 s67, 0x3200
	v_mad_i64_i32 v[88:89], s[6:7], v80, s67, v[74:75]
	v_ashrrev_i32_e32 v81, 31, v80
	s_movk_i32 s6, 0x380
	v_lshlrev_b64 v[86:87], 11, v[80:81]
	v_and_or_b32 v78, v96, s6, v132
	v_lshl_add_u64 v[86:87], v[76:77], 0, v[86:87]
	v_exp_f32_e32 v129, v79
	v_lshlrev_b32_e32 v78, 1, v78
	v_mov_b32_e32 v79, v97
	v_exp_f32_e32 v130, v84
	v_lshlrev_b32_e32 v96, 1, v132
	v_lshl_add_u64 v[84:85], v[86:87], 0, v[78:79]
	v_exp_f32_e32 v128, v83
	v_exp_f32_e32 v131, v82
	v_lshl_add_u64 v[82:83], v[88:89], 0, v[96:97]
	global_load_dwordx2 v[88:89], v[84:85], off
	v_pk_add_f32 v[128:129], v[128:129], 1.0 op_sel_hi:[1,0]
	s_waitcnt vmcnt(0)
	v_lshlrev_b32_e32 v87, 16, v89
	v_lshlrev_b32_e32 v86, 16, v88
	v_and_b32_e32 v89, 0xffff0000, v89
	v_and_b32_e32 v88, 0xffff0000, v88
	v_rcp_f32_e32 v81, v129
	s_nop 0
	v_mul_f32_e32 v129, v62, v81
	s_nop 0
	v_rcp_f32_e32 v62, v128
	s_nop 0
	v_mul_f32_e32 v128, v60, v62
	v_pk_mul_f32 v[86:87], v[128:129], v[86:87]
	v_pk_add_f32 v[128:129], v[130:131], 1.0 op_sel_hi:[1,0]
	s_nop 0
	s_nop 0
	v_rcp_f32_e32 v60, v129
	s_nop 0
	v_mul_f32_e32 v63, v63, v60
	s_nop 0
	v_rcp_f32_e32 v60, v128
	s_nop 0
	v_mul_f32_e32 v62, v61, v60
	v_pk_mul_f32 v[60:61], v[62:63], v[88:89]
	v_and_b32_sdwa v63, v86, v154 dst_sel:DWORD dst_unused:UNUSED_PAD src0_sel:WORD_1 src1_sel:DWORD
	v_add3_u32 v63, v86, v63, s33
	v_and_b32_sdwa v81, v61, v154 dst_sel:DWORD dst_unused:UNUSED_PAD src0_sel:WORD_1 src1_sel:DWORD
	v_and_b32_sdwa v86, v60, v154 dst_sel:DWORD dst_unused:UNUSED_PAD src0_sel:WORD_1 src1_sel:DWORD
	v_and_b32_sdwa v62, v87, v154 dst_sel:DWORD dst_unused:UNUSED_PAD src0_sel:WORD_1 src1_sel:DWORD
	v_add3_u32 v61, v61, v81, s33
	v_add3_u32 v60, v60, v86, s33
	v_add3_u32 v62, v87, v62, s33
	v_and_b32_e32 v61, 0xffff0000, v61
	v_and_b32_e32 v60, 0xffff0000, v60
	v_or_b32_sdwa v61, v61, v62 dst_sel:DWORD dst_unused:UNUSED_PAD src0_sel:DWORD src1_sel:WORD_1
	v_or_b32_sdwa v60, v60, v63 dst_sel:DWORD dst_unused:UNUSED_PAD src0_sel:DWORD src1_sel:WORD_1
	global_store_dwordx2 v[82:83], v[60:61], off
	global_load_dwordx2 v[62:63], v[84:85], off offset:32
	v_exp_f32_e32 v60, v126
	v_exp_f32_e32 v61, v124
	v_exp_f32_e32 v87, v125
	v_exp_f32_e32 v86, v127
	v_pk_add_f32 v[60:61], v[60:61], 1.0 op_sel_hi:[1,0]
	s_nop 0
	v_pk_add_f32 v[86:87], v[86:87], 1.0 op_sel_hi:[1,0]
	v_rcp_f32_e32 v81, v61
	s_nop 0
	v_mul_f32_e32 v61, v58, v81
	s_waitcnt vmcnt(0)
	v_lshlrev_b32_e32 v89, 16, v63
	v_rcp_f32_e32 v58, v60
	s_nop 0
	v_mul_f32_e32 v60, v56, v58
	v_div_scale_f32 v56, s[6:7], v87, v87, v59
	v_rcp_f32_e32 v58, v56
	v_lshlrev_b32_e32 v88, 16, v62
	v_pk_mul_f32 v[60:61], v[60:61], v[88:89]
	v_and_b32_e32 v63, 0xffff0000, v63
	v_fma_f32 v81, -v56, v58, 1.0
	v_fmac_f32_e32 v58, v81, v58
	v_div_scale_f32 v81, vcc, v59, v87, v59
	v_mul_f32_e32 v88, v81, v58
	v_fma_f32 v89, -v56, v88, v81
	v_fmac_f32_e32 v88, v89, v58
	v_fma_f32 v56, -v56, v88, v81
	v_div_fmas_f32 v56, v56, v58, v88
	v_div_fixup_f32 v59, v56, v87, v59
	v_and_b32_e32 v62, 0xffff0000, v62
	v_rcp_f32_e32 v56, v86
	s_nop 0
	v_mul_f32_e32 v58, v57, v56
	v_pk_mul_f32 v[56:57], v[58:59], v[62:63]
	v_and_b32_sdwa v58, v61, v154 dst_sel:DWORD dst_unused:UNUSED_PAD src0_sel:WORD_1 src1_sel:DWORD
	v_and_b32_sdwa v59, v60, v154 dst_sel:DWORD dst_unused:UNUSED_PAD src0_sel:WORD_1 src1_sel:DWORD
	v_add3_u32 v59, v60, v59, s33
	v_add3_u32 v58, v61, v58, s33
	v_and_b32_sdwa v60, v57, v154 dst_sel:DWORD dst_unused:UNUSED_PAD src0_sel:WORD_1 src1_sel:DWORD
	v_and_b32_sdwa v61, v56, v154 dst_sel:DWORD dst_unused:UNUSED_PAD src0_sel:WORD_1 src1_sel:DWORD
	v_add3_u32 v57, v57, v60, s33
	v_add3_u32 v56, v56, v61, s33
	v_and_b32_e32 v57, 0xffff0000, v57
	v_and_b32_e32 v56, 0xffff0000, v56
	v_or_b32_sdwa v57, v57, v58 dst_sel:DWORD dst_unused:UNUSED_PAD src0_sel:DWORD src1_sel:WORD_1
	v_or_b32_sdwa v56, v56, v59 dst_sel:DWORD dst_unused:UNUSED_PAD src0_sel:DWORD src1_sel:WORD_1
	global_store_dwordx2 v[82:83], v[56:57], off offset:32
	global_load_dwordx2 v[58:59], v[84:85], off offset:64
	v_exp_f32_e32 v56, v122
	v_exp_f32_e32 v57, v120
	v_exp_f32_e32 v60, v123
	v_exp_f32_e32 v61, v121
	v_pk_add_f32 v[56:57], v[56:57], 1.0 op_sel_hi:[1,0]
	s_nop 0
	v_pk_add_f32 v[60:61], v[60:61], 1.0 op_sel_hi:[1,0]
	v_rcp_f32_e32 v81, v57
	s_nop 0
	v_mul_f32_e32 v57, v54, v81
	s_waitcnt vmcnt(0)
	v_lshlrev_b32_e32 v63, 16, v59
	v_rcp_f32_e32 v54, v56
	s_nop 0
	v_mul_f32_e32 v56, v52, v54
	v_div_scale_f32 v52, s[6:7], v61, v61, v55
	v_rcp_f32_e32 v54, v52
	v_lshlrev_b32_e32 v62, 16, v58
	v_pk_mul_f32 v[56:57], v[56:57], v[62:63]
	v_and_b32_e32 v59, 0xffff0000, v59
	v_fma_f32 v62, -v52, v54, 1.0
	v_fmac_f32_e32 v54, v62, v54
	v_div_scale_f32 v62, vcc, v55, v61, v55
	v_mul_f32_e32 v63, v62, v54
	v_fma_f32 v81, -v52, v63, v62
	v_fmac_f32_e32 v63, v81, v54
	v_fma_f32 v52, -v52, v63, v62
	v_div_fmas_f32 v52, v52, v54, v63
	v_div_fixup_f32 v55, v52, v61, v55
	v_and_b32_e32 v58, 0xffff0000, v58
	v_rcp_f32_e32 v52, v60
	s_nop 0
	v_mul_f32_e32 v54, v53, v52
	v_pk_mul_f32 v[52:53], v[54:55], v[58:59]
	v_and_b32_sdwa v54, v57, v154 dst_sel:DWORD dst_unused:UNUSED_PAD src0_sel:WORD_1 src1_sel:DWORD
	v_and_b32_sdwa v55, v56, v154 dst_sel:DWORD dst_unused:UNUSED_PAD src0_sel:WORD_1 src1_sel:DWORD
	v_add3_u32 v55, v56, v55, s33
	v_add3_u32 v54, v57, v54, s33
	v_and_b32_sdwa v56, v53, v154 dst_sel:DWORD dst_unused:UNUSED_PAD src0_sel:WORD_1 src1_sel:DWORD
	v_and_b32_sdwa v57, v52, v154 dst_sel:DWORD dst_unused:UNUSED_PAD src0_sel:WORD_1 src1_sel:DWORD
	v_add3_u32 v53, v53, v56, s33
	v_add3_u32 v52, v52, v57, s33
	v_and_b32_e32 v53, 0xffff0000, v53
	v_and_b32_e32 v52, 0xffff0000, v52
	v_or_b32_sdwa v53, v53, v54 dst_sel:DWORD dst_unused:UNUSED_PAD src0_sel:DWORD src1_sel:WORD_1
	v_or_b32_sdwa v52, v52, v55 dst_sel:DWORD dst_unused:UNUSED_PAD src0_sel:DWORD src1_sel:WORD_1
	global_store_dwordx2 v[82:83], v[52:53], off offset:64
	global_load_dwordx2 v[54:55], v[84:85], off offset:96
	v_exp_f32_e32 v52, v118
	v_exp_f32_e32 v53, v116
	v_exp_f32_e32 v56, v119
	v_exp_f32_e32 v57, v117
	v_pk_add_f32 v[52:53], v[52:53], 1.0 op_sel_hi:[1,0]
	s_nop 0
	v_pk_add_f32 v[56:57], v[56:57], 1.0 op_sel_hi:[1,0]
	v_rcp_f32_e32 v60, v53
	s_nop 0
	v_mul_f32_e32 v53, v50, v60
	s_waitcnt vmcnt(0)
	v_lshlrev_b32_e32 v59, 16, v55
	v_rcp_f32_e32 v50, v52
	s_nop 0
	v_mul_f32_e32 v52, v48, v50
	v_div_scale_f32 v48, s[6:7], v57, v57, v51
	v_rcp_f32_e32 v50, v48
	v_lshlrev_b32_e32 v58, 16, v54
	v_pk_mul_f32 v[52:53], v[52:53], v[58:59]
	v_and_b32_e32 v55, 0xffff0000, v55
	v_fma_f32 v58, -v48, v50, 1.0
	v_fmac_f32_e32 v50, v58, v50
	v_div_scale_f32 v58, vcc, v51, v57, v51
	v_mul_f32_e32 v59, v58, v50
	v_fma_f32 v60, -v48, v59, v58
	v_fmac_f32_e32 v59, v60, v50
	v_fma_f32 v48, -v48, v59, v58
	v_div_fmas_f32 v48, v48, v50, v59
	v_div_fixup_f32 v51, v48, v57, v51
	v_and_b32_e32 v54, 0xffff0000, v54
	v_rcp_f32_e32 v48, v56
	s_nop 0
	v_mul_f32_e32 v50, v49, v48
	v_pk_mul_f32 v[48:49], v[50:51], v[54:55]
	v_and_b32_sdwa v50, v53, v154 dst_sel:DWORD dst_unused:UNUSED_PAD src0_sel:WORD_1 src1_sel:DWORD
	v_and_b32_sdwa v51, v52, v154 dst_sel:DWORD dst_unused:UNUSED_PAD src0_sel:WORD_1 src1_sel:DWORD
	v_add3_u32 v51, v52, v51, s33
	v_add3_u32 v50, v53, v50, s33
	v_and_b32_sdwa v52, v49, v154 dst_sel:DWORD dst_unused:UNUSED_PAD src0_sel:WORD_1 src1_sel:DWORD
	v_and_b32_sdwa v53, v48, v154 dst_sel:DWORD dst_unused:UNUSED_PAD src0_sel:WORD_1 src1_sel:DWORD
	v_add3_u32 v49, v49, v52, s33
	v_add3_u32 v48, v48, v53, s33
	v_and_b32_e32 v49, 0xffff0000, v49
	v_and_b32_e32 v48, 0xffff0000, v48
	v_or_b32_sdwa v49, v49, v50 dst_sel:DWORD dst_unused:UNUSED_PAD src0_sel:DWORD src1_sel:WORD_1
	v_or_b32_sdwa v48, v48, v51 dst_sel:DWORD dst_unused:UNUSED_PAD src0_sel:DWORD src1_sel:WORD_1
	global_store_dwordx2 v[82:83], v[48:49], off offset:96
	v_or_b32_e32 v48, 16, v80
	v_ashrrev_i32_e32 v49, 31, v48
	v_lshlrev_b64 v[50:51], 11, v[48:49]
	v_lshl_add_u64 v[50:51], v[76:77], 0, v[50:51]
	v_lshl_add_u64 v[50:51], v[50:51], 0, v[78:79]
	global_load_dwordx2 v[54:55], v[50:51], off
	v_exp_f32_e32 v52, v114
	v_exp_f32_e32 v53, v112
	v_exp_f32_e32 v56, v115
	v_exp_f32_e32 v57, v113
	v_mad_i64_i32 v[48:49], s[6:7], v48, s67, v[74:75]
	v_pk_add_f32 v[52:53], v[52:53], 1.0 op_sel_hi:[1,0]
	v_pk_add_f32 v[56:57], v[56:57], 1.0 op_sel_hi:[1,0]
	v_lshl_add_u64 v[48:49], v[48:49], 0, v[96:97]
	v_rcp_f32_e32 v60, v53
	s_nop 0
	v_mul_f32_e32 v53, v46, v60
	s_waitcnt vmcnt(0)
	v_lshlrev_b32_e32 v59, 16, v55
	v_rcp_f32_e32 v46, v52
	s_nop 0
	v_mul_f32_e32 v52, v44, v46
	v_div_scale_f32 v44, s[6:7], v57, v57, v47
	v_rcp_f32_e32 v46, v44
	v_lshlrev_b32_e32 v58, 16, v54
	v_pk_mul_f32 v[52:53], v[52:53], v[58:59]
	v_and_b32_e32 v55, 0xffff0000, v55
	v_fma_f32 v58, -v44, v46, 1.0
	v_fmac_f32_e32 v46, v58, v46
	v_div_scale_f32 v58, vcc, v47, v57, v47
	v_mul_f32_e32 v59, v58, v46
	v_fma_f32 v60, -v44, v59, v58
	v_fmac_f32_e32 v59, v60, v46
	v_fma_f32 v44, -v44, v59, v58
	v_div_fmas_f32 v44, v44, v46, v59
	v_div_fixup_f32 v47, v44, v57, v47
	v_and_b32_e32 v54, 0xffff0000, v54
	v_rcp_f32_e32 v44, v56
	s_nop 0
	v_mul_f32_e32 v46, v45, v44
	v_pk_mul_f32 v[44:45], v[46:47], v[54:55]
	v_and_b32_sdwa v46, v53, v154 dst_sel:DWORD dst_unused:UNUSED_PAD src0_sel:WORD_1 src1_sel:DWORD
	v_and_b32_sdwa v47, v52, v154 dst_sel:DWORD dst_unused:UNUSED_PAD src0_sel:WORD_1 src1_sel:DWORD
	v_add3_u32 v47, v52, v47, s33
	v_add3_u32 v46, v53, v46, s33
	v_and_b32_sdwa v52, v45, v154 dst_sel:DWORD dst_unused:UNUSED_PAD src0_sel:WORD_1 src1_sel:DWORD
	v_and_b32_sdwa v53, v44, v154 dst_sel:DWORD dst_unused:UNUSED_PAD src0_sel:WORD_1 src1_sel:DWORD
	v_add3_u32 v45, v45, v52, s33
	v_add3_u32 v44, v44, v53, s33
	v_and_b32_e32 v45, 0xffff0000, v45
	v_and_b32_e32 v44, 0xffff0000, v44
	v_or_b32_sdwa v45, v45, v46 dst_sel:DWORD dst_unused:UNUSED_PAD src0_sel:DWORD src1_sel:WORD_1
	v_or_b32_sdwa v44, v44, v47 dst_sel:DWORD dst_unused:UNUSED_PAD src0_sel:DWORD src1_sel:WORD_1
	global_store_dwordx2 v[48:49], v[44:45], off
	global_load_dwordx2 v[46:47], v[50:51], off offset:32
	v_exp_f32_e32 v44, v110
	v_exp_f32_e32 v45, v67
	v_exp_f32_e32 v52, v111
	v_exp_f32_e32 v53, v109
	v_pk_add_f32 v[44:45], v[44:45], 1.0 op_sel_hi:[1,0]
	s_nop 0
	v_pk_add_f32 v[52:53], v[52:53], 1.0 op_sel_hi:[1,0]
	v_rcp_f32_e32 v56, v45
	s_nop 0
	v_mul_f32_e32 v45, v42, v56
	s_waitcnt vmcnt(0)
	v_lshlrev_b32_e32 v55, 16, v47
	v_rcp_f32_e32 v42, v44
	s_nop 0
	v_mul_f32_e32 v44, v40, v42
	v_div_scale_f32 v40, s[6:7], v53, v53, v43
	v_rcp_f32_e32 v42, v40
	v_lshlrev_b32_e32 v54, 16, v46
	v_pk_mul_f32 v[44:45], v[44:45], v[54:55]
	v_and_b32_e32 v47, 0xffff0000, v47
	v_fma_f32 v54, -v40, v42, 1.0
	v_fmac_f32_e32 v42, v54, v42
	v_div_scale_f32 v54, vcc, v43, v53, v43
	v_mul_f32_e32 v55, v54, v42
	v_fma_f32 v56, -v40, v55, v54
	v_fmac_f32_e32 v55, v56, v42
	v_fma_f32 v40, -v40, v55, v54
	v_div_fmas_f32 v40, v40, v42, v55
	v_div_fixup_f32 v43, v40, v53, v43
	v_and_b32_e32 v46, 0xffff0000, v46
	v_rcp_f32_e32 v40, v52
	s_nop 0
	v_mul_f32_e32 v42, v41, v40
	v_pk_mul_f32 v[40:41], v[42:43], v[46:47]
	v_and_b32_sdwa v42, v45, v154 dst_sel:DWORD dst_unused:UNUSED_PAD src0_sel:WORD_1 src1_sel:DWORD
	v_and_b32_sdwa v43, v44, v154 dst_sel:DWORD dst_unused:UNUSED_PAD src0_sel:WORD_1 src1_sel:DWORD
	v_add3_u32 v43, v44, v43, s33
	v_add3_u32 v42, v45, v42, s33
	v_and_b32_sdwa v44, v41, v154 dst_sel:DWORD dst_unused:UNUSED_PAD src0_sel:WORD_1 src1_sel:DWORD
	v_and_b32_sdwa v45, v40, v154 dst_sel:DWORD dst_unused:UNUSED_PAD src0_sel:WORD_1 src1_sel:DWORD
	v_add3_u32 v41, v41, v44, s33
	v_add3_u32 v40, v40, v45, s33
	v_and_b32_e32 v41, 0xffff0000, v41
	v_and_b32_e32 v40, 0xffff0000, v40
	v_or_b32_sdwa v41, v41, v42 dst_sel:DWORD dst_unused:UNUSED_PAD src0_sel:DWORD src1_sel:WORD_1
	v_or_b32_sdwa v40, v40, v43 dst_sel:DWORD dst_unused:UNUSED_PAD src0_sel:DWORD src1_sel:WORD_1
	global_store_dwordx2 v[48:49], v[40:41], off offset:32
	v_mul_f32_e32 v42, 0xbfb8aa3b, v39
	v_exp_f32_e32 v45, v42
	global_load_dwordx2 v[42:43], v[50:51], off offset:64
	v_mul_f32_e32 v41, 0xbfb8aa3b, v37
	v_mul_f32_e32 v40, 0xbfb8aa3b, v36
	v_exp_f32_e32 v44, v41
	v_mul_f32_e32 v41, 0xbfb8aa3b, v38
	v_exp_f32_e32 v40, v40
	v_exp_f32_e32 v41, v41
	v_pk_add_f32 v[44:45], v[44:45], 1.0 op_sel_hi:[1,0]
	v_pk_add_f32 v[40:41], v[40:41], 1.0 op_sel_hi:[1,0]
	s_nop 0
	s_waitcnt vmcnt(0)
	v_lshlrev_b32_e32 v47, 16, v43
	v_rcp_f32_e32 v52, v41
	s_nop 0
	v_mul_f32_e32 v41, v38, v52
	v_lshlrev_b32_e32 v46, 16, v42
	v_and_b32_e32 v43, 0xffff0000, v43
	v_and_b32_e32 v42, 0xffff0000, v42
	v_rcp_f32_e32 v38, v40
	s_nop 0
	v_mul_f32_e32 v40, v36, v38
	v_div_scale_f32 v36, s[6:7], v45, v45, v39
	v_rcp_f32_e32 v38, v36
	v_pk_mul_f32 v[40:41], v[40:41], v[46:47]
	v_fma_f32 v46, -v36, v38, 1.0
	v_fmac_f32_e32 v38, v46, v38
	v_div_scale_f32 v46, vcc, v39, v45, v39
	v_mul_f32_e32 v47, v46, v38
	v_fma_f32 v52, -v36, v47, v46
	v_fmac_f32_e32 v47, v52, v38
	v_fma_f32 v36, -v36, v47, v46
	v_div_fmas_f32 v36, v36, v38, v47
	v_div_fixup_f32 v39, v36, v45, v39
	s_nop 0
	v_rcp_f32_e32 v36, v44
	s_nop 0
	v_mul_f32_e32 v38, v37, v36
	v_pk_mul_f32 v[36:37], v[38:39], v[42:43]
	v_and_b32_sdwa v38, v41, v154 dst_sel:DWORD dst_unused:UNUSED_PAD src0_sel:WORD_1 src1_sel:DWORD
	v_and_b32_sdwa v39, v40, v154 dst_sel:DWORD dst_unused:UNUSED_PAD src0_sel:WORD_1 src1_sel:DWORD
	v_add3_u32 v39, v40, v39, s33
	v_add3_u32 v38, v41, v38, s33
	v_and_b32_sdwa v40, v37, v154 dst_sel:DWORD dst_unused:UNUSED_PAD src0_sel:WORD_1 src1_sel:DWORD
	v_and_b32_sdwa v41, v36, v154 dst_sel:DWORD dst_unused:UNUSED_PAD src0_sel:WORD_1 src1_sel:DWORD
	v_add3_u32 v37, v37, v40, s33
	v_add3_u32 v36, v36, v41, s33
	v_and_b32_e32 v37, 0xffff0000, v37
	v_and_b32_e32 v36, 0xffff0000, v36
	v_or_b32_sdwa v37, v37, v38 dst_sel:DWORD dst_unused:UNUSED_PAD src0_sel:DWORD src1_sel:WORD_1
	v_or_b32_sdwa v36, v36, v39 dst_sel:DWORD dst_unused:UNUSED_PAD src0_sel:DWORD src1_sel:WORD_1
	global_store_dwordx2 v[48:49], v[36:37], off offset:64
	v_mul_f32_e32 v38, 0xbfb8aa3b, v35
	v_exp_f32_e32 v41, v38
	global_load_dwordx2 v[38:39], v[50:51], off offset:96
	v_mul_f32_e32 v37, 0xbfb8aa3b, v33
	v_mul_f32_e32 v36, 0xbfb8aa3b, v32
	v_exp_f32_e32 v40, v37
	v_mul_f32_e32 v37, 0xbfb8aa3b, v34
	v_exp_f32_e32 v36, v36
	v_exp_f32_e32 v37, v37
	v_pk_add_f32 v[40:41], v[40:41], 1.0 op_sel_hi:[1,0]
	v_pk_add_f32 v[36:37], v[36:37], 1.0 op_sel_hi:[1,0]
	s_nop 0
	s_waitcnt vmcnt(0)
	v_lshlrev_b32_e32 v43, 16, v39
	v_rcp_f32_e32 v44, v37
	s_nop 0
	v_mul_f32_e32 v37, v34, v44
	v_lshlrev_b32_e32 v42, 16, v38
	v_and_b32_e32 v39, 0xffff0000, v39
	v_and_b32_e32 v38, 0xffff0000, v38
	v_rcp_f32_e32 v34, v36
	s_nop 0
	v_mul_f32_e32 v36, v32, v34
	v_div_scale_f32 v32, s[6:7], v41, v41, v35
	v_rcp_f32_e32 v34, v32
	v_pk_mul_f32 v[36:37], v[36:37], v[42:43]
	v_fma_f32 v42, -v32, v34, 1.0
	v_fmac_f32_e32 v34, v42, v34
	v_div_scale_f32 v42, vcc, v35, v41, v35
	v_mul_f32_e32 v43, v42, v34
	v_fma_f32 v44, -v32, v43, v42
	v_fmac_f32_e32 v43, v44, v34
	v_fma_f32 v32, -v32, v43, v42
	v_div_fmas_f32 v32, v32, v34, v43
	v_div_fixup_f32 v35, v32, v41, v35
	s_nop 0
	v_rcp_f32_e32 v32, v40
	s_nop 0
	v_mul_f32_e32 v34, v33, v32
	v_pk_mul_f32 v[32:33], v[34:35], v[38:39]
	v_and_b32_sdwa v34, v37, v154 dst_sel:DWORD dst_unused:UNUSED_PAD src0_sel:WORD_1 src1_sel:DWORD
	v_and_b32_sdwa v35, v36, v154 dst_sel:DWORD dst_unused:UNUSED_PAD src0_sel:WORD_1 src1_sel:DWORD
	v_add3_u32 v35, v36, v35, s33
	v_add3_u32 v34, v37, v34, s33
	v_and_b32_sdwa v36, v33, v154 dst_sel:DWORD dst_unused:UNUSED_PAD src0_sel:WORD_1 src1_sel:DWORD
	v_and_b32_sdwa v37, v32, v154 dst_sel:DWORD dst_unused:UNUSED_PAD src0_sel:WORD_1 src1_sel:DWORD
	v_add3_u32 v33, v33, v36, s33
	v_add3_u32 v32, v32, v37, s33
	v_and_b32_e32 v33, 0xffff0000, v33
	v_and_b32_e32 v32, 0xffff0000, v32
	v_or_b32_sdwa v33, v33, v34 dst_sel:DWORD dst_unused:UNUSED_PAD src0_sel:DWORD src1_sel:WORD_1
	v_or_b32_sdwa v32, v32, v35 dst_sel:DWORD dst_unused:UNUSED_PAD src0_sel:DWORD src1_sel:WORD_1
	global_store_dwordx2 v[48:49], v[32:33], off offset:96
	v_or_b32_e32 v32, 32, v80
	v_ashrrev_i32_e32 v33, 31, v32
	v_lshlrev_b64 v[34:35], 11, v[32:33]
	v_lshl_add_u64 v[34:35], v[76:77], 0, v[34:35]
	v_mul_f32_e32 v38, 0xbfb8aa3b, v31
	v_lshl_add_u64 v[34:35], v[34:35], 0, v[78:79]
	v_exp_f32_e32 v41, v38
	global_load_dwordx2 v[38:39], v[34:35], off
	v_mul_f32_e32 v37, 0xbfb8aa3b, v29
	v_mul_f32_e32 v36, 0xbfb8aa3b, v28
	v_exp_f32_e32 v40, v37
	v_mul_f32_e32 v37, 0xbfb8aa3b, v30
	v_exp_f32_e32 v36, v36
	v_exp_f32_e32 v37, v37
	v_pk_add_f32 v[40:41], v[40:41], 1.0 op_sel_hi:[1,0]
	v_mad_i64_i32 v[32:33], s[6:7], v32, s67, v[74:75]
	v_pk_add_f32 v[36:37], v[36:37], 1.0 op_sel_hi:[1,0]
	v_lshl_add_u64 v[32:33], v[32:33], 0, v[96:97]
	s_waitcnt vmcnt(0)
	v_lshlrev_b32_e32 v43, 16, v39
	v_rcp_f32_e32 v44, v37
	s_nop 0
	v_mul_f32_e32 v37, v30, v44
	v_lshlrev_b32_e32 v42, 16, v38
	v_and_b32_e32 v39, 0xffff0000, v39
	v_and_b32_e32 v38, 0xffff0000, v38
	v_rcp_f32_e32 v30, v36
	s_nop 0
	v_mul_f32_e32 v36, v28, v30
	v_div_scale_f32 v28, s[6:7], v41, v41, v31
	v_rcp_f32_e32 v30, v28
	v_pk_mul_f32 v[36:37], v[36:37], v[42:43]
	v_fma_f32 v42, -v28, v30, 1.0
	v_fmac_f32_e32 v30, v42, v30
	v_div_scale_f32 v42, vcc, v31, v41, v31
	v_mul_f32_e32 v43, v42, v30
	v_fma_f32 v44, -v28, v43, v42
	v_fmac_f32_e32 v43, v44, v30
	v_fma_f32 v28, -v28, v43, v42
	v_div_fmas_f32 v28, v28, v30, v43
	v_div_fixup_f32 v31, v28, v41, v31
	s_nop 0
	v_rcp_f32_e32 v28, v40
	s_nop 0
	v_mul_f32_e32 v30, v29, v28
	v_pk_mul_f32 v[28:29], v[30:31], v[38:39]
	v_and_b32_sdwa v30, v37, v154 dst_sel:DWORD dst_unused:UNUSED_PAD src0_sel:WORD_1 src1_sel:DWORD
	v_and_b32_sdwa v31, v36, v154 dst_sel:DWORD dst_unused:UNUSED_PAD src0_sel:WORD_1 src1_sel:DWORD
	v_add3_u32 v31, v36, v31, s33
	v_add3_u32 v30, v37, v30, s33
	v_and_b32_sdwa v36, v29, v154 dst_sel:DWORD dst_unused:UNUSED_PAD src0_sel:WORD_1 src1_sel:DWORD
	v_and_b32_sdwa v37, v28, v154 dst_sel:DWORD dst_unused:UNUSED_PAD src0_sel:WORD_1 src1_sel:DWORD
	v_add3_u32 v29, v29, v36, s33
	v_add3_u32 v28, v28, v37, s33
	v_and_b32_e32 v29, 0xffff0000, v29
	v_and_b32_e32 v28, 0xffff0000, v28
	v_or_b32_sdwa v29, v29, v30 dst_sel:DWORD dst_unused:UNUSED_PAD src0_sel:DWORD src1_sel:WORD_1
	v_or_b32_sdwa v28, v28, v31 dst_sel:DWORD dst_unused:UNUSED_PAD src0_sel:DWORD src1_sel:WORD_1
	global_store_dwordx2 v[32:33], v[28:29], off
	v_mul_f32_e32 v30, 0xbfb8aa3b, v27
	v_exp_f32_e32 v37, v30
	global_load_dwordx2 v[30:31], v[34:35], off offset:32
	v_mul_f32_e32 v29, 0xbfb8aa3b, v25
	v_mul_f32_e32 v28, 0xbfb8aa3b, v24
	v_exp_f32_e32 v36, v29
	v_mul_f32_e32 v29, 0xbfb8aa3b, v26
	v_exp_f32_e32 v28, v28
	v_exp_f32_e32 v29, v29
	v_pk_add_f32 v[36:37], v[36:37], 1.0 op_sel_hi:[1,0]
	v_pk_add_f32 v[28:29], v[28:29], 1.0 op_sel_hi:[1,0]
	s_nop 0
	s_waitcnt vmcnt(0)
	v_lshlrev_b32_e32 v39, 16, v31
	v_rcp_f32_e32 v40, v29
	s_nop 0
	v_mul_f32_e32 v29, v26, v40
	v_lshlrev_b32_e32 v38, 16, v30
	v_and_b32_e32 v31, 0xffff0000, v31
	v_and_b32_e32 v30, 0xffff0000, v30
	v_rcp_f32_e32 v26, v28
	s_nop 0
	v_mul_f32_e32 v28, v24, v26
	v_div_scale_f32 v24, s[6:7], v37, v37, v27
	v_rcp_f32_e32 v26, v24
	v_pk_mul_f32 v[28:29], v[28:29], v[38:39]
	v_fma_f32 v38, -v24, v26, 1.0
	v_fmac_f32_e32 v26, v38, v26
	v_div_scale_f32 v38, vcc, v27, v37, v27
	v_mul_f32_e32 v39, v38, v26
	v_fma_f32 v40, -v24, v39, v38
	v_fmac_f32_e32 v39, v40, v26
	v_fma_f32 v24, -v24, v39, v38
	v_div_fmas_f32 v24, v24, v26, v39
	v_div_fixup_f32 v27, v24, v37, v27
	s_nop 0
	v_rcp_f32_e32 v24, v36
	s_nop 0
	v_mul_f32_e32 v26, v25, v24
	v_pk_mul_f32 v[24:25], v[26:27], v[30:31]
	v_and_b32_sdwa v26, v29, v154 dst_sel:DWORD dst_unused:UNUSED_PAD src0_sel:WORD_1 src1_sel:DWORD
	v_and_b32_sdwa v27, v28, v154 dst_sel:DWORD dst_unused:UNUSED_PAD src0_sel:WORD_1 src1_sel:DWORD
	v_add3_u32 v27, v28, v27, s33
	v_add3_u32 v26, v29, v26, s33
	v_and_b32_sdwa v28, v25, v154 dst_sel:DWORD dst_unused:UNUSED_PAD src0_sel:WORD_1 src1_sel:DWORD
	v_and_b32_sdwa v29, v24, v154 dst_sel:DWORD dst_unused:UNUSED_PAD src0_sel:WORD_1 src1_sel:DWORD
	v_add3_u32 v25, v25, v28, s33
	v_add3_u32 v24, v24, v29, s33
	v_and_b32_e32 v25, 0xffff0000, v25
	v_and_b32_e32 v24, 0xffff0000, v24
	v_or_b32_sdwa v25, v25, v26 dst_sel:DWORD dst_unused:UNUSED_PAD src0_sel:DWORD src1_sel:WORD_1
	v_or_b32_sdwa v24, v24, v27 dst_sel:DWORD dst_unused:UNUSED_PAD src0_sel:DWORD src1_sel:WORD_1
	global_store_dwordx2 v[32:33], v[24:25], off offset:32
	v_mul_f32_e32 v26, 0xbfb8aa3b, v23
	v_exp_f32_e32 v29, v26
	global_load_dwordx2 v[26:27], v[34:35], off offset:64
	v_mul_f32_e32 v25, 0xbfb8aa3b, v21
	v_mul_f32_e32 v24, 0xbfb8aa3b, v20
	v_exp_f32_e32 v28, v25
	v_mul_f32_e32 v25, 0xbfb8aa3b, v22
	v_exp_f32_e32 v24, v24
	v_exp_f32_e32 v25, v25
	v_pk_add_f32 v[28:29], v[28:29], 1.0 op_sel_hi:[1,0]
	v_pk_add_f32 v[24:25], v[24:25], 1.0 op_sel_hi:[1,0]
	s_nop 0
	s_waitcnt vmcnt(0)
	v_lshlrev_b32_e32 v31, 16, v27
	v_rcp_f32_e32 v36, v25
	s_nop 0
	v_mul_f32_e32 v25, v22, v36
	v_lshlrev_b32_e32 v30, 16, v26
	v_and_b32_e32 v27, 0xffff0000, v27
	v_and_b32_e32 v26, 0xffff0000, v26
	v_rcp_f32_e32 v22, v24
	s_nop 0
	v_mul_f32_e32 v24, v20, v22
	v_div_scale_f32 v20, s[6:7], v29, v29, v23
	v_rcp_f32_e32 v22, v20
	v_pk_mul_f32 v[24:25], v[24:25], v[30:31]
	v_fma_f32 v30, -v20, v22, 1.0
	v_fmac_f32_e32 v22, v30, v22
	v_div_scale_f32 v30, vcc, v23, v29, v23
	v_mul_f32_e32 v31, v30, v22
	v_fma_f32 v36, -v20, v31, v30
	v_fmac_f32_e32 v31, v36, v22
	v_fma_f32 v20, -v20, v31, v30
	v_div_fmas_f32 v20, v20, v22, v31
	v_div_fixup_f32 v23, v20, v29, v23
	s_nop 0
	v_rcp_f32_e32 v20, v28
	s_nop 0
	v_mul_f32_e32 v22, v21, v20
	v_pk_mul_f32 v[20:21], v[22:23], v[26:27]
	v_and_b32_sdwa v22, v25, v154 dst_sel:DWORD dst_unused:UNUSED_PAD src0_sel:WORD_1 src1_sel:DWORD
	v_and_b32_sdwa v23, v24, v154 dst_sel:DWORD dst_unused:UNUSED_PAD src0_sel:WORD_1 src1_sel:DWORD
	v_add3_u32 v23, v24, v23, s33
	v_add3_u32 v22, v25, v22, s33
	v_and_b32_sdwa v24, v21, v154 dst_sel:DWORD dst_unused:UNUSED_PAD src0_sel:WORD_1 src1_sel:DWORD
	v_and_b32_sdwa v25, v20, v154 dst_sel:DWORD dst_unused:UNUSED_PAD src0_sel:WORD_1 src1_sel:DWORD
	v_add3_u32 v21, v21, v24, s33
	v_add3_u32 v20, v20, v25, s33
	v_and_b32_e32 v21, 0xffff0000, v21
	v_and_b32_e32 v20, 0xffff0000, v20
	v_or_b32_sdwa v21, v21, v22 dst_sel:DWORD dst_unused:UNUSED_PAD src0_sel:DWORD src1_sel:WORD_1
	v_or_b32_sdwa v20, v20, v23 dst_sel:DWORD dst_unused:UNUSED_PAD src0_sel:DWORD src1_sel:WORD_1
	global_store_dwordx2 v[32:33], v[20:21], off offset:64
	v_mul_f32_e32 v22, 0xbfb8aa3b, v19
	v_exp_f32_e32 v25, v22
	global_load_dwordx2 v[22:23], v[34:35], off offset:96
	v_mul_f32_e32 v21, 0xbfb8aa3b, v17
	v_mul_f32_e32 v20, 0xbfb8aa3b, v16
	v_exp_f32_e32 v24, v21
	v_mul_f32_e32 v21, 0xbfb8aa3b, v18
	v_exp_f32_e32 v20, v20
	v_exp_f32_e32 v21, v21
	v_pk_add_f32 v[24:25], v[24:25], 1.0 op_sel_hi:[1,0]
	v_pk_add_f32 v[20:21], v[20:21], 1.0 op_sel_hi:[1,0]
	s_nop 0
	s_waitcnt vmcnt(0)
	v_lshlrev_b32_e32 v27, 16, v23
	v_rcp_f32_e32 v28, v21
	s_nop 0
	v_mul_f32_e32 v21, v18, v28
	v_lshlrev_b32_e32 v26, 16, v22
	v_and_b32_e32 v23, 0xffff0000, v23
	v_and_b32_e32 v22, 0xffff0000, v22
	v_rcp_f32_e32 v18, v20
	s_nop 0
	v_mul_f32_e32 v20, v16, v18
	v_div_scale_f32 v16, s[6:7], v25, v25, v19
	v_rcp_f32_e32 v18, v16
	v_pk_mul_f32 v[20:21], v[20:21], v[26:27]
	v_fma_f32 v26, -v16, v18, 1.0
	v_fmac_f32_e32 v18, v26, v18
	v_div_scale_f32 v26, vcc, v19, v25, v19
	v_mul_f32_e32 v27, v26, v18
	v_fma_f32 v28, -v16, v27, v26
	v_fmac_f32_e32 v27, v28, v18
	v_fma_f32 v16, -v16, v27, v26
	v_div_fmas_f32 v16, v16, v18, v27
	v_div_fixup_f32 v19, v16, v25, v19
	s_nop 0
	v_rcp_f32_e32 v16, v24
	s_nop 0
	v_mul_f32_e32 v18, v17, v16
	v_pk_mul_f32 v[16:17], v[18:19], v[22:23]
	v_and_b32_sdwa v18, v21, v154 dst_sel:DWORD dst_unused:UNUSED_PAD src0_sel:WORD_1 src1_sel:DWORD
	v_and_b32_sdwa v19, v20, v154 dst_sel:DWORD dst_unused:UNUSED_PAD src0_sel:WORD_1 src1_sel:DWORD
	v_add3_u32 v19, v20, v19, s33
	v_add3_u32 v18, v21, v18, s33
	v_and_b32_sdwa v20, v17, v154 dst_sel:DWORD dst_unused:UNUSED_PAD src0_sel:WORD_1 src1_sel:DWORD
	v_and_b32_sdwa v21, v16, v154 dst_sel:DWORD dst_unused:UNUSED_PAD src0_sel:WORD_1 src1_sel:DWORD
	v_add3_u32 v17, v17, v20, s33
	v_add3_u32 v16, v16, v21, s33
	v_and_b32_e32 v17, 0xffff0000, v17
	v_and_b32_e32 v16, 0xffff0000, v16
	v_or_b32_sdwa v17, v17, v18 dst_sel:DWORD dst_unused:UNUSED_PAD src0_sel:DWORD src1_sel:WORD_1
	v_or_b32_sdwa v16, v16, v19 dst_sel:DWORD dst_unused:UNUSED_PAD src0_sel:DWORD src1_sel:WORD_1
	global_store_dwordx2 v[32:33], v[16:17], off offset:96
	v_or_b32_e32 v16, 48, v80
	v_ashrrev_i32_e32 v17, 31, v16
	v_lshlrev_b64 v[18:19], 11, v[16:17]
	v_lshl_add_u64 v[18:19], v[76:77], 0, v[18:19]
	v_mul_f32_e32 v22, 0xbfb8aa3b, v15
	v_lshl_add_u64 v[18:19], v[18:19], 0, v[78:79]
	v_exp_f32_e32 v25, v22
	global_load_dwordx2 v[22:23], v[18:19], off
	v_mul_f32_e32 v21, 0xbfb8aa3b, v13
	v_mul_f32_e32 v20, 0xbfb8aa3b, v12
	v_exp_f32_e32 v24, v21
	v_mul_f32_e32 v21, 0xbfb8aa3b, v14
	v_exp_f32_e32 v20, v20
	v_exp_f32_e32 v21, v21
	v_pk_add_f32 v[24:25], v[24:25], 1.0 op_sel_hi:[1,0]
	v_mad_i64_i32 v[16:17], s[6:7], v16, s67, v[74:75]
	v_pk_add_f32 v[20:21], v[20:21], 1.0 op_sel_hi:[1,0]
	v_lshl_add_u64 v[16:17], v[16:17], 0, v[96:97]
	s_waitcnt vmcnt(0)
	v_lshlrev_b32_e32 v27, 16, v23
	v_rcp_f32_e32 v28, v21
	s_nop 0
	v_mul_f32_e32 v21, v14, v28
	v_lshlrev_b32_e32 v26, 16, v22
	v_and_b32_e32 v23, 0xffff0000, v23
	v_and_b32_e32 v22, 0xffff0000, v22
	v_rcp_f32_e32 v14, v20
	s_nop 0
	v_mul_f32_e32 v20, v12, v14
	v_div_scale_f32 v12, s[6:7], v25, v25, v15
	v_rcp_f32_e32 v14, v12
	v_pk_mul_f32 v[20:21], v[20:21], v[26:27]
	v_fma_f32 v26, -v12, v14, 1.0
	v_fmac_f32_e32 v14, v26, v14
	v_div_scale_f32 v26, vcc, v15, v25, v15
	v_mul_f32_e32 v27, v26, v14
	v_fma_f32 v28, -v12, v27, v26
	v_fmac_f32_e32 v27, v28, v14
	v_fma_f32 v12, -v12, v27, v26
	v_div_fmas_f32 v12, v12, v14, v27
	v_div_fixup_f32 v15, v12, v25, v15
	s_nop 0
	v_rcp_f32_e32 v12, v24
	s_nop 0
	v_mul_f32_e32 v14, v13, v12
	v_pk_mul_f32 v[12:13], v[14:15], v[22:23]
	v_and_b32_sdwa v14, v21, v154 dst_sel:DWORD dst_unused:UNUSED_PAD src0_sel:WORD_1 src1_sel:DWORD
	v_and_b32_sdwa v15, v20, v154 dst_sel:DWORD dst_unused:UNUSED_PAD src0_sel:WORD_1 src1_sel:DWORD
	v_add3_u32 v15, v20, v15, s33
	v_add3_u32 v14, v21, v14, s33
	v_and_b32_sdwa v20, v13, v154 dst_sel:DWORD dst_unused:UNUSED_PAD src0_sel:WORD_1 src1_sel:DWORD
	v_and_b32_sdwa v21, v12, v154 dst_sel:DWORD dst_unused:UNUSED_PAD src0_sel:WORD_1 src1_sel:DWORD
	v_add3_u32 v13, v13, v20, s33
	v_add3_u32 v12, v12, v21, s33
	v_and_b32_e32 v13, 0xffff0000, v13
	v_and_b32_e32 v12, 0xffff0000, v12
	v_or_b32_sdwa v13, v13, v14 dst_sel:DWORD dst_unused:UNUSED_PAD src0_sel:DWORD src1_sel:WORD_1
	v_or_b32_sdwa v12, v12, v15 dst_sel:DWORD dst_unused:UNUSED_PAD src0_sel:DWORD src1_sel:WORD_1
	global_store_dwordx2 v[16:17], v[12:13], off
	v_mul_f32_e32 v14, 0xbfb8aa3b, v11
	v_exp_f32_e32 v21, v14
	global_load_dwordx2 v[14:15], v[18:19], off offset:32
	v_mul_f32_e32 v13, 0xbfb8aa3b, v9
	v_mul_f32_e32 v12, 0xbfb8aa3b, v8
	v_exp_f32_e32 v20, v13
	v_mul_f32_e32 v13, 0xbfb8aa3b, v10
	v_exp_f32_e32 v12, v12
	v_exp_f32_e32 v13, v13
	v_pk_add_f32 v[20:21], v[20:21], 1.0 op_sel_hi:[1,0]
	v_pk_add_f32 v[12:13], v[12:13], 1.0 op_sel_hi:[1,0]
	s_nop 0
	s_waitcnt vmcnt(0)
	v_lshlrev_b32_e32 v23, 16, v15
	v_rcp_f32_e32 v24, v13
	s_nop 0
	v_mul_f32_e32 v13, v10, v24
	v_lshlrev_b32_e32 v22, 16, v14
	v_and_b32_e32 v15, 0xffff0000, v15
	v_and_b32_e32 v14, 0xffff0000, v14
	v_rcp_f32_e32 v10, v12
	s_nop 0
	v_mul_f32_e32 v12, v8, v10
	v_div_scale_f32 v8, s[6:7], v21, v21, v11
	v_rcp_f32_e32 v10, v8
	v_pk_mul_f32 v[12:13], v[12:13], v[22:23]
	v_fma_f32 v22, -v8, v10, 1.0
	v_fmac_f32_e32 v10, v22, v10
	v_div_scale_f32 v22, vcc, v11, v21, v11
	v_mul_f32_e32 v23, v22, v10
	v_fma_f32 v24, -v8, v23, v22
	v_fmac_f32_e32 v23, v24, v10
	v_fma_f32 v8, -v8, v23, v22
	v_div_fmas_f32 v8, v8, v10, v23
	v_div_fixup_f32 v11, v8, v21, v11
	s_nop 0
	v_rcp_f32_e32 v8, v20
	s_nop 0
	v_mul_f32_e32 v10, v9, v8
	v_pk_mul_f32 v[8:9], v[10:11], v[14:15]
	v_and_b32_sdwa v10, v13, v154 dst_sel:DWORD dst_unused:UNUSED_PAD src0_sel:WORD_1 src1_sel:DWORD
	v_and_b32_sdwa v11, v12, v154 dst_sel:DWORD dst_unused:UNUSED_PAD src0_sel:WORD_1 src1_sel:DWORD
	v_add3_u32 v11, v12, v11, s33
	v_add3_u32 v10, v13, v10, s33
	v_and_b32_sdwa v12, v9, v154 dst_sel:DWORD dst_unused:UNUSED_PAD src0_sel:WORD_1 src1_sel:DWORD
	v_and_b32_sdwa v13, v8, v154 dst_sel:DWORD dst_unused:UNUSED_PAD src0_sel:WORD_1 src1_sel:DWORD
	v_add3_u32 v9, v9, v12, s33
	v_add3_u32 v8, v8, v13, s33
	v_and_b32_e32 v9, 0xffff0000, v9
	v_and_b32_e32 v8, 0xffff0000, v8
	v_or_b32_sdwa v9, v9, v10 dst_sel:DWORD dst_unused:UNUSED_PAD src0_sel:DWORD src1_sel:WORD_1
	v_or_b32_sdwa v8, v8, v11 dst_sel:DWORD dst_unused:UNUSED_PAD src0_sel:DWORD src1_sel:WORD_1
	global_store_dwordx2 v[16:17], v[8:9], off offset:32
	v_mul_f32_e32 v10, 0xbfb8aa3b, v7
	v_exp_f32_e32 v13, v10
	global_load_dwordx2 v[10:11], v[18:19], off offset:64
	v_mul_f32_e32 v9, 0xbfb8aa3b, v5
	v_mul_f32_e32 v8, 0xbfb8aa3b, v4
	v_exp_f32_e32 v12, v9
	v_mul_f32_e32 v9, 0xbfb8aa3b, v6
	v_exp_f32_e32 v8, v8
	v_exp_f32_e32 v9, v9
	v_pk_add_f32 v[12:13], v[12:13], 1.0 op_sel_hi:[1,0]
	v_pk_add_f32 v[8:9], v[8:9], 1.0 op_sel_hi:[1,0]
	s_nop 0
	s_waitcnt vmcnt(0)
	v_lshlrev_b32_e32 v15, 16, v11
	v_rcp_f32_e32 v20, v9
	s_nop 0
	v_mul_f32_e32 v9, v6, v20
	v_lshlrev_b32_e32 v14, 16, v10
	v_and_b32_e32 v11, 0xffff0000, v11
	v_and_b32_e32 v10, 0xffff0000, v10
	v_rcp_f32_e32 v6, v8
	s_nop 0
	v_mul_f32_e32 v8, v4, v6
	v_div_scale_f32 v4, s[6:7], v13, v13, v7
	v_rcp_f32_e32 v6, v4
	v_pk_mul_f32 v[8:9], v[8:9], v[14:15]
	v_fma_f32 v14, -v4, v6, 1.0
	v_fmac_f32_e32 v6, v14, v6
	v_div_scale_f32 v14, vcc, v7, v13, v7
	v_mul_f32_e32 v15, v14, v6
	v_fma_f32 v20, -v4, v15, v14
	v_fmac_f32_e32 v15, v20, v6
	v_fma_f32 v4, -v4, v15, v14
	v_div_fmas_f32 v4, v4, v6, v15
	v_div_fixup_f32 v7, v4, v13, v7
	s_nop 0
	v_rcp_f32_e32 v4, v12
	s_nop 0
	v_mul_f32_e32 v6, v5, v4
	v_pk_mul_f32 v[4:5], v[6:7], v[10:11]
	v_and_b32_sdwa v6, v9, v154 dst_sel:DWORD dst_unused:UNUSED_PAD src0_sel:WORD_1 src1_sel:DWORD
	v_and_b32_sdwa v7, v8, v154 dst_sel:DWORD dst_unused:UNUSED_PAD src0_sel:WORD_1 src1_sel:DWORD
	v_add3_u32 v7, v8, v7, s33
	v_add3_u32 v6, v9, v6, s33
	v_and_b32_sdwa v8, v5, v154 dst_sel:DWORD dst_unused:UNUSED_PAD src0_sel:WORD_1 src1_sel:DWORD
	v_and_b32_sdwa v9, v4, v154 dst_sel:DWORD dst_unused:UNUSED_PAD src0_sel:WORD_1 src1_sel:DWORD
	v_add3_u32 v5, v5, v8, s33
	v_add3_u32 v4, v4, v9, s33
	v_and_b32_e32 v5, 0xffff0000, v5
	v_and_b32_e32 v4, 0xffff0000, v4
	v_or_b32_sdwa v5, v5, v6 dst_sel:DWORD dst_unused:UNUSED_PAD src0_sel:DWORD src1_sel:WORD_1
	v_or_b32_sdwa v4, v4, v7 dst_sel:DWORD dst_unused:UNUSED_PAD src0_sel:DWORD src1_sel:WORD_1
	global_store_dwordx2 v[16:17], v[4:5], off offset:64
	global_load_dwordx2 v[4:5], v[18:19], off offset:96
	v_mul_f32_e32 v7, 0xbfb8aa3b, v0
	v_exp_f32_e32 v7, v7
	s_waitcnt vmcnt(0)
	v_lshlrev_b32_e32 v6, 16, v4
	v_add_f32_e32 v7, 1.0, v7
	v_and_b32_e32 v4, 0xffff0000, v4
	v_rcp_f32_e32 v8, v7
	s_nop 0
	v_mul_f32_e32 v0, v0, v8
	v_mul_f32_e32 v0, v0, v6
	v_mul_f32_e32 v6, 0xbfb8aa3b, v1
	v_exp_f32_e32 v6, v6
	s_nop 0
	v_add_f32_e32 v6, 1.0, v6
	s_nop 0
	v_rcp_f32_e32 v7, v6
	s_nop 0
	v_mul_f32_e32 v1, v1, v7
	v_mul_f32_e32 v1, v1, v4
	v_mul_f32_e32 v4, 0xbfb8aa3b, v2
	v_exp_f32_e32 v6, v4
	v_mul_f32_e32 v4, 0xbfb8aa3b, v3
	v_exp_f32_e32 v7, v4
	v_bfe_u32 v4, v0, 16, 1
	v_add3_u32 v0, v0, v4, s33
	v_lshrrev_b32_e32 v8, 16, v0
	v_bfe_u32 v0, v1, 16, 1
	v_add3_u32 v9, v1, v0, s33
	v_and_b32_e32 v1, 0xffff0000, v5
	v_lshlrev_b32_e32 v0, 16, v5
	v_pk_add_f32 v[4:5], v[6:7], 1.0 op_sel_hi:[1,0]
	s_nop 0
	s_nop 0
	v_rcp_f32_e32 v6, v5
	s_nop 0
	v_mul_f32_e32 v3, v3, v6
	s_mov_b32 s6, 0xffff0000
	v_rcp_f32_e32 v5, v4
	s_nop 0
	v_mul_f32_e32 v2, v2, v5
	v_pk_mul_f32 v[0:1], v[2:3], v[0:1]
	s_nop 0
	v_and_b32_sdwa v3, v0, v154 dst_sel:DWORD dst_unused:UNUSED_PAD src0_sel:WORD_1 src1_sel:DWORD
	v_and_b32_sdwa v2, v1, v154 dst_sel:DWORD dst_unused:UNUSED_PAD src0_sel:WORD_1 src1_sel:DWORD
	v_add3_u32 v0, v0, v3, s33
	v_add3_u32 v1, v1, v2, s33
	v_lshrrev_b32_e32 v0, 16, v0
	v_and_or_b32 v2, v9, s6, v8
	v_and_or_b32 v81, v1, s6, v0
	s_mov_b64 s[6:7], 0x60
	v_lshl_add_u64 v[76:77], v[16:17], 0, s[6:7]
	global_store_dword v[16:17], v2, off offset:96
	s_branch .LBB0_159

.LBB0_381:
	s_cmpk_gt_i32 s67, 0x41f
	s_mov_b64 s[0:1], -1
	s_cbranch_scc0 .LBB0_391
	s_cmpk_gt_u32 s67, 0x82f
	v_add_u32_e32 v188, v123, v121
	v_add_u32_e32 v189, v123, v122
	v_add_u32_e32 v89, v124, v121
	v_add_u32_e32 v85, v124, v122
	v_lshlrev_b32_e32 v90, 1, v70
	v_add_u32_e32 v196, 0x4000, v126
	v_add_u32_e32 v195, 0x1000, v126
	v_add_u32_e32 v194, 0x5000, v126
	v_add_u32_e32 v193, 0x2000, v126
	v_add_u32_e32 v192, 0x6000, v126
	v_add_u32_e32 v191, 0x3000, v126
	v_add_u32_e32 v190, 0x7000, v126
	s_cbranch_scc0 .LBB0_388
	s_add_i32 s0, s67, 0xfffff7d0
	s_lshr_b32 s2, s0, 4
	s_bfe_u32 s9, s67, 0x30001
	s_and_b32 s6, s67, 1
	s_lshl_b64 s[0:1], s[2:3], 15
	v_readlane_b32 s4, v254, 45
	s_add_u32 s0, s4, s0
	v_readlane_b32 s4, v254, 47
	s_addc_u32 s1, s4, s1
	s_lshl_b32 s7, s6, 7
	s_add_u32 s0, s0, s7
	v_readlane_b32 s4, v254, 41
	s_addc_u32 s1, s1, 0
	s_or_b32 s6, s6, s4
	s_ashr_i32 s7, s6, 31
	s_lshl_b64 s[6:7], s[6:7], 17
	v_readlane_b32 s4, v254, 49
	s_add_u32 s6, s4, s6
	v_readlane_b32 s4, v254, 51
	s_addc_u32 s7, s4, s7
	s_lshl_b32 s46, s9, 14
	s_add_u32 s6, s6, s46
	s_addc_u32 s7, s7, 0
	v_lshl_add_u64 v[0:1], s[0:1], 0, v[72:73]
	v_mov_b32_e32 v91, v97
	v_readfirstlane_b32 s0, v126
	v_lshl_add_u64 v[0:1], v[0:1], 0, v[90:91]
	v_lshl_add_u64 v[2:3], s[6:7], 0, v[76:77]
	s_mov_b32 m0, s0
	v_readfirstlane_b32 s0, v196
	s_waitcnt vmcnt(63) expcnt(7) lgkmcnt(15)
	s_barrier
	v_lshl_add_u64 v[2:3], v[2:3], 0, v[90:91]
	global_load_lds_dwordx4 v[0:1], off
	s_mov_b32 m0, s0
	s_mov_b64 s[6:7], 0x2000
	v_readfirstlane_b32 s0, v195
	global_load_lds_dwordx4 v[2:3], off
	v_lshl_add_u64 v[4:5], v[0:1], 0, s[6:7]
	s_mov_b32 m0, s0
	s_mov_b64 s[0:1], 0x1000
	global_load_lds_dwordx4 v[4:5], off
	v_lshl_add_u64 v[4:5], v[2:3], 0, s[0:1]
	v_readfirstlane_b32 s0, v194
	s_mov_b32 m0, s0
	s_mov_b64 s[0:1], 0x4000
	global_load_lds_dwordx4 v[4:5], off
	v_lshl_add_u64 v[4:5], v[0:1], 0, s[0:1]
	v_readfirstlane_b32 s0, v193
	s_mov_b32 m0, s0
	v_readfirstlane_b32 s0, v192
	global_load_lds_dwordx4 v[4:5], off
	s_mov_b32 m0, s0
	s_mov_b64 s[0:1], 0x6000
	v_lshl_add_u64 v[4:5], v[2:3], 0, s[6:7]
	v_lshl_add_u64 v[0:1], v[0:1], 0, s[0:1]
	v_readfirstlane_b32 s0, v191
	global_load_lds_dwordx4 v[4:5], off
	s_mov_b32 m0, s0
	s_mov_b64 s[0:1], 0x3000
	global_load_lds_dwordx4 v[0:1], off
	v_lshl_add_u64 v[0:1], v[2:3], 0, s[0:1]
	v_readfirstlane_b32 s0, v190
	s_mov_b32 m0, s0
	s_nop 0
	global_load_lds_dwordx4 v[0:1], off
	s_waitcnt vmcnt(0)
	s_waitcnt vmcnt(0) lgkmcnt(0)
	s_barrier
	ds_read_b128 v[0:3], v188
	ds_read_b128 v[4:7], v188 offset:2048
	ds_read_b128 v[8:11], v188 offset:4096
	ds_read_b128 v[12:15], v188 offset:6144
	ds_read_b128 v[16:19], v189 offset:16384
	ds_read_b128 v[20:23], v189 offset:18432
	ds_read_b128 v[24:27], v189 offset:20480
	ds_read_b128 v[28:31], v189 offset:22528
	s_setprio 1
	s_waitcnt lgkmcnt(3)
	v_mfma_f32_16x16x32_bf16 v[32:35], v[16:19], v[0:3], 0
	s_waitcnt lgkmcnt(2)
	v_mfma_f32_16x16x32_bf16 v[36:39], v[20:23], v[0:3], 0
	s_waitcnt lgkmcnt(1)
	v_mfma_f32_16x16x32_bf16 v[40:43], v[24:27], v[0:3], 0
	s_waitcnt lgkmcnt(0)
	v_mfma_f32_16x16x32_bf16 v[0:3], v[28:31], v[0:3], 0
	v_mfma_f32_16x16x32_bf16 v[44:47], v[16:19], v[4:7], 0
	v_mfma_f32_16x16x32_bf16 v[64:67], v[20:23], v[4:7], 0
	v_mfma_f32_16x16x32_bf16 v[92:95], v[24:27], v[4:7], 0
	v_mfma_f32_16x16x32_bf16 v[4:7], v[28:31], v[4:7], 0
	v_mfma_f32_16x16x32_bf16 v[100:103], v[16:19], v[8:11], 0
	v_mfma_f32_16x16x32_bf16 v[104:107], v[20:23], v[8:11], 0
	v_mfma_f32_16x16x32_bf16 v[108:111], v[24:27], v[8:11], 0
	v_mfma_f32_16x16x32_bf16 v[8:11], v[28:31], v[8:11], 0
	v_mfma_f32_16x16x32_bf16 v[112:115], v[16:19], v[12:15], 0
	v_mfma_f32_16x16x32_bf16 v[156:159], v[20:23], v[12:15], 0
	v_mfma_f32_16x16x32_bf16 v[166:169], v[24:27], v[12:15], 0
	v_mfma_f32_16x16x32_bf16 v[198:201], v[28:31], v[12:15], 0
	s_setprio 0
	ds_read_b128 v[12:15], v89
	ds_read_b128 v[16:19], v89 offset:2048
	ds_read_b128 v[206:209], v89 offset:4096
	ds_read_b128 v[210:213], v89 offset:6144
	ds_read_b128 v[214:217], v85 offset:16384
	ds_read_b128 v[218:221], v85 offset:18432
	ds_read_b128 v[222:225], v85 offset:20480
	ds_read_b128 v[226:229], v85 offset:22528
	s_setprio 1
	s_waitcnt lgkmcnt(3)
	v_mfma_f32_16x16x32_bf16 v[60:63], v[214:217], v[12:15], v[32:35]
	s_waitcnt lgkmcnt(2)
	v_mfma_f32_16x16x32_bf16 v[56:59], v[218:221], v[12:15], v[36:39]
	s_waitcnt lgkmcnt(1)
	v_mfma_f32_16x16x32_bf16 v[52:55], v[222:225], v[12:15], v[40:43]
	s_waitcnt lgkmcnt(0)
	v_mfma_f32_16x16x32_bf16 v[48:51], v[226:229], v[12:15], v[0:3]
	v_mfma_f32_16x16x32_bf16 v[44:47], v[214:217], v[16:19], v[44:47]
	v_mfma_f32_16x16x32_bf16 v[40:43], v[218:221], v[16:19], v[64:67]
	v_mfma_f32_16x16x32_bf16 v[36:39], v[222:225], v[16:19], v[92:95]
	v_mfma_f32_16x16x32_bf16 v[32:35], v[226:229], v[16:19], v[4:7]
	v_mfma_f32_16x16x32_bf16 v[28:31], v[214:217], v[206:209], v[100:103]
	v_mfma_f32_16x16x32_bf16 v[24:27], v[218:221], v[206:209], v[104:107]
	v_mfma_f32_16x16x32_bf16 v[20:23], v[222:225], v[206:209], v[108:111]
	v_mfma_f32_16x16x32_bf16 v[16:19], v[226:229], v[206:209], v[8:11]
	v_mfma_f32_16x16x32_bf16 v[12:15], v[214:217], v[210:213], v[112:115]
	v_mfma_f32_16x16x32_bf16 v[8:11], v[218:221], v[210:213], v[156:159]
	v_mfma_f32_16x16x32_bf16 v[4:7], v[222:225], v[210:213], v[166:169]
	v_mfma_f32_16x16x32_bf16 v[0:3], v[226:229], v[210:213], v[198:201]
	s_setprio 0
	s_waitcnt vmcnt(0)
	s_bitcmp1_b32 s67, 0
	s_cselect_b64 s[46:47], -1, 0
	s_lshl_b32 s6, s2, 7
	s_lshl_b32 s2, s9, 7
	s_mov_b64 s[0:1], -1
	s_and_b64 vcc, exec, s[46:47]
	s_barrier
	s_cbranch_vccz .LBB0_385
	v_mov_b32_e32 v64, v97
	s_nop 0
	v_add_u32_e32 v64, v64, v176
	v_ashrrev_i32_e32 v66, 1, v64
	v_lshrrev_b32_e32 v67, 2, v64
	v_and_b32_e32 v65, 64, v64
	v_and_b32_e32 v66, 0xffffffc0, v66
	v_and_b32_e32 v67, 12, v67
	v_and_or_b32 v64, v64, 15, s6
	v_add_u32_e32 v66, v64, v66
	v_or3_b32 v91, v65, v67, s2
	v_ashrrev_i32_e32 v67, 31, v66
	v_lshlrev_b64 v[64:65], 11, v[66:67]
	v_lshlrev_b32_e32 v67, 2, v91
	global_load_dwordx4 v[92:95], v67, s[90:91]
	v_readlane_b32 s4, v254, 53
	v_readlane_b32 s5, v254, 54
	s_nop 1
	v_lshl_add_u64 v[100:101], s[4:5], 0, v[64:65]
	v_mov_b32_e32 v65, v97
	s_waitcnt vmcnt(0)
	v_add_f32_e32 v64, v60, v92
	v_mul_f32_e32 v64, 0xbfb8aa3b, v64
	v_exp_f32_e32 v102, v64
	v_add_f32_e32 v64, v61, v93
	v_mul_f32_e32 v64, 0xbfb8aa3b, v64
	v_exp_f32_e32 v104, v64
	v_add_f32_e32 v64, v62, v94
	v_mul_f32_e32 v64, 0xbfb8aa3b, v64
	v_exp_f32_e32 v103, v64
	v_add_f32_e32 v64, v63, v95
	v_mul_f32_e32 v64, 0xbfb8aa3b, v64
	v_exp_f32_e32 v105, v64
	v_pk_add_f32 v[94:95], v[102:103], 1.0 op_sel_hi:[1,0]
	v_lshlrev_b32_e32 v64, 1, v91
	v_div_scale_f32 v91, s[0:1], v94, v94, 1.0
	v_lshl_add_u64 v[92:93], v[100:101], 0, v[64:65]
	v_rcp_f32_e32 v100, v91
	s_nop 0
	v_fma_f32 v101, -v91, v100, 1.0
	v_fmac_f32_e32 v100, v101, v100
	v_div_scale_f32 v101, vcc, 1.0, v94, 1.0
	v_mul_f32_e32 v102, v101, v100
	v_fma_f32 v103, -v91, v102, v101
	v_fmac_f32_e32 v102, v103, v100
	v_fma_f32 v91, -v91, v102, v101
	v_div_fmas_f32 v91, v91, v100, v102
	v_div_fixup_f32 v91, v91, v94, 1.0
	s_nop 0
	v_rcp_f32_e32 v100, v95
	v_pk_add_f32 v[94:95], v[104:105], 1.0 op_sel_hi:[1,0]
	s_nop 0
	s_nop 0
	v_rcp_f32_e32 v94, v94
	s_nop 0
	v_rcp_f32_e32 v95, v95
	v_and_b32_sdwa v101, v100, v154 dst_sel:DWORD dst_unused:UNUSED_PAD src0_sel:WORD_1 src1_sel:DWORD
	v_and_b32_sdwa v102, v91, v154 dst_sel:DWORD dst_unused:UNUSED_PAD src0_sel:WORD_1 src1_sel:DWORD
	v_add3_u32 v91, v91, v102, s33
	v_add3_u32 v100, v100, v101, s33
	v_and_b32_sdwa v101, v95, v154 dst_sel:DWORD dst_unused:UNUSED_PAD src0_sel:WORD_1 src1_sel:DWORD
	v_and_b32_sdwa v102, v94, v154 dst_sel:DWORD dst_unused:UNUSED_PAD src0_sel:WORD_1 src1_sel:DWORD
	v_add3_u32 v95, v95, v101, s33
	v_add3_u32 v94, v94, v102, s33
	v_and_b32_e32 v95, 0xffff0000, v95
	v_and_b32_e32 v94, 0xffff0000, v94
	v_or_b32_sdwa v95, v95, v100 dst_sel:DWORD dst_unused:UNUSED_PAD src0_sel:DWORD src1_sel:WORD_1
	v_or_b32_sdwa v94, v94, v91 dst_sel:DWORD dst_unused:UNUSED_PAD src0_sel:DWORD src1_sel:WORD_1
	global_store_dwordx2 v[92:93], v[94:95], off
	global_load_dwordx4 v[100:103], v67, s[90:91] offset:64
	s_waitcnt vmcnt(0)
	v_add_f32_e32 v91, v56, v100
	v_mul_f32_e32 v91, 0xbfb8aa3b, v91
	v_exp_f32_e32 v94, v91
	v_add_f32_e32 v91, v57, v101
	v_mul_f32_e32 v91, 0xbfb8aa3b, v91
	v_exp_f32_e32 v100, v91
	v_add_f32_e32 v91, v58, v102
	v_mul_f32_e32 v91, 0xbfb8aa3b, v91
	v_exp_f32_e32 v95, v91
	v_add_f32_e32 v91, v59, v103
	v_mul_f32_e32 v91, 0xbfb8aa3b, v91
	v_exp_f32_e32 v101, v91
	v_pk_add_f32 v[94:95], v[94:95], 1.0 op_sel_hi:[1,0]
	s_nop 0
	s_nop 0
	v_rcp_f32_e32 v91, v94
	s_nop 0
	v_rcp_f32_e32 v102, v95
	v_pk_add_f32 v[94:95], v[100:101], 1.0 op_sel_hi:[1,0]
	s_nop 0
	s_nop 0
	v_rcp_f32_e32 v94, v94
	s_nop 0
	v_rcp_f32_e32 v95, v95
	v_and_b32_sdwa v100, v102, v154 dst_sel:DWORD dst_unused:UNUSED_PAD src0_sel:WORD_1 src1_sel:DWORD
	v_and_b32_sdwa v101, v91, v154 dst_sel:DWORD dst_unused:UNUSED_PAD src0_sel:WORD_1 src1_sel:DWORD
	v_add3_u32 v91, v91, v101, s33
	v_add3_u32 v100, v102, v100, s33
	v_and_b32_sdwa v101, v95, v154 dst_sel:DWORD dst_unused:UNUSED_PAD src0_sel:WORD_1 src1_sel:DWORD
	v_and_b32_sdwa v102, v94, v154 dst_sel:DWORD dst_unused:UNUSED_PAD src0_sel:WORD_1 src1_sel:DWORD
	v_add3_u32 v95, v95, v101, s33
	v_add3_u32 v94, v94, v102, s33
	v_and_b32_e32 v95, 0xffff0000, v95
	v_and_b32_e32 v94, 0xffff0000, v94
	v_or_b32_sdwa v95, v95, v100 dst_sel:DWORD dst_unused:UNUSED_PAD src0_sel:DWORD src1_sel:WORD_1
	v_or_b32_sdwa v94, v94, v91 dst_sel:DWORD dst_unused:UNUSED_PAD src0_sel:DWORD src1_sel:WORD_1
	global_store_dwordx2 v[92:93], v[94:95], off offset:32
	global_load_dwordx4 v[100:103], v67, s[90:91] offset:128
	s_waitcnt vmcnt(0)
	v_add_f32_e32 v91, v52, v100
	v_mul_f32_e32 v91, 0xbfb8aa3b, v91
	v_exp_f32_e32 v94, v91
	v_add_f32_e32 v91, v53, v101
	v_mul_f32_e32 v91, 0xbfb8aa3b, v91
	v_exp_f32_e32 v100, v91
	v_add_f32_e32 v91, v54, v102
	v_mul_f32_e32 v91, 0xbfb8aa3b, v91
	v_exp_f32_e32 v95, v91
	v_add_f32_e32 v91, v55, v103
	v_mul_f32_e32 v91, 0xbfb8aa3b, v91
	v_exp_f32_e32 v101, v91
	v_pk_add_f32 v[94:95], v[94:95], 1.0 op_sel_hi:[1,0]
	s_nop 0
	s_nop 0
	v_rcp_f32_e32 v91, v94
	s_nop 0
	v_rcp_f32_e32 v102, v95
	v_pk_add_f32 v[94:95], v[100:101], 1.0 op_sel_hi:[1,0]
	s_nop 0
	s_nop 0
	v_rcp_f32_e32 v94, v94
	s_nop 0
	v_rcp_f32_e32 v95, v95
	v_and_b32_sdwa v100, v102, v154 dst_sel:DWORD dst_unused:UNUSED_PAD src0_sel:WORD_1 src1_sel:DWORD
	v_and_b32_sdwa v101, v91, v154 dst_sel:DWORD dst_unused:UNUSED_PAD src0_sel:WORD_1 src1_sel:DWORD
	v_add3_u32 v91, v91, v101, s33
	v_add3_u32 v100, v102, v100, s33
	v_and_b32_sdwa v101, v95, v154 dst_sel:DWORD dst_unused:UNUSED_PAD src0_sel:WORD_1 src1_sel:DWORD
	v_and_b32_sdwa v102, v94, v154 dst_sel:DWORD dst_unused:UNUSED_PAD src0_sel:WORD_1 src1_sel:DWORD
	v_add3_u32 v95, v95, v101, s33
	v_add3_u32 v94, v94, v102, s33
	v_and_b32_e32 v95, 0xffff0000, v95
	v_and_b32_e32 v94, 0xffff0000, v94
	v_or_b32_sdwa v95, v95, v100 dst_sel:DWORD dst_unused:UNUSED_PAD src0_sel:DWORD src1_sel:WORD_1
	v_or_b32_sdwa v94, v94, v91 dst_sel:DWORD dst_unused:UNUSED_PAD src0_sel:DWORD src1_sel:WORD_1
	global_store_dwordx2 v[92:93], v[94:95], off offset:64
	global_load_dwordx4 v[100:103], v67, s[90:91] offset:192
	s_waitcnt vmcnt(0)
	v_add_f32_e32 v91, v48, v100
	v_mul_f32_e32 v91, 0xbfb8aa3b, v91
	v_exp_f32_e32 v94, v91
	v_add_f32_e32 v91, v49, v101
	v_mul_f32_e32 v91, 0xbfb8aa3b, v91
	v_exp_f32_e32 v100, v91
	v_add_f32_e32 v91, v50, v102
	v_mul_f32_e32 v91, 0xbfb8aa3b, v91
	v_exp_f32_e32 v95, v91
	v_add_f32_e32 v91, v51, v103
	v_mul_f32_e32 v91, 0xbfb8aa3b, v91
	v_exp_f32_e32 v101, v91
	v_pk_add_f32 v[94:95], v[94:95], 1.0 op_sel_hi:[1,0]
	s_nop 0
	s_nop 0
	v_rcp_f32_e32 v91, v94
	s_nop 0
	v_rcp_f32_e32 v102, v95
	v_pk_add_f32 v[94:95], v[100:101], 1.0 op_sel_hi:[1,0]
	s_nop 0
	s_nop 0
	v_rcp_f32_e32 v94, v94
	s_nop 0
	v_rcp_f32_e32 v95, v95
	v_and_b32_sdwa v100, v102, v154 dst_sel:DWORD dst_unused:UNUSED_PAD src0_sel:WORD_1 src1_sel:DWORD
	v_and_b32_sdwa v101, v91, v154 dst_sel:DWORD dst_unused:UNUSED_PAD src0_sel:WORD_1 src1_sel:DWORD
	v_add3_u32 v91, v91, v101, s33
	v_add3_u32 v100, v102, v100, s33
	v_and_b32_sdwa v101, v95, v154 dst_sel:DWORD dst_unused:UNUSED_PAD src0_sel:WORD_1 src1_sel:DWORD
	v_and_b32_sdwa v102, v94, v154 dst_sel:DWORD dst_unused:UNUSED_PAD src0_sel:WORD_1 src1_sel:DWORD
	v_add3_u32 v95, v95, v101, s33
	v_add3_u32 v94, v94, v102, s33
	v_and_b32_e32 v95, 0xffff0000, v95
	v_and_b32_e32 v94, 0xffff0000, v94
	v_or_b32_sdwa v95, v95, v100 dst_sel:DWORD dst_unused:UNUSED_PAD src0_sel:DWORD src1_sel:WORD_1
	v_or_b32_sdwa v94, v94, v91 dst_sel:DWORD dst_unused:UNUSED_PAD src0_sel:DWORD src1_sel:WORD_1
	global_store_dwordx2 v[92:93], v[94:95], off offset:96
	v_or_b32_e32 v92, 16, v66
	v_ashrrev_i32_e32 v93, 31, v92
	v_lshlrev_b64 v[92:93], 11, v[92:93]
	v_lshl_add_u64 v[100:101], s[4:5], 0, v[92:93]
	global_load_dwordx4 v[92:95], v67, s[90:91]
	s_waitcnt vmcnt(0)
	v_add_f32_e32 v91, v44, v92
	v_mul_f32_e32 v91, 0xbfb8aa3b, v91
	v_exp_f32_e32 v102, v91
	v_add_f32_e32 v91, v45, v93
	v_mul_f32_e32 v91, 0xbfb8aa3b, v91
	v_exp_f32_e32 v104, v91
	v_add_f32_e32 v91, v46, v94
	v_mul_f32_e32 v91, 0xbfb8aa3b, v91
	v_exp_f32_e32 v103, v91
	v_add_f32_e32 v91, v47, v95
	v_mul_f32_e32 v91, 0xbfb8aa3b, v91
	v_exp_f32_e32 v105, v91
	v_pk_add_f32 v[94:95], v[102:103], 1.0 op_sel_hi:[1,0]
	v_lshl_add_u64 v[92:93], v[100:101], 0, v[64:65]
	s_nop 0
	v_rcp_f32_e32 v91, v94
	s_nop 0
	v_rcp_f32_e32 v100, v95
	v_pk_add_f32 v[94:95], v[104:105], 1.0 op_sel_hi:[1,0]
	s_nop 0
	s_nop 0
	v_rcp_f32_e32 v94, v94
	s_nop 0
	v_rcp_f32_e32 v95, v95
	v_and_b32_sdwa v101, v100, v154 dst_sel:DWORD dst_unused:UNUSED_PAD src0_sel:WORD_1 src1_sel:DWORD
	v_and_b32_sdwa v102, v91, v154 dst_sel:DWORD dst_unused:UNUSED_PAD src0_sel:WORD_1 src1_sel:DWORD
	v_add3_u32 v91, v91, v102, s33
	v_add3_u32 v100, v100, v101, s33
	v_and_b32_sdwa v101, v95, v154 dst_sel:DWORD dst_unused:UNUSED_PAD src0_sel:WORD_1 src1_sel:DWORD
	v_and_b32_sdwa v102, v94, v154 dst_sel:DWORD dst_unused:UNUSED_PAD src0_sel:WORD_1 src1_sel:DWORD
	v_add3_u32 v95, v95, v101, s33
	v_add3_u32 v94, v94, v102, s33
	v_and_b32_e32 v95, 0xffff0000, v95
	v_and_b32_e32 v94, 0xffff0000, v94
	v_or_b32_sdwa v95, v95, v100 dst_sel:DWORD dst_unused:UNUSED_PAD src0_sel:DWORD src1_sel:WORD_1
	v_or_b32_sdwa v94, v94, v91 dst_sel:DWORD dst_unused:UNUSED_PAD src0_sel:DWORD src1_sel:WORD_1
	global_store_dwordx2 v[92:93], v[94:95], off
	global_load_dwordx4 v[100:103], v67, s[90:91] offset:64
	s_waitcnt vmcnt(0)
	v_add_f32_e32 v91, v40, v100
	v_mul_f32_e32 v91, 0xbfb8aa3b, v91
	v_exp_f32_e32 v94, v91
	v_add_f32_e32 v91, v41, v101
	v_mul_f32_e32 v91, 0xbfb8aa3b, v91
	v_exp_f32_e32 v100, v91
	v_add_f32_e32 v91, v42, v102
	v_mul_f32_e32 v91, 0xbfb8aa3b, v91
	v_exp_f32_e32 v95, v91
	v_add_f32_e32 v91, v43, v103
	v_mul_f32_e32 v91, 0xbfb8aa3b, v91
	v_exp_f32_e32 v101, v91
	v_pk_add_f32 v[94:95], v[94:95], 1.0 op_sel_hi:[1,0]
	s_nop 0
	s_nop 0
	v_rcp_f32_e32 v91, v94
	s_nop 0
	v_rcp_f32_e32 v102, v95
	v_pk_add_f32 v[94:95], v[100:101], 1.0 op_sel_hi:[1,0]
	s_nop 0
	s_nop 0
	v_rcp_f32_e32 v94, v94
	s_nop 0
	v_rcp_f32_e32 v95, v95
	v_and_b32_sdwa v100, v102, v154 dst_sel:DWORD dst_unused:UNUSED_PAD src0_sel:WORD_1 src1_sel:DWORD
	v_and_b32_sdwa v101, v91, v154 dst_sel:DWORD dst_unused:UNUSED_PAD src0_sel:WORD_1 src1_sel:DWORD
	v_add3_u32 v91, v91, v101, s33
	v_add3_u32 v100, v102, v100, s33
	v_and_b32_sdwa v101, v95, v154 dst_sel:DWORD dst_unused:UNUSED_PAD src0_sel:WORD_1 src1_sel:DWORD
	v_and_b32_sdwa v102, v94, v154 dst_sel:DWORD dst_unused:UNUSED_PAD src0_sel:WORD_1 src1_sel:DWORD
	v_add3_u32 v95, v95, v101, s33
	v_add3_u32 v94, v94, v102, s33
	v_and_b32_e32 v95, 0xffff0000, v95
	v_and_b32_e32 v94, 0xffff0000, v94
	v_or_b32_sdwa v95, v95, v100 dst_sel:DWORD dst_unused:UNUSED_PAD src0_sel:DWORD src1_sel:WORD_1
	v_or_b32_sdwa v94, v94, v91 dst_sel:DWORD dst_unused:UNUSED_PAD src0_sel:DWORD src1_sel:WORD_1
	global_store_dwordx2 v[92:93], v[94:95], off offset:32
	global_load_dwordx4 v[100:103], v67, s[90:91] offset:128
	s_waitcnt vmcnt(0)
	v_add_f32_e32 v91, v36, v100
	v_mul_f32_e32 v91, 0xbfb8aa3b, v91
	v_exp_f32_e32 v94, v91
	v_add_f32_e32 v91, v37, v101
	v_mul_f32_e32 v91, 0xbfb8aa3b, v91
	v_exp_f32_e32 v100, v91
	v_add_f32_e32 v91, v38, v102
	v_mul_f32_e32 v91, 0xbfb8aa3b, v91
	v_exp_f32_e32 v95, v91
	v_add_f32_e32 v91, v39, v103
	v_mul_f32_e32 v91, 0xbfb8aa3b, v91
	v_exp_f32_e32 v101, v91
	v_pk_add_f32 v[94:95], v[94:95], 1.0 op_sel_hi:[1,0]
	s_nop 0
	s_nop 0
	v_rcp_f32_e32 v91, v94
	s_nop 0
	v_rcp_f32_e32 v102, v95
	v_pk_add_f32 v[94:95], v[100:101], 1.0 op_sel_hi:[1,0]
	s_nop 0
	s_nop 0
	v_rcp_f32_e32 v94, v94
	s_nop 0
	v_rcp_f32_e32 v95, v95
	v_and_b32_sdwa v100, v102, v154 dst_sel:DWORD dst_unused:UNUSED_PAD src0_sel:WORD_1 src1_sel:DWORD
	v_and_b32_sdwa v101, v91, v154 dst_sel:DWORD dst_unused:UNUSED_PAD src0_sel:WORD_1 src1_sel:DWORD
	v_add3_u32 v91, v91, v101, s33
	v_add3_u32 v100, v102, v100, s33
	v_and_b32_sdwa v101, v95, v154 dst_sel:DWORD dst_unused:UNUSED_PAD src0_sel:WORD_1 src1_sel:DWORD
	v_and_b32_sdwa v102, v94, v154 dst_sel:DWORD dst_unused:UNUSED_PAD src0_sel:WORD_1 src1_sel:DWORD
	v_add3_u32 v95, v95, v101, s33
	v_add3_u32 v94, v94, v102, s33
	v_and_b32_e32 v95, 0xffff0000, v95
	v_and_b32_e32 v94, 0xffff0000, v94
	v_or_b32_sdwa v95, v95, v100 dst_sel:DWORD dst_unused:UNUSED_PAD src0_sel:DWORD src1_sel:WORD_1
	v_or_b32_sdwa v94, v94, v91 dst_sel:DWORD dst_unused:UNUSED_PAD src0_sel:DWORD src1_sel:WORD_1
	global_store_dwordx2 v[92:93], v[94:95], off offset:64
	global_load_dwordx4 v[100:103], v67, s[90:91] offset:192
	s_waitcnt vmcnt(0)
	v_add_f32_e32 v91, v32, v100
	v_mul_f32_e32 v91, 0xbfb8aa3b, v91
	v_exp_f32_e32 v94, v91
	v_add_f32_e32 v91, v33, v101
	v_mul_f32_e32 v91, 0xbfb8aa3b, v91
	v_exp_f32_e32 v100, v91
	v_add_f32_e32 v91, v34, v102
	v_mul_f32_e32 v91, 0xbfb8aa3b, v91
	v_exp_f32_e32 v95, v91
	v_add_f32_e32 v91, v35, v103
	v_mul_f32_e32 v91, 0xbfb8aa3b, v91
	v_exp_f32_e32 v101, v91
	v_pk_add_f32 v[94:95], v[94:95], 1.0 op_sel_hi:[1,0]
	s_nop 0
	s_nop 0
	v_rcp_f32_e32 v91, v94
	s_nop 0
	v_rcp_f32_e32 v102, v95
	v_pk_add_f32 v[94:95], v[100:101], 1.0 op_sel_hi:[1,0]
	s_nop 0
	s_nop 0
	v_rcp_f32_e32 v94, v94
	s_nop 0
	v_rcp_f32_e32 v95, v95
	v_and_b32_sdwa v100, v102, v154 dst_sel:DWORD dst_unused:UNUSED_PAD src0_sel:WORD_1 src1_sel:DWORD
	v_and_b32_sdwa v101, v91, v154 dst_sel:DWORD dst_unused:UNUSED_PAD src0_sel:WORD_1 src1_sel:DWORD
	v_add3_u32 v91, v91, v101, s33
	v_add3_u32 v100, v102, v100, s33
	v_and_b32_sdwa v101, v95, v154 dst_sel:DWORD dst_unused:UNUSED_PAD src0_sel:WORD_1 src1_sel:DWORD
	v_and_b32_sdwa v102, v94, v154 dst_sel:DWORD dst_unused:UNUSED_PAD src0_sel:WORD_1 src1_sel:DWORD
	v_add3_u32 v95, v95, v101, s33
	v_add3_u32 v94, v94, v102, s33
	v_and_b32_e32 v95, 0xffff0000, v95
	v_and_b32_e32 v94, 0xffff0000, v94
	v_or_b32_sdwa v95, v95, v100 dst_sel:DWORD dst_unused:UNUSED_PAD src0_sel:DWORD src1_sel:WORD_1
	v_or_b32_sdwa v94, v94, v91 dst_sel:DWORD dst_unused:UNUSED_PAD src0_sel:DWORD src1_sel:WORD_1
	global_store_dwordx2 v[92:93], v[94:95], off offset:96
	v_or_b32_e32 v92, 32, v66
	v_ashrrev_i32_e32 v93, 31, v92
	v_lshlrev_b64 v[92:93], 11, v[92:93]
	v_lshl_add_u64 v[100:101], s[4:5], 0, v[92:93]
	global_load_dwordx4 v[92:95], v67, s[90:91]
	s_waitcnt vmcnt(0)
	v_add_f32_e32 v91, v28, v92
	v_mul_f32_e32 v91, 0xbfb8aa3b, v91
	v_exp_f32_e32 v102, v91
	v_add_f32_e32 v91, v29, v93
	v_mul_f32_e32 v91, 0xbfb8aa3b, v91
	v_exp_f32_e32 v104, v91
	v_add_f32_e32 v91, v30, v94
	v_mul_f32_e32 v91, 0xbfb8aa3b, v91
	v_exp_f32_e32 v103, v91
	v_add_f32_e32 v91, v31, v95
	v_mul_f32_e32 v91, 0xbfb8aa3b, v91
	v_exp_f32_e32 v105, v91
	v_pk_add_f32 v[94:95], v[102:103], 1.0 op_sel_hi:[1,0]
	v_lshl_add_u64 v[92:93], v[100:101], 0, v[64:65]
	s_nop 0
	v_rcp_f32_e32 v91, v94
	s_nop 0
	v_rcp_f32_e32 v100, v95
	v_pk_add_f32 v[94:95], v[104:105], 1.0 op_sel_hi:[1,0]
	s_nop 0
	s_nop 0
	v_rcp_f32_e32 v94, v94
	s_nop 0
	v_rcp_f32_e32 v95, v95
	v_and_b32_sdwa v101, v100, v154 dst_sel:DWORD dst_unused:UNUSED_PAD src0_sel:WORD_1 src1_sel:DWORD
	v_and_b32_sdwa v102, v91, v154 dst_sel:DWORD dst_unused:UNUSED_PAD src0_sel:WORD_1 src1_sel:DWORD
	v_add3_u32 v91, v91, v102, s33
	v_add3_u32 v100, v100, v101, s33
	v_and_b32_sdwa v101, v95, v154 dst_sel:DWORD dst_unused:UNUSED_PAD src0_sel:WORD_1 src1_sel:DWORD
	v_and_b32_sdwa v102, v94, v154 dst_sel:DWORD dst_unused:UNUSED_PAD src0_sel:WORD_1 src1_sel:DWORD
	v_add3_u32 v95, v95, v101, s33
	v_add3_u32 v94, v94, v102, s33
	v_and_b32_e32 v95, 0xffff0000, v95
	v_and_b32_e32 v94, 0xffff0000, v94
	v_or_b32_sdwa v95, v95, v100 dst_sel:DWORD dst_unused:UNUSED_PAD src0_sel:DWORD src1_sel:WORD_1
	v_or_b32_sdwa v94, v94, v91 dst_sel:DWORD dst_unused:UNUSED_PAD src0_sel:DWORD src1_sel:WORD_1
	global_store_dwordx2 v[92:93], v[94:95], off
	global_load_dwordx4 v[100:103], v67, s[90:91] offset:64
	s_waitcnt vmcnt(0)
	v_add_f32_e32 v91, v24, v100
	v_mul_f32_e32 v91, 0xbfb8aa3b, v91
	v_exp_f32_e32 v94, v91
	v_add_f32_e32 v91, v25, v101
	v_mul_f32_e32 v91, 0xbfb8aa3b, v91
	v_exp_f32_e32 v100, v91
	v_add_f32_e32 v91, v26, v102
	v_mul_f32_e32 v91, 0xbfb8aa3b, v91
	v_exp_f32_e32 v95, v91
	v_add_f32_e32 v91, v27, v103
	v_mul_f32_e32 v91, 0xbfb8aa3b, v91
	v_exp_f32_e32 v101, v91
	v_pk_add_f32 v[94:95], v[94:95], 1.0 op_sel_hi:[1,0]
	s_nop 0
	s_nop 0
	v_rcp_f32_e32 v91, v94
	s_nop 0
	v_rcp_f32_e32 v102, v95
	v_pk_add_f32 v[94:95], v[100:101], 1.0 op_sel_hi:[1,0]
	s_nop 0
	s_nop 0
	v_rcp_f32_e32 v94, v94
	s_nop 0
	v_rcp_f32_e32 v95, v95
	v_and_b32_sdwa v100, v102, v154 dst_sel:DWORD dst_unused:UNUSED_PAD src0_sel:WORD_1 src1_sel:DWORD
	v_and_b32_sdwa v101, v91, v154 dst_sel:DWORD dst_unused:UNUSED_PAD src0_sel:WORD_1 src1_sel:DWORD
	v_add3_u32 v91, v91, v101, s33
	v_add3_u32 v100, v102, v100, s33
	v_and_b32_sdwa v101, v95, v154 dst_sel:DWORD dst_unused:UNUSED_PAD src0_sel:WORD_1 src1_sel:DWORD
	v_and_b32_sdwa v102, v94, v154 dst_sel:DWORD dst_unused:UNUSED_PAD src0_sel:WORD_1 src1_sel:DWORD
	v_add3_u32 v95, v95, v101, s33
	v_add3_u32 v94, v94, v102, s33
	v_and_b32_e32 v95, 0xffff0000, v95
	v_and_b32_e32 v94, 0xffff0000, v94
	v_or_b32_sdwa v95, v95, v100 dst_sel:DWORD dst_unused:UNUSED_PAD src0_sel:DWORD src1_sel:WORD_1
	v_or_b32_sdwa v94, v94, v91 dst_sel:DWORD dst_unused:UNUSED_PAD src0_sel:DWORD src1_sel:WORD_1
	global_store_dwordx2 v[92:93], v[94:95], off offset:32
	global_load_dwordx4 v[100:103], v67, s[90:91] offset:128
	s_waitcnt vmcnt(0)
	v_add_f32_e32 v91, v20, v100
	v_mul_f32_e32 v91, 0xbfb8aa3b, v91
	v_exp_f32_e32 v94, v91
	v_add_f32_e32 v91, v21, v101
	v_mul_f32_e32 v91, 0xbfb8aa3b, v91
	v_exp_f32_e32 v100, v91
	v_add_f32_e32 v91, v22, v102
	v_mul_f32_e32 v91, 0xbfb8aa3b, v91
	v_exp_f32_e32 v95, v91
	v_add_f32_e32 v91, v23, v103
	v_mul_f32_e32 v91, 0xbfb8aa3b, v91
	v_exp_f32_e32 v101, v91
	v_pk_add_f32 v[94:95], v[94:95], 1.0 op_sel_hi:[1,0]
	s_nop 0
	s_nop 0
	v_rcp_f32_e32 v91, v94
	s_nop 0
	v_rcp_f32_e32 v102, v95
	v_pk_add_f32 v[94:95], v[100:101], 1.0 op_sel_hi:[1,0]
	s_nop 0
	s_nop 0
	v_rcp_f32_e32 v94, v94
	s_nop 0
	v_rcp_f32_e32 v95, v95
	v_and_b32_sdwa v100, v102, v154 dst_sel:DWORD dst_unused:UNUSED_PAD src0_sel:WORD_1 src1_sel:DWORD
	v_and_b32_sdwa v101, v91, v154 dst_sel:DWORD dst_unused:UNUSED_PAD src0_sel:WORD_1 src1_sel:DWORD
	v_add3_u32 v91, v91, v101, s33
	v_add3_u32 v100, v102, v100, s33
	v_and_b32_sdwa v101, v95, v154 dst_sel:DWORD dst_unused:UNUSED_PAD src0_sel:WORD_1 src1_sel:DWORD
	v_and_b32_sdwa v102, v94, v154 dst_sel:DWORD dst_unused:UNUSED_PAD src0_sel:WORD_1 src1_sel:DWORD
	v_add3_u32 v95, v95, v101, s33
	v_add3_u32 v94, v94, v102, s33
	v_and_b32_e32 v95, 0xffff0000, v95
	v_and_b32_e32 v94, 0xffff0000, v94
	v_or_b32_sdwa v95, v95, v100 dst_sel:DWORD dst_unused:UNUSED_PAD src0_sel:DWORD src1_sel:WORD_1
	v_or_b32_sdwa v94, v94, v91 dst_sel:DWORD dst_unused:UNUSED_PAD src0_sel:DWORD src1_sel:WORD_1
	global_store_dwordx2 v[92:93], v[94:95], off offset:64
	global_load_dwordx4 v[100:103], v67, s[90:91] offset:192
	s_waitcnt vmcnt(0)
	v_add_f32_e32 v91, v16, v100
	v_mul_f32_e32 v91, 0xbfb8aa3b, v91
	v_exp_f32_e32 v94, v91
	v_add_f32_e32 v91, v17, v101
	v_mul_f32_e32 v91, 0xbfb8aa3b, v91
	v_exp_f32_e32 v100, v91
	v_add_f32_e32 v91, v18, v102
	v_mul_f32_e32 v91, 0xbfb8aa3b, v91
	v_exp_f32_e32 v95, v91
	v_add_f32_e32 v91, v19, v103
	v_mul_f32_e32 v91, 0xbfb8aa3b, v91
	v_exp_f32_e32 v101, v91
	v_pk_add_f32 v[94:95], v[94:95], 1.0 op_sel_hi:[1,0]
	s_nop 0
	s_nop 0
	v_rcp_f32_e32 v91, v94
	s_nop 0
	v_rcp_f32_e32 v102, v95
	v_pk_add_f32 v[94:95], v[100:101], 1.0 op_sel_hi:[1,0]
	s_nop 0
	s_nop 0
	v_rcp_f32_e32 v94, v94
	s_nop 0
	v_rcp_f32_e32 v95, v95
	v_and_b32_sdwa v100, v102, v154 dst_sel:DWORD dst_unused:UNUSED_PAD src0_sel:WORD_1 src1_sel:DWORD
	v_and_b32_sdwa v101, v91, v154 dst_sel:DWORD dst_unused:UNUSED_PAD src0_sel:WORD_1 src1_sel:DWORD
	v_add3_u32 v91, v91, v101, s33
	v_add3_u32 v100, v102, v100, s33
	v_and_b32_sdwa v101, v95, v154 dst_sel:DWORD dst_unused:UNUSED_PAD src0_sel:WORD_1 src1_sel:DWORD
	v_and_b32_sdwa v102, v94, v154 dst_sel:DWORD dst_unused:UNUSED_PAD src0_sel:WORD_1 src1_sel:DWORD
	v_add3_u32 v95, v95, v101, s33
	v_add3_u32 v94, v94, v102, s33
	v_and_b32_e32 v95, 0xffff0000, v95
	v_and_b32_e32 v94, 0xffff0000, v94
	v_or_b32_sdwa v95, v95, v100 dst_sel:DWORD dst_unused:UNUSED_PAD src0_sel:DWORD src1_sel:WORD_1
	v_or_b32_sdwa v94, v94, v91 dst_sel:DWORD dst_unused:UNUSED_PAD src0_sel:DWORD src1_sel:WORD_1
	global_store_dwordx2 v[92:93], v[94:95], off offset:96
	v_or_b32_e32 v92, 48, v66
	v_ashrrev_i32_e32 v93, 31, v92
	v_lshlrev_b64 v[92:93], 11, v[92:93]
	v_lshl_add_u64 v[100:101], s[4:5], 0, v[92:93]
	global_load_dwordx4 v[92:95], v67, s[90:91]
	v_lshl_add_u64 v[64:65], v[100:101], 0, v[64:65]
	s_waitcnt vmcnt(0)
	v_add_f32_e32 v66, v12, v92
	v_mul_f32_e32 v66, 0xbfb8aa3b, v66
	v_exp_f32_e32 v92, v66
	v_add_f32_e32 v66, v13, v93
	v_mul_f32_e32 v66, 0xbfb8aa3b, v66
	v_exp_f32_e32 v102, v66
	v_add_f32_e32 v66, v14, v94
	v_mul_f32_e32 v66, 0xbfb8aa3b, v66
	v_exp_f32_e32 v93, v66
	v_add_f32_e32 v66, v15, v95
	v_mul_f32_e32 v66, 0xbfb8aa3b, v66
	v_exp_f32_e32 v103, v66
	v_pk_add_f32 v[92:93], v[92:93], 1.0 op_sel_hi:[1,0]
	s_nop 0
	s_nop 0
	v_div_scale_f32 v91, s[0:1], v93, v93, 1.0
	v_rcp_f32_e32 v66, v92
	v_rcp_f32_e32 v92, v91
	s_nop 0
	v_fma_f32 v94, -v91, v92, 1.0
	v_fmac_f32_e32 v92, v94, v92
	v_div_scale_f32 v94, vcc, 1.0, v93, 1.0
	v_mul_f32_e32 v95, v94, v92
	v_fma_f32 v100, -v91, v95, v94
	v_fmac_f32_e32 v95, v100, v92
	v_fma_f32 v91, -v91, v95, v94
	v_div_fmas_f32 v91, v91, v92, v95
	v_div_fixup_f32 v91, v91, v93, 1.0
	v_pk_add_f32 v[92:93], v[102:103], 1.0 op_sel_hi:[1,0]
	s_nop 0
	s_nop 0
	v_rcp_f32_e32 v92, v92
	s_nop 0
	v_rcp_f32_e32 v93, v93
	v_and_b32_sdwa v94, v91, v154 dst_sel:DWORD dst_unused:UNUSED_PAD src0_sel:WORD_1 src1_sel:DWORD
	v_and_b32_sdwa v95, v66, v154 dst_sel:DWORD dst_unused:UNUSED_PAD src0_sel:WORD_1 src1_sel:DWORD
	v_add3_u32 v66, v66, v95, s33
	v_add3_u32 v91, v91, v94, s33
	v_and_b32_sdwa v94, v93, v154 dst_sel:DWORD dst_unused:UNUSED_PAD src0_sel:WORD_1 src1_sel:DWORD
	v_and_b32_sdwa v95, v92, v154 dst_sel:DWORD dst_unused:UNUSED_PAD src0_sel:WORD_1 src1_sel:DWORD
	v_add3_u32 v93, v93, v94, s33
	v_add3_u32 v92, v92, v95, s33
	v_and_b32_e32 v93, 0xffff0000, v93
	v_and_b32_e32 v92, 0xffff0000, v92
	v_or_b32_sdwa v93, v93, v91 dst_sel:DWORD dst_unused:UNUSED_PAD src0_sel:DWORD src1_sel:WORD_1
	v_or_b32_sdwa v92, v92, v66 dst_sel:DWORD dst_unused:UNUSED_PAD src0_sel:DWORD src1_sel:WORD_1
	global_store_dwordx2 v[64:65], v[92:93], off
	global_load_dwordx4 v[92:95], v67, s[90:91] offset:64
	s_waitcnt vmcnt(0)
	v_add_f32_e32 v66, v8, v92
	v_mul_f32_e32 v66, 0xbfb8aa3b, v66
	v_exp_f32_e32 v92, v66
	v_add_f32_e32 v66, v9, v93
	v_mul_f32_e32 v66, 0xbfb8aa3b, v66
	v_exp_f32_e32 v100, v66
	v_add_f32_e32 v66, v10, v94
	v_mul_f32_e32 v66, 0xbfb8aa3b, v66
	v_exp_f32_e32 v93, v66
	v_add_f32_e32 v66, v11, v95
	v_mul_f32_e32 v66, 0xbfb8aa3b, v66
	v_exp_f32_e32 v101, v66
	v_pk_add_f32 v[92:93], v[92:93], 1.0 op_sel_hi:[1,0]
	s_nop 0
	s_nop 0
	v_div_scale_f32 v91, s[0:1], v93, v93, 1.0
	v_rcp_f32_e32 v66, v92
	v_rcp_f32_e32 v92, v91
	s_nop 0
	v_fma_f32 v94, -v91, v92, 1.0
	v_fmac_f32_e32 v92, v94, v92
	v_div_scale_f32 v94, vcc, 1.0, v93, 1.0
	v_mul_f32_e32 v95, v94, v92
	v_fma_f32 v102, -v91, v95, v94
	v_fmac_f32_e32 v95, v102, v92
	v_fma_f32 v91, -v91, v95, v94
	v_div_fmas_f32 v91, v91, v92, v95
	v_div_fixup_f32 v91, v91, v93, 1.0
	v_pk_add_f32 v[92:93], v[100:101], 1.0 op_sel_hi:[1,0]
	s_nop 0
	s_nop 0
	v_rcp_f32_e32 v92, v92
	s_nop 0
	v_rcp_f32_e32 v93, v93
	v_and_b32_sdwa v94, v91, v154 dst_sel:DWORD dst_unused:UNUSED_PAD src0_sel:WORD_1 src1_sel:DWORD
	v_and_b32_sdwa v95, v66, v154 dst_sel:DWORD dst_unused:UNUSED_PAD src0_sel:WORD_1 src1_sel:DWORD
	v_add3_u32 v66, v66, v95, s33
	v_add3_u32 v91, v91, v94, s33
	v_and_b32_sdwa v94, v93, v154 dst_sel:DWORD dst_unused:UNUSED_PAD src0_sel:WORD_1 src1_sel:DWORD
	v_and_b32_sdwa v95, v92, v154 dst_sel:DWORD dst_unused:UNUSED_PAD src0_sel:WORD_1 src1_sel:DWORD
	v_add3_u32 v93, v93, v94, s33
	v_add3_u32 v92, v92, v95, s33
	v_and_b32_e32 v93, 0xffff0000, v93
	v_and_b32_e32 v92, 0xffff0000, v92
	v_or_b32_sdwa v93, v93, v91 dst_sel:DWORD dst_unused:UNUSED_PAD src0_sel:DWORD src1_sel:WORD_1
	v_or_b32_sdwa v92, v92, v66 dst_sel:DWORD dst_unused:UNUSED_PAD src0_sel:DWORD src1_sel:WORD_1
	global_store_dwordx2 v[64:65], v[92:93], off offset:32
	global_load_dwordx4 v[92:95], v67, s[90:91] offset:128
	s_waitcnt vmcnt(0)
	v_add_f32_e32 v66, v4, v92
	v_mul_f32_e32 v66, 0xbfb8aa3b, v66
	v_exp_f32_e32 v92, v66
	v_add_f32_e32 v66, v5, v93
	v_mul_f32_e32 v66, 0xbfb8aa3b, v66
	v_exp_f32_e32 v100, v66
	v_add_f32_e32 v66, v6, v94
	v_mul_f32_e32 v66, 0xbfb8aa3b, v66
	v_exp_f32_e32 v93, v66
	v_add_f32_e32 v66, v7, v95
	v_mul_f32_e32 v66, 0xbfb8aa3b, v66
	v_exp_f32_e32 v101, v66
	v_pk_add_f32 v[92:93], v[92:93], 1.0 op_sel_hi:[1,0]
	s_nop 0
	s_nop 0
	v_div_scale_f32 v91, s[0:1], v93, v93, 1.0
	v_rcp_f32_e32 v66, v92
	v_rcp_f32_e32 v92, v91
	s_nop 0
	v_fma_f32 v94, -v91, v92, 1.0
	v_fmac_f32_e32 v92, v94, v92
	v_div_scale_f32 v94, vcc, 1.0, v93, 1.0
	v_mul_f32_e32 v95, v94, v92
	v_fma_f32 v102, -v91, v95, v94
	v_fmac_f32_e32 v95, v102, v92
	v_fma_f32 v91, -v91, v95, v94
	v_div_fmas_f32 v91, v91, v92, v95
	v_div_fixup_f32 v91, v91, v93, 1.0
	v_pk_add_f32 v[92:93], v[100:101], 1.0 op_sel_hi:[1,0]
	s_nop 0
	s_nop 0
	v_rcp_f32_e32 v92, v92
	s_nop 0
	v_rcp_f32_e32 v93, v93
	v_and_b32_sdwa v94, v91, v154 dst_sel:DWORD dst_unused:UNUSED_PAD src0_sel:WORD_1 src1_sel:DWORD
	v_and_b32_sdwa v95, v66, v154 dst_sel:DWORD dst_unused:UNUSED_PAD src0_sel:WORD_1 src1_sel:DWORD
	v_add3_u32 v66, v66, v95, s33
	v_add3_u32 v91, v91, v94, s33
	v_and_b32_sdwa v94, v93, v154 dst_sel:DWORD dst_unused:UNUSED_PAD src0_sel:WORD_1 src1_sel:DWORD
	v_and_b32_sdwa v95, v92, v154 dst_sel:DWORD dst_unused:UNUSED_PAD src0_sel:WORD_1 src1_sel:DWORD
	v_add3_u32 v93, v93, v94, s33
	v_add3_u32 v92, v92, v95, s33
	v_and_b32_e32 v93, 0xffff0000, v93
	v_and_b32_e32 v92, 0xffff0000, v92
	v_or_b32_sdwa v93, v93, v91 dst_sel:DWORD dst_unused:UNUSED_PAD src0_sel:DWORD src1_sel:WORD_1
	v_or_b32_sdwa v92, v92, v66 dst_sel:DWORD dst_unused:UNUSED_PAD src0_sel:DWORD src1_sel:WORD_1
	global_store_dwordx2 v[64:65], v[92:93], off offset:64
	global_load_dwordx4 v[92:95], v67, s[90:91] offset:192
	s_waitcnt vmcnt(0)
	v_add_f32_e32 v67, v1, v93
	v_mul_f32_e32 v67, 0xbfb8aa3b, v67
	v_add_f32_e32 v66, v0, v92
	v_exp_f32_e32 v92, v67
	v_add_f32_e32 v67, v2, v94
	v_mul_f32_e32 v66, 0xbfb8aa3b, v66
	v_mul_f32_e32 v67, 0xbfb8aa3b, v67
	v_exp_f32_e32 v66, v66
	v_exp_f32_e32 v67, v67
	v_add_f32_e32 v91, v3, v95
	v_mul_f32_e32 v91, 0xbfb8aa3b, v91
	v_exp_f32_e32 v93, v91
	v_pk_add_f32 v[66:67], v[66:67], 1.0 op_sel_hi:[1,0]
	s_nop 0
	s_nop 0
	v_rcp_f32_e32 v91, v66
	s_nop 0
	v_rcp_f32_e32 v94, v67
	v_pk_add_f32 v[66:67], v[92:93], 1.0 op_sel_hi:[1,0]
	s_nop 0
	s_nop 0
	v_rcp_f32_e32 v66, v66
	s_mov_b64 s[0:1], 0
	v_rcp_f32_e32 v67, v67
	v_and_b32_sdwa v92, v94, v154 dst_sel:DWORD dst_unused:UNUSED_PAD src0_sel:WORD_1 src1_sel:DWORD
	v_and_b32_sdwa v93, v91, v154 dst_sel:DWORD dst_unused:UNUSED_PAD src0_sel:WORD_1 src1_sel:DWORD
	v_add3_u32 v91, v91, v93, s33
	v_add3_u32 v92, v94, v92, s33
	v_and_b32_sdwa v93, v67, v154 dst_sel:DWORD dst_unused:UNUSED_PAD src0_sel:WORD_1 src1_sel:DWORD
	v_and_b32_sdwa v94, v66, v154 dst_sel:DWORD dst_unused:UNUSED_PAD src0_sel:WORD_1 src1_sel:DWORD
	v_add3_u32 v67, v67, v93, s33
	v_add3_u32 v66, v66, v94, s33
	v_and_b32_e32 v67, 0xffff0000, v67
	v_and_b32_e32 v66, 0xffff0000, v66
	v_or_b32_sdwa v67, v67, v92 dst_sel:DWORD dst_unused:UNUSED_PAD src0_sel:DWORD src1_sel:WORD_1
	v_or_b32_sdwa v66, v66, v91 dst_sel:DWORD dst_unused:UNUSED_PAD src0_sel:DWORD src1_sel:WORD_1
	global_store_dwordx2 v[64:65], v[66:67], off offset:96
.LBB0_385:
	s_andn2_b64 vcc, exec, s[0:1]
	s_cbranch_vccnz .LBB0_387
	v_mov_b32_e32 v64, v97
	s_nop 0
	v_add_u32_e32 v64, v64, v176
	v_ashrrev_i32_e32 v66, 1, v64
	v_lshrrev_b32_e32 v67, 2, v64
	v_and_b32_e32 v65, 64, v64
	v_and_b32_e32 v66, 0xffffffc0, v66
	v_and_b32_e32 v67, 12, v67
	v_and_or_b32 v64, v64, 15, s6
	v_add_u32_e32 v94, v64, v66
	v_or3_b32 v66, v65, v67, s2
	v_ashrrev_i32_e32 v95, 31, v94
	v_readlane_b32 s4, v254, 55
	v_lshlrev_b64 v[64:65], 12, v[94:95]
	v_readlane_b32 s5, v254, 56
	v_lshlrev_b32_e32 v92, 2, v66
	v_mov_b32_e32 v93, v97
	v_lshl_add_u64 v[100:101], s[4:5], 0, v[64:65]
	global_load_dwordx4 v[64:67], v92, s[48:49]
	s_waitcnt vmcnt(0)
	v_add_f32_e32 v60, v60, v64
	v_mul_f32_e32 v60, 0xbfb8aa3b, v60
	v_exp_f32_e32 v60, v60
	v_add_f32_e32 v61, v61, v65
	v_mul_f32_e32 v61, 0xbfb8aa3b, v61
	v_exp_f32_e32 v61, v61
	v_add_f32_e32 v60, 1.0, v60
	v_add_f32_e32 v61, 1.0, v61
	v_add_f32_e32 v62, v62, v66
	v_mul_f32_e32 v62, 0xbfb8aa3b, v62
	v_rcp_f32_e32 v60, v60
	v_exp_f32_e32 v62, v62
	v_add_f32_e32 v63, v63, v67
	v_mul_f32_e32 v63, 0xbfb8aa3b, v63
	v_add_f32_e32 v62, 1.0, v62
	v_rcp_f32_e32 v61, v61
	v_exp_f32_e32 v63, v63
	v_mul_f32_e32 v60, 0xbf1b4598, v60
	v_mul_f32_e32 v61, 0xbf1b4598, v61
	v_add_f32_e32 v63, 1.0, v63
	v_rcp_f32_e32 v62, v62
	s_nop 0
	v_mul_f32_e32 v62, 0xbf1b4598, v62
	v_mul_f32_e32 v60, 0x3fb8aa3b, v60
	v_mul_f32_e32 v61, 0x3fb8aa3b, v61
	v_rcp_f32_e32 v63, v63
	s_nop 0
	v_mul_f32_e32 v63, 0xbf1b4598, v63
	v_mul_f32_e32 v62, 0x3fb8aa3b, v62
	v_mul_f32_e32 v63, 0x3fb8aa3b, v63
	v_exp_f32_e32 v60, v60
	v_exp_f32_e32 v61, v61
	v_exp_f32_e32 v62, v62
	v_exp_f32_e32 v63, v63
	v_lshl_add_u64 v[64:65], v[100:101], 0, v[92:93]
	global_store_dwordx4 v[64:65], v[60:63], off
	global_load_dwordx4 v[60:63], v92, s[48:49] offset:64
	s_waitcnt vmcnt(0)
	v_add_f32_e32 v56, v56, v60
	v_mul_f32_e32 v56, 0xbfb8aa3b, v56
	v_exp_f32_e32 v56, v56
	v_add_f32_e32 v57, v57, v61
	v_mul_f32_e32 v57, 0xbfb8aa3b, v57
	v_exp_f32_e32 v57, v57
	v_add_f32_e32 v56, 1.0, v56
	v_add_f32_e32 v57, 1.0, v57
	v_add_f32_e32 v58, v58, v62
	v_mul_f32_e32 v58, 0xbfb8aa3b, v58
	v_rcp_f32_e32 v56, v56
	v_exp_f32_e32 v58, v58
	v_add_f32_e32 v59, v59, v63
	v_mul_f32_e32 v59, 0xbfb8aa3b, v59
	v_add_f32_e32 v58, 1.0, v58
	v_rcp_f32_e32 v57, v57
	v_exp_f32_e32 v59, v59
	v_mul_f32_e32 v56, 0xbf1b4598, v56
	v_mul_f32_e32 v57, 0xbf1b4598, v57
	v_add_f32_e32 v59, 1.0, v59
	v_rcp_f32_e32 v58, v58
	s_nop 0
	v_mul_f32_e32 v58, 0xbf1b4598, v58
	v_mul_f32_e32 v56, 0x3fb8aa3b, v56
	v_mul_f32_e32 v57, 0x3fb8aa3b, v57
	v_rcp_f32_e32 v59, v59
	s_nop 0
	v_mul_f32_e32 v59, 0xbf1b4598, v59
	v_mul_f32_e32 v58, 0x3fb8aa3b, v58
	v_mul_f32_e32 v59, 0x3fb8aa3b, v59
	v_exp_f32_e32 v56, v56
	v_exp_f32_e32 v57, v57
	v_exp_f32_e32 v58, v58
	v_exp_f32_e32 v59, v59
	s_nop 0
	global_store_dwordx4 v[64:65], v[56:59], off offset:64
	global_load_dwordx4 v[56:59], v92, s[48:49] offset:128
	s_waitcnt vmcnt(0)
	v_add_f32_e32 v52, v52, v56
	v_mul_f32_e32 v52, 0xbfb8aa3b, v52
	v_exp_f32_e32 v52, v52
	v_add_f32_e32 v53, v53, v57
	v_mul_f32_e32 v53, 0xbfb8aa3b, v53
	v_exp_f32_e32 v53, v53
	v_add_f32_e32 v52, 1.0, v52
	v_add_f32_e32 v53, 1.0, v53
	v_add_f32_e32 v54, v54, v58
	v_mul_f32_e32 v54, 0xbfb8aa3b, v54
	v_rcp_f32_e32 v52, v52
	v_exp_f32_e32 v54, v54
	v_add_f32_e32 v55, v55, v59
	v_mul_f32_e32 v55, 0xbfb8aa3b, v55
	v_add_f32_e32 v54, 1.0, v54
	v_rcp_f32_e32 v53, v53
	v_exp_f32_e32 v55, v55
	v_mul_f32_e32 v52, 0xbf1b4598, v52
	v_mul_f32_e32 v53, 0xbf1b4598, v53
	v_add_f32_e32 v55, 1.0, v55
	v_rcp_f32_e32 v54, v54
	s_nop 0
	v_mul_f32_e32 v54, 0xbf1b4598, v54
	v_mul_f32_e32 v52, 0x3fb8aa3b, v52
	v_mul_f32_e32 v53, 0x3fb8aa3b, v53
	v_rcp_f32_e32 v55, v55
	s_nop 0
	v_mul_f32_e32 v55, 0xbf1b4598, v55
	v_mul_f32_e32 v54, 0x3fb8aa3b, v54
	v_mul_f32_e32 v55, 0x3fb8aa3b, v55
	v_exp_f32_e32 v52, v52
	v_exp_f32_e32 v53, v53
	v_exp_f32_e32 v54, v54
	v_exp_f32_e32 v55, v55
	s_nop 0
	global_store_dwordx4 v[64:65], v[52:55], off offset:128
	global_load_dwordx4 v[52:55], v92, s[48:49] offset:192
	s_waitcnt vmcnt(0)
	v_add_f32_e32 v48, v48, v52
	v_mul_f32_e32 v48, 0xbfb8aa3b, v48
	v_exp_f32_e32 v48, v48
	v_add_f32_e32 v49, v49, v53
	v_mul_f32_e32 v49, 0xbfb8aa3b, v49
	v_exp_f32_e32 v49, v49
	v_add_f32_e32 v48, 1.0, v48
	v_add_f32_e32 v49, 1.0, v49
	v_add_f32_e32 v50, v50, v54
	v_mul_f32_e32 v50, 0xbfb8aa3b, v50
	v_rcp_f32_e32 v48, v48
	v_exp_f32_e32 v50, v50
	v_add_f32_e32 v51, v51, v55
	v_mul_f32_e32 v51, 0xbfb8aa3b, v51
	v_add_f32_e32 v50, 1.0, v50
	v_rcp_f32_e32 v49, v49
	v_exp_f32_e32 v51, v51
	v_mul_f32_e32 v48, 0xbf1b4598, v48
	v_mul_f32_e32 v49, 0xbf1b4598, v49
	v_add_f32_e32 v51, 1.0, v51
	v_rcp_f32_e32 v50, v50
	s_nop 0
	v_mul_f32_e32 v50, 0xbf1b4598, v50
	v_mul_f32_e32 v48, 0x3fb8aa3b, v48
	v_mul_f32_e32 v49, 0x3fb8aa3b, v49
	v_rcp_f32_e32 v51, v51
	s_nop 0
	v_mul_f32_e32 v51, 0xbf1b4598, v51
	v_mul_f32_e32 v50, 0x3fb8aa3b, v50
	v_mul_f32_e32 v51, 0x3fb8aa3b, v51
	v_exp_f32_e32 v48, v48
	v_exp_f32_e32 v49, v49
	v_exp_f32_e32 v50, v50
	v_exp_f32_e32 v51, v51
	s_nop 0
	global_store_dwordx4 v[64:65], v[48:51], off offset:192
	s_nop 1
	v_or_b32_e32 v48, 16, v94
	v_ashrrev_i32_e32 v49, 31, v48
	v_lshlrev_b64 v[48:49], 12, v[48:49]
	v_lshl_add_u64 v[52:53], s[4:5], 0, v[48:49]
	global_load_dwordx4 v[48:51], v92, s[48:49]
	s_waitcnt vmcnt(0)
	v_add_f32_e32 v44, v44, v48
	v_mul_f32_e32 v44, 0xbfb8aa3b, v44
	v_exp_f32_e32 v44, v44
	v_add_f32_e32 v45, v45, v49
	v_mul_f32_e32 v45, 0xbfb8aa3b, v45
	v_exp_f32_e32 v45, v45
	v_add_f32_e32 v44, 1.0, v44
	v_add_f32_e32 v45, 1.0, v45
	v_add_f32_e32 v46, v46, v50
	v_mul_f32_e32 v46, 0xbfb8aa3b, v46
	v_rcp_f32_e32 v44, v44
	v_exp_f32_e32 v46, v46
	v_add_f32_e32 v47, v47, v51
	v_mul_f32_e32 v47, 0xbfb8aa3b, v47
	v_add_f32_e32 v46, 1.0, v46
	v_rcp_f32_e32 v45, v45
	v_exp_f32_e32 v47, v47
	v_mul_f32_e32 v44, 0xbf1b4598, v44
	v_mul_f32_e32 v45, 0xbf1b4598, v45
	v_add_f32_e32 v47, 1.0, v47
	v_rcp_f32_e32 v46, v46
	s_nop 0
	v_mul_f32_e32 v46, 0xbf1b4598, v46
	v_mul_f32_e32 v44, 0x3fb8aa3b, v44
	v_mul_f32_e32 v45, 0x3fb8aa3b, v45
	v_rcp_f32_e32 v47, v47
	s_nop 0
	v_mul_f32_e32 v47, 0xbf1b4598, v47
	v_mul_f32_e32 v46, 0x3fb8aa3b, v46
	v_mul_f32_e32 v47, 0x3fb8aa3b, v47
	v_exp_f32_e32 v44, v44
	v_exp_f32_e32 v45, v45
	v_exp_f32_e32 v46, v46
	v_exp_f32_e32 v47, v47
	v_lshl_add_u64 v[48:49], v[52:53], 0, v[92:93]
	global_store_dwordx4 v[48:49], v[44:47], off
	global_load_dwordx4 v[44:47], v92, s[48:49] offset:64
	s_waitcnt vmcnt(0)
	v_add_f32_e32 v40, v40, v44
	v_mul_f32_e32 v40, 0xbfb8aa3b, v40
	v_exp_f32_e32 v40, v40
	v_add_f32_e32 v41, v41, v45
	v_mul_f32_e32 v41, 0xbfb8aa3b, v41
	v_exp_f32_e32 v41, v41
	v_add_f32_e32 v40, 1.0, v40
	v_add_f32_e32 v41, 1.0, v41
	v_add_f32_e32 v42, v42, v46
	v_mul_f32_e32 v42, 0xbfb8aa3b, v42
	v_rcp_f32_e32 v40, v40
	v_exp_f32_e32 v42, v42
	v_add_f32_e32 v43, v43, v47
	v_mul_f32_e32 v43, 0xbfb8aa3b, v43
	v_add_f32_e32 v42, 1.0, v42
	v_rcp_f32_e32 v41, v41
	v_exp_f32_e32 v43, v43
	v_mul_f32_e32 v40, 0xbf1b4598, v40
	v_mul_f32_e32 v41, 0xbf1b4598, v41
	v_add_f32_e32 v43, 1.0, v43
	v_rcp_f32_e32 v42, v42
	s_nop 0
	v_mul_f32_e32 v42, 0xbf1b4598, v42
	v_mul_f32_e32 v40, 0x3fb8aa3b, v40
	v_mul_f32_e32 v41, 0x3fb8aa3b, v41
	v_rcp_f32_e32 v43, v43
	s_nop 0
	v_mul_f32_e32 v43, 0xbf1b4598, v43
	v_mul_f32_e32 v42, 0x3fb8aa3b, v42
	v_mul_f32_e32 v43, 0x3fb8aa3b, v43
	v_exp_f32_e32 v40, v40
	v_exp_f32_e32 v41, v41
	v_exp_f32_e32 v42, v42
	v_exp_f32_e32 v43, v43
	s_nop 0
	global_store_dwordx4 v[48:49], v[40:43], off offset:64
	global_load_dwordx4 v[40:43], v92, s[48:49] offset:128
	s_waitcnt vmcnt(0)
	v_add_f32_e32 v36, v36, v40
	v_mul_f32_e32 v36, 0xbfb8aa3b, v36
	v_exp_f32_e32 v36, v36
	v_add_f32_e32 v37, v37, v41
	v_mul_f32_e32 v37, 0xbfb8aa3b, v37
	v_exp_f32_e32 v37, v37
	v_add_f32_e32 v36, 1.0, v36
	v_add_f32_e32 v37, 1.0, v37
	v_add_f32_e32 v38, v38, v42
	v_mul_f32_e32 v38, 0xbfb8aa3b, v38
	v_rcp_f32_e32 v36, v36
	v_exp_f32_e32 v38, v38
	v_add_f32_e32 v39, v39, v43
	v_mul_f32_e32 v39, 0xbfb8aa3b, v39
	v_add_f32_e32 v38, 1.0, v38
	v_rcp_f32_e32 v37, v37
	v_exp_f32_e32 v39, v39
	v_mul_f32_e32 v36, 0xbf1b4598, v36
	v_mul_f32_e32 v37, 0xbf1b4598, v37
	v_add_f32_e32 v39, 1.0, v39
	v_rcp_f32_e32 v38, v38
	s_nop 0
	v_mul_f32_e32 v38, 0xbf1b4598, v38
	v_mul_f32_e32 v36, 0x3fb8aa3b, v36
	v_mul_f32_e32 v37, 0x3fb8aa3b, v37
	v_rcp_f32_e32 v39, v39
	s_nop 0
	v_mul_f32_e32 v39, 0xbf1b4598, v39
	v_mul_f32_e32 v38, 0x3fb8aa3b, v38
	v_mul_f32_e32 v39, 0x3fb8aa3b, v39
	v_exp_f32_e32 v36, v36
	v_exp_f32_e32 v37, v37
	v_exp_f32_e32 v38, v38
	v_exp_f32_e32 v39, v39
	s_nop 0
	global_store_dwordx4 v[48:49], v[36:39], off offset:128
	global_load_dwordx4 v[36:39], v92, s[48:49] offset:192
	s_waitcnt vmcnt(0)
	v_add_f32_e32 v32, v32, v36
	v_mul_f32_e32 v32, 0xbfb8aa3b, v32
	v_exp_f32_e32 v32, v32
	v_add_f32_e32 v33, v33, v37
	v_mul_f32_e32 v33, 0xbfb8aa3b, v33
	v_exp_f32_e32 v33, v33
	v_add_f32_e32 v32, 1.0, v32
	v_add_f32_e32 v33, 1.0, v33
	v_add_f32_e32 v34, v34, v38
	v_mul_f32_e32 v34, 0xbfb8aa3b, v34
	v_rcp_f32_e32 v32, v32
	v_exp_f32_e32 v34, v34
	v_add_f32_e32 v35, v35, v39
	v_mul_f32_e32 v35, 0xbfb8aa3b, v35
	v_add_f32_e32 v34, 1.0, v34
	v_rcp_f32_e32 v33, v33
	v_exp_f32_e32 v35, v35
	v_mul_f32_e32 v32, 0xbf1b4598, v32
	v_mul_f32_e32 v33, 0xbf1b4598, v33
	v_add_f32_e32 v35, 1.0, v35
	v_rcp_f32_e32 v34, v34
	s_nop 0
	v_mul_f32_e32 v34, 0xbf1b4598, v34
	v_mul_f32_e32 v32, 0x3fb8aa3b, v32
	v_mul_f32_e32 v33, 0x3fb8aa3b, v33
	v_rcp_f32_e32 v35, v35
	s_nop 0
	v_mul_f32_e32 v35, 0xbf1b4598, v35
	v_mul_f32_e32 v34, 0x3fb8aa3b, v34
	v_mul_f32_e32 v35, 0x3fb8aa3b, v35
	v_exp_f32_e32 v32, v32
	v_exp_f32_e32 v33, v33
	v_exp_f32_e32 v34, v34
	v_exp_f32_e32 v35, v35
	s_nop 0
	global_store_dwordx4 v[48:49], v[32:35], off offset:192
	s_nop 1
	v_or_b32_e32 v32, 32, v94
	v_ashrrev_i32_e32 v33, 31, v32
	v_lshlrev_b64 v[32:33], 12, v[32:33]
	v_lshl_add_u64 v[36:37], s[4:5], 0, v[32:33]
	global_load_dwordx4 v[32:35], v92, s[48:49]
	s_waitcnt vmcnt(0)
	v_add_f32_e32 v28, v28, v32
	v_mul_f32_e32 v28, 0xbfb8aa3b, v28
	v_exp_f32_e32 v28, v28
	v_add_f32_e32 v29, v29, v33
	v_mul_f32_e32 v29, 0xbfb8aa3b, v29
	v_exp_f32_e32 v29, v29
	v_add_f32_e32 v28, 1.0, v28
	v_add_f32_e32 v29, 1.0, v29
	v_add_f32_e32 v30, v30, v34
	v_mul_f32_e32 v30, 0xbfb8aa3b, v30
	v_rcp_f32_e32 v28, v28
	v_exp_f32_e32 v30, v30
	v_add_f32_e32 v31, v31, v35
	v_mul_f32_e32 v31, 0xbfb8aa3b, v31
	v_add_f32_e32 v30, 1.0, v30
	v_rcp_f32_e32 v29, v29
	v_exp_f32_e32 v31, v31
	v_mul_f32_e32 v28, 0xbf1b4598, v28
	v_mul_f32_e32 v29, 0xbf1b4598, v29
	v_add_f32_e32 v31, 1.0, v31
	v_rcp_f32_e32 v30, v30
	s_nop 0
	v_mul_f32_e32 v30, 0xbf1b4598, v30
	v_mul_f32_e32 v28, 0x3fb8aa3b, v28
	v_mul_f32_e32 v29, 0x3fb8aa3b, v29
	v_rcp_f32_e32 v31, v31
	s_nop 0
	v_mul_f32_e32 v31, 0xbf1b4598, v31
	v_mul_f32_e32 v30, 0x3fb8aa3b, v30
	v_mul_f32_e32 v31, 0x3fb8aa3b, v31
	v_exp_f32_e32 v28, v28
	v_exp_f32_e32 v29, v29
	v_exp_f32_e32 v30, v30
	v_exp_f32_e32 v31, v31
	v_lshl_add_u64 v[32:33], v[36:37], 0, v[92:93]
	global_store_dwordx4 v[32:33], v[28:31], off
	global_load_dwordx4 v[28:31], v92, s[48:49] offset:64
	s_waitcnt vmcnt(0)
	v_add_f32_e32 v24, v24, v28
	v_mul_f32_e32 v24, 0xbfb8aa3b, v24
	v_exp_f32_e32 v24, v24
	v_add_f32_e32 v25, v25, v29
	v_mul_f32_e32 v25, 0xbfb8aa3b, v25
	v_exp_f32_e32 v25, v25
	v_add_f32_e32 v24, 1.0, v24
	v_add_f32_e32 v25, 1.0, v25
	v_add_f32_e32 v26, v26, v30
	v_mul_f32_e32 v26, 0xbfb8aa3b, v26
	v_rcp_f32_e32 v24, v24
	v_exp_f32_e32 v26, v26
	v_add_f32_e32 v27, v27, v31
	v_mul_f32_e32 v27, 0xbfb8aa3b, v27
	v_add_f32_e32 v26, 1.0, v26
	v_rcp_f32_e32 v25, v25
	v_exp_f32_e32 v27, v27
	v_mul_f32_e32 v24, 0xbf1b4598, v24
	v_mul_f32_e32 v25, 0xbf1b4598, v25
	v_add_f32_e32 v27, 1.0, v27
	v_rcp_f32_e32 v26, v26
	s_nop 0
	v_mul_f32_e32 v26, 0xbf1b4598, v26
	v_mul_f32_e32 v24, 0x3fb8aa3b, v24
	v_mul_f32_e32 v25, 0x3fb8aa3b, v25
	v_rcp_f32_e32 v27, v27
	s_nop 0
	v_mul_f32_e32 v27, 0xbf1b4598, v27
	v_mul_f32_e32 v26, 0x3fb8aa3b, v26
	v_mul_f32_e32 v27, 0x3fb8aa3b, v27
	v_exp_f32_e32 v24, v24
	v_exp_f32_e32 v25, v25
	v_exp_f32_e32 v26, v26
	v_exp_f32_e32 v27, v27
	s_nop 0
	global_store_dwordx4 v[32:33], v[24:27], off offset:64
	global_load_dwordx4 v[24:27], v92, s[48:49] offset:128
	s_waitcnt vmcnt(0)
	v_add_f32_e32 v20, v20, v24
	v_mul_f32_e32 v20, 0xbfb8aa3b, v20
	v_exp_f32_e32 v20, v20
	v_add_f32_e32 v21, v21, v25
	v_mul_f32_e32 v21, 0xbfb8aa3b, v21
	v_exp_f32_e32 v21, v21
	v_add_f32_e32 v20, 1.0, v20
	v_add_f32_e32 v21, 1.0, v21
	v_add_f32_e32 v22, v22, v26
	v_mul_f32_e32 v22, 0xbfb8aa3b, v22
	v_rcp_f32_e32 v20, v20
	v_exp_f32_e32 v22, v22
	v_add_f32_e32 v23, v23, v27
	v_mul_f32_e32 v23, 0xbfb8aa3b, v23
	v_add_f32_e32 v22, 1.0, v22
	v_rcp_f32_e32 v21, v21
	v_exp_f32_e32 v23, v23
	v_mul_f32_e32 v20, 0xbf1b4598, v20
	v_mul_f32_e32 v21, 0xbf1b4598, v21
	v_add_f32_e32 v23, 1.0, v23
	v_rcp_f32_e32 v22, v22
	s_nop 0
	v_mul_f32_e32 v22, 0xbf1b4598, v22
	v_mul_f32_e32 v20, 0x3fb8aa3b, v20
	v_mul_f32_e32 v21, 0x3fb8aa3b, v21
	v_rcp_f32_e32 v23, v23
	s_nop 0
	v_mul_f32_e32 v23, 0xbf1b4598, v23
	v_mul_f32_e32 v22, 0x3fb8aa3b, v22
	v_mul_f32_e32 v23, 0x3fb8aa3b, v23
	v_exp_f32_e32 v20, v20
	v_exp_f32_e32 v21, v21
	v_exp_f32_e32 v22, v22
	v_exp_f32_e32 v23, v23
	s_nop 0
	global_store_dwordx4 v[32:33], v[20:23], off offset:128
	global_load_dwordx4 v[20:23], v92, s[48:49] offset:192
	s_waitcnt vmcnt(0)
	v_add_f32_e32 v16, v16, v20
	v_mul_f32_e32 v16, 0xbfb8aa3b, v16
	v_exp_f32_e32 v16, v16
	v_add_f32_e32 v17, v17, v21
	v_mul_f32_e32 v17, 0xbfb8aa3b, v17
	v_exp_f32_e32 v17, v17
	v_add_f32_e32 v16, 1.0, v16
	v_add_f32_e32 v17, 1.0, v17
	v_add_f32_e32 v18, v18, v22
	v_mul_f32_e32 v18, 0xbfb8aa3b, v18
	v_rcp_f32_e32 v16, v16
	v_exp_f32_e32 v18, v18
	v_add_f32_e32 v19, v19, v23
	v_mul_f32_e32 v19, 0xbfb8aa3b, v19
	v_add_f32_e32 v18, 1.0, v18
	v_rcp_f32_e32 v17, v17
	v_exp_f32_e32 v19, v19
	v_mul_f32_e32 v16, 0xbf1b4598, v16
	v_mul_f32_e32 v17, 0xbf1b4598, v17
	v_add_f32_e32 v19, 1.0, v19
	v_rcp_f32_e32 v18, v18
	s_nop 0
	v_mul_f32_e32 v18, 0xbf1b4598, v18
	v_mul_f32_e32 v16, 0x3fb8aa3b, v16
	v_mul_f32_e32 v17, 0x3fb8aa3b, v17
	v_rcp_f32_e32 v19, v19
	s_nop 0
	v_mul_f32_e32 v19, 0xbf1b4598, v19
	v_mul_f32_e32 v18, 0x3fb8aa3b, v18
	v_mul_f32_e32 v19, 0x3fb8aa3b, v19
	v_exp_f32_e32 v16, v16
	v_exp_f32_e32 v17, v17
	v_exp_f32_e32 v18, v18
	v_exp_f32_e32 v19, v19
	s_nop 0
	global_store_dwordx4 v[32:33], v[16:19], off offset:192
	s_nop 1
	v_or_b32_e32 v16, 48, v94
	v_ashrrev_i32_e32 v17, 31, v16
	v_lshlrev_b64 v[16:17], 12, v[16:17]
	v_lshl_add_u64 v[20:21], s[4:5], 0, v[16:17]
	global_load_dwordx4 v[16:19], v92, s[48:49]
	s_waitcnt vmcnt(0)
	v_add_f32_e32 v12, v12, v16
	v_mul_f32_e32 v12, 0xbfb8aa3b, v12
	v_exp_f32_e32 v12, v12
	v_add_f32_e32 v13, v13, v17
	v_mul_f32_e32 v13, 0xbfb8aa3b, v13
	v_exp_f32_e32 v13, v13
	v_add_f32_e32 v12, 1.0, v12
	v_add_f32_e32 v13, 1.0, v13
	v_add_f32_e32 v14, v14, v18
	v_mul_f32_e32 v14, 0xbfb8aa3b, v14
	v_rcp_f32_e32 v12, v12
	v_exp_f32_e32 v14, v14
	v_add_f32_e32 v15, v15, v19
	v_mul_f32_e32 v15, 0xbfb8aa3b, v15
	v_add_f32_e32 v14, 1.0, v14
	v_rcp_f32_e32 v13, v13
	v_exp_f32_e32 v15, v15
	v_mul_f32_e32 v12, 0xbf1b4598, v12
	v_mul_f32_e32 v13, 0xbf1b4598, v13
	v_add_f32_e32 v15, 1.0, v15
	v_rcp_f32_e32 v14, v14
	s_nop 0
	v_mul_f32_e32 v14, 0xbf1b4598, v14
	v_mul_f32_e32 v12, 0x3fb8aa3b, v12
	v_mul_f32_e32 v13, 0x3fb8aa3b, v13
	v_rcp_f32_e32 v15, v15
	s_nop 0
	v_mul_f32_e32 v15, 0xbf1b4598, v15
	v_mul_f32_e32 v14, 0x3fb8aa3b, v14
	v_mul_f32_e32 v15, 0x3fb8aa3b, v15
	v_exp_f32_e32 v12, v12
	v_exp_f32_e32 v13, v13
	v_exp_f32_e32 v14, v14
	v_exp_f32_e32 v15, v15
	v_lshl_add_u64 v[16:17], v[20:21], 0, v[92:93]
	global_store_dwordx4 v[16:17], v[12:15], off
	global_load_dwordx4 v[12:15], v92, s[48:49] offset:64
	s_waitcnt vmcnt(0)
	v_add_f32_e32 v8, v8, v12
	v_mul_f32_e32 v8, 0xbfb8aa3b, v8
	v_exp_f32_e32 v8, v8
	v_add_f32_e32 v9, v9, v13
	v_mul_f32_e32 v9, 0xbfb8aa3b, v9
	v_exp_f32_e32 v9, v9
	v_add_f32_e32 v8, 1.0, v8
	v_add_f32_e32 v9, 1.0, v9
	v_add_f32_e32 v10, v10, v14
	v_mul_f32_e32 v10, 0xbfb8aa3b, v10
	v_rcp_f32_e32 v8, v8
	v_exp_f32_e32 v10, v10
	v_add_f32_e32 v11, v11, v15
	v_mul_f32_e32 v11, 0xbfb8aa3b, v11
	v_add_f32_e32 v10, 1.0, v10
	v_rcp_f32_e32 v9, v9
	v_exp_f32_e32 v11, v11
	v_mul_f32_e32 v8, 0xbf1b4598, v8
	v_mul_f32_e32 v9, 0xbf1b4598, v9
	v_add_f32_e32 v11, 1.0, v11
	v_rcp_f32_e32 v10, v10
	s_nop 0
	v_mul_f32_e32 v10, 0xbf1b4598, v10
	v_mul_f32_e32 v8, 0x3fb8aa3b, v8
	v_mul_f32_e32 v9, 0x3fb8aa3b, v9
	v_rcp_f32_e32 v11, v11
	s_nop 0
	v_mul_f32_e32 v11, 0xbf1b4598, v11
	v_mul_f32_e32 v10, 0x3fb8aa3b, v10
	v_mul_f32_e32 v11, 0x3fb8aa3b, v11
	v_exp_f32_e32 v8, v8
	v_exp_f32_e32 v9, v9
	v_exp_f32_e32 v10, v10
	v_exp_f32_e32 v11, v11
	s_nop 0
	global_store_dwordx4 v[16:17], v[8:11], off offset:64
	global_load_dwordx4 v[8:11], v92, s[48:49] offset:128
	s_waitcnt vmcnt(0)
	v_add_f32_e32 v4, v4, v8
	v_mul_f32_e32 v4, 0xbfb8aa3b, v4
	v_exp_f32_e32 v4, v4
	v_add_f32_e32 v5, v5, v9
	v_mul_f32_e32 v5, 0xbfb8aa3b, v5
	v_exp_f32_e32 v5, v5
	v_add_f32_e32 v4, 1.0, v4
	v_add_f32_e32 v5, 1.0, v5
	v_add_f32_e32 v6, v6, v10
	v_mul_f32_e32 v6, 0xbfb8aa3b, v6
	v_rcp_f32_e32 v4, v4
	v_exp_f32_e32 v6, v6
	v_add_f32_e32 v7, v7, v11
	v_mul_f32_e32 v7, 0xbfb8aa3b, v7
	v_add_f32_e32 v6, 1.0, v6
	v_rcp_f32_e32 v5, v5
	v_exp_f32_e32 v7, v7
	v_mul_f32_e32 v4, 0xbf1b4598, v4
	v_mul_f32_e32 v5, 0xbf1b4598, v5
	v_add_f32_e32 v7, 1.0, v7
	v_rcp_f32_e32 v6, v6
	s_nop 0
	v_mul_f32_e32 v6, 0xbf1b4598, v6
	v_mul_f32_e32 v4, 0x3fb8aa3b, v4
	v_mul_f32_e32 v5, 0x3fb8aa3b, v5
	v_rcp_f32_e32 v7, v7
	s_nop 0
	v_mul_f32_e32 v7, 0xbf1b4598, v7
	v_mul_f32_e32 v6, 0x3fb8aa3b, v6
	v_mul_f32_e32 v7, 0x3fb8aa3b, v7
	v_exp_f32_e32 v4, v4
	v_exp_f32_e32 v5, v5
	v_exp_f32_e32 v6, v6
	v_exp_f32_e32 v7, v7
	s_nop 0
	global_store_dwordx4 v[16:17], v[4:7], off offset:128
	global_load_dwordx4 v[4:7], v92, s[48:49] offset:192
	s_waitcnt vmcnt(0)
	v_add_f32_e32 v0, v0, v4
	v_mul_f32_e32 v0, 0xbfb8aa3b, v0
	v_exp_f32_e32 v0, v0
	v_add_f32_e32 v1, v1, v5
	v_mul_f32_e32 v1, 0xbfb8aa3b, v1
	v_exp_f32_e32 v1, v1
	v_add_f32_e32 v0, 1.0, v0
	v_add_f32_e32 v1, 1.0, v1
	v_add_f32_e32 v2, v2, v6
	v_mul_f32_e32 v2, 0xbfb8aa3b, v2
	v_rcp_f32_e32 v0, v0
	v_exp_f32_e32 v2, v2
	v_add_f32_e32 v3, v3, v7
	v_mul_f32_e32 v3, 0xbfb8aa3b, v3
	v_add_f32_e32 v2, 1.0, v2
	v_rcp_f32_e32 v1, v1
	v_exp_f32_e32 v3, v3
	v_mul_f32_e32 v0, 0xbf1b4598, v0
	v_mul_f32_e32 v1, 0xbf1b4598, v1
	v_add_f32_e32 v3, 1.0, v3
	v_rcp_f32_e32 v2, v2
	s_nop 0
	v_mul_f32_e32 v2, 0xbf1b4598, v2
	v_mul_f32_e32 v0, 0x3fb8aa3b, v0
	v_mul_f32_e32 v1, 0x3fb8aa3b, v1
	v_rcp_f32_e32 v3, v3
	s_nop 0
	v_mul_f32_e32 v3, 0xbf1b4598, v3
	v_mul_f32_e32 v2, 0x3fb8aa3b, v2
	v_mul_f32_e32 v3, 0x3fb8aa3b, v3
	v_exp_f32_e32 v0, v0
	v_exp_f32_e32 v1, v1
	v_exp_f32_e32 v2, v2
	v_exp_f32_e32 v3, v3
	s_nop 0
	global_store_dwordx4 v[16:17], v[0:3], off offset:192

.LBB0_388:
	s_andn2_b64 vcc, exec, s[0:1]
	s_cbranch_vccnz .LBB0_390
	s_add_i32 s0, s67, 0xfffffbe0
	s_lshr_b32 s2, s0, 3
	s_and_b32 s7, s67, 7
	s_lshl_b64 s[0:1], s[2:3], 18
	s_add_u32 s0, s70, s0
	s_addc_u32 s1, s71, s1
	s_lshl_b32 s6, s7, 7
	s_lshl_b32 s9, s7, 8
	s_add_u32 s46, s0, s9
	s_addc_u32 s47, s1, 0
	s_or_b32 s0, s7, s66
	s_ashr_i32 s1, s0, 31
	s_lshl_b64 vcc, s[0:1], 15
	v_lshl_add_u64 v[0:1], s[46:47], 0, v[78:79]
	v_mov_b32_e32 v91, v97
	v_readfirstlane_b32 s1, v126
	v_lshl_add_u64 v[104:105], v[0:1], 0, v[90:91]
	s_mov_b32 m0, s1
	v_readfirstlane_b32 s1, v196
	s_waitcnt vmcnt(63) expcnt(7) lgkmcnt(15)
	s_barrier
	v_lshl_add_u64 v[0:1], v[80:81], 0, vcc
	global_load_lds_dwordx4 v[104:105], off
	s_mov_b32 m0, s1
	s_mov_b64 s[44:45], 0x10000
	v_readfirstlane_b32 s1, v195
	global_load_lds_dwordx4 v[0:1], off
	v_lshl_add_u64 v[102:103], v[104:105], 0, s[44:45]
	s_mov_b32 m0, s1
	s_mov_b64 s[8:9], 0x2000
	v_readfirstlane_b32 s1, v194
	global_load_lds_dwordx4 v[102:103], off
	v_lshl_add_u64 v[2:3], v[0:1], 0, s[8:9]
	s_mov_b32 m0, s1
	s_mov_b64 s[44:45], 0x20000
	v_readfirstlane_b32 s1, v193
	global_load_lds_dwordx4 v[2:3], off
	v_lshl_add_u64 v[100:101], v[104:105], 0, s[44:45]
	s_mov_b32 m0, s1
	s_mov_b64 s[62:63], 0x4000
	v_readfirstlane_b32 s1, v192
	global_load_lds_dwordx4 v[100:101], off
	v_lshl_add_u64 v[2:3], v[0:1], 0, s[62:63]
	s_mov_b32 m0, s1
	s_mov_b64 s[44:45], 0x30000
	v_readfirstlane_b32 s1, v191
	global_load_lds_dwordx4 v[2:3], off
	v_lshl_add_u64 v[94:95], v[104:105], 0, s[44:45]
	s_mov_b32 m0, s1
	s_mov_b64 s[38:39], 0x6000
	v_readfirstlane_b32 s1, v190
	v_add_u32_e32 v204, 0x8000, v126
	global_load_lds_dwordx4 v[94:95], off
	v_lshl_add_u64 v[2:3], v[0:1], 0, s[38:39]
	s_mov_b32 m0, s1
	s_mov_b64 s[46:47], 0x30080
	s_mov_b64 s[44:45], 0x80
	v_readfirstlane_b32 s1, v204
	v_add_u32_e32 v203, 0xc000, v126
	global_load_lds_dwordx4 v[2:3], off
	s_mov_b64 s[4:5], 0x6080
	v_lshl_add_u64 v[64:65], v[104:105], 0, s[46:47]
	s_mov_b64 s[92:93], 0x4080
	s_mov_b64 s[46:47], 0x20080
	s_mov_b64 s[88:89], 0x2080
	v_lshl_add_u64 v[92:93], v[104:105], 0, s[44:45]
	s_mov_b32 m0, s1
	v_readfirstlane_b32 s1, v203
	v_add_u32_e32 v202, 0x9000, v126
	s_waitcnt vmcnt(0)
	s_waitcnt vmcnt(0) lgkmcnt(0)
	s_barrier
	v_lshl_add_u64 v[2:3], v[0:1], 0, s[4:5]
	v_lshl_add_u64 v[4:5], v[0:1], 0, s[92:93]
	v_lshl_add_u64 v[66:67], v[104:105], 0, s[46:47]
	v_lshl_add_u64 v[6:7], v[0:1], 0, s[88:89]
	s_mov_b64 s[46:47], 0x10080
	v_lshl_add_u64 v[0:1], v[0:1], 0, s[44:45]
	global_load_lds_dwordx4 v[92:93], off
	s_mov_b32 m0, s1
	v_readfirstlane_b32 s1, v202
	v_add_u32_e32 v201, 0xd000, v126
	v_lshl_add_u64 v[90:91], v[104:105], 0, s[46:47]
	global_load_lds_dwordx4 v[0:1], off
	s_mov_b32 m0, s1
	v_readfirstlane_b32 s1, v201
	v_add_u32_e32 v200, 0xa000, v126
	global_load_lds_dwordx4 v[90:91], off
	s_mov_b32 m0, s1
	v_readfirstlane_b32 s1, v200
	v_add_u32_e32 v199, 0xe000, v126
	global_load_lds_dwordx4 v[6:7], off
	s_mov_b32 m0, s1
	v_readfirstlane_b32 s1, v199
	v_add_u32_e32 v198, 0xb000, v126
	global_load_lds_dwordx4 v[66:67], off
	s_mov_b32 m0, s1
	v_readfirstlane_b32 s1, v198
	v_add_u32_e32 v197, 0xf000, v126
	global_load_lds_dwordx4 v[4:5], off
	s_mov_b32 m0, s1
	v_readfirstlane_b32 s1, v197
	global_load_lds_dwordx4 v[64:65], off
	s_mov_b32 m0, s1
	s_nop 0
	global_load_lds_dwordx4 v[2:3], off
	ds_read_b128 v[0:3], v188
	ds_read_b128 v[4:7], v188 offset:2048
	ds_read_b128 v[8:11], v188 offset:4096
	ds_read_b128 v[12:15], v188 offset:6144
	ds_read_b128 v[16:19], v189 offset:16384
	ds_read_b128 v[20:23], v189 offset:18432
	ds_read_b128 v[24:27], v189 offset:20480
	ds_read_b128 v[28:31], v189 offset:22528
	s_setprio 1
	s_waitcnt lgkmcnt(0)
	v_mfma_f32_16x16x32_bf16 v[32:35], v[16:19], v[0:3], 0
	v_mfma_f32_16x16x32_bf16 v[36:39], v[20:23], v[0:3], 0
	v_mfma_f32_16x16x32_bf16 v[40:43], v[24:27], v[0:3], 0
	v_mfma_f32_16x16x32_bf16 v[0:3], v[28:31], v[0:3], 0
	v_mfma_f32_16x16x32_bf16 v[44:47], v[16:19], v[4:7], 0
	v_mfma_f32_16x16x32_bf16 v[48:51], v[20:23], v[4:7], 0
	v_mfma_f32_16x16x32_bf16 v[52:55], v[24:27], v[4:7], 0
	v_mfma_f32_16x16x32_bf16 v[4:7], v[28:31], v[4:7], 0
	v_mfma_f32_16x16x32_bf16 v[56:59], v[16:19], v[8:11], 0
	v_mfma_f32_16x16x32_bf16 v[60:63], v[20:23], v[8:11], 0
	v_mfma_f32_16x16x32_bf16 v[106:109], v[24:27], v[8:11], 0
	v_mfma_f32_16x16x32_bf16 v[8:11], v[28:31], v[8:11], 0
	v_mfma_f32_16x16x32_bf16 v[16:19], v[16:19], v[12:15], 0
	v_mfma_f32_16x16x32_bf16 v[20:23], v[20:23], v[12:15], 0
	v_mfma_f32_16x16x32_bf16 v[24:27], v[24:27], v[12:15], 0
	v_mfma_f32_16x16x32_bf16 v[12:15], v[28:31], v[12:15], 0
	s_setprio 0
	ds_read_b128 v[28:31], v89
	ds_read_b128 v[110:113], v89 offset:2048
	ds_read_b128 v[206:209], v89 offset:4096
	ds_read_b128 v[210:213], v89 offset:6144
	ds_read_b128 v[214:217], v85 offset:16384
	ds_read_b128 v[218:221], v85 offset:18432
	ds_read_b128 v[222:225], v85 offset:20480
	ds_read_b128 v[226:229], v85 offset:22528
	s_setprio 1
	s_waitcnt lgkmcnt(0)
	v_mfma_f32_16x16x32_bf16 v[32:35], v[214:217], v[28:31], v[32:35]
	v_mfma_f32_16x16x32_bf16 v[36:39], v[218:221], v[28:31], v[36:39]
	v_mfma_f32_16x16x32_bf16 v[40:43], v[222:225], v[28:31], v[40:43]
	v_mfma_f32_16x16x32_bf16 v[0:3], v[226:229], v[28:31], v[0:3]
	v_mfma_f32_16x16x32_bf16 v[28:31], v[214:217], v[110:113], v[44:47]
	v_mfma_f32_16x16x32_bf16 v[44:47], v[218:221], v[110:113], v[48:51]
	v_mfma_f32_16x16x32_bf16 v[48:51], v[222:225], v[110:113], v[52:55]
	v_mfma_f32_16x16x32_bf16 v[4:7], v[226:229], v[110:113], v[4:7]
	v_mfma_f32_16x16x32_bf16 v[52:55], v[214:217], v[206:209], v[56:59]
	v_mfma_f32_16x16x32_bf16 v[56:59], v[218:221], v[206:209], v[60:63]
	v_mfma_f32_16x16x32_bf16 v[60:63], v[222:225], v[206:209], v[106:109]
	v_mfma_f32_16x16x32_bf16 v[8:11], v[226:229], v[206:209], v[8:11]
	v_mfma_f32_16x16x32_bf16 v[16:19], v[214:217], v[210:213], v[16:19]
	v_mfma_f32_16x16x32_bf16 v[20:23], v[218:221], v[210:213], v[20:23]
	v_mfma_f32_16x16x32_bf16 v[24:27], v[222:225], v[210:213], v[24:27]
	v_mfma_f32_16x16x32_bf16 v[12:15], v[226:229], v[210:213], v[12:15]
	s_setprio 0
	s_waitcnt vmcnt(0)
	s_waitcnt vmcnt(0)
	s_barrier
	ds_read_b128 v[106:109], v189 offset:55296
	ds_read_b128 v[110:113], v189 offset:53248
	ds_read_b128 v[206:209], v189 offset:51200
	ds_read_b128 v[210:213], v189 offset:49152
	ds_read_b128 v[214:217], v188 offset:38912
	ds_read_b128 v[218:221], v188 offset:36864
	ds_read_b128 v[222:225], v188 offset:34816
	ds_read_b128 v[226:229], v188 offset:32768
	s_setprio 1
	s_waitcnt lgkmcnt(0)
	v_mfma_f32_16x16x32_bf16 v[32:35], v[210:213], v[226:229], v[32:35]
	v_mfma_f32_16x16x32_bf16 v[36:39], v[206:209], v[226:229], v[36:39]
	v_mfma_f32_16x16x32_bf16 v[40:43], v[110:113], v[226:229], v[40:43]
	v_mfma_f32_16x16x32_bf16 v[0:3], v[106:109], v[226:229], v[0:3]
	v_mfma_f32_16x16x32_bf16 v[28:31], v[210:213], v[222:225], v[28:31]
	v_mfma_f32_16x16x32_bf16 v[226:229], v[206:209], v[222:225], v[44:47]
	v_mfma_f32_16x16x32_bf16 v[230:233], v[110:113], v[222:225], v[48:51]
	v_mfma_f32_16x16x32_bf16 v[4:7], v[106:109], v[222:225], v[4:7]
	v_mfma_f32_16x16x32_bf16 v[222:225], v[210:213], v[218:221], v[52:55]
	v_mfma_f32_16x16x32_bf16 v[234:237], v[206:209], v[218:221], v[56:59]
	v_mfma_f32_16x16x32_bf16 v[60:63], v[110:113], v[218:221], v[60:63]
	v_mfma_f32_16x16x32_bf16 v[8:11], v[106:109], v[218:221], v[8:11]
	v_mfma_f32_16x16x32_bf16 v[210:213], v[210:213], v[214:217], v[16:19]
	v_mfma_f32_16x16x32_bf16 v[206:209], v[206:209], v[214:217], v[20:23]
	v_mfma_f32_16x16x32_bf16 v[110:113], v[110:113], v[214:217], v[24:27]
	v_mfma_f32_16x16x32_bf16 v[106:109], v[106:109], v[214:217], v[12:15]
	s_setprio 0
	s_nop 1
	ds_read_b128 v[12:15], v89 offset:32768
	ds_read_b128 v[16:19], v89 offset:34816
	ds_read_b128 v[214:217], v89 offset:36864
	ds_read_b128 v[218:221], v89 offset:38912
	ds_read_b128 v[238:241], v85 offset:49152
	ds_read_b128 v[242:245], v85 offset:51200
	ds_read_b128 v[246:249], v85 offset:53248
	ds_read_b128 v[156:159], v85 offset:55296
	s_setprio 1
	s_waitcnt lgkmcnt(3)
	v_mfma_f32_16x16x32_bf16 v[166:169], v[238:241], v[12:15], v[32:35]
	s_waitcnt lgkmcnt(2)
	v_mfma_f32_16x16x32_bf16 v[56:59], v[242:245], v[12:15], v[36:39]
	s_waitcnt lgkmcnt(1)
	v_mfma_f32_16x16x32_bf16 v[52:55], v[246:249], v[12:15], v[40:43]
	s_waitcnt lgkmcnt(0)
	v_mfma_f32_16x16x32_bf16 v[48:51], v[156:159], v[12:15], v[0:3]
	v_mfma_f32_16x16x32_bf16 v[44:47], v[238:241], v[16:19], v[28:31]
	v_mfma_f32_16x16x32_bf16 v[40:43], v[242:245], v[16:19], v[226:229]
	v_mfma_f32_16x16x32_bf16 v[36:39], v[246:249], v[16:19], v[230:233]
	v_mfma_f32_16x16x32_bf16 v[32:35], v[156:159], v[16:19], v[4:7]
	v_mfma_f32_16x16x32_bf16 v[28:31], v[238:241], v[214:217], v[222:225]
	v_mfma_f32_16x16x32_bf16 v[24:27], v[242:245], v[214:217], v[234:237]
	v_mfma_f32_16x16x32_bf16 v[20:23], v[246:249], v[214:217], v[60:63]
	v_mfma_f32_16x16x32_bf16 v[16:19], v[156:159], v[214:217], v[8:11]
	v_mfma_f32_16x16x32_bf16 v[12:15], v[238:241], v[218:221], v[210:213]
	v_mfma_f32_16x16x32_bf16 v[8:11], v[242:245], v[218:221], v[206:209]
	v_mfma_f32_16x16x32_bf16 v[4:7], v[246:249], v[218:221], v[110:113]
	v_mfma_f32_16x16x32_bf16 v[0:3], v[156:159], v[218:221], v[106:109]
	s_setprio 0
	v_mov_b32_e32 v60, v97
	s_waitcnt vmcnt(0)
	s_barrier
	s_lshl_b32 s1, s2, 7
	v_add_u32_e32 v60, v60, v176
	v_ashrrev_i32_e32 v62, 1, v60
	v_lshrrev_b32_e32 v63, 2, v60
	v_and_b32_e32 v61, 64, v60
	v_and_b32_e32 v62, 0xffffffc0, v62
	v_and_b32_e32 v63, 12, v63
	v_and_or_b32 v60, v60, 15, s1
	v_add_u32_e32 v106, v60, v62
	v_or3_b32 v108, v61, v63, s6
	v_ashrrev_i32_e32 v107, 31, v106
	s_mov_b64 s[4:5], s[34:35]
	v_readlane_b32 s34, v254, 57
	v_lshlrev_b64 v[60:61], 11, v[106:107]
	v_readlane_b32 s35, v254, 58
	v_lshlrev_b32_e32 v107, 2, v108
	v_lshlrev_b32_e32 v108, 1, v108
	v_lshl_add_u64 v[110:111], s[34:35], 0, v[60:61]
	global_load_dwordx4 v[60:63], v107, s[14:15]
	v_mov_b32_e32 v109, v97
	v_lshl_add_u64 v[110:111], v[110:111], 0, v[108:109]
	s_waitcnt vmcnt(0)
	v_add_f32_e32 v60, v166, v60
	v_mul_f32_e32 v60, 0xbfb8aa3b, v60
	v_exp_f32_e32 v112, v60
	v_add_f32_e32 v60, v167, v61
	v_mul_f32_e32 v60, 0xbfb8aa3b, v60
	v_exp_f32_e32 v114, v60
	v_add_f32_e32 v60, v168, v62
	v_mul_f32_e32 v60, 0xbfb8aa3b, v60
	v_exp_f32_e32 v113, v60
	v_add_f32_e32 v60, v169, v63
	v_mul_f32_e32 v60, 0xbfb8aa3b, v60
	v_exp_f32_e32 v115, v60
	global_load_dwordx4 v[60:63], v107, s[12:13]
	v_pk_add_f32 v[112:113], v[112:113], 1.0 op_sel_hi:[1,0]
	v_pk_add_f32 v[114:115], v[114:115], 1.0 op_sel_hi:[1,0]
	s_nop 0
	v_rcp_f32_e32 v113, v113
	s_nop 0
	v_rcp_f32_e32 v112, v112
	s_waitcnt vmcnt(0)
	v_mov_b32_e32 v156, v60
	v_div_scale_f32 v60, s[46:47], v115, v115, 1.0
	v_mov_b32_e32 v157, v62
	v_rcp_f32_e32 v62, v60
	v_pk_mul_f32 v[112:113], v[156:157], v[112:113]
	v_fma_f32 v156, -v60, v62, 1.0
	v_fmac_f32_e32 v62, v156, v62
	v_div_scale_f32 v156, vcc, 1.0, v115, 1.0
	v_mul_f32_e32 v157, v156, v62
	v_fma_f32 v158, -v60, v157, v156
	v_fmac_f32_e32 v157, v158, v62
	v_fma_f32 v60, -v60, v157, v156
	v_div_fmas_f32 v60, v60, v62, v157
	v_div_fixup_f32 v115, v60, v115, 1.0
	s_nop 0
	v_rcp_f32_e32 v114, v114
	v_mov_b32_e32 v62, v61
	v_pk_mul_f32 v[60:61], v[62:63], v[114:115]
	v_and_b32_sdwa v62, v113, v154 dst_sel:DWORD dst_unused:UNUSED_PAD src0_sel:WORD_1 src1_sel:DWORD
	v_and_b32_sdwa v63, v112, v154 dst_sel:DWORD dst_unused:UNUSED_PAD src0_sel:WORD_1 src1_sel:DWORD
	v_add3_u32 v63, v112, v63, s33
	v_add3_u32 v62, v113, v62, s33
	v_and_b32_sdwa v112, v61, v154 dst_sel:DWORD dst_unused:UNUSED_PAD src0_sel:WORD_1 src1_sel:DWORD
	v_and_b32_sdwa v113, v60, v154 dst_sel:DWORD dst_unused:UNUSED_PAD src0_sel:WORD_1 src1_sel:DWORD
	v_add3_u32 v61, v61, v112, s33
	v_add3_u32 v60, v60, v113, s33
	v_and_b32_e32 v61, 0xffff0000, v61
	v_and_b32_e32 v60, 0xffff0000, v60
	v_or_b32_sdwa v61, v61, v62 dst_sel:DWORD dst_unused:UNUSED_PAD src0_sel:DWORD src1_sel:WORD_1
	v_or_b32_sdwa v60, v60, v63 dst_sel:DWORD dst_unused:UNUSED_PAD src0_sel:DWORD src1_sel:WORD_1
	global_store_dwordx2 v[110:111], v[60:61], off
	global_load_dwordx4 v[60:63], v107, s[14:15] offset:64
	s_waitcnt vmcnt(0)
	v_add_f32_e32 v56, v56, v60
	v_mul_f32_e32 v56, 0xbfb8aa3b, v56
	v_exp_f32_e32 v60, v56
	v_add_f32_e32 v56, v57, v61
	v_mul_f32_e32 v56, 0xbfb8aa3b, v56
	v_exp_f32_e32 v112, v56
	v_add_f32_e32 v56, v58, v62
	v_mul_f32_e32 v56, 0xbfb8aa3b, v56
	v_exp_f32_e32 v61, v56
	v_add_f32_e32 v56, v59, v63
	v_mul_f32_e32 v56, 0xbfb8aa3b, v56
	v_exp_f32_e32 v113, v56
	global_load_dwordx4 v[56:59], v107, s[12:13] offset:64
	v_pk_add_f32 v[60:61], v[60:61], 1.0 op_sel_hi:[1,0]
	s_nop 0
	s_nop 0
	v_rcp_f32_e32 v61, v61
	s_nop 0
	v_rcp_f32_e32 v60, v60
	s_waitcnt vmcnt(0)
	v_mov_b32_e32 v62, v56
	v_mov_b32_e32 v63, v58
	v_pk_mul_f32 v[60:61], v[62:63], v[60:61]
	v_pk_add_f32 v[62:63], v[112:113], 1.0 op_sel_hi:[1,0]
	s_nop 0
	s_nop 0
	v_rcp_f32_e32 v63, v63
	s_nop 0
	v_rcp_f32_e32 v62, v62
	v_mov_b32_e32 v58, v57
	v_pk_mul_f32 v[56:57], v[58:59], v[62:63]
	v_and_b32_sdwa v58, v61, v154 dst_sel:DWORD dst_unused:UNUSED_PAD src0_sel:WORD_1 src1_sel:DWORD
	v_and_b32_sdwa v59, v60, v154 dst_sel:DWORD dst_unused:UNUSED_PAD src0_sel:WORD_1 src1_sel:DWORD
	v_add3_u32 v59, v60, v59, s33
	v_add3_u32 v58, v61, v58, s33
	v_and_b32_sdwa v60, v57, v154 dst_sel:DWORD dst_unused:UNUSED_PAD src0_sel:WORD_1 src1_sel:DWORD
	v_and_b32_sdwa v61, v56, v154 dst_sel:DWORD dst_unused:UNUSED_PAD src0_sel:WORD_1 src1_sel:DWORD
	v_add3_u32 v57, v57, v60, s33
	v_add3_u32 v56, v56, v61, s33
	v_and_b32_e32 v57, 0xffff0000, v57
	v_and_b32_e32 v56, 0xffff0000, v56
	v_or_b32_sdwa v57, v57, v58 dst_sel:DWORD dst_unused:UNUSED_PAD src0_sel:DWORD src1_sel:WORD_1
	v_or_b32_sdwa v56, v56, v59 dst_sel:DWORD dst_unused:UNUSED_PAD src0_sel:DWORD src1_sel:WORD_1
	global_store_dwordx2 v[110:111], v[56:57], off offset:32
	global_load_dwordx4 v[56:59], v107, s[14:15] offset:128
	s_waitcnt vmcnt(0)
	v_add_f32_e32 v52, v52, v56
	v_mul_f32_e32 v52, 0xbfb8aa3b, v52
	v_exp_f32_e32 v56, v52
	v_add_f32_e32 v52, v53, v57
	v_mul_f32_e32 v52, 0xbfb8aa3b, v52
	v_exp_f32_e32 v60, v52
	v_add_f32_e32 v52, v54, v58
	v_mul_f32_e32 v52, 0xbfb8aa3b, v52
	v_exp_f32_e32 v57, v52
	v_add_f32_e32 v52, v55, v59
	v_mul_f32_e32 v52, 0xbfb8aa3b, v52
	v_exp_f32_e32 v61, v52
	global_load_dwordx4 v[52:55], v107, s[12:13] offset:128
	v_pk_add_f32 v[56:57], v[56:57], 1.0 op_sel_hi:[1,0]
	s_nop 0
	s_nop 0
	v_rcp_f32_e32 v57, v57
	s_nop 0
	v_rcp_f32_e32 v56, v56
	s_waitcnt vmcnt(0)
	v_mov_b32_e32 v58, v52
	v_mov_b32_e32 v59, v54
	v_pk_mul_f32 v[56:57], v[58:59], v[56:57]
	v_pk_add_f32 v[58:59], v[60:61], 1.0 op_sel_hi:[1,0]
	s_nop 0
	s_nop 0
	v_rcp_f32_e32 v59, v59
	s_nop 0
	v_rcp_f32_e32 v58, v58
	v_mov_b32_e32 v54, v53
	v_pk_mul_f32 v[52:53], v[54:55], v[58:59]
	v_and_b32_sdwa v54, v57, v154 dst_sel:DWORD dst_unused:UNUSED_PAD src0_sel:WORD_1 src1_sel:DWORD
	v_and_b32_sdwa v55, v56, v154 dst_sel:DWORD dst_unused:UNUSED_PAD src0_sel:WORD_1 src1_sel:DWORD
	v_add3_u32 v55, v56, v55, s33
	v_add3_u32 v54, v57, v54, s33
	v_and_b32_sdwa v56, v53, v154 dst_sel:DWORD dst_unused:UNUSED_PAD src0_sel:WORD_1 src1_sel:DWORD
	v_and_b32_sdwa v57, v52, v154 dst_sel:DWORD dst_unused:UNUSED_PAD src0_sel:WORD_1 src1_sel:DWORD
	v_add3_u32 v53, v53, v56, s33
	v_add3_u32 v52, v52, v57, s33
	v_and_b32_e32 v53, 0xffff0000, v53
	v_and_b32_e32 v52, 0xffff0000, v52
	v_or_b32_sdwa v53, v53, v54 dst_sel:DWORD dst_unused:UNUSED_PAD src0_sel:DWORD src1_sel:WORD_1
	v_or_b32_sdwa v52, v52, v55 dst_sel:DWORD dst_unused:UNUSED_PAD src0_sel:DWORD src1_sel:WORD_1
	global_store_dwordx2 v[110:111], v[52:53], off offset:64
	global_load_dwordx4 v[52:55], v107, s[14:15] offset:192
	s_waitcnt vmcnt(0)
	v_add_f32_e32 v48, v48, v52
	v_mul_f32_e32 v48, 0xbfb8aa3b, v48
	v_exp_f32_e32 v52, v48
	v_add_f32_e32 v48, v49, v53
	v_mul_f32_e32 v48, 0xbfb8aa3b, v48
	v_exp_f32_e32 v56, v48
	v_add_f32_e32 v48, v50, v54
	v_mul_f32_e32 v48, 0xbfb8aa3b, v48
	v_exp_f32_e32 v53, v48
	v_add_f32_e32 v48, v51, v55
	v_mul_f32_e32 v48, 0xbfb8aa3b, v48
	v_exp_f32_e32 v57, v48
	global_load_dwordx4 v[48:51], v107, s[12:13] offset:192
	v_pk_add_f32 v[52:53], v[52:53], 1.0 op_sel_hi:[1,0]
	s_nop 0
	s_nop 0
	v_rcp_f32_e32 v53, v53
	s_nop 0
	v_rcp_f32_e32 v52, v52
	s_waitcnt vmcnt(0)
	v_mov_b32_e32 v54, v48
	v_mov_b32_e32 v55, v50
	v_pk_mul_f32 v[52:53], v[54:55], v[52:53]
	v_pk_add_f32 v[54:55], v[56:57], 1.0 op_sel_hi:[1,0]
	s_nop 0
	s_nop 0
	v_rcp_f32_e32 v55, v55
	s_nop 0
	v_rcp_f32_e32 v54, v54
	v_mov_b32_e32 v50, v49
	v_pk_mul_f32 v[48:49], v[50:51], v[54:55]
	v_and_b32_sdwa v50, v53, v154 dst_sel:DWORD dst_unused:UNUSED_PAD src0_sel:WORD_1 src1_sel:DWORD
	v_and_b32_sdwa v51, v52, v154 dst_sel:DWORD dst_unused:UNUSED_PAD src0_sel:WORD_1 src1_sel:DWORD
	v_add3_u32 v51, v52, v51, s33
	v_add3_u32 v50, v53, v50, s33
	v_and_b32_sdwa v52, v49, v154 dst_sel:DWORD dst_unused:UNUSED_PAD src0_sel:WORD_1 src1_sel:DWORD
	v_and_b32_sdwa v53, v48, v154 dst_sel:DWORD dst_unused:UNUSED_PAD src0_sel:WORD_1 src1_sel:DWORD
	v_add3_u32 v49, v49, v52, s33
	v_add3_u32 v48, v48, v53, s33
	v_and_b32_e32 v49, 0xffff0000, v49
	v_and_b32_e32 v48, 0xffff0000, v48
	v_or_b32_sdwa v49, v49, v50 dst_sel:DWORD dst_unused:UNUSED_PAD src0_sel:DWORD src1_sel:WORD_1
	v_or_b32_sdwa v48, v48, v51 dst_sel:DWORD dst_unused:UNUSED_PAD src0_sel:DWORD src1_sel:WORD_1
	global_store_dwordx2 v[110:111], v[48:49], off offset:96
	v_or_b32_e32 v48, 16, v106
	v_ashrrev_i32_e32 v49, 31, v48
	v_lshlrev_b64 v[48:49], 11, v[48:49]
	v_lshl_add_u64 v[54:55], s[34:35], 0, v[48:49]
	global_load_dwordx4 v[48:51], v107, s[14:15]
	s_waitcnt vmcnt(0)
	v_add_f32_e32 v44, v44, v48
	v_mul_f32_e32 v44, 0xbfb8aa3b, v44
	v_exp_f32_e32 v56, v44
	v_add_f32_e32 v44, v45, v49
	v_mul_f32_e32 v44, 0xbfb8aa3b, v44
	v_exp_f32_e32 v52, v44
	v_add_f32_e32 v44, v46, v50
	v_mul_f32_e32 v44, 0xbfb8aa3b, v44
	v_exp_f32_e32 v57, v44
	v_add_f32_e32 v44, v47, v51
	v_mul_f32_e32 v44, 0xbfb8aa3b, v44
	v_exp_f32_e32 v53, v44
	global_load_dwordx4 v[44:47], v107, s[12:13]
	v_pk_add_f32 v[50:51], v[56:57], 1.0 op_sel_hi:[1,0]
	v_lshl_add_u64 v[48:49], v[54:55], 0, v[108:109]
	v_pk_add_f32 v[52:53], v[52:53], 1.0 op_sel_hi:[1,0]
	v_rcp_f32_e32 v51, v51
	s_nop 0
	v_rcp_f32_e32 v50, v50
	s_waitcnt vmcnt(0)
	v_mov_b32_e32 v54, v44
	v_div_scale_f32 v44, s[46:47], v53, v53, 1.0
	v_mov_b32_e32 v55, v46
	v_rcp_f32_e32 v46, v44
	v_pk_mul_f32 v[50:51], v[54:55], v[50:51]
	v_fma_f32 v54, -v44, v46, 1.0
	v_fmac_f32_e32 v46, v54, v46
	v_div_scale_f32 v54, vcc, 1.0, v53, 1.0
	v_mul_f32_e32 v55, v54, v46
	v_fma_f32 v56, -v44, v55, v54
	v_fmac_f32_e32 v55, v56, v46
	v_fma_f32 v44, -v44, v55, v54
	v_div_fmas_f32 v44, v44, v46, v55
	v_div_fixup_f32 v53, v44, v53, 1.0
	s_nop 0
	v_rcp_f32_e32 v52, v52
	v_mov_b32_e32 v46, v45
	v_pk_mul_f32 v[44:45], v[46:47], v[52:53]
	v_and_b32_sdwa v46, v51, v154 dst_sel:DWORD dst_unused:UNUSED_PAD src0_sel:WORD_1 src1_sel:DWORD
	v_and_b32_sdwa v47, v50, v154 dst_sel:DWORD dst_unused:UNUSED_PAD src0_sel:WORD_1 src1_sel:DWORD
	v_add3_u32 v47, v50, v47, s33
	v_add3_u32 v46, v51, v46, s33
	v_and_b32_sdwa v50, v45, v154 dst_sel:DWORD dst_unused:UNUSED_PAD src0_sel:WORD_1 src1_sel:DWORD
	v_and_b32_sdwa v51, v44, v154 dst_sel:DWORD dst_unused:UNUSED_PAD src0_sel:WORD_1 src1_sel:DWORD
	v_add3_u32 v45, v45, v50, s33
	v_add3_u32 v44, v44, v51, s33
	v_and_b32_e32 v45, 0xffff0000, v45
	v_and_b32_e32 v44, 0xffff0000, v44
	v_or_b32_sdwa v45, v45, v46 dst_sel:DWORD dst_unused:UNUSED_PAD src0_sel:DWORD src1_sel:WORD_1
	v_or_b32_sdwa v44, v44, v47 dst_sel:DWORD dst_unused:UNUSED_PAD src0_sel:DWORD src1_sel:WORD_1
	global_store_dwordx2 v[48:49], v[44:45], off
	global_load_dwordx4 v[44:47], v107, s[14:15] offset:64
	s_waitcnt vmcnt(0)
	v_add_f32_e32 v40, v40, v44
	v_mul_f32_e32 v40, 0xbfb8aa3b, v40
	v_exp_f32_e32 v44, v40
	v_add_f32_e32 v40, v41, v45
	v_mul_f32_e32 v40, 0xbfb8aa3b, v40
	v_exp_f32_e32 v50, v40
	v_add_f32_e32 v40, v42, v46
	v_mul_f32_e32 v40, 0xbfb8aa3b, v40
	v_exp_f32_e32 v45, v40
	v_add_f32_e32 v40, v43, v47
	v_mul_f32_e32 v40, 0xbfb8aa3b, v40
	v_exp_f32_e32 v51, v40
	global_load_dwordx4 v[40:43], v107, s[12:13] offset:64
	v_pk_add_f32 v[44:45], v[44:45], 1.0 op_sel_hi:[1,0]
	s_nop 0
	s_nop 0
	v_rcp_f32_e32 v45, v45
	s_nop 0
	v_rcp_f32_e32 v44, v44
	s_waitcnt vmcnt(0)
	v_mov_b32_e32 v46, v40
	v_mov_b32_e32 v47, v42
	v_pk_mul_f32 v[44:45], v[46:47], v[44:45]
	v_pk_add_f32 v[46:47], v[50:51], 1.0 op_sel_hi:[1,0]
	s_nop 0
	s_nop 0
	v_rcp_f32_e32 v47, v47
	s_nop 0
	v_rcp_f32_e32 v46, v46
	v_mov_b32_e32 v42, v41
	v_pk_mul_f32 v[40:41], v[42:43], v[46:47]
	v_and_b32_sdwa v42, v45, v154 dst_sel:DWORD dst_unused:UNUSED_PAD src0_sel:WORD_1 src1_sel:DWORD
	v_and_b32_sdwa v43, v44, v154 dst_sel:DWORD dst_unused:UNUSED_PAD src0_sel:WORD_1 src1_sel:DWORD
	v_add3_u32 v43, v44, v43, s33
	v_add3_u32 v42, v45, v42, s33
	v_and_b32_sdwa v44, v41, v154 dst_sel:DWORD dst_unused:UNUSED_PAD src0_sel:WORD_1 src1_sel:DWORD
	v_and_b32_sdwa v45, v40, v154 dst_sel:DWORD dst_unused:UNUSED_PAD src0_sel:WORD_1 src1_sel:DWORD
	v_add3_u32 v41, v41, v44, s33
	v_add3_u32 v40, v40, v45, s33
	v_and_b32_e32 v41, 0xffff0000, v41
	v_and_b32_e32 v40, 0xffff0000, v40
	v_or_b32_sdwa v41, v41, v42 dst_sel:DWORD dst_unused:UNUSED_PAD src0_sel:DWORD src1_sel:WORD_1
	v_or_b32_sdwa v40, v40, v43 dst_sel:DWORD dst_unused:UNUSED_PAD src0_sel:DWORD src1_sel:WORD_1
	global_store_dwordx2 v[48:49], v[40:41], off offset:32
	global_load_dwordx4 v[40:43], v107, s[14:15] offset:128
	s_waitcnt vmcnt(0)
	v_add_f32_e32 v36, v36, v40
	v_mul_f32_e32 v36, 0xbfb8aa3b, v36
	v_exp_f32_e32 v40, v36
	v_add_f32_e32 v36, v37, v41
	v_mul_f32_e32 v36, 0xbfb8aa3b, v36
	v_exp_f32_e32 v44, v36
	v_add_f32_e32 v36, v38, v42
	v_mul_f32_e32 v36, 0xbfb8aa3b, v36
	v_exp_f32_e32 v41, v36
	v_add_f32_e32 v36, v39, v43
	v_mul_f32_e32 v36, 0xbfb8aa3b, v36
	v_exp_f32_e32 v45, v36
	global_load_dwordx4 v[36:39], v107, s[12:13] offset:128
	v_pk_add_f32 v[40:41], v[40:41], 1.0 op_sel_hi:[1,0]
	s_nop 0
	s_nop 0
	v_rcp_f32_e32 v41, v41
	s_nop 0
	v_rcp_f32_e32 v40, v40
	s_waitcnt vmcnt(0)
	v_mov_b32_e32 v42, v36
	v_mov_b32_e32 v43, v38
	v_pk_mul_f32 v[40:41], v[42:43], v[40:41]
	v_pk_add_f32 v[42:43], v[44:45], 1.0 op_sel_hi:[1,0]
	s_nop 0
	s_nop 0
	v_rcp_f32_e32 v43, v43
	s_nop 0
	v_rcp_f32_e32 v42, v42
	v_mov_b32_e32 v38, v37
	v_pk_mul_f32 v[36:37], v[38:39], v[42:43]
	v_and_b32_sdwa v38, v41, v154 dst_sel:DWORD dst_unused:UNUSED_PAD src0_sel:WORD_1 src1_sel:DWORD
	v_and_b32_sdwa v39, v40, v154 dst_sel:DWORD dst_unused:UNUSED_PAD src0_sel:WORD_1 src1_sel:DWORD
	v_add3_u32 v39, v40, v39, s33
	v_add3_u32 v38, v41, v38, s33
	v_and_b32_sdwa v40, v37, v154 dst_sel:DWORD dst_unused:UNUSED_PAD src0_sel:WORD_1 src1_sel:DWORD
	v_and_b32_sdwa v41, v36, v154 dst_sel:DWORD dst_unused:UNUSED_PAD src0_sel:WORD_1 src1_sel:DWORD
	v_add3_u32 v37, v37, v40, s33
	v_add3_u32 v36, v36, v41, s33
	v_and_b32_e32 v37, 0xffff0000, v37
	v_and_b32_e32 v36, 0xffff0000, v36
	v_or_b32_sdwa v37, v37, v38 dst_sel:DWORD dst_unused:UNUSED_PAD src0_sel:DWORD src1_sel:WORD_1
	v_or_b32_sdwa v36, v36, v39 dst_sel:DWORD dst_unused:UNUSED_PAD src0_sel:DWORD src1_sel:WORD_1
	global_store_dwordx2 v[48:49], v[36:37], off offset:64
	global_load_dwordx4 v[36:39], v107, s[14:15] offset:192
	s_waitcnt vmcnt(0)
	v_add_f32_e32 v32, v32, v36
	v_mul_f32_e32 v32, 0xbfb8aa3b, v32
	v_exp_f32_e32 v36, v32
	v_add_f32_e32 v32, v33, v37
	v_mul_f32_e32 v32, 0xbfb8aa3b, v32
	v_exp_f32_e32 v40, v32
	v_add_f32_e32 v32, v34, v38
	v_mul_f32_e32 v32, 0xbfb8aa3b, v32
	v_exp_f32_e32 v37, v32
	v_add_f32_e32 v32, v35, v39
	v_mul_f32_e32 v32, 0xbfb8aa3b, v32
	v_exp_f32_e32 v41, v32
	global_load_dwordx4 v[32:35], v107, s[12:13] offset:192
	v_pk_add_f32 v[36:37], v[36:37], 1.0 op_sel_hi:[1,0]
	s_nop 0
	s_nop 0
	v_rcp_f32_e32 v37, v37
	s_nop 0
	v_rcp_f32_e32 v36, v36
	s_waitcnt vmcnt(0)
	v_mov_b32_e32 v38, v32
	v_mov_b32_e32 v39, v34
	v_pk_mul_f32 v[36:37], v[38:39], v[36:37]
	v_pk_add_f32 v[38:39], v[40:41], 1.0 op_sel_hi:[1,0]
	s_nop 0
	s_nop 0
	v_rcp_f32_e32 v39, v39
	s_nop 0
	v_rcp_f32_e32 v38, v38
	v_mov_b32_e32 v34, v33
	v_pk_mul_f32 v[32:33], v[34:35], v[38:39]
	v_and_b32_sdwa v34, v37, v154 dst_sel:DWORD dst_unused:UNUSED_PAD src0_sel:WORD_1 src1_sel:DWORD
	v_and_b32_sdwa v35, v36, v154 dst_sel:DWORD dst_unused:UNUSED_PAD src0_sel:WORD_1 src1_sel:DWORD
	v_add3_u32 v35, v36, v35, s33
	v_add3_u32 v34, v37, v34, s33
	v_and_b32_sdwa v36, v33, v154 dst_sel:DWORD dst_unused:UNUSED_PAD src0_sel:WORD_1 src1_sel:DWORD
	v_and_b32_sdwa v37, v32, v154 dst_sel:DWORD dst_unused:UNUSED_PAD src0_sel:WORD_1 src1_sel:DWORD
	v_add3_u32 v33, v33, v36, s33
	v_add3_u32 v32, v32, v37, s33
	v_and_b32_e32 v33, 0xffff0000, v33
	v_and_b32_e32 v32, 0xffff0000, v32
	v_or_b32_sdwa v33, v33, v34 dst_sel:DWORD dst_unused:UNUSED_PAD src0_sel:DWORD src1_sel:WORD_1
	v_or_b32_sdwa v32, v32, v35 dst_sel:DWORD dst_unused:UNUSED_PAD src0_sel:DWORD src1_sel:WORD_1
	global_store_dwordx2 v[48:49], v[32:33], off offset:96
	v_or_b32_e32 v32, 32, v106
	v_ashrrev_i32_e32 v33, 31, v32
	v_lshlrev_b64 v[32:33], 11, v[32:33]
	v_lshl_add_u64 v[38:39], s[34:35], 0, v[32:33]
	global_load_dwordx4 v[32:35], v107, s[14:15]
	s_waitcnt vmcnt(0)
	v_add_f32_e32 v28, v28, v32
	v_mul_f32_e32 v28, 0xbfb8aa3b, v28
	v_exp_f32_e32 v40, v28
	v_add_f32_e32 v28, v29, v33
	v_mul_f32_e32 v28, 0xbfb8aa3b, v28
	v_exp_f32_e32 v36, v28
	v_add_f32_e32 v28, v30, v34
	v_mul_f32_e32 v28, 0xbfb8aa3b, v28
	v_exp_f32_e32 v41, v28
	v_add_f32_e32 v28, v31, v35
	v_mul_f32_e32 v28, 0xbfb8aa3b, v28
	v_exp_f32_e32 v37, v28
	global_load_dwordx4 v[28:31], v107, s[12:13]
	v_pk_add_f32 v[34:35], v[40:41], 1.0 op_sel_hi:[1,0]
	v_lshl_add_u64 v[32:33], v[38:39], 0, v[108:109]
	v_pk_add_f32 v[36:37], v[36:37], 1.0 op_sel_hi:[1,0]
	v_rcp_f32_e32 v35, v35
	s_nop 0
	v_rcp_f32_e32 v34, v34
	s_waitcnt vmcnt(0)
	v_mov_b32_e32 v38, v28
	v_div_scale_f32 v28, s[46:47], v37, v37, 1.0
	v_mov_b32_e32 v39, v30
	v_rcp_f32_e32 v30, v28
	v_pk_mul_f32 v[34:35], v[38:39], v[34:35]
	v_fma_f32 v38, -v28, v30, 1.0
	v_fmac_f32_e32 v30, v38, v30
	v_div_scale_f32 v38, vcc, 1.0, v37, 1.0
	v_mul_f32_e32 v39, v38, v30
	v_fma_f32 v40, -v28, v39, v38
	v_fmac_f32_e32 v39, v40, v30
	v_fma_f32 v28, -v28, v39, v38
	v_div_fmas_f32 v28, v28, v30, v39
	v_div_fixup_f32 v37, v28, v37, 1.0
	s_nop 0
	v_rcp_f32_e32 v36, v36
	v_mov_b32_e32 v30, v29
	v_pk_mul_f32 v[28:29], v[30:31], v[36:37]
	v_and_b32_sdwa v30, v35, v154 dst_sel:DWORD dst_unused:UNUSED_PAD src0_sel:WORD_1 src1_sel:DWORD
	v_and_b32_sdwa v31, v34, v154 dst_sel:DWORD dst_unused:UNUSED_PAD src0_sel:WORD_1 src1_sel:DWORD
	v_add3_u32 v31, v34, v31, s33
	v_add3_u32 v30, v35, v30, s33
	v_and_b32_sdwa v34, v29, v154 dst_sel:DWORD dst_unused:UNUSED_PAD src0_sel:WORD_1 src1_sel:DWORD
	v_and_b32_sdwa v35, v28, v154 dst_sel:DWORD dst_unused:UNUSED_PAD src0_sel:WORD_1 src1_sel:DWORD
	v_add3_u32 v29, v29, v34, s33
	v_add3_u32 v28, v28, v35, s33
	v_and_b32_e32 v29, 0xffff0000, v29
	v_and_b32_e32 v28, 0xffff0000, v28
	v_or_b32_sdwa v29, v29, v30 dst_sel:DWORD dst_unused:UNUSED_PAD src0_sel:DWORD src1_sel:WORD_1
	v_or_b32_sdwa v28, v28, v31 dst_sel:DWORD dst_unused:UNUSED_PAD src0_sel:DWORD src1_sel:WORD_1
	global_store_dwordx2 v[32:33], v[28:29], off
	global_load_dwordx4 v[28:31], v107, s[14:15] offset:64
	s_waitcnt vmcnt(0)
	v_add_f32_e32 v24, v24, v28
	v_mul_f32_e32 v24, 0xbfb8aa3b, v24
	v_exp_f32_e32 v28, v24
	v_add_f32_e32 v24, v25, v29
	v_mul_f32_e32 v24, 0xbfb8aa3b, v24
	v_exp_f32_e32 v34, v24
	v_add_f32_e32 v24, v26, v30
	v_mul_f32_e32 v24, 0xbfb8aa3b, v24
	v_exp_f32_e32 v29, v24
	v_add_f32_e32 v24, v27, v31
	v_mul_f32_e32 v24, 0xbfb8aa3b, v24
	v_exp_f32_e32 v35, v24
	global_load_dwordx4 v[24:27], v107, s[12:13] offset:64
	v_pk_add_f32 v[28:29], v[28:29], 1.0 op_sel_hi:[1,0]
	s_nop 0
	s_nop 0
	v_rcp_f32_e32 v29, v29
	s_nop 0
	v_rcp_f32_e32 v28, v28
	s_waitcnt vmcnt(0)
	v_mov_b32_e32 v30, v24
	v_mov_b32_e32 v31, v26
	v_pk_mul_f32 v[28:29], v[30:31], v[28:29]
	v_pk_add_f32 v[30:31], v[34:35], 1.0 op_sel_hi:[1,0]
	s_nop 0
	s_nop 0
	v_rcp_f32_e32 v31, v31
	s_nop 0
	v_rcp_f32_e32 v30, v30
	v_mov_b32_e32 v26, v25
	v_pk_mul_f32 v[24:25], v[26:27], v[30:31]
	v_and_b32_sdwa v26, v29, v154 dst_sel:DWORD dst_unused:UNUSED_PAD src0_sel:WORD_1 src1_sel:DWORD
	v_and_b32_sdwa v27, v28, v154 dst_sel:DWORD dst_unused:UNUSED_PAD src0_sel:WORD_1 src1_sel:DWORD
	v_add3_u32 v27, v28, v27, s33
	v_add3_u32 v26, v29, v26, s33
	v_and_b32_sdwa v28, v25, v154 dst_sel:DWORD dst_unused:UNUSED_PAD src0_sel:WORD_1 src1_sel:DWORD
	v_and_b32_sdwa v29, v24, v154 dst_sel:DWORD dst_unused:UNUSED_PAD src0_sel:WORD_1 src1_sel:DWORD
	v_add3_u32 v25, v25, v28, s33
	v_add3_u32 v24, v24, v29, s33
	v_and_b32_e32 v25, 0xffff0000, v25
	v_and_b32_e32 v24, 0xffff0000, v24
	v_or_b32_sdwa v25, v25, v26 dst_sel:DWORD dst_unused:UNUSED_PAD src0_sel:DWORD src1_sel:WORD_1
	v_or_b32_sdwa v24, v24, v27 dst_sel:DWORD dst_unused:UNUSED_PAD src0_sel:DWORD src1_sel:WORD_1
	global_store_dwordx2 v[32:33], v[24:25], off offset:32
	global_load_dwordx4 v[24:27], v107, s[14:15] offset:128
	s_waitcnt vmcnt(0)
	v_add_f32_e32 v20, v20, v24
	v_mul_f32_e32 v20, 0xbfb8aa3b, v20
	v_exp_f32_e32 v24, v20
	v_add_f32_e32 v20, v21, v25
	v_mul_f32_e32 v20, 0xbfb8aa3b, v20
	v_exp_f32_e32 v28, v20
	v_add_f32_e32 v20, v22, v26
	v_mul_f32_e32 v20, 0xbfb8aa3b, v20
	v_exp_f32_e32 v25, v20
	v_add_f32_e32 v20, v23, v27
	v_mul_f32_e32 v20, 0xbfb8aa3b, v20
	v_exp_f32_e32 v29, v20
	global_load_dwordx4 v[20:23], v107, s[12:13] offset:128
	v_pk_add_f32 v[24:25], v[24:25], 1.0 op_sel_hi:[1,0]
	s_nop 0
	s_nop 0
	v_rcp_f32_e32 v25, v25
	s_nop 0
	v_rcp_f32_e32 v24, v24
	s_waitcnt vmcnt(0)
	v_mov_b32_e32 v26, v20
	v_mov_b32_e32 v27, v22
	v_pk_mul_f32 v[24:25], v[26:27], v[24:25]
	v_pk_add_f32 v[26:27], v[28:29], 1.0 op_sel_hi:[1,0]
	s_nop 0
	s_nop 0
	v_rcp_f32_e32 v27, v27
	s_nop 0
	v_rcp_f32_e32 v26, v26
	v_mov_b32_e32 v22, v21
	v_pk_mul_f32 v[20:21], v[22:23], v[26:27]
	v_and_b32_sdwa v22, v25, v154 dst_sel:DWORD dst_unused:UNUSED_PAD src0_sel:WORD_1 src1_sel:DWORD
	v_and_b32_sdwa v23, v24, v154 dst_sel:DWORD dst_unused:UNUSED_PAD src0_sel:WORD_1 src1_sel:DWORD
	v_add3_u32 v23, v24, v23, s33
	v_add3_u32 v22, v25, v22, s33
	v_and_b32_sdwa v24, v21, v154 dst_sel:DWORD dst_unused:UNUSED_PAD src0_sel:WORD_1 src1_sel:DWORD
	v_and_b32_sdwa v25, v20, v154 dst_sel:DWORD dst_unused:UNUSED_PAD src0_sel:WORD_1 src1_sel:DWORD
	v_add3_u32 v21, v21, v24, s33
	v_add3_u32 v20, v20, v25, s33
	v_and_b32_e32 v21, 0xffff0000, v21
	v_and_b32_e32 v20, 0xffff0000, v20
	v_or_b32_sdwa v21, v21, v22 dst_sel:DWORD dst_unused:UNUSED_PAD src0_sel:DWORD src1_sel:WORD_1
	v_or_b32_sdwa v20, v20, v23 dst_sel:DWORD dst_unused:UNUSED_PAD src0_sel:DWORD src1_sel:WORD_1
	global_store_dwordx2 v[32:33], v[20:21], off offset:64
	global_load_dwordx4 v[20:23], v107, s[14:15] offset:192
	s_waitcnt vmcnt(0)
	v_add_f32_e32 v16, v16, v20
	v_mul_f32_e32 v16, 0xbfb8aa3b, v16
	v_exp_f32_e32 v20, v16
	v_add_f32_e32 v16, v17, v21
	v_mul_f32_e32 v16, 0xbfb8aa3b, v16
	v_exp_f32_e32 v24, v16
	v_add_f32_e32 v16, v18, v22
	v_mul_f32_e32 v16, 0xbfb8aa3b, v16
	v_exp_f32_e32 v21, v16
	v_add_f32_e32 v16, v19, v23
	v_mul_f32_e32 v16, 0xbfb8aa3b, v16
	v_exp_f32_e32 v25, v16
	global_load_dwordx4 v[16:19], v107, s[12:13] offset:192
	v_pk_add_f32 v[20:21], v[20:21], 1.0 op_sel_hi:[1,0]
	s_nop 0
	s_nop 0
	v_rcp_f32_e32 v21, v21
	s_nop 0
	v_rcp_f32_e32 v20, v20
	s_waitcnt vmcnt(0)
	v_mov_b32_e32 v22, v16
	v_mov_b32_e32 v23, v18
	v_pk_mul_f32 v[20:21], v[22:23], v[20:21]
	v_pk_add_f32 v[22:23], v[24:25], 1.0 op_sel_hi:[1,0]
	s_nop 0
	s_nop 0
	v_rcp_f32_e32 v23, v23
	s_nop 0
	v_rcp_f32_e32 v22, v22
	v_mov_b32_e32 v18, v17
	v_pk_mul_f32 v[16:17], v[18:19], v[22:23]
	v_and_b32_sdwa v18, v21, v154 dst_sel:DWORD dst_unused:UNUSED_PAD src0_sel:WORD_1 src1_sel:DWORD
	v_and_b32_sdwa v19, v20, v154 dst_sel:DWORD dst_unused:UNUSED_PAD src0_sel:WORD_1 src1_sel:DWORD
	v_add3_u32 v19, v20, v19, s33
	v_add3_u32 v18, v21, v18, s33
	v_and_b32_sdwa v20, v17, v154 dst_sel:DWORD dst_unused:UNUSED_PAD src0_sel:WORD_1 src1_sel:DWORD
	v_and_b32_sdwa v21, v16, v154 dst_sel:DWORD dst_unused:UNUSED_PAD src0_sel:WORD_1 src1_sel:DWORD
	v_add3_u32 v17, v17, v20, s33
	v_add3_u32 v16, v16, v21, s33
	v_and_b32_e32 v17, 0xffff0000, v17
	v_and_b32_e32 v16, 0xffff0000, v16
	v_or_b32_sdwa v17, v17, v18 dst_sel:DWORD dst_unused:UNUSED_PAD src0_sel:DWORD src1_sel:WORD_1
	v_or_b32_sdwa v16, v16, v19 dst_sel:DWORD dst_unused:UNUSED_PAD src0_sel:DWORD src1_sel:WORD_1
	global_store_dwordx2 v[32:33], v[16:17], off offset:96
	v_or_b32_e32 v16, 48, v106
	v_ashrrev_i32_e32 v17, 31, v16
	v_lshlrev_b64 v[16:17], 11, v[16:17]
	v_lshl_add_u64 v[22:23], s[34:35], 0, v[16:17]
	global_load_dwordx4 v[16:19], v107, s[14:15]
	s_mov_b64 s[34:35], s[4:5]
	s_mov_b64 s[4:5], 0x6080
	s_waitcnt vmcnt(0)
	v_add_f32_e32 v12, v12, v16
	v_mul_f32_e32 v12, 0xbfb8aa3b, v12
	v_exp_f32_e32 v24, v12
	v_add_f32_e32 v12, v13, v17
	v_mul_f32_e32 v12, 0xbfb8aa3b, v12
	v_exp_f32_e32 v20, v12
	v_add_f32_e32 v12, v14, v18
	v_mul_f32_e32 v12, 0xbfb8aa3b, v12
	v_exp_f32_e32 v25, v12
	v_add_f32_e32 v12, v15, v19
	v_mul_f32_e32 v12, 0xbfb8aa3b, v12
	v_exp_f32_e32 v21, v12
	global_load_dwordx4 v[12:15], v107, s[12:13]
	v_pk_add_f32 v[18:19], v[24:25], 1.0 op_sel_hi:[1,0]
	v_lshl_add_u64 v[16:17], v[22:23], 0, v[108:109]
	v_pk_add_f32 v[20:21], v[20:21], 1.0 op_sel_hi:[1,0]
	v_rcp_f32_e32 v19, v19
	s_nop 0
	v_rcp_f32_e32 v18, v18
	s_waitcnt vmcnt(0)
	v_mov_b32_e32 v22, v12
	v_div_scale_f32 v12, s[46:47], v21, v21, 1.0
	v_mov_b32_e32 v23, v14
	v_rcp_f32_e32 v14, v12
	v_pk_mul_f32 v[18:19], v[22:23], v[18:19]
	v_fma_f32 v22, -v12, v14, 1.0
	v_fmac_f32_e32 v14, v22, v14
	v_div_scale_f32 v22, vcc, 1.0, v21, 1.0
	v_mul_f32_e32 v23, v22, v14
	v_fma_f32 v24, -v12, v23, v22
	v_fmac_f32_e32 v23, v24, v14
	v_fma_f32 v12, -v12, v23, v22
	v_div_fmas_f32 v12, v12, v14, v23
	v_div_fixup_f32 v21, v12, v21, 1.0
	s_nop 0
	v_rcp_f32_e32 v20, v20
	v_mov_b32_e32 v14, v13
	v_pk_mul_f32 v[12:13], v[14:15], v[20:21]
	v_and_b32_sdwa v14, v19, v154 dst_sel:DWORD dst_unused:UNUSED_PAD src0_sel:WORD_1 src1_sel:DWORD
	v_and_b32_sdwa v15, v18, v154 dst_sel:DWORD dst_unused:UNUSED_PAD src0_sel:WORD_1 src1_sel:DWORD
	v_add3_u32 v15, v18, v15, s33
	v_add3_u32 v14, v19, v14, s33
	v_and_b32_sdwa v18, v13, v154 dst_sel:DWORD dst_unused:UNUSED_PAD src0_sel:WORD_1 src1_sel:DWORD
	v_and_b32_sdwa v19, v12, v154 dst_sel:DWORD dst_unused:UNUSED_PAD src0_sel:WORD_1 src1_sel:DWORD
	v_add3_u32 v13, v13, v18, s33
	v_add3_u32 v12, v12, v19, s33
	v_and_b32_e32 v13, 0xffff0000, v13
	v_and_b32_e32 v12, 0xffff0000, v12
	v_or_b32_sdwa v13, v13, v14 dst_sel:DWORD dst_unused:UNUSED_PAD src0_sel:DWORD src1_sel:WORD_1
	v_or_b32_sdwa v12, v12, v15 dst_sel:DWORD dst_unused:UNUSED_PAD src0_sel:DWORD src1_sel:WORD_1
	global_store_dwordx2 v[16:17], v[12:13], off
	global_load_dwordx4 v[12:15], v107, s[14:15] offset:64
	s_waitcnt vmcnt(0)
	v_add_f32_e32 v8, v8, v12
	v_mul_f32_e32 v8, 0xbfb8aa3b, v8
	v_exp_f32_e32 v12, v8
	v_add_f32_e32 v8, v9, v13
	v_mul_f32_e32 v8, 0xbfb8aa3b, v8
	v_exp_f32_e32 v18, v8
	v_add_f32_e32 v8, v10, v14
	v_mul_f32_e32 v8, 0xbfb8aa3b, v8
	v_exp_f32_e32 v13, v8
	v_add_f32_e32 v8, v11, v15
	v_mul_f32_e32 v8, 0xbfb8aa3b, v8
	v_exp_f32_e32 v19, v8
	global_load_dwordx4 v[8:11], v107, s[12:13] offset:64
	v_pk_add_f32 v[12:13], v[12:13], 1.0 op_sel_hi:[1,0]
	s_nop 0
	s_nop 0
	v_rcp_f32_e32 v13, v13
	s_nop 0
	v_rcp_f32_e32 v12, v12
	s_waitcnt vmcnt(0)
	v_mov_b32_e32 v14, v8
	v_mov_b32_e32 v15, v10
	v_pk_mul_f32 v[12:13], v[14:15], v[12:13]
	v_pk_add_f32 v[14:15], v[18:19], 1.0 op_sel_hi:[1,0]
	s_nop 0
	s_nop 0
	v_rcp_f32_e32 v15, v15
	s_nop 0
	v_rcp_f32_e32 v14, v14
	v_mov_b32_e32 v10, v9
	v_pk_mul_f32 v[8:9], v[10:11], v[14:15]
	v_and_b32_sdwa v10, v13, v154 dst_sel:DWORD dst_unused:UNUSED_PAD src0_sel:WORD_1 src1_sel:DWORD
	v_and_b32_sdwa v11, v12, v154 dst_sel:DWORD dst_unused:UNUSED_PAD src0_sel:WORD_1 src1_sel:DWORD
	v_add3_u32 v11, v12, v11, s33
	v_add3_u32 v10, v13, v10, s33
	v_and_b32_sdwa v12, v9, v154 dst_sel:DWORD dst_unused:UNUSED_PAD src0_sel:WORD_1 src1_sel:DWORD
	v_and_b32_sdwa v13, v8, v154 dst_sel:DWORD dst_unused:UNUSED_PAD src0_sel:WORD_1 src1_sel:DWORD
	v_add3_u32 v9, v9, v12, s33
	v_add3_u32 v8, v8, v13, s33
	v_and_b32_e32 v9, 0xffff0000, v9
	v_and_b32_e32 v8, 0xffff0000, v8
	v_or_b32_sdwa v9, v9, v10 dst_sel:DWORD dst_unused:UNUSED_PAD src0_sel:DWORD src1_sel:WORD_1
	v_or_b32_sdwa v8, v8, v11 dst_sel:DWORD dst_unused:UNUSED_PAD src0_sel:DWORD src1_sel:WORD_1
	global_store_dwordx2 v[16:17], v[8:9], off offset:32
	global_load_dwordx4 v[8:11], v107, s[14:15] offset:128
	s_waitcnt vmcnt(0)
	v_add_f32_e32 v4, v4, v8
	v_mul_f32_e32 v4, 0xbfb8aa3b, v4
	v_exp_f32_e32 v8, v4
	v_add_f32_e32 v4, v5, v9
	v_mul_f32_e32 v4, 0xbfb8aa3b, v4
	v_exp_f32_e32 v12, v4
	v_add_f32_e32 v4, v6, v10
	v_mul_f32_e32 v4, 0xbfb8aa3b, v4
	v_exp_f32_e32 v9, v4
	v_add_f32_e32 v4, v7, v11
	v_mul_f32_e32 v4, 0xbfb8aa3b, v4
	v_exp_f32_e32 v13, v4
	global_load_dwordx4 v[4:7], v107, s[12:13] offset:128
	v_pk_add_f32 v[8:9], v[8:9], 1.0 op_sel_hi:[1,0]
	s_nop 0
	s_nop 0
	v_rcp_f32_e32 v9, v9
	s_nop 0
	v_rcp_f32_e32 v8, v8
	s_waitcnt vmcnt(0)
	v_mov_b32_e32 v10, v4
	v_mov_b32_e32 v11, v6
	v_pk_mul_f32 v[8:9], v[10:11], v[8:9]
	v_pk_add_f32 v[10:11], v[12:13], 1.0 op_sel_hi:[1,0]
	s_nop 0
	s_nop 0
	v_rcp_f32_e32 v11, v11
	s_nop 0
	v_rcp_f32_e32 v10, v10
	v_mov_b32_e32 v6, v5
	v_pk_mul_f32 v[4:5], v[6:7], v[10:11]
	v_and_b32_sdwa v6, v9, v154 dst_sel:DWORD dst_unused:UNUSED_PAD src0_sel:WORD_1 src1_sel:DWORD
	v_and_b32_sdwa v7, v8, v154 dst_sel:DWORD dst_unused:UNUSED_PAD src0_sel:WORD_1 src1_sel:DWORD
	v_add3_u32 v7, v8, v7, s33
	v_add3_u32 v6, v9, v6, s33
	v_and_b32_sdwa v8, v5, v154 dst_sel:DWORD dst_unused:UNUSED_PAD src0_sel:WORD_1 src1_sel:DWORD
	v_and_b32_sdwa v9, v4, v154 dst_sel:DWORD dst_unused:UNUSED_PAD src0_sel:WORD_1 src1_sel:DWORD
	v_add3_u32 v5, v5, v8, s33
	v_add3_u32 v4, v4, v9, s33
	v_and_b32_e32 v5, 0xffff0000, v5
	v_and_b32_e32 v4, 0xffff0000, v4
	v_or_b32_sdwa v5, v5, v6 dst_sel:DWORD dst_unused:UNUSED_PAD src0_sel:DWORD src1_sel:WORD_1
	v_or_b32_sdwa v4, v4, v7 dst_sel:DWORD dst_unused:UNUSED_PAD src0_sel:DWORD src1_sel:WORD_1
	global_store_dwordx2 v[16:17], v[4:5], off offset:64
	global_load_dwordx4 v[4:7], v107, s[14:15] offset:192
	s_waitcnt vmcnt(0)
	v_add_f32_e32 v0, v0, v4
	v_mul_f32_e32 v0, 0xbfb8aa3b, v0
	v_exp_f32_e32 v4, v0
	v_add_f32_e32 v0, v1, v5
	v_mul_f32_e32 v0, 0xbfb8aa3b, v0
	v_exp_f32_e32 v8, v0
	v_add_f32_e32 v0, v2, v6
	v_mul_f32_e32 v0, 0xbfb8aa3b, v0
	v_exp_f32_e32 v5, v0
	v_add_f32_e32 v0, v3, v7
	v_mul_f32_e32 v0, 0xbfb8aa3b, v0
	v_exp_f32_e32 v9, v0
	global_load_dwordx4 v[0:3], v107, s[12:13] offset:192
	v_pk_add_f32 v[4:5], v[4:5], 1.0 op_sel_hi:[1,0]
	s_nop 0
	s_nop 0
	v_rcp_f32_e32 v5, v5
	s_nop 0
	v_rcp_f32_e32 v4, v4
	s_waitcnt vmcnt(0)
	v_mov_b32_e32 v6, v0
	v_mov_b32_e32 v7, v2
	v_pk_mul_f32 v[4:5], v[6:7], v[4:5]
	v_pk_add_f32 v[6:7], v[8:9], 1.0 op_sel_hi:[1,0]
	s_nop 0
	s_nop 0
	v_rcp_f32_e32 v7, v7
	s_or_b32 s46, s0, 8
	s_ashr_i32 s47, s46, 31
	v_readfirstlane_b32 s0, v126
	v_rcp_f32_e32 v6, v6
	v_mov_b32_e32 v2, v1
	v_pk_mul_f32 v[0:1], v[2:3], v[6:7]
	v_and_b32_sdwa v2, v5, v154 dst_sel:DWORD dst_unused:UNUSED_PAD src0_sel:WORD_1 src1_sel:DWORD
	v_and_b32_sdwa v3, v4, v154 dst_sel:DWORD dst_unused:UNUSED_PAD src0_sel:WORD_1 src1_sel:DWORD
	v_add3_u32 v3, v4, v3, s33
	v_add3_u32 v2, v5, v2, s33
	v_and_b32_sdwa v4, v1, v154 dst_sel:DWORD dst_unused:UNUSED_PAD src0_sel:WORD_1 src1_sel:DWORD
	v_and_b32_sdwa v5, v0, v154 dst_sel:DWORD dst_unused:UNUSED_PAD src0_sel:WORD_1 src1_sel:DWORD
	v_add3_u32 v1, v1, v4, s33
	v_add3_u32 v0, v0, v5, s33
	v_and_b32_e32 v1, 0xffff0000, v1
	v_and_b32_e32 v0, 0xffff0000, v0
	s_lshl_b64 s[46:47], s[46:47], 15
	s_mov_b32 m0, s0
	v_readfirstlane_b32 s0, v196
	v_or_b32_sdwa v1, v1, v2 dst_sel:DWORD dst_unused:UNUSED_PAD src0_sel:DWORD src1_sel:WORD_1
	v_or_b32_sdwa v0, v0, v3 dst_sel:DWORD dst_unused:UNUSED_PAD src0_sel:DWORD src1_sel:WORD_1
	v_lshl_add_u64 v[2:3], v[80:81], 0, s[46:47]
	global_load_lds_dwordx4 v[104:105], off
	s_mov_b32 m0, s0
	v_readfirstlane_b32 s0, v195
	global_load_lds_dwordx4 v[2:3], off
	s_mov_b32 m0, s0
	v_readfirstlane_b32 s0, v194
	global_store_dwordx2 v[16:17], v[0:1], off offset:96
	global_load_lds_dwordx4 v[102:103], off
	v_lshl_add_u64 v[0:1], v[2:3], 0, s[8:9]
	s_mov_b32 m0, s0
	v_readfirstlane_b32 s0, v193
	global_load_lds_dwordx4 v[0:1], off
	s_mov_b32 m0, s0
	v_readfirstlane_b32 s0, v192
	global_load_lds_dwordx4 v[100:101], off
	v_lshl_add_u64 v[0:1], v[2:3], 0, s[62:63]
	s_mov_b32 m0, s0
	v_readfirstlane_b32 s0, v191
	global_load_lds_dwordx4 v[0:1], off
	s_mov_b32 m0, s0
	v_readfirstlane_b32 s0, v190
	global_load_lds_dwordx4 v[94:95], off
	v_lshl_add_u64 v[0:1], v[2:3], 0, s[38:39]
	s_mov_b32 m0, s0
	v_readfirstlane_b32 s0, v204
	global_load_lds_dwordx4 v[0:1], off
	s_mov_b32 m0, s0
	v_readfirstlane_b32 s0, v203
	s_waitcnt vmcnt(0)
	s_waitcnt vmcnt(0) lgkmcnt(0)
	s_barrier
	v_lshl_add_u64 v[0:1], v[2:3], 0, s[4:5]
	v_lshl_add_u64 v[4:5], v[2:3], 0, s[92:93]
	v_lshl_add_u64 v[6:7], v[2:3], 0, s[88:89]
	v_lshl_add_u64 v[2:3], v[2:3], 0, s[44:45]
	global_load_lds_dwordx4 v[92:93], off
	s_mov_b32 m0, s0
	v_readfirstlane_b32 s0, v202
	global_load_lds_dwordx4 v[2:3], off
	s_mov_b32 m0, s0
	v_readfirstlane_b32 s0, v201
	global_load_lds_dwordx4 v[90:91], off
	s_mov_b32 m0, s0
	v_readfirstlane_b32 s0, v200
	global_load_lds_dwordx4 v[6:7], off
	s_mov_b32 m0, s0
	v_readfirstlane_b32 s0, v199
	global_load_lds_dwordx4 v[66:67], off
	s_mov_b32 m0, s0
	v_readfirstlane_b32 s0, v198
	global_load_lds_dwordx4 v[4:5], off
	s_mov_b32 m0, s0
	v_readfirstlane_b32 s0, v197
	global_load_lds_dwordx4 v[64:65], off
	s_mov_b32 m0, s0
	s_nop 0
	global_load_lds_dwordx4 v[0:1], off
	ds_read_b128 v[0:3], v188
	ds_read_b128 v[4:7], v188 offset:2048
	ds_read_b128 v[8:11], v188 offset:4096
	ds_read_b128 v[12:15], v188 offset:6144
	ds_read_b128 v[16:19], v189 offset:16384
	ds_read_b128 v[20:23], v189 offset:18432
	ds_read_b128 v[24:27], v189 offset:20480
	ds_read_b128 v[28:31], v189 offset:22528
	s_setprio 1
	s_waitcnt lgkmcnt(0)
	v_mfma_f32_16x16x32_bf16 v[32:35], v[16:19], v[0:3], 0
	v_mfma_f32_16x16x32_bf16 v[36:39], v[20:23], v[0:3], 0
	v_mfma_f32_16x16x32_bf16 v[40:43], v[24:27], v[0:3], 0
	v_mfma_f32_16x16x32_bf16 v[0:3], v[28:31], v[0:3], 0
	v_mfma_f32_16x16x32_bf16 v[44:47], v[16:19], v[4:7], 0
	v_mfma_f32_16x16x32_bf16 v[48:51], v[20:23], v[4:7], 0
	v_mfma_f32_16x16x32_bf16 v[52:55], v[24:27], v[4:7], 0
	v_mfma_f32_16x16x32_bf16 v[4:7], v[28:31], v[4:7], 0
	v_mfma_f32_16x16x32_bf16 v[56:59], v[16:19], v[8:11], 0
	v_mfma_f32_16x16x32_bf16 v[60:63], v[20:23], v[8:11], 0
	v_mfma_f32_16x16x32_bf16 v[64:67], v[24:27], v[8:11], 0
	v_mfma_f32_16x16x32_bf16 v[8:11], v[28:31], v[8:11], 0
	v_mfma_f32_16x16x32_bf16 v[16:19], v[16:19], v[12:15], 0
	v_mfma_f32_16x16x32_bf16 v[20:23], v[20:23], v[12:15], 0
	v_mfma_f32_16x16x32_bf16 v[24:27], v[24:27], v[12:15], 0
	v_mfma_f32_16x16x32_bf16 v[12:15], v[28:31], v[12:15], 0
	s_setprio 0
	ds_read_b128 v[28:31], v89
	ds_read_b128 v[90:93], v89 offset:2048
	ds_read_b128 v[100:103], v89 offset:4096
	ds_read_b128 v[104:107], v89 offset:6144
	ds_read_b128 v[108:111], v85 offset:16384
	ds_read_b128 v[112:115], v85 offset:18432
	ds_read_b128 v[156:159], v85 offset:20480
	ds_read_b128 v[166:169], v85 offset:22528
	s_setprio 1
	s_waitcnt lgkmcnt(0)
	v_mfma_f32_16x16x32_bf16 v[32:35], v[108:111], v[28:31], v[32:35]
	v_mfma_f32_16x16x32_bf16 v[36:39], v[112:115], v[28:31], v[36:39]
	v_mfma_f32_16x16x32_bf16 v[40:43], v[156:159], v[28:31], v[40:43]
	v_mfma_f32_16x16x32_bf16 v[0:3], v[166:169], v[28:31], v[0:3]
	v_mfma_f32_16x16x32_bf16 v[28:31], v[108:111], v[90:93], v[44:47]
	v_mfma_f32_16x16x32_bf16 v[44:47], v[112:115], v[90:93], v[48:51]
	v_mfma_f32_16x16x32_bf16 v[48:51], v[156:159], v[90:93], v[52:55]
	v_mfma_f32_16x16x32_bf16 v[4:7], v[166:169], v[90:93], v[4:7]
	v_mfma_f32_16x16x32_bf16 v[52:55], v[108:111], v[100:103], v[56:59]
	v_mfma_f32_16x16x32_bf16 v[56:59], v[112:115], v[100:103], v[60:63]
	v_mfma_f32_16x16x32_bf16 v[60:63], v[156:159], v[100:103], v[64:67]
	v_mfma_f32_16x16x32_bf16 v[8:11], v[166:169], v[100:103], v[8:11]
	v_mfma_f32_16x16x32_bf16 v[16:19], v[108:111], v[104:107], v[16:19]
	v_mfma_f32_16x16x32_bf16 v[20:23], v[112:115], v[104:107], v[20:23]
	v_mfma_f32_16x16x32_bf16 v[24:27], v[156:159], v[104:107], v[24:27]
	v_mfma_f32_16x16x32_bf16 v[12:15], v[166:169], v[104:107], v[12:15]
	s_setprio 0
	s_waitcnt vmcnt(0)
	s_waitcnt vmcnt(0)
	s_barrier
	ds_read_b128 v[64:67], v189 offset:55296
	ds_read_b128 v[90:93], v189 offset:53248
	ds_read_b128 v[100:103], v189 offset:51200
	ds_read_b128 v[104:107], v189 offset:49152
	ds_read_b128 v[108:111], v188 offset:38912
	ds_read_b128 v[112:115], v188 offset:36864
	ds_read_b128 v[156:159], v188 offset:34816
	ds_read_b128 v[166:169], v188 offset:32768
	s_setprio 1
	s_waitcnt lgkmcnt(0)
	v_mfma_f32_16x16x32_bf16 v[32:35], v[104:107], v[166:169], v[32:35]
	v_mfma_f32_16x16x32_bf16 v[36:39], v[100:103], v[166:169], v[36:39]
	v_mfma_f32_16x16x32_bf16 v[40:43], v[90:93], v[166:169], v[40:43]
	v_mfma_f32_16x16x32_bf16 v[0:3], v[64:67], v[166:169], v[0:3]
	v_mfma_f32_16x16x32_bf16 v[28:31], v[104:107], v[156:159], v[28:31]
	v_mfma_f32_16x16x32_bf16 v[166:169], v[100:103], v[156:159], v[44:47]
	v_mfma_f32_16x16x32_bf16 v[188:191], v[90:93], v[156:159], v[48:51]
	v_mfma_f32_16x16x32_bf16 v[4:7], v[64:67], v[156:159], v[4:7]
	v_mfma_f32_16x16x32_bf16 v[156:159], v[104:107], v[112:115], v[52:55]
	v_mfma_f32_16x16x32_bf16 v[192:195], v[100:103], v[112:115], v[56:59]
	v_mfma_f32_16x16x32_bf16 v[60:63], v[90:93], v[112:115], v[60:63]
	v_mfma_f32_16x16x32_bf16 v[8:11], v[64:67], v[112:115], v[8:11]
	v_mfma_f32_16x16x32_bf16 v[104:107], v[104:107], v[108:111], v[16:19]
	v_mfma_f32_16x16x32_bf16 v[100:103], v[100:103], v[108:111], v[20:23]
	v_mfma_f32_16x16x32_bf16 v[90:93], v[90:93], v[108:111], v[24:27]
	v_mfma_f32_16x16x32_bf16 v[64:67], v[64:67], v[108:111], v[12:15]
	s_setprio 0
	s_nop 1
	ds_read_b128 v[12:15], v89 offset:32768
	ds_read_b128 v[16:19], v89 offset:34816
	ds_read_b128 v[108:111], v89 offset:36864
	ds_read_b128 v[112:115], v89 offset:38912
	ds_read_b128 v[196:199], v85 offset:49152
	ds_read_b128 v[200:203], v85 offset:51200
	ds_read_b128 v[206:209], v85 offset:53248
	ds_read_b128 v[210:213], v85 offset:55296
	s_setprio 1
	s_waitcnt lgkmcnt(3)
	v_mfma_f32_16x16x32_bf16 v[214:217], v[196:199], v[12:15], v[32:35]
	s_waitcnt lgkmcnt(2)
	v_mfma_f32_16x16x32_bf16 v[56:59], v[200:203], v[12:15], v[36:39]
	s_waitcnt lgkmcnt(1)
	v_mfma_f32_16x16x32_bf16 v[52:55], v[206:209], v[12:15], v[40:43]
	s_waitcnt lgkmcnt(0)
	v_mfma_f32_16x16x32_bf16 v[48:51], v[210:213], v[12:15], v[0:3]
	v_mfma_f32_16x16x32_bf16 v[44:47], v[196:199], v[16:19], v[28:31]
	v_mfma_f32_16x16x32_bf16 v[40:43], v[200:203], v[16:19], v[166:169]
	v_mfma_f32_16x16x32_bf16 v[36:39], v[206:209], v[16:19], v[188:191]
	v_mfma_f32_16x16x32_bf16 v[32:35], v[210:213], v[16:19], v[4:7]
	v_mfma_f32_16x16x32_bf16 v[28:31], v[196:199], v[108:111], v[156:159]
	v_mfma_f32_16x16x32_bf16 v[24:27], v[200:203], v[108:111], v[192:195]
	v_mfma_f32_16x16x32_bf16 v[20:23], v[206:209], v[108:111], v[60:63]
	v_mfma_f32_16x16x32_bf16 v[16:19], v[210:213], v[108:111], v[8:11]
	v_mfma_f32_16x16x32_bf16 v[12:15], v[196:199], v[112:115], v[104:107]
	v_mfma_f32_16x16x32_bf16 v[8:11], v[200:203], v[112:115], v[100:103]
	v_mfma_f32_16x16x32_bf16 v[4:7], v[206:209], v[112:115], v[90:93]
	v_mfma_f32_16x16x32_bf16 v[0:3], v[210:213], v[112:115], v[64:67]
	s_setprio 0
	v_mov_b32_e32 v60, v97
	s_waitcnt vmcnt(0)
	s_barrier
	s_nop 0
	v_add_u32_e32 v60, v60, v176
	v_ashrrev_i32_e32 v62, 1, v60
	v_lshrrev_b32_e32 v63, 2, v60
	v_and_b32_e32 v61, 64, v60
	v_and_b32_e32 v62, 0xffffffc0, v62
	v_and_b32_e32 v63, 12, v63
	v_and_or_b32 v60, v60, 15, s1
	v_add_u32_e32 v62, v60, v62
	v_or3_b32 v66, v61, v63, s6
	v_ashrrev_i32_e32 v63, 31, v62
	v_lshlrev_b64 v[60:61], 11, v[62:63]
	v_lshlrev_b32_e32 v63, 2, v66
	global_load_dwordx4 v[90:93], v63, s[36:37]
	v_readlane_b32 s4, v254, 59
	v_readlane_b32 s5, v254, 60
	v_lshl_add_u64 v[64:65], s[70:71], 0, v[60:61]
	s_nop 0
	v_lshl_add_u64 v[94:95], s[4:5], 0, v[60:61]
	v_lshlrev_b32_e32 v60, 1, v66
	v_mov_b32_e32 v61, v97
	v_lshl_add_u64 v[66:67], v[64:65], 0, v[60:61]
	s_waitcnt vmcnt(0)
	v_add_f32_e32 v64, v214, v90
	v_mul_f32_e32 v64, 0xbfb8aa3b, v64
	v_exp_f32_e32 v90, v64
	v_add_f32_e32 v64, v215, v91
	v_mul_f32_e32 v64, 0xbfb8aa3b, v64
	v_exp_f32_e32 v100, v64
	v_add_f32_e32 v64, v216, v92
	v_mul_f32_e32 v64, 0xbfb8aa3b, v64
	v_exp_f32_e32 v91, v64
	v_add_f32_e32 v64, v217, v93
	v_mul_f32_e32 v64, 0xbfb8aa3b, v64
	v_exp_f32_e32 v101, v64
	v_pk_add_f32 v[90:91], v[90:91], 1.0 op_sel_hi:[1,0]
	v_lshl_add_u64 v[64:65], v[94:95], 0, v[60:61]
	s_nop 0
	v_rcp_f32_e32 v91, v91
	s_nop 0
	global_load_dwordx2 v[92:93], v[66:67], off
	v_rcp_f32_e32 v90, v90
	s_waitcnt vmcnt(0)
	v_lshlrev_b32_e32 v95, 16, v93
	v_lshlrev_b32_e32 v94, 16, v92
	v_pk_mul_f32 v[90:91], v[90:91], v[94:95]
	v_pk_add_f32 v[94:95], v[100:101], 1.0 op_sel_hi:[1,0]
	v_and_b32_e32 v93, 0xffff0000, v93
	v_and_b32_e32 v92, 0xffff0000, v92
	v_rcp_f32_e32 v95, v95
	s_nop 0
	v_rcp_f32_e32 v94, v94
	s_nop 0
	v_pk_mul_f32 v[92:93], v[94:95], v[92:93]
	v_and_b32_sdwa v85, v91, v154 dst_sel:DWORD dst_unused:UNUSED_PAD src0_sel:WORD_1 src1_sel:DWORD
	v_and_b32_sdwa v89, v90, v154 dst_sel:DWORD dst_unused:UNUSED_PAD src0_sel:WORD_1 src1_sel:DWORD
	v_add3_u32 v89, v90, v89, s33
	v_add3_u32 v85, v91, v85, s33
	v_and_b32_sdwa v90, v93, v154 dst_sel:DWORD dst_unused:UNUSED_PAD src0_sel:WORD_1 src1_sel:DWORD
	v_and_b32_sdwa v91, v92, v154 dst_sel:DWORD dst_unused:UNUSED_PAD src0_sel:WORD_1 src1_sel:DWORD
	v_add3_u32 v90, v93, v90, s33
	v_add3_u32 v91, v92, v91, s33
	v_and_b32_e32 v90, 0xffff0000, v90
	v_and_b32_e32 v92, 0xffff0000, v91
	v_or_b32_sdwa v91, v90, v85 dst_sel:DWORD dst_unused:UNUSED_PAD src0_sel:DWORD src1_sel:WORD_1
	v_or_b32_sdwa v90, v92, v89 dst_sel:DWORD dst_unused:UNUSED_PAD src0_sel:DWORD src1_sel:WORD_1
	global_store_dwordx2 v[64:65], v[90:91], off
	global_load_dwordx4 v[90:93], v63, s[36:37] offset:64
	s_waitcnt vmcnt(0)
	v_add_f32_e32 v56, v56, v90
	v_mul_f32_e32 v56, 0xbfb8aa3b, v56
	v_exp_f32_e32 v90, v56
	v_add_f32_e32 v56, v57, v91
	v_add_f32_e32 v57, v58, v92
	v_mul_f32_e32 v57, 0xbfb8aa3b, v57
	v_exp_f32_e32 v91, v57
	v_add_f32_e32 v57, v59, v93
	v_mul_f32_e32 v56, 0xbfb8aa3b, v56
	v_mul_f32_e32 v57, 0xbfb8aa3b, v57
	v_pk_add_f32 v[58:59], v[90:91], 1.0 op_sel_hi:[1,0]
	v_exp_f32_e32 v56, v56
	v_exp_f32_e32 v57, v57
	v_rcp_f32_e32 v59, v59
	v_pk_add_f32 v[56:57], v[56:57], 1.0 op_sel_hi:[1,0]
	global_load_dwordx2 v[90:91], v[66:67], off offset:32
	v_rcp_f32_e32 v58, v58
	v_div_scale_f32 v85, s[0:1], v57, v57, 1.0
	v_rcp_f32_e32 v89, v85
	s_waitcnt vmcnt(0)
	v_lshlrev_b32_e32 v93, 16, v91
	v_lshlrev_b32_e32 v92, 16, v90
	v_pk_mul_f32 v[58:59], v[58:59], v[92:93]
	v_fma_f32 v92, -v85, v89, 1.0
	v_fmac_f32_e32 v89, v92, v89
	v_div_scale_f32 v92, vcc, 1.0, v57, 1.0
	v_mul_f32_e32 v93, v92, v89
	v_fma_f32 v94, -v85, v93, v92
	v_fmac_f32_e32 v93, v94, v89
	v_fma_f32 v85, -v85, v93, v92
	v_div_fmas_f32 v85, v85, v89, v93
	v_div_fixup_f32 v57, v85, v57, 1.0
	v_and_b32_e32 v91, 0xffff0000, v91
	v_and_b32_e32 v90, 0xffff0000, v90
	v_rcp_f32_e32 v56, v56
	s_nop 0
	v_pk_mul_f32 v[56:57], v[56:57], v[90:91]
	v_and_b32_sdwa v85, v59, v154 dst_sel:DWORD dst_unused:UNUSED_PAD src0_sel:WORD_1 src1_sel:DWORD
	v_and_b32_sdwa v89, v58, v154 dst_sel:DWORD dst_unused:UNUSED_PAD src0_sel:WORD_1 src1_sel:DWORD
	v_add3_u32 v58, v58, v89, s33
	v_add3_u32 v59, v59, v85, s33
	v_and_b32_sdwa v85, v57, v154 dst_sel:DWORD dst_unused:UNUSED_PAD src0_sel:WORD_1 src1_sel:DWORD
	v_and_b32_sdwa v89, v56, v154 dst_sel:DWORD dst_unused:UNUSED_PAD src0_sel:WORD_1 src1_sel:DWORD
	v_add3_u32 v57, v57, v85, s33
	v_add3_u32 v56, v56, v89, s33
	v_and_b32_e32 v57, 0xffff0000, v57
	v_and_b32_e32 v56, 0xffff0000, v56
	v_or_b32_sdwa v57, v57, v59 dst_sel:DWORD dst_unused:UNUSED_PAD src0_sel:DWORD src1_sel:WORD_1
	v_or_b32_sdwa v56, v56, v58 dst_sel:DWORD dst_unused:UNUSED_PAD src0_sel:DWORD src1_sel:WORD_1
	global_store_dwordx2 v[64:65], v[56:57], off offset:32
	global_load_dwordx4 v[56:59], v63, s[36:37] offset:128
	s_waitcnt vmcnt(0)
	v_add_f32_e32 v52, v52, v56
	v_mul_f32_e32 v52, 0xbfb8aa3b, v52
	v_exp_f32_e32 v56, v52
	v_add_f32_e32 v52, v53, v57
	v_add_f32_e32 v53, v54, v58
	v_mul_f32_e32 v53, 0xbfb8aa3b, v53
	v_exp_f32_e32 v57, v53
	v_add_f32_e32 v53, v55, v59
	v_mul_f32_e32 v52, 0xbfb8aa3b, v52
	v_mul_f32_e32 v53, 0xbfb8aa3b, v53
	v_pk_add_f32 v[54:55], v[56:57], 1.0 op_sel_hi:[1,0]
	v_exp_f32_e32 v52, v52
	v_exp_f32_e32 v53, v53
	v_rcp_f32_e32 v55, v55
	v_pk_add_f32 v[52:53], v[52:53], 1.0 op_sel_hi:[1,0]
	v_rcp_f32_e32 v54, v54
	global_load_dwordx2 v[56:57], v[66:67], off offset:64
	s_waitcnt vmcnt(0)
	v_lshlrev_b32_e32 v59, 16, v57
	v_lshlrev_b32_e32 v58, 16, v56
	v_pk_mul_f32 v[54:55], v[54:55], v[58:59]
	v_and_b32_e32 v57, 0xffff0000, v57
	v_and_b32_e32 v56, 0xffff0000, v56
	v_rcp_f32_e32 v53, v53
	s_nop 0
	v_rcp_f32_e32 v52, v52
	s_nop 0
	v_pk_mul_f32 v[52:53], v[52:53], v[56:57]
	v_and_b32_sdwa v56, v55, v154 dst_sel:DWORD dst_unused:UNUSED_PAD src0_sel:WORD_1 src1_sel:DWORD
	v_and_b32_sdwa v57, v54, v154 dst_sel:DWORD dst_unused:UNUSED_PAD src0_sel:WORD_1 src1_sel:DWORD
	v_add3_u32 v54, v54, v57, s33
	v_add3_u32 v55, v55, v56, s33
	v_and_b32_sdwa v56, v53, v154 dst_sel:DWORD dst_unused:UNUSED_PAD src0_sel:WORD_1 src1_sel:DWORD
	v_and_b32_sdwa v57, v52, v154 dst_sel:DWORD dst_unused:UNUSED_PAD src0_sel:WORD_1 src1_sel:DWORD
	v_add3_u32 v53, v53, v56, s33
	v_add3_u32 v52, v52, v57, s33
	v_and_b32_e32 v53, 0xffff0000, v53
	v_and_b32_e32 v52, 0xffff0000, v52
	v_or_b32_sdwa v53, v53, v55 dst_sel:DWORD dst_unused:UNUSED_PAD src0_sel:DWORD src1_sel:WORD_1
	v_or_b32_sdwa v52, v52, v54 dst_sel:DWORD dst_unused:UNUSED_PAD src0_sel:DWORD src1_sel:WORD_1
	global_store_dwordx2 v[64:65], v[52:53], off offset:64
	global_load_dwordx4 v[52:55], v63, s[36:37] offset:192
	s_waitcnt vmcnt(0)
	v_add_f32_e32 v48, v48, v52
	v_mul_f32_e32 v48, 0xbfb8aa3b, v48
	v_exp_f32_e32 v52, v48
	v_add_f32_e32 v48, v49, v53
	v_add_f32_e32 v49, v50, v54
	v_mul_f32_e32 v49, 0xbfb8aa3b, v49
	v_exp_f32_e32 v53, v49
	v_add_f32_e32 v49, v51, v55
	v_mul_f32_e32 v48, 0xbfb8aa3b, v48
	v_mul_f32_e32 v49, 0xbfb8aa3b, v49
	v_pk_add_f32 v[50:51], v[52:53], 1.0 op_sel_hi:[1,0]
	v_exp_f32_e32 v48, v48
	v_exp_f32_e32 v49, v49
	v_rcp_f32_e32 v51, v51
	v_pk_add_f32 v[48:49], v[48:49], 1.0 op_sel_hi:[1,0]
	v_rcp_f32_e32 v50, v50
	global_load_dwordx2 v[52:53], v[66:67], off offset:96
	s_waitcnt vmcnt(0)
	v_lshlrev_b32_e32 v55, 16, v53
	v_lshlrev_b32_e32 v54, 16, v52
	v_pk_mul_f32 v[50:51], v[50:51], v[54:55]
	v_and_b32_e32 v53, 0xffff0000, v53
	v_and_b32_e32 v52, 0xffff0000, v52
	v_rcp_f32_e32 v49, v49
	s_nop 0
	v_rcp_f32_e32 v48, v48
	s_nop 0
	v_pk_mul_f32 v[48:49], v[48:49], v[52:53]
	v_and_b32_sdwa v52, v51, v154 dst_sel:DWORD dst_unused:UNUSED_PAD src0_sel:WORD_1 src1_sel:DWORD
	v_and_b32_sdwa v53, v50, v154 dst_sel:DWORD dst_unused:UNUSED_PAD src0_sel:WORD_1 src1_sel:DWORD
	v_add3_u32 v50, v50, v53, s33
	v_add3_u32 v51, v51, v52, s33
	v_and_b32_sdwa v52, v49, v154 dst_sel:DWORD dst_unused:UNUSED_PAD src0_sel:WORD_1 src1_sel:DWORD
	v_and_b32_sdwa v53, v48, v154 dst_sel:DWORD dst_unused:UNUSED_PAD src0_sel:WORD_1 src1_sel:DWORD
	v_add3_u32 v49, v49, v52, s33
	v_add3_u32 v48, v48, v53, s33
	v_and_b32_e32 v49, 0xffff0000, v49
	v_and_b32_e32 v48, 0xffff0000, v48
	v_or_b32_sdwa v49, v49, v51 dst_sel:DWORD dst_unused:UNUSED_PAD src0_sel:DWORD src1_sel:WORD_1
	v_or_b32_sdwa v48, v48, v50 dst_sel:DWORD dst_unused:UNUSED_PAD src0_sel:DWORD src1_sel:WORD_1
	global_store_dwordx2 v[64:65], v[48:49], off offset:96
	global_load_dwordx4 v[50:53], v63, s[36:37]
	v_or_b32_e32 v48, 16, v62
	v_ashrrev_i32_e32 v49, 31, v48
	v_lshlrev_b64 v[48:49], 11, v[48:49]
	v_lshl_add_u64 v[54:55], s[70:71], 0, v[48:49]
	v_lshl_add_u64 v[56:57], s[4:5], 0, v[48:49]
	v_lshl_add_u64 v[48:49], v[54:55], 0, v[60:61]
	s_waitcnt vmcnt(0)
	v_add_f32_e32 v44, v44, v50
	v_mul_f32_e32 v44, 0xbfb8aa3b, v44
	v_exp_f32_e32 v50, v44
	v_add_f32_e32 v44, v45, v51
	v_mul_f32_e32 v44, 0xbfb8aa3b, v44
	v_exp_f32_e32 v54, v44
	v_add_f32_e32 v44, v46, v52
	v_mul_f32_e32 v44, 0xbfb8aa3b, v44
	v_exp_f32_e32 v51, v44
	v_add_f32_e32 v44, v47, v53
	v_mul_f32_e32 v44, 0xbfb8aa3b, v44
	v_exp_f32_e32 v55, v44
	v_pk_add_f32 v[46:47], v[50:51], 1.0 op_sel_hi:[1,0]
	v_lshl_add_u64 v[44:45], v[56:57], 0, v[60:61]
	s_nop 0
	v_rcp_f32_e32 v47, v47
	s_nop 0
	v_rcp_f32_e32 v46, v46
	global_load_dwordx2 v[50:51], v[48:49], off
	s_waitcnt vmcnt(0)
	v_lshlrev_b32_e32 v53, 16, v51
	v_lshlrev_b32_e32 v52, 16, v50
	v_pk_mul_f32 v[46:47], v[46:47], v[52:53]
	v_pk_add_f32 v[52:53], v[54:55], 1.0 op_sel_hi:[1,0]
	v_and_b32_e32 v51, 0xffff0000, v51
	v_and_b32_e32 v50, 0xffff0000, v50
	v_rcp_f32_e32 v53, v53
	s_nop 0
	v_rcp_f32_e32 v52, v52
	s_nop 0
	v_pk_mul_f32 v[50:51], v[52:53], v[50:51]
	v_and_b32_sdwa v52, v47, v154 dst_sel:DWORD dst_unused:UNUSED_PAD src0_sel:WORD_1 src1_sel:DWORD
	v_and_b32_sdwa v53, v46, v154 dst_sel:DWORD dst_unused:UNUSED_PAD src0_sel:WORD_1 src1_sel:DWORD
	v_add3_u32 v46, v46, v53, s33
	v_add3_u32 v47, v47, v52, s33
	v_and_b32_sdwa v52, v51, v154 dst_sel:DWORD dst_unused:UNUSED_PAD src0_sel:WORD_1 src1_sel:DWORD
	v_and_b32_sdwa v53, v50, v154 dst_sel:DWORD dst_unused:UNUSED_PAD src0_sel:WORD_1 src1_sel:DWORD
	v_add3_u32 v51, v51, v52, s33
	v_add3_u32 v50, v50, v53, s33
	v_and_b32_e32 v51, 0xffff0000, v51
	v_and_b32_e32 v50, 0xffff0000, v50
	v_or_b32_sdwa v47, v51, v47 dst_sel:DWORD dst_unused:UNUSED_PAD src0_sel:DWORD src1_sel:WORD_1
	v_or_b32_sdwa v46, v50, v46 dst_sel:DWORD dst_unused:UNUSED_PAD src0_sel:DWORD src1_sel:WORD_1
	global_store_dwordx2 v[44:45], v[46:47], off
	global_load_dwordx4 v[50:53], v63, s[36:37] offset:64
	s_waitcnt vmcnt(0)
	v_add_f32_e32 v40, v40, v50
	v_mul_f32_e32 v40, 0xbfb8aa3b, v40
	v_exp_f32_e32 v46, v40
	v_add_f32_e32 v40, v41, v51
	v_add_f32_e32 v41, v42, v52
	v_mul_f32_e32 v41, 0xbfb8aa3b, v41
	v_exp_f32_e32 v47, v41
	v_add_f32_e32 v41, v43, v53
	v_mul_f32_e32 v40, 0xbfb8aa3b, v40
	v_mul_f32_e32 v41, 0xbfb8aa3b, v41
	v_pk_add_f32 v[42:43], v[46:47], 1.0 op_sel_hi:[1,0]
	v_exp_f32_e32 v40, v40
	v_exp_f32_e32 v41, v41
	v_rcp_f32_e32 v43, v43
	v_pk_add_f32 v[40:41], v[40:41], 1.0 op_sel_hi:[1,0]
	v_rcp_f32_e32 v42, v42
	global_load_dwordx2 v[46:47], v[48:49], off offset:32
	s_waitcnt vmcnt(0)
	v_lshlrev_b32_e32 v51, 16, v47
	v_lshlrev_b32_e32 v50, 16, v46
	v_pk_mul_f32 v[42:43], v[42:43], v[50:51]
	v_and_b32_e32 v47, 0xffff0000, v47
	v_and_b32_e32 v46, 0xffff0000, v46
	v_rcp_f32_e32 v41, v41
	s_nop 0
	v_rcp_f32_e32 v40, v40
	s_nop 0
	v_pk_mul_f32 v[40:41], v[40:41], v[46:47]
	v_and_b32_sdwa v46, v43, v154 dst_sel:DWORD dst_unused:UNUSED_PAD src0_sel:WORD_1 src1_sel:DWORD
	v_and_b32_sdwa v47, v42, v154 dst_sel:DWORD dst_unused:UNUSED_PAD src0_sel:WORD_1 src1_sel:DWORD
	v_add3_u32 v42, v42, v47, s33
	v_add3_u32 v43, v43, v46, s33
	v_and_b32_sdwa v46, v41, v154 dst_sel:DWORD dst_unused:UNUSED_PAD src0_sel:WORD_1 src1_sel:DWORD
	v_and_b32_sdwa v47, v40, v154 dst_sel:DWORD dst_unused:UNUSED_PAD src0_sel:WORD_1 src1_sel:DWORD
	v_add3_u32 v41, v41, v46, s33
	v_add3_u32 v40, v40, v47, s33
	v_and_b32_e32 v41, 0xffff0000, v41
	v_and_b32_e32 v40, 0xffff0000, v40
	v_or_b32_sdwa v41, v41, v43 dst_sel:DWORD dst_unused:UNUSED_PAD src0_sel:DWORD src1_sel:WORD_1
	v_or_b32_sdwa v40, v40, v42 dst_sel:DWORD dst_unused:UNUSED_PAD src0_sel:DWORD src1_sel:WORD_1
	global_store_dwordx2 v[44:45], v[40:41], off offset:32
	global_load_dwordx4 v[40:43], v63, s[36:37] offset:128
	s_waitcnt vmcnt(0)
	v_add_f32_e32 v36, v36, v40
	v_mul_f32_e32 v36, 0xbfb8aa3b, v36
	v_exp_f32_e32 v40, v36
	v_add_f32_e32 v36, v37, v41
	v_add_f32_e32 v37, v38, v42
	v_mul_f32_e32 v37, 0xbfb8aa3b, v37
	v_exp_f32_e32 v41, v37
	v_add_f32_e32 v37, v39, v43
	v_mul_f32_e32 v36, 0xbfb8aa3b, v36
	v_mul_f32_e32 v37, 0xbfb8aa3b, v37
	v_pk_add_f32 v[38:39], v[40:41], 1.0 op_sel_hi:[1,0]
	v_exp_f32_e32 v36, v36
	v_exp_f32_e32 v37, v37
	v_rcp_f32_e32 v39, v39
	v_pk_add_f32 v[36:37], v[36:37], 1.0 op_sel_hi:[1,0]
	v_rcp_f32_e32 v38, v38
	global_load_dwordx2 v[40:41], v[48:49], off offset:64
	s_waitcnt vmcnt(0)
	v_lshlrev_b32_e32 v43, 16, v41
	v_lshlrev_b32_e32 v42, 16, v40
	v_pk_mul_f32 v[38:39], v[38:39], v[42:43]
	v_and_b32_e32 v41, 0xffff0000, v41
	v_and_b32_e32 v40, 0xffff0000, v40
	v_rcp_f32_e32 v37, v37
	s_nop 0
	v_rcp_f32_e32 v36, v36
	s_nop 0
	v_pk_mul_f32 v[36:37], v[36:37], v[40:41]
	v_and_b32_sdwa v40, v39, v154 dst_sel:DWORD dst_unused:UNUSED_PAD src0_sel:WORD_1 src1_sel:DWORD
	v_and_b32_sdwa v41, v38, v154 dst_sel:DWORD dst_unused:UNUSED_PAD src0_sel:WORD_1 src1_sel:DWORD
	v_add3_u32 v38, v38, v41, s33
	v_add3_u32 v39, v39, v40, s33
	v_and_b32_sdwa v40, v37, v154 dst_sel:DWORD dst_unused:UNUSED_PAD src0_sel:WORD_1 src1_sel:DWORD
	v_and_b32_sdwa v41, v36, v154 dst_sel:DWORD dst_unused:UNUSED_PAD src0_sel:WORD_1 src1_sel:DWORD
	v_add3_u32 v37, v37, v40, s33
	v_add3_u32 v36, v36, v41, s33
	v_and_b32_e32 v37, 0xffff0000, v37
	v_and_b32_e32 v36, 0xffff0000, v36
	v_or_b32_sdwa v37, v37, v39 dst_sel:DWORD dst_unused:UNUSED_PAD src0_sel:DWORD src1_sel:WORD_1
	v_or_b32_sdwa v36, v36, v38 dst_sel:DWORD dst_unused:UNUSED_PAD src0_sel:DWORD src1_sel:WORD_1
	global_store_dwordx2 v[44:45], v[36:37], off offset:64
	global_load_dwordx4 v[36:39], v63, s[36:37] offset:192
	s_waitcnt vmcnt(0)
	v_add_f32_e32 v32, v32, v36
	v_mul_f32_e32 v32, 0xbfb8aa3b, v32
	v_exp_f32_e32 v36, v32
	v_add_f32_e32 v32, v33, v37
	v_add_f32_e32 v33, v34, v38
	v_mul_f32_e32 v33, 0xbfb8aa3b, v33
	v_exp_f32_e32 v37, v33
	v_add_f32_e32 v33, v35, v39
	v_mul_f32_e32 v32, 0xbfb8aa3b, v32
	v_mul_f32_e32 v33, 0xbfb8aa3b, v33
	v_pk_add_f32 v[34:35], v[36:37], 1.0 op_sel_hi:[1,0]
	v_exp_f32_e32 v32, v32
	v_exp_f32_e32 v33, v33
	v_rcp_f32_e32 v35, v35
	v_pk_add_f32 v[32:33], v[32:33], 1.0 op_sel_hi:[1,0]
	v_rcp_f32_e32 v34, v34
	global_load_dwordx2 v[36:37], v[48:49], off offset:96
	s_waitcnt vmcnt(0)
	v_lshlrev_b32_e32 v39, 16, v37
	v_lshlrev_b32_e32 v38, 16, v36
	v_pk_mul_f32 v[34:35], v[34:35], v[38:39]
	v_and_b32_e32 v37, 0xffff0000, v37
	v_and_b32_e32 v36, 0xffff0000, v36
	v_rcp_f32_e32 v33, v33
	s_nop 0
	v_rcp_f32_e32 v32, v32
	s_nop 0
	v_pk_mul_f32 v[32:33], v[32:33], v[36:37]
	v_and_b32_sdwa v36, v35, v154 dst_sel:DWORD dst_unused:UNUSED_PAD src0_sel:WORD_1 src1_sel:DWORD
	v_and_b32_sdwa v37, v34, v154 dst_sel:DWORD dst_unused:UNUSED_PAD src0_sel:WORD_1 src1_sel:DWORD
	v_add3_u32 v34, v34, v37, s33
	v_add3_u32 v35, v35, v36, s33
	v_and_b32_sdwa v36, v33, v154 dst_sel:DWORD dst_unused:UNUSED_PAD src0_sel:WORD_1 src1_sel:DWORD
	v_and_b32_sdwa v37, v32, v154 dst_sel:DWORD dst_unused:UNUSED_PAD src0_sel:WORD_1 src1_sel:DWORD
	v_add3_u32 v33, v33, v36, s33
	v_add3_u32 v32, v32, v37, s33
	v_and_b32_e32 v33, 0xffff0000, v33
	v_and_b32_e32 v32, 0xffff0000, v32
	v_or_b32_sdwa v33, v33, v35 dst_sel:DWORD dst_unused:UNUSED_PAD src0_sel:DWORD src1_sel:WORD_1
	v_or_b32_sdwa v32, v32, v34 dst_sel:DWORD dst_unused:UNUSED_PAD src0_sel:DWORD src1_sel:WORD_1
	global_store_dwordx2 v[44:45], v[32:33], off offset:96
	global_load_dwordx4 v[34:37], v63, s[36:37]
	v_or_b32_e32 v32, 32, v62
	v_ashrrev_i32_e32 v33, 31, v32
	v_lshlrev_b64 v[32:33], 11, v[32:33]
	v_lshl_add_u64 v[38:39], s[70:71], 0, v[32:33]
	v_lshl_add_u64 v[40:41], s[4:5], 0, v[32:33]
	v_lshl_add_u64 v[32:33], v[38:39], 0, v[60:61]
	s_waitcnt vmcnt(0)
	v_add_f32_e32 v28, v28, v34
	v_mul_f32_e32 v28, 0xbfb8aa3b, v28
	v_exp_f32_e32 v34, v28
	v_add_f32_e32 v28, v29, v35
	v_mul_f32_e32 v28, 0xbfb8aa3b, v28
	v_exp_f32_e32 v38, v28
	v_add_f32_e32 v28, v30, v36
	v_mul_f32_e32 v28, 0xbfb8aa3b, v28
	v_exp_f32_e32 v35, v28
	v_add_f32_e32 v28, v31, v37
	v_mul_f32_e32 v28, 0xbfb8aa3b, v28
	v_exp_f32_e32 v39, v28
	v_pk_add_f32 v[30:31], v[34:35], 1.0 op_sel_hi:[1,0]
	v_lshl_add_u64 v[28:29], v[40:41], 0, v[60:61]
	s_nop 0
	v_rcp_f32_e32 v31, v31
	s_nop 0
	v_rcp_f32_e32 v30, v30
	global_load_dwordx2 v[34:35], v[32:33], off
	s_waitcnt vmcnt(0)
	v_lshlrev_b32_e32 v37, 16, v35
	v_lshlrev_b32_e32 v36, 16, v34
	v_pk_mul_f32 v[30:31], v[30:31], v[36:37]
	v_pk_add_f32 v[36:37], v[38:39], 1.0 op_sel_hi:[1,0]
	v_and_b32_e32 v35, 0xffff0000, v35
	v_and_b32_e32 v34, 0xffff0000, v34
	v_rcp_f32_e32 v37, v37
	s_nop 0
	v_rcp_f32_e32 v36, v36
	s_nop 0
	v_pk_mul_f32 v[34:35], v[36:37], v[34:35]
	v_and_b32_sdwa v36, v31, v154 dst_sel:DWORD dst_unused:UNUSED_PAD src0_sel:WORD_1 src1_sel:DWORD
	v_and_b32_sdwa v37, v30, v154 dst_sel:DWORD dst_unused:UNUSED_PAD src0_sel:WORD_1 src1_sel:DWORD
	v_add3_u32 v30, v30, v37, s33
	v_add3_u32 v31, v31, v36, s33
	v_and_b32_sdwa v36, v35, v154 dst_sel:DWORD dst_unused:UNUSED_PAD src0_sel:WORD_1 src1_sel:DWORD
	v_and_b32_sdwa v37, v34, v154 dst_sel:DWORD dst_unused:UNUSED_PAD src0_sel:WORD_1 src1_sel:DWORD
	v_add3_u32 v35, v35, v36, s33
	v_add3_u32 v34, v34, v37, s33
	v_and_b32_e32 v35, 0xffff0000, v35
	v_and_b32_e32 v34, 0xffff0000, v34
	v_or_b32_sdwa v31, v35, v31 dst_sel:DWORD dst_unused:UNUSED_PAD src0_sel:DWORD src1_sel:WORD_1
	v_or_b32_sdwa v30, v34, v30 dst_sel:DWORD dst_unused:UNUSED_PAD src0_sel:DWORD src1_sel:WORD_1
	global_store_dwordx2 v[28:29], v[30:31], off
	global_load_dwordx4 v[34:37], v63, s[36:37] offset:64
	s_waitcnt vmcnt(0)
	v_add_f32_e32 v24, v24, v34
	v_mul_f32_e32 v24, 0xbfb8aa3b, v24
	v_exp_f32_e32 v30, v24
	v_add_f32_e32 v24, v25, v35
	v_add_f32_e32 v25, v26, v36
	v_mul_f32_e32 v25, 0xbfb8aa3b, v25
	v_exp_f32_e32 v31, v25
	v_add_f32_e32 v25, v27, v37
	v_mul_f32_e32 v24, 0xbfb8aa3b, v24
	v_mul_f32_e32 v25, 0xbfb8aa3b, v25
	v_pk_add_f32 v[26:27], v[30:31], 1.0 op_sel_hi:[1,0]
	v_exp_f32_e32 v24, v24
	v_exp_f32_e32 v25, v25
	v_rcp_f32_e32 v27, v27
	v_pk_add_f32 v[24:25], v[24:25], 1.0 op_sel_hi:[1,0]
	v_rcp_f32_e32 v26, v26
	global_load_dwordx2 v[30:31], v[32:33], off offset:32
	s_waitcnt vmcnt(0)
	v_lshlrev_b32_e32 v35, 16, v31
	v_lshlrev_b32_e32 v34, 16, v30
	v_pk_mul_f32 v[26:27], v[26:27], v[34:35]
	v_and_b32_e32 v31, 0xffff0000, v31
	v_and_b32_e32 v30, 0xffff0000, v30
	v_rcp_f32_e32 v25, v25
	s_nop 0
	v_rcp_f32_e32 v24, v24
	s_nop 0
	v_pk_mul_f32 v[24:25], v[24:25], v[30:31]
	v_and_b32_sdwa v30, v27, v154 dst_sel:DWORD dst_unused:UNUSED_PAD src0_sel:WORD_1 src1_sel:DWORD
	v_and_b32_sdwa v31, v26, v154 dst_sel:DWORD dst_unused:UNUSED_PAD src0_sel:WORD_1 src1_sel:DWORD
	v_add3_u32 v26, v26, v31, s33
	v_add3_u32 v27, v27, v30, s33
	v_and_b32_sdwa v30, v25, v154 dst_sel:DWORD dst_unused:UNUSED_PAD src0_sel:WORD_1 src1_sel:DWORD
	v_and_b32_sdwa v31, v24, v154 dst_sel:DWORD dst_unused:UNUSED_PAD src0_sel:WORD_1 src1_sel:DWORD
	v_add3_u32 v25, v25, v30, s33
	v_add3_u32 v24, v24, v31, s33
	v_and_b32_e32 v25, 0xffff0000, v25
	v_and_b32_e32 v24, 0xffff0000, v24
	v_or_b32_sdwa v25, v25, v27 dst_sel:DWORD dst_unused:UNUSED_PAD src0_sel:DWORD src1_sel:WORD_1
	v_or_b32_sdwa v24, v24, v26 dst_sel:DWORD dst_unused:UNUSED_PAD src0_sel:DWORD src1_sel:WORD_1
	global_store_dwordx2 v[28:29], v[24:25], off offset:32
	global_load_dwordx4 v[24:27], v63, s[36:37] offset:128
	s_waitcnt vmcnt(0)
	v_add_f32_e32 v20, v20, v24
	v_mul_f32_e32 v20, 0xbfb8aa3b, v20
	v_exp_f32_e32 v24, v20
	v_add_f32_e32 v20, v21, v25
	v_add_f32_e32 v21, v22, v26
	v_mul_f32_e32 v21, 0xbfb8aa3b, v21
	v_exp_f32_e32 v25, v21
	v_add_f32_e32 v21, v23, v27
	v_mul_f32_e32 v20, 0xbfb8aa3b, v20
	v_mul_f32_e32 v21, 0xbfb8aa3b, v21
	v_pk_add_f32 v[22:23], v[24:25], 1.0 op_sel_hi:[1,0]
	v_exp_f32_e32 v20, v20
	v_exp_f32_e32 v21, v21
	v_rcp_f32_e32 v23, v23
	v_pk_add_f32 v[20:21], v[20:21], 1.0 op_sel_hi:[1,0]
	v_rcp_f32_e32 v22, v22
	global_load_dwordx2 v[24:25], v[32:33], off offset:64
	s_waitcnt vmcnt(0)
	v_lshlrev_b32_e32 v27, 16, v25
	v_lshlrev_b32_e32 v26, 16, v24
	v_pk_mul_f32 v[22:23], v[22:23], v[26:27]
	v_and_b32_e32 v25, 0xffff0000, v25
	v_and_b32_e32 v24, 0xffff0000, v24
	v_rcp_f32_e32 v21, v21
	s_nop 0
	v_rcp_f32_e32 v20, v20
	s_nop 0
	v_pk_mul_f32 v[20:21], v[20:21], v[24:25]
	v_and_b32_sdwa v24, v23, v154 dst_sel:DWORD dst_unused:UNUSED_PAD src0_sel:WORD_1 src1_sel:DWORD
	v_and_b32_sdwa v25, v22, v154 dst_sel:DWORD dst_unused:UNUSED_PAD src0_sel:WORD_1 src1_sel:DWORD
	v_add3_u32 v22, v22, v25, s33
	v_add3_u32 v23, v23, v24, s33
	v_and_b32_sdwa v24, v21, v154 dst_sel:DWORD dst_unused:UNUSED_PAD src0_sel:WORD_1 src1_sel:DWORD
	v_and_b32_sdwa v25, v20, v154 dst_sel:DWORD dst_unused:UNUSED_PAD src0_sel:WORD_1 src1_sel:DWORD
	v_add3_u32 v21, v21, v24, s33
	v_add3_u32 v20, v20, v25, s33
	v_and_b32_e32 v21, 0xffff0000, v21
	v_and_b32_e32 v20, 0xffff0000, v20
	v_or_b32_sdwa v21, v21, v23 dst_sel:DWORD dst_unused:UNUSED_PAD src0_sel:DWORD src1_sel:WORD_1
	v_or_b32_sdwa v20, v20, v22 dst_sel:DWORD dst_unused:UNUSED_PAD src0_sel:DWORD src1_sel:WORD_1
	global_store_dwordx2 v[28:29], v[20:21], off offset:64
	global_load_dwordx4 v[20:23], v63, s[36:37] offset:192
	s_waitcnt vmcnt(0)
	v_add_f32_e32 v16, v16, v20
	v_mul_f32_e32 v16, 0xbfb8aa3b, v16
	v_exp_f32_e32 v20, v16
	v_add_f32_e32 v16, v17, v21
	v_add_f32_e32 v17, v18, v22
	v_mul_f32_e32 v17, 0xbfb8aa3b, v17
	v_exp_f32_e32 v21, v17
	v_add_f32_e32 v17, v19, v23
	v_mul_f32_e32 v16, 0xbfb8aa3b, v16
	v_mul_f32_e32 v17, 0xbfb8aa3b, v17
	v_pk_add_f32 v[18:19], v[20:21], 1.0 op_sel_hi:[1,0]
	v_exp_f32_e32 v16, v16
	v_exp_f32_e32 v17, v17
	v_rcp_f32_e32 v19, v19
	v_pk_add_f32 v[16:17], v[16:17], 1.0 op_sel_hi:[1,0]
	v_rcp_f32_e32 v18, v18
	global_load_dwordx2 v[20:21], v[32:33], off offset:96
	s_waitcnt vmcnt(0)
	v_lshlrev_b32_e32 v23, 16, v21
	v_lshlrev_b32_e32 v22, 16, v20
	v_pk_mul_f32 v[18:19], v[18:19], v[22:23]
	v_and_b32_e32 v21, 0xffff0000, v21
	v_and_b32_e32 v20, 0xffff0000, v20
	v_rcp_f32_e32 v17, v17
	s_nop 0
	v_rcp_f32_e32 v16, v16
	s_nop 0
	v_pk_mul_f32 v[16:17], v[16:17], v[20:21]
	v_and_b32_sdwa v20, v19, v154 dst_sel:DWORD dst_unused:UNUSED_PAD src0_sel:WORD_1 src1_sel:DWORD
	v_and_b32_sdwa v21, v18, v154 dst_sel:DWORD dst_unused:UNUSED_PAD src0_sel:WORD_1 src1_sel:DWORD
	v_add3_u32 v18, v18, v21, s33
	v_add3_u32 v19, v19, v20, s33
	v_and_b32_sdwa v20, v17, v154 dst_sel:DWORD dst_unused:UNUSED_PAD src0_sel:WORD_1 src1_sel:DWORD
	v_and_b32_sdwa v21, v16, v154 dst_sel:DWORD dst_unused:UNUSED_PAD src0_sel:WORD_1 src1_sel:DWORD
	v_add3_u32 v17, v17, v20, s33
	v_add3_u32 v16, v16, v21, s33
	v_and_b32_e32 v17, 0xffff0000, v17
	v_and_b32_e32 v16, 0xffff0000, v16
	v_or_b32_sdwa v17, v17, v19 dst_sel:DWORD dst_unused:UNUSED_PAD src0_sel:DWORD src1_sel:WORD_1
	v_or_b32_sdwa v16, v16, v18 dst_sel:DWORD dst_unused:UNUSED_PAD src0_sel:DWORD src1_sel:WORD_1
	global_store_dwordx2 v[28:29], v[16:17], off offset:96
	global_load_dwordx4 v[18:21], v63, s[36:37]
	v_or_b32_e32 v16, 48, v62
	v_ashrrev_i32_e32 v17, 31, v16
	v_lshlrev_b64 v[16:17], 11, v[16:17]
	v_lshl_add_u64 v[22:23], s[70:71], 0, v[16:17]
	v_lshl_add_u64 v[24:25], s[4:5], 0, v[16:17]
	v_lshl_add_u64 v[16:17], v[22:23], 0, v[60:61]
	s_waitcnt vmcnt(0)
	v_add_f32_e32 v12, v12, v18
	v_mul_f32_e32 v12, 0xbfb8aa3b, v12
	v_exp_f32_e32 v18, v12
	v_add_f32_e32 v12, v13, v19
	v_mul_f32_e32 v12, 0xbfb8aa3b, v12
	v_exp_f32_e32 v22, v12
	v_add_f32_e32 v12, v14, v20
	v_mul_f32_e32 v12, 0xbfb8aa3b, v12
	v_exp_f32_e32 v19, v12
	v_add_f32_e32 v12, v15, v21
	v_mul_f32_e32 v12, 0xbfb8aa3b, v12
	v_exp_f32_e32 v23, v12
	v_pk_add_f32 v[14:15], v[18:19], 1.0 op_sel_hi:[1,0]
	v_lshl_add_u64 v[12:13], v[24:25], 0, v[60:61]
	s_nop 0
	v_rcp_f32_e32 v15, v15
	s_nop 0
	v_rcp_f32_e32 v14, v14
	global_load_dwordx2 v[18:19], v[16:17], off
	s_waitcnt vmcnt(0)
	v_lshlrev_b32_e32 v21, 16, v19
	v_lshlrev_b32_e32 v20, 16, v18
	v_pk_mul_f32 v[14:15], v[14:15], v[20:21]
	v_pk_add_f32 v[20:21], v[22:23], 1.0 op_sel_hi:[1,0]
	v_and_b32_e32 v19, 0xffff0000, v19
	v_and_b32_e32 v18, 0xffff0000, v18
	v_rcp_f32_e32 v21, v21
	s_nop 0
	v_rcp_f32_e32 v20, v20
	s_nop 0
	v_pk_mul_f32 v[18:19], v[20:21], v[18:19]
	v_and_b32_sdwa v20, v15, v154 dst_sel:DWORD dst_unused:UNUSED_PAD src0_sel:WORD_1 src1_sel:DWORD
	v_and_b32_sdwa v21, v14, v154 dst_sel:DWORD dst_unused:UNUSED_PAD src0_sel:WORD_1 src1_sel:DWORD
	v_add3_u32 v14, v14, v21, s33
	v_add3_u32 v15, v15, v20, s33
	v_and_b32_sdwa v20, v19, v154 dst_sel:DWORD dst_unused:UNUSED_PAD src0_sel:WORD_1 src1_sel:DWORD
	v_and_b32_sdwa v21, v18, v154 dst_sel:DWORD dst_unused:UNUSED_PAD src0_sel:WORD_1 src1_sel:DWORD
	v_add3_u32 v19, v19, v20, s33
	v_add3_u32 v18, v18, v21, s33
	v_and_b32_e32 v19, 0xffff0000, v19
	v_and_b32_e32 v18, 0xffff0000, v18
	v_or_b32_sdwa v15, v19, v15 dst_sel:DWORD dst_unused:UNUSED_PAD src0_sel:DWORD src1_sel:WORD_1
	v_or_b32_sdwa v14, v18, v14 dst_sel:DWORD dst_unused:UNUSED_PAD src0_sel:DWORD src1_sel:WORD_1
	global_store_dwordx2 v[12:13], v[14:15], off
	global_load_dwordx4 v[18:21], v63, s[36:37] offset:64
	s_waitcnt vmcnt(0)
	v_add_f32_e32 v8, v8, v18
	v_mul_f32_e32 v8, 0xbfb8aa3b, v8
	v_exp_f32_e32 v14, v8
	v_add_f32_e32 v8, v9, v19
	v_add_f32_e32 v9, v10, v20
	v_mul_f32_e32 v9, 0xbfb8aa3b, v9
	v_exp_f32_e32 v15, v9
	v_add_f32_e32 v9, v11, v21
	v_mul_f32_e32 v8, 0xbfb8aa3b, v8
	v_mul_f32_e32 v9, 0xbfb8aa3b, v9
	v_pk_add_f32 v[10:11], v[14:15], 1.0 op_sel_hi:[1,0]
	v_exp_f32_e32 v8, v8
	v_exp_f32_e32 v9, v9
	v_rcp_f32_e32 v11, v11
	v_pk_add_f32 v[8:9], v[8:9], 1.0 op_sel_hi:[1,0]
	v_rcp_f32_e32 v10, v10
	global_load_dwordx2 v[14:15], v[16:17], off offset:32
	s_waitcnt vmcnt(0)
	v_lshlrev_b32_e32 v19, 16, v15
	v_lshlrev_b32_e32 v18, 16, v14
	v_pk_mul_f32 v[10:11], v[10:11], v[18:19]
	v_and_b32_e32 v15, 0xffff0000, v15
	v_and_b32_e32 v14, 0xffff0000, v14
	v_rcp_f32_e32 v9, v9
	s_nop 0
	v_rcp_f32_e32 v8, v8
	s_nop 0
	v_pk_mul_f32 v[8:9], v[8:9], v[14:15]
	v_and_b32_sdwa v14, v11, v154 dst_sel:DWORD dst_unused:UNUSED_PAD src0_sel:WORD_1 src1_sel:DWORD
	v_and_b32_sdwa v15, v10, v154 dst_sel:DWORD dst_unused:UNUSED_PAD src0_sel:WORD_1 src1_sel:DWORD
	v_add3_u32 v10, v10, v15, s33
	v_add3_u32 v11, v11, v14, s33
	v_and_b32_sdwa v14, v9, v154 dst_sel:DWORD dst_unused:UNUSED_PAD src0_sel:WORD_1 src1_sel:DWORD
	v_and_b32_sdwa v15, v8, v154 dst_sel:DWORD dst_unused:UNUSED_PAD src0_sel:WORD_1 src1_sel:DWORD
	v_add3_u32 v9, v9, v14, s33
	v_add3_u32 v8, v8, v15, s33
	v_and_b32_e32 v9, 0xffff0000, v9
	v_and_b32_e32 v8, 0xffff0000, v8
	v_or_b32_sdwa v9, v9, v11 dst_sel:DWORD dst_unused:UNUSED_PAD src0_sel:DWORD src1_sel:WORD_1
	v_or_b32_sdwa v8, v8, v10 dst_sel:DWORD dst_unused:UNUSED_PAD src0_sel:DWORD src1_sel:WORD_1
	global_store_dwordx2 v[12:13], v[8:9], off offset:32
	global_load_dwordx4 v[8:11], v63, s[36:37] offset:128
	s_waitcnt vmcnt(0)
	v_add_f32_e32 v4, v4, v8
	v_mul_f32_e32 v4, 0xbfb8aa3b, v4
	v_exp_f32_e32 v8, v4
	v_add_f32_e32 v4, v5, v9
	v_add_f32_e32 v5, v6, v10
	v_mul_f32_e32 v5, 0xbfb8aa3b, v5
	v_exp_f32_e32 v9, v5
	v_add_f32_e32 v5, v7, v11
	v_mul_f32_e32 v4, 0xbfb8aa3b, v4
	v_mul_f32_e32 v5, 0xbfb8aa3b, v5
	v_pk_add_f32 v[6:7], v[8:9], 1.0 op_sel_hi:[1,0]
	v_exp_f32_e32 v4, v4
	v_exp_f32_e32 v5, v5
	v_rcp_f32_e32 v7, v7
	v_pk_add_f32 v[4:5], v[4:5], 1.0 op_sel_hi:[1,0]
	v_rcp_f32_e32 v6, v6
	global_load_dwordx2 v[8:9], v[16:17], off offset:64
	s_waitcnt vmcnt(0)
	v_lshlrev_b32_e32 v11, 16, v9
	v_lshlrev_b32_e32 v10, 16, v8
	v_pk_mul_f32 v[6:7], v[6:7], v[10:11]
	v_and_b32_e32 v9, 0xffff0000, v9
	v_and_b32_e32 v8, 0xffff0000, v8
	v_rcp_f32_e32 v5, v5
	s_nop 0
	v_rcp_f32_e32 v4, v4
	s_nop 0
	v_pk_mul_f32 v[4:5], v[4:5], v[8:9]
	v_and_b32_sdwa v8, v7, v154 dst_sel:DWORD dst_unused:UNUSED_PAD src0_sel:WORD_1 src1_sel:DWORD
	v_and_b32_sdwa v9, v6, v154 dst_sel:DWORD dst_unused:UNUSED_PAD src0_sel:WORD_1 src1_sel:DWORD
	v_add3_u32 v6, v6, v9, s33
	v_add3_u32 v7, v7, v8, s33
	v_and_b32_sdwa v8, v5, v154 dst_sel:DWORD dst_unused:UNUSED_PAD src0_sel:WORD_1 src1_sel:DWORD
	v_and_b32_sdwa v9, v4, v154 dst_sel:DWORD dst_unused:UNUSED_PAD src0_sel:WORD_1 src1_sel:DWORD
	v_add3_u32 v5, v5, v8, s33
	v_add3_u32 v4, v4, v9, s33
	v_and_b32_e32 v5, 0xffff0000, v5
	v_and_b32_e32 v4, 0xffff0000, v4
	v_or_b32_sdwa v5, v5, v7 dst_sel:DWORD dst_unused:UNUSED_PAD src0_sel:DWORD src1_sel:WORD_1
	v_or_b32_sdwa v4, v4, v6 dst_sel:DWORD dst_unused:UNUSED_PAD src0_sel:DWORD src1_sel:WORD_1
	global_store_dwordx2 v[12:13], v[4:5], off offset:64
	global_load_dwordx4 v[4:7], v63, s[36:37] offset:192
	s_waitcnt vmcnt(0)
	v_add_f32_e32 v0, v0, v4
	v_mul_f32_e32 v0, 0xbfb8aa3b, v0
	v_exp_f32_e32 v4, v0
	v_add_f32_e32 v0, v1, v5
	v_add_f32_e32 v1, v2, v6
	v_mul_f32_e32 v1, 0xbfb8aa3b, v1
	v_exp_f32_e32 v5, v1
	v_add_f32_e32 v1, v3, v7
	v_mul_f32_e32 v0, 0xbfb8aa3b, v0
	v_mul_f32_e32 v1, 0xbfb8aa3b, v1
	v_pk_add_f32 v[2:3], v[4:5], 1.0 op_sel_hi:[1,0]
	v_exp_f32_e32 v0, v0
	v_exp_f32_e32 v1, v1
	v_rcp_f32_e32 v3, v3
	v_pk_add_f32 v[0:1], v[0:1], 1.0 op_sel_hi:[1,0]
	v_rcp_f32_e32 v2, v2
	global_load_dwordx2 v[4:5], v[16:17], off offset:96
	s_waitcnt vmcnt(0)
	v_lshlrev_b32_e32 v7, 16, v5
	v_lshlrev_b32_e32 v6, 16, v4
	v_pk_mul_f32 v[2:3], v[2:3], v[6:7]
	v_and_b32_e32 v5, 0xffff0000, v5
	v_and_b32_e32 v4, 0xffff0000, v4
	v_rcp_f32_e32 v1, v1
	s_nop 0
	v_rcp_f32_e32 v0, v0
	s_nop 0
	v_pk_mul_f32 v[0:1], v[0:1], v[4:5]
	v_and_b32_sdwa v4, v3, v154 dst_sel:DWORD dst_unused:UNUSED_PAD src0_sel:WORD_1 src1_sel:DWORD
	v_and_b32_sdwa v5, v2, v154 dst_sel:DWORD dst_unused:UNUSED_PAD src0_sel:WORD_1 src1_sel:DWORD
	v_add3_u32 v2, v2, v5, s33
	v_add3_u32 v3, v3, v4, s33
	v_and_b32_sdwa v4, v1, v154 dst_sel:DWORD dst_unused:UNUSED_PAD src0_sel:WORD_1 src1_sel:DWORD
	v_and_b32_sdwa v5, v0, v154 dst_sel:DWORD dst_unused:UNUSED_PAD src0_sel:WORD_1 src1_sel:DWORD
	v_add3_u32 v1, v1, v4, s33
	v_add3_u32 v0, v0, v5, s33
	v_and_b32_e32 v1, 0xffff0000, v1
	v_and_b32_e32 v0, 0xffff0000, v0
	v_or_b32_sdwa v1, v1, v3 dst_sel:DWORD dst_unused:UNUSED_PAD src0_sel:DWORD src1_sel:WORD_1
	v_or_b32_sdwa v0, v0, v2 dst_sel:DWORD dst_unused:UNUSED_PAD src0_sel:DWORD src1_sel:WORD_1
	global_store_dwordx2 v[12:13], v[0:1], off offset:96

.LBB0_582:
	s_add_i32 s7, s5, 1
	s_bitcmp1_b32 s7, 0
	s_cselect_b32 s13, 0x9000, 0
	v_add_u32_e32 v106, s13, v92
	v_lshl_add_u64 v[102:103], v[88:89], 0, s[8:9]
	s_mov_b64 s[14:15], 0x1c9b1080
	v_readfirstlane_b32 s13, v106
	v_add_u32_e32 v107, 0x1000, v106
	v_lshl_add_u64 v[104:105], v[102:103], 0, s[14:15]
	s_mov_b32 m0, s13
	s_mov_b64 s[14:15], 0x1c9c1080
	v_readfirstlane_b32 s13, v107
	v_add_u32_e32 v107, 0x2000, v106
	global_load_lds_dwordx4 v[104:105], off
	v_lshl_add_u64 v[104:105], v[102:103], 0, s[14:15]
	s_mov_b32 m0, s13
	s_mov_b64 s[14:15], 0x1c9d1080
	v_readfirstlane_b32 s13, v107
	v_add_u32_e32 v107, 0x3000, v106
	global_load_lds_dwordx4 v[104:105], off
	v_lshl_add_u64 v[104:105], v[102:103], 0, s[14:15]
	s_mov_b32 m0, s13
	s_mov_b64 s[14:15], 0x1c9e1080
	v_readfirstlane_b32 s13, v107
	global_load_lds_dwordx4 v[104:105], off
	v_lshl_add_u64 v[104:105], v[102:103], 0, s[14:15]
	s_mov_b32 m0, s13
	s_mov_b64 s[14:15], 0x1c9f1080
	global_load_lds_dwordx4 v[104:105], off
	v_add_u32_e32 v104, 0x4000, v106
	v_lshl_add_u64 v[102:103], v[102:103], 0, s[14:15]
	v_readfirstlane_b32 s13, v104
	s_mov_b32 m0, s13
	v_add_u32_e32 v107, 0x5000, v106
	global_load_lds_dwordx4 v[102:103], off
	v_lshl_add_u64 v[102:103], v[90:91], 0, s[8:9]
	s_mov_b64 s[14:15], 0x14b31080
	v_readfirstlane_b32 s13, v107
	v_add_u32_e32 v107, 0x6000, v106
	v_lshl_add_u64 v[104:105], v[102:103], 0, s[14:15]
	s_mov_b32 m0, s13
	s_mov_b64 s[14:15], 0x14b41080
	v_readfirstlane_b32 s13, v107
	v_add_u32_e32 v107, 0x7000, v106
	global_load_lds_dwordx4 v[104:105], off
	v_lshl_add_u64 v[104:105], v[102:103], 0, s[14:15]
	s_mov_b32 m0, s13
	s_mov_b64 s[14:15], 0x14b51080
	v_readfirstlane_b32 s13, v107
	global_load_lds_dwordx4 v[104:105], off
	v_lshl_add_u64 v[104:105], v[102:103], 0, s[14:15]
	s_mov_b32 m0, s13
	s_mov_b64 s[14:15], 0x14b61080
	global_load_lds_dwordx4 v[104:105], off
	v_add_u32_e32 v104, 0x8000, v106
	v_lshl_add_u64 v[102:103], v[102:103], 0, s[14:15]
	v_readfirstlane_b32 s13, v104
	s_mov_b32 m0, s13
	s_bitcmp1_b32 s5, 0
	global_load_lds_dwordx4 v[102:103], off
	s_cselect_b32 s5, 0x9000, 0
	s_add_i32 s5, s5, 0
	v_add_u32_e32 v118, s5, v93
	v_add_u32_e32 v119, v118, v94
	v_add_u32_e32 v156, v118, v95
	ds_read_b128 v[102:105], v119
	ds_read_b128 v[106:109], v119 offset:2048
	ds_read_b128 v[110:113], v119 offset:4096
	ds_read_b128 v[114:117], v119 offset:6144
	ds_read_b128 v[118:121], v119 offset:8192
	ds_read_b128 v[122:125], v156 offset:20480
	ds_read_b128 v[126:129], v156 offset:22528
	ds_read_b128 v[130:133], v156 offset:24576
	ds_read_b128 v[156:159], v156 offset:26624
	v_add_u32_e32 v206, s5, v96
	v_add_u32_e32 v207, v206, v94
	v_add_u32_e32 v208, v206, v95
	ds_read_b128 v[210:213], v207
	ds_read_b128 v[214:217], v207 offset:2048
	ds_read_b128 v[218:221], v207 offset:4096
	ds_read_b128 v[222:225], v207 offset:6144
	ds_read_b128 v[226:229], v207 offset:8192
	ds_read_b128 v[230:233], v208 offset:20480
	ds_read_b128 v[234:237], v208 offset:22528
	ds_read_b128 v[238:241], v208 offset:24576
	ds_read_b128 v[242:245], v208 offset:26624
	s_setprio 1
	s_waitcnt lgkmcnt(9)
	v_mfma_f32_16x16x32_bf16 v[76:79], v[122:125], v[102:105], v[76:79]
	v_mfma_f32_16x16x32_bf16 v[72:75], v[126:129], v[102:105], v[72:75]
	v_mfma_f32_16x16x32_bf16 v[68:71], v[130:133], v[102:105], v[68:71]
	v_mfma_f32_16x16x32_bf16 v[64:67], v[156:159], v[102:105], v[64:67]
	v_mfma_f32_16x16x32_bf16 v[60:63], v[122:125], v[106:109], v[60:63]
	v_mfma_f32_16x16x32_bf16 v[56:59], v[126:129], v[106:109], v[56:59]
	v_mfma_f32_16x16x32_bf16 v[52:55], v[130:133], v[106:109], v[52:55]
	v_mfma_f32_16x16x32_bf16 v[48:51], v[156:159], v[106:109], v[48:51]
	v_mfma_f32_16x16x32_bf16 v[44:47], v[122:125], v[110:113], v[44:47]
	v_mfma_f32_16x16x32_bf16 v[40:43], v[126:129], v[110:113], v[40:43]
	v_mfma_f32_16x16x32_bf16 v[36:39], v[130:133], v[110:113], v[36:39]
	v_mfma_f32_16x16x32_bf16 v[32:35], v[156:159], v[110:113], v[32:35]
	v_mfma_f32_16x16x32_bf16 v[28:31], v[122:125], v[114:117], v[28:31]
	v_mfma_f32_16x16x32_bf16 v[24:27], v[126:129], v[114:117], v[24:27]
	v_mfma_f32_16x16x32_bf16 v[20:23], v[130:133], v[114:117], v[20:23]
	v_mfma_f32_16x16x32_bf16 v[16:19], v[156:159], v[114:117], v[16:19]
	v_mfma_f32_16x16x32_bf16 v[12:15], v[122:125], v[118:121], v[12:15]
	v_mfma_f32_16x16x32_bf16 v[8:11], v[126:129], v[118:121], v[8:11]
	v_mfma_f32_16x16x32_bf16 v[4:7], v[130:133], v[118:121], v[4:7]
	v_mfma_f32_16x16x32_bf16 v[0:3], v[156:159], v[118:121], v[0:3]
	s_setprio 0
	s_setprio 1
	s_waitcnt lgkmcnt(0)
	v_mfma_f32_16x16x32_bf16 v[76:79], v[230:233], v[210:213], v[76:79]
	v_mfma_f32_16x16x32_bf16 v[72:75], v[234:237], v[210:213], v[72:75]
	v_mfma_f32_16x16x32_bf16 v[68:71], v[238:241], v[210:213], v[68:71]
	v_mfma_f32_16x16x32_bf16 v[64:67], v[242:245], v[210:213], v[64:67]
	v_mfma_f32_16x16x32_bf16 v[60:63], v[230:233], v[214:217], v[60:63]
	v_mfma_f32_16x16x32_bf16 v[56:59], v[234:237], v[214:217], v[56:59]
	v_mfma_f32_16x16x32_bf16 v[52:55], v[238:241], v[214:217], v[52:55]
	v_mfma_f32_16x16x32_bf16 v[48:51], v[242:245], v[214:217], v[48:51]
	v_mfma_f32_16x16x32_bf16 v[44:47], v[230:233], v[218:221], v[44:47]
	v_mfma_f32_16x16x32_bf16 v[40:43], v[234:237], v[218:221], v[40:43]
	v_mfma_f32_16x16x32_bf16 v[36:39], v[238:241], v[218:221], v[36:39]
	v_mfma_f32_16x16x32_bf16 v[32:35], v[242:245], v[218:221], v[32:35]
	v_mfma_f32_16x16x32_bf16 v[28:31], v[230:233], v[222:225], v[28:31]
	v_mfma_f32_16x16x32_bf16 v[24:27], v[234:237], v[222:225], v[24:27]
	v_mfma_f32_16x16x32_bf16 v[20:23], v[238:241], v[222:225], v[20:23]
	v_mfma_f32_16x16x32_bf16 v[16:19], v[242:245], v[222:225], v[16:19]
	v_mfma_f32_16x16x32_bf16 v[12:15], v[230:233], v[226:229], v[12:15]
	v_mfma_f32_16x16x32_bf16 v[8:11], v[234:237], v[226:229], v[8:11]
	v_mfma_f32_16x16x32_bf16 v[4:7], v[238:241], v[226:229], v[4:7]
	v_mfma_f32_16x16x32_bf16 v[0:3], v[242:245], v[226:229], v[0:3]
	s_setprio 0
	s_waitcnt vmcnt(0)
	s_add_u32 s8, s8, 0x80
	s_addc_u32 s9, s9, 0
	s_cmpk_lg_i32 s8, 0x780
	s_mov_b32 s5, s7
	s_waitcnt vmcnt(0)
	s_barrier
	s_cbranch_scc1 .LBB0_582
	v_add_u32_e32 v110, v100, v95
	v_add_u32_e32 v130, v100, v94
	ds_read_b128 v[88:91], v110 offset:63488
	ds_read_b128 v[102:105], v110 offset:61440
	ds_read_b128 v[106:109], v110 offset:59392
	ds_read_b128 v[110:113], v110 offset:57344
	ds_read_b128 v[114:117], v130 offset:45056
	ds_read_b128 v[118:121], v130 offset:43008
	ds_read_b128 v[122:125], v130 offset:40960
	ds_read_b128 v[126:129], v130 offset:38912
	ds_read_b128 v[130:133], v130 offset:36864
	s_setprio 1
	s_waitcnt lgkmcnt(0)
	v_mfma_f32_16x16x32_bf16 v[76:79], v[110:113], v[130:133], v[76:79]
	v_mfma_f32_16x16x32_bf16 v[72:75], v[106:109], v[130:133], v[72:75]
	v_mfma_f32_16x16x32_bf16 v[68:71], v[102:105], v[130:133], v[68:71]
	v_mfma_f32_16x16x32_bf16 v[64:67], v[88:91], v[130:133], v[64:67]
	v_mfma_f32_16x16x32_bf16 v[60:63], v[110:113], v[126:129], v[60:63]
	v_mfma_f32_16x16x32_bf16 v[56:59], v[106:109], v[126:129], v[56:59]
	v_mfma_f32_16x16x32_bf16 v[52:55], v[102:105], v[126:129], v[52:55]
	v_mfma_f32_16x16x32_bf16 v[48:51], v[88:91], v[126:129], v[48:51]
	v_mfma_f32_16x16x32_bf16 v[44:47], v[110:113], v[122:125], v[44:47]
	v_mfma_f32_16x16x32_bf16 v[40:43], v[106:109], v[122:125], v[40:43]
	v_mfma_f32_16x16x32_bf16 v[36:39], v[102:105], v[122:125], v[36:39]
	v_mfma_f32_16x16x32_bf16 v[32:35], v[88:91], v[122:125], v[32:35]
	v_mfma_f32_16x16x32_bf16 v[28:31], v[110:113], v[118:121], v[28:31]
	v_mfma_f32_16x16x32_bf16 v[24:27], v[106:109], v[118:121], v[24:27]
	v_mfma_f32_16x16x32_bf16 v[20:23], v[102:105], v[118:121], v[20:23]
	v_mfma_f32_16x16x32_bf16 v[16:19], v[88:91], v[118:121], v[16:19]
	v_mfma_f32_16x16x32_bf16 v[12:15], v[110:113], v[114:117], v[12:15]
	v_mfma_f32_16x16x32_bf16 v[8:11], v[106:109], v[114:117], v[8:11]
	v_mfma_f32_16x16x32_bf16 v[4:7], v[102:105], v[114:117], v[4:7]
	v_mfma_f32_16x16x32_bf16 v[0:3], v[88:91], v[114:117], v[0:3]
	s_setprio 0
	v_add_u32_e32 v114, v101, v94
	v_add_u32_e32 v130, v101, v95
	ds_read_b128 v[88:91], v114 offset:36864
	ds_read_b128 v[102:105], v114 offset:38912
	ds_read_b128 v[106:109], v114 offset:40960
	ds_read_b128 v[110:113], v114 offset:43008
	ds_read_b128 v[114:117], v114 offset:45056
	ds_read_b128 v[118:121], v130 offset:57344
	ds_read_b128 v[122:125], v130 offset:59392
	ds_read_b128 v[126:129], v130 offset:61440
	ds_read_b128 v[130:133], v130 offset:63488
	s_setprio 1
	s_waitcnt lgkmcnt(3)
	v_mfma_f32_16x16x32_bf16 v[76:79], v[118:121], v[88:91], v[76:79]
	s_waitcnt lgkmcnt(2)
	v_mfma_f32_16x16x32_bf16 v[72:75], v[122:125], v[88:91], v[72:75]
	s_waitcnt lgkmcnt(1)
	v_mfma_f32_16x16x32_bf16 v[68:71], v[126:129], v[88:91], v[68:71]
	s_waitcnt lgkmcnt(0)
	v_mfma_f32_16x16x32_bf16 v[64:67], v[130:133], v[88:91], v[64:67]
	v_mfma_f32_16x16x32_bf16 v[60:63], v[118:121], v[102:105], v[60:63]
	v_mfma_f32_16x16x32_bf16 v[56:59], v[122:125], v[102:105], v[56:59]
	v_mfma_f32_16x16x32_bf16 v[88:91], v[126:129], v[102:105], v[52:55]
	v_mfma_f32_16x16x32_bf16 v[48:51], v[130:133], v[102:105], v[48:51]
	v_mfma_f32_16x16x32_bf16 v[44:47], v[118:121], v[106:109], v[44:47]
	v_mfma_f32_16x16x32_bf16 v[40:43], v[122:125], v[106:109], v[40:43]
	v_mfma_f32_16x16x32_bf16 v[36:39], v[126:129], v[106:109], v[36:39]
	v_mfma_f32_16x16x32_bf16 v[32:35], v[130:133], v[106:109], v[32:35]
	v_mfma_f32_16x16x32_bf16 v[28:31], v[118:121], v[110:113], v[28:31]
	v_mfma_f32_16x16x32_bf16 v[24:27], v[122:125], v[110:113], v[24:27]
	v_mfma_f32_16x16x32_bf16 v[20:23], v[126:129], v[110:113], v[20:23]
	v_mfma_f32_16x16x32_bf16 v[16:19], v[130:133], v[110:113], v[16:19]
	v_mfma_f32_16x16x32_bf16 v[12:15], v[118:121], v[114:117], v[12:15]
	v_mfma_f32_16x16x32_bf16 v[8:11], v[122:125], v[114:117], v[8:11]
	v_mfma_f32_16x16x32_bf16 v[4:7], v[126:129], v[114:117], v[4:7]
	v_mfma_f32_16x16x32_bf16 v[0:3], v[130:133], v[114:117], v[0:3]
	s_setprio 0
	v_mov_b32_e32 v52, v97
	s_waitcnt vmcnt(0)
	s_barrier
	s_mov_b32 s8, 0
	v_add_u32_e32 v52, v52, v176
	v_lshrrev_b32_e32 v55, 2, v52
	v_ashrrev_i32_e32 v53, 7, v52
	v_and_b32_e32 v54, 64, v52
	v_and_b32_e32 v55, 12, v55
	v_and_or_b32 v52, v52, 15, s6
	s_movk_i32 s5, 0x50
	s_lshl_b32 s4, s4, 7
	v_mad_u64_u32 v[52:53], s[6:7], v53, s5, v[52:53]
	v_or3_b32 v54, v54, v55, s4
	v_ashrrev_i32_e32 v53, 31, v52
	v_lshlrev_b64 v[52:53], 12, v[52:53]
	v_lshl_add_u64 v[52:53], s[0:1], 0, v[52:53]
	v_ashrrev_i32_e32 v55, 31, v54
	v_lshl_add_u64 v[52:53], v[54:55], 2, v[52:53]
	global_load_dwordx4 v[102:105], v[52:53], off
	s_waitcnt vmcnt(0)
	v_pk_add_f32 v[76:77], v[76:77], v[102:103]
	v_pk_add_f32 v[78:79], v[78:79], v[104:105]
	s_nop 0
	global_store_dwordx4 v[52:53], v[76:79], off
	global_load_dwordx4 v[76:79], v[52:53], off offset:64
	s_waitcnt vmcnt(0)
	v_pk_add_f32 v[72:73], v[72:73], v[76:77]
	v_pk_add_f32 v[74:75], v[74:75], v[78:79]
	s_nop 0
	global_store_dwordx4 v[52:53], v[72:75], off offset:64
	global_load_dwordx4 v[72:75], v[52:53], off offset:128
	s_waitcnt vmcnt(0)
	v_pk_add_f32 v[68:69], v[68:69], v[72:73]
	v_pk_add_f32 v[70:71], v[70:71], v[74:75]
	s_nop 0
	global_store_dwordx4 v[52:53], v[68:71], off offset:128
	global_load_dwordx4 v[68:71], v[52:53], off offset:192
	s_waitcnt vmcnt(0)
	v_pk_add_f32 v[64:65], v[64:65], v[68:69]
	v_pk_add_f32 v[66:67], v[66:67], v[70:71]
	s_nop 0
	global_store_dwordx4 v[52:53], v[64:67], off offset:192
	s_mov_b32 s4, 0x10000
	v_add_co_u32_e32 v54, vcc, s4, v52
	v_lshl_add_u64 v[68:69], v[52:53], 0, s[34:35]
	s_nop 0
	v_addc_co_u32_e32 v55, vcc, 0, v53, vcc
	global_load_dwordx4 v[64:67], v[54:55], off
	s_waitcnt vmcnt(0)
	v_pk_add_f32 v[60:61], v[60:61], v[64:65]
	v_pk_add_f32 v[62:63], v[62:63], v[66:67]
	s_nop 0
	global_store_dwordx4 v[54:55], v[60:63], off
	global_load_dwordx4 v[60:63], v[68:69], off offset:64
	s_waitcnt vmcnt(0)
	v_pk_add_f32 v[54:55], v[56:57], v[60:61]
	v_pk_add_f32 v[56:57], v[58:59], v[62:63]
	s_nop 0
	global_store_dwordx4 v[68:69], v[54:57], off offset:64
	global_load_dwordx4 v[54:57], v[68:69], off offset:128
	s_waitcnt vmcnt(0)
	v_pk_add_f32 v[54:55], v[88:89], v[54:55]
	v_pk_add_f32 v[56:57], v[90:91], v[56:57]
	s_nop 0
	global_store_dwordx4 v[68:69], v[54:57], off offset:128
	global_load_dwordx4 v[54:57], v[68:69], off offset:192
	s_waitcnt vmcnt(0)
	v_pk_add_f32 v[48:49], v[48:49], v[54:55]
	v_pk_add_f32 v[50:51], v[50:51], v[56:57]
	s_nop 0
	global_store_dwordx4 v[68:69], v[48:51], off offset:192
	s_mov_b64 s[4:5], 0x20000
	v_lshl_add_u64 v[54:55], v[52:53], 0, s[4:5]
	s_mov_b32 s4, 0x20000
	v_add_co_u32_e32 v56, vcc, s4, v52
	s_nop 1
	v_addc_co_u32_e32 v57, vcc, 0, v53, vcc
	global_load_dwordx4 v[48:51], v[56:57], off
	s_waitcnt vmcnt(0)
	v_pk_add_f32 v[44:45], v[44:45], v[48:49]
	v_pk_add_f32 v[46:47], v[46:47], v[50:51]
	s_nop 0
	global_store_dwordx4 v[56:57], v[44:47], off
	global_load_dwordx4 v[44:47], v[54:55], off offset:64
	s_waitcnt vmcnt(0)
	v_pk_add_f32 v[40:41], v[40:41], v[44:45]
	v_pk_add_f32 v[42:43], v[42:43], v[46:47]
	s_nop 0
	global_store_dwordx4 v[54:55], v[40:43], off offset:64
	global_load_dwordx4 v[40:43], v[54:55], off offset:128
	s_waitcnt vmcnt(0)
	v_pk_add_f32 v[36:37], v[36:37], v[40:41]
	v_pk_add_f32 v[38:39], v[38:39], v[42:43]
	s_nop 0
	global_store_dwordx4 v[54:55], v[36:39], off offset:128
	global_load_dwordx4 v[36:39], v[54:55], off offset:192
	s_waitcnt vmcnt(0)
	v_pk_add_f32 v[32:33], v[32:33], v[36:37]
	v_pk_add_f32 v[34:35], v[34:35], v[38:39]
	s_nop 0
	global_store_dwordx4 v[54:55], v[32:35], off offset:192
	s_mov_b64 s[4:5], 0x30000
	v_lshl_add_u64 v[36:37], v[52:53], 0, s[4:5]
	s_mov_b32 s4, 0x30000
	v_add_co_u32_e32 v38, vcc, s4, v52
	s_nop 1
	v_addc_co_u32_e32 v39, vcc, 0, v53, vcc
	global_load_dwordx4 v[32:35], v[38:39], off
	s_waitcnt vmcnt(0)
	v_pk_add_f32 v[28:29], v[28:29], v[32:33]
	v_pk_add_f32 v[30:31], v[30:31], v[34:35]
	s_nop 0
	global_store_dwordx4 v[38:39], v[28:31], off
	global_load_dwordx4 v[28:31], v[36:37], off offset:64
	s_waitcnt vmcnt(0)
	v_pk_add_f32 v[24:25], v[24:25], v[28:29]
	v_pk_add_f32 v[26:27], v[26:27], v[30:31]
	s_nop 0
	global_store_dwordx4 v[36:37], v[24:27], off offset:64
	global_load_dwordx4 v[24:27], v[36:37], off offset:128
	s_waitcnt vmcnt(0)
	v_pk_add_f32 v[20:21], v[20:21], v[24:25]
	v_pk_add_f32 v[22:23], v[22:23], v[26:27]
	s_nop 0
	global_store_dwordx4 v[36:37], v[20:23], off offset:128
	global_load_dwordx4 v[20:23], v[36:37], off offset:192
	s_waitcnt vmcnt(0)
	v_pk_add_f32 v[16:17], v[16:17], v[20:21]
	v_pk_add_f32 v[18:19], v[18:19], v[22:23]
	s_nop 0
	global_store_dwordx4 v[36:37], v[16:19], off offset:192
	s_mov_b64 s[4:5], 0x40000
	v_lshl_add_u64 v[20:21], v[52:53], 0, s[4:5]
	s_mov_b32 s4, 0x40000
	v_add_co_u32_e32 v22, vcc, s4, v52
	s_nop 1
	v_addc_co_u32_e32 v23, vcc, 0, v53, vcc
	global_load_dwordx4 v[16:19], v[22:23], off
	s_waitcnt vmcnt(0)
	v_pk_add_f32 v[12:13], v[12:13], v[16:17]
	v_pk_add_f32 v[14:15], v[14:15], v[18:19]
	s_nop 0
	global_store_dwordx4 v[22:23], v[12:15], off
	global_load_dwordx4 v[12:15], v[20:21], off offset:64
	s_waitcnt vmcnt(0)
	v_pk_add_f32 v[8:9], v[8:9], v[12:13]
	v_pk_add_f32 v[10:11], v[10:11], v[14:15]
	s_nop 0
	global_store_dwordx4 v[20:21], v[8:11], off offset:64
	global_load_dwordx4 v[8:11], v[20:21], off offset:128
	s_waitcnt vmcnt(0)
	v_pk_add_f32 v[4:5], v[4:5], v[8:9]
	v_pk_add_f32 v[6:7], v[6:7], v[10:11]
	s_nop 0
	global_store_dwordx4 v[20:21], v[4:7], off offset:128
	global_load_dwordx4 v[4:7], v[20:21], off offset:192
	s_waitcnt vmcnt(0)
	v_pk_add_f32 v[0:1], v[0:1], v[4:5]
	v_pk_add_f32 v[2:3], v[2:3], v[6:7]
	s_nop 0
	global_store_dwordx4 v[20:21], v[0:3], off offset:192
